# loop-edge rotation (7.11): K-loop pointer increments + next-iteration selects + exit test moved from the load segment head into the last MFMA block; compiler vmcnt(0) dropped from 3 K-loop heads
# speedup vs baseline: 1.0052x; 1.0052x over previous
.Llbb_0:
	s_add_i32 s47, s44, 2
	s_add_u32 s4, s42, 0x80
	s_addc_u32 s5, s43, 0
	s_add_i32 s54, 0, 0x10000
	s_cmp_eq_u32 s69, s44
	s_cselect_b32 s45, s13, s5
	s_cselect_b32 s44, s12, s4
	s_cselect_b32 vcc_hi, s1, s11
	s_cselect_b32 vcc_lo, s0, s10
	s_add_i32 s4, 0, 0x14000
	v_add_u32_e32 v140, s54, v223
	v_add_u32_e32 v156, s4, v223
	s_waitcnt lgkmcnt(0)
	ds_read_b128 v[128:131], v140
	ds_read_b128 v[132:135], v140 offset:1024
	ds_read_b128 v[136:139], v140 offset:2048
	ds_read_b128 v[140:143], v140 offset:3072
	ds_read_b128 v[144:147], v156
	ds_read_b128 v[148:151], v156 offset:1024
	ds_read_b128 v[152:155], v156 offset:2048
	ds_read_b128 v[156:159], v156 offset:3072
	v_lshl_add_u64 v[214:215], s[42:43], 0, v[194:195]
	s_add_i32 m0, s59, 0xc000
	ds_read_b128 v[160:163], v228
	ds_read_b128 v[164:167], v228 offset:1024
	ds_read_b128 v[168:171], v228 offset:2048
	ds_read_b128 v[172:175], v228 offset:3072
	ds_read_b128 v[198:201], v228 offset:4096
	ds_read_b128 v[202:205], v228 offset:5120
	ds_read_b128 v[206:209], v228 offset:6144
	ds_read_b128 v[210:213], v228 offset:7168
	global_load_lds_dwordx4 v[214:215], off
	v_lshl_add_u64 v[214:215], s[42:43], 0, v[196:197]
	s_add_i32 m0, s59, 0xe000
	s_nop 0
	global_load_lds_dwordx4 v[214:215], off
	s_waitcnt vmcnt(8)
	s_waitcnt lgkmcnt(0)
	s_barrier
	s_waitcnt lgkmcnt(0)
	v_mfma_f32_16x16x32_bf16 v[120:123], v[128:131], v[160:163], 0
	v_mfma_f32_16x16x32_bf16 v[116:119], v[136:139], v[160:163], 0
	v_mfma_f32_16x16x32_bf16 v[108:111], v[128:131], v[168:171], 0
	v_mfma_f32_16x16x32_bf16 v[100:103], v[136:139], v[168:171], 0
	v_mfma_f32_16x16x32_bf16 v[92:95], v[128:131], v[198:201], 0
	v_mfma_f32_16x16x32_bf16 v[84:87], v[136:139], v[198:201], 0
	v_mfma_f32_16x16x32_bf16 v[76:79], v[128:131], v[206:209], 0
	v_mfma_f32_16x16x32_bf16 v[68:71], v[136:139], v[206:209], 0
	v_mfma_f32_16x16x32_bf16 v[120:123], v[132:135], v[164:167], v[120:123]
	v_mfma_f32_16x16x32_bf16 v[116:119], v[140:143], v[164:167], v[116:119]
	v_mfma_f32_16x16x32_bf16 v[108:111], v[132:135], v[172:175], v[108:111]
	v_mfma_f32_16x16x32_bf16 v[100:103], v[140:143], v[172:175], v[100:103]
	v_mfma_f32_16x16x32_bf16 v[92:95], v[132:135], v[202:205], v[92:95]
	v_mfma_f32_16x16x32_bf16 v[84:87], v[140:143], v[202:205], v[84:87]
	v_mfma_f32_16x16x32_bf16 v[76:79], v[132:135], v[210:213], v[76:79]
	v_mfma_f32_16x16x32_bf16 v[68:71], v[140:143], v[210:213], v[68:71]
	v_mfma_f32_16x16x32_bf16 v[124:127], v[144:147], v[160:163], 0
	v_mfma_f32_16x16x32_bf16 v[112:115], v[152:155], v[160:163], 0
	v_mfma_f32_16x16x32_bf16 v[104:107], v[144:147], v[168:171], 0
	v_mfma_f32_16x16x32_bf16 v[96:99], v[152:155], v[168:171], 0
	v_mfma_f32_16x16x32_bf16 v[88:91], v[144:147], v[198:201], 0
	v_mfma_f32_16x16x32_bf16 v[80:83], v[152:155], v[198:201], 0
	v_mfma_f32_16x16x32_bf16 v[72:75], v[144:147], v[206:209], 0
	v_mfma_f32_16x16x32_bf16 v[64:67], v[152:155], v[206:209], 0
	v_mfma_f32_16x16x32_bf16 v[124:127], v[148:151], v[164:167], v[124:127]
	v_mfma_f32_16x16x32_bf16 v[112:115], v[156:159], v[164:167], v[112:115]
	v_mfma_f32_16x16x32_bf16 v[104:107], v[148:151], v[172:175], v[104:107]
	v_mfma_f32_16x16x32_bf16 v[96:99], v[156:159], v[172:175], v[96:99]
	v_mfma_f32_16x16x32_bf16 v[88:91], v[148:151], v[202:205], v[88:91]
	v_mfma_f32_16x16x32_bf16 v[80:83], v[156:159], v[202:205], v[80:83]
	v_mfma_f32_16x16x32_bf16 v[72:75], v[148:151], v[210:213], v[72:75]
	v_mfma_f32_16x16x32_bf16 v[64:67], v[156:159], v[210:213], v[64:67]
	s_barrier
	s_add_i32 s5, s54, s58
	v_lshl_add_u64 v[214:215], vcc, 0, v[190:191]
	s_mov_b32 m0, s5
	ds_read_b128 v[160:163], v228 offset:16384
	ds_read_b128 v[164:167], v228 offset:17408
	ds_read_b128 v[168:171], v228 offset:18432
	ds_read_b128 v[172:175], v228 offset:19456
	ds_read_b128 v[198:201], v228 offset:20480
	ds_read_b128 v[202:205], v228 offset:21504
	ds_read_b128 v[206:209], v228 offset:22528
	ds_read_b128 v[210:213], v228 offset:23552
	global_load_lds_dwordx4 v[214:215], off
	s_add_i32 m0, s5, 0x2000
	v_lshl_add_u64 v[216:217], vcc, 0, v[186:187]
	s_add_u32 vcc_lo, vcc_lo, s24
	s_addc_u32 vcc_hi, vcc_hi, s25
	s_add_i32 s4, s4, s58
	global_load_lds_dwordx4 v[216:217], off
	v_lshl_add_u64 v[230:231], vcc, 0, v[190:191]
	s_mov_b32 m0, s4
	v_lshl_add_u64 v[232:233], vcc, 0, v[186:187]
	global_load_lds_dwordx4 v[230:231], off
	s_add_i32 m0, s4, 0x2000
	v_lshl_add_u64 v[234:235], s[44:45], 0, v[192:193]
	global_load_lds_dwordx4 v[232:233], off
	s_mov_b32 m0, s59
	v_lshl_add_u64 v[236:237], s[44:45], 0, v[188:189]
	global_load_lds_dwordx4 v[234:235], off
	s_mov_b32 m0, s60
	s_nop 0
	global_load_lds_dwordx4 v[236:237], off
	s_waitcnt vmcnt(8)
	s_waitcnt lgkmcnt(0)
	s_barrier
	s_waitcnt lgkmcnt(0)
	v_mfma_f32_16x16x32_bf16 v[60:63], v[128:131], v[160:163], 0
	v_mfma_f32_16x16x32_bf16 v[52:55], v[136:139], v[160:163], 0
	v_mfma_f32_16x16x32_bf16 v[44:47], v[128:131], v[168:171], 0
	v_mfma_f32_16x16x32_bf16 v[36:39], v[136:139], v[168:171], 0
	v_mfma_f32_16x16x32_bf16 v[28:31], v[128:131], v[198:201], 0
	v_mfma_f32_16x16x32_bf16 v[20:23], v[136:139], v[198:201], 0
	v_mfma_f32_16x16x32_bf16 v[12:15], v[128:131], v[206:209], 0
	v_mfma_f32_16x16x32_bf16 v[4:7], v[136:139], v[206:209], 0
	v_mfma_f32_16x16x32_bf16 v[60:63], v[132:135], v[164:167], v[60:63]
	v_mfma_f32_16x16x32_bf16 v[52:55], v[140:143], v[164:167], v[52:55]
	v_mfma_f32_16x16x32_bf16 v[44:47], v[132:135], v[172:175], v[44:47]
	v_mfma_f32_16x16x32_bf16 v[36:39], v[140:143], v[172:175], v[36:39]
	v_mfma_f32_16x16x32_bf16 v[28:31], v[132:135], v[202:205], v[28:31]
	v_mfma_f32_16x16x32_bf16 v[20:23], v[140:143], v[202:205], v[20:23]
	v_mfma_f32_16x16x32_bf16 v[12:15], v[132:135], v[210:213], v[12:15]
	v_mfma_f32_16x16x32_bf16 v[4:7], v[140:143], v[210:213], v[4:7]
	v_mfma_f32_16x16x32_bf16 v[56:59], v[144:147], v[160:163], 0
	v_mfma_f32_16x16x32_bf16 v[48:51], v[152:155], v[160:163], 0
	v_mfma_f32_16x16x32_bf16 v[40:43], v[144:147], v[168:171], 0
	v_mfma_f32_16x16x32_bf16 v[32:35], v[152:155], v[168:171], 0
	v_mfma_f32_16x16x32_bf16 v[24:27], v[144:147], v[198:201], 0
	v_mfma_f32_16x16x32_bf16 v[16:19], v[152:155], v[198:201], 0
	v_mfma_f32_16x16x32_bf16 v[8:11], v[144:147], v[206:209], 0
	v_mfma_f32_16x16x32_bf16 v[0:3], v[152:155], v[206:209], 0
	v_mfma_f32_16x16x32_bf16 v[56:59], v[148:151], v[164:167], v[56:59]
	v_mfma_f32_16x16x32_bf16 v[48:51], v[156:159], v[164:167], v[48:51]
	v_mfma_f32_16x16x32_bf16 v[40:43], v[148:151], v[172:175], v[40:43]
	v_mfma_f32_16x16x32_bf16 v[32:35], v[156:159], v[172:175], v[32:35]
	v_mfma_f32_16x16x32_bf16 v[24:27], v[148:151], v[202:205], v[24:27]
	v_mfma_f32_16x16x32_bf16 v[16:19], v[156:159], v[202:205], v[16:19]
	v_mfma_f32_16x16x32_bf16 v[8:11], v[148:151], v[210:213], v[8:11]
	v_mfma_f32_16x16x32_bf16 v[0:3], v[156:159], v[210:213], v[0:3]
	s_barrier
	s_add_i32 s4, 0, 0x18000
	s_add_i32 s5, 0, 0x1c000
	v_add_u32_e32 v140, s4, v223
	v_add_u32_e32 v156, s5, v223
	ds_read_b128 v[128:131], v140
	ds_read_b128 v[132:135], v140 offset:1024
	ds_read_b128 v[136:139], v140 offset:2048
	ds_read_b128 v[140:143], v140 offset:3072
	ds_read_b128 v[144:147], v156
	ds_read_b128 v[148:151], v156 offset:1024
	ds_read_b128 v[152:155], v156 offset:2048
	ds_read_b128 v[156:159], v156 offset:3072
	s_add_u32 s44, s44, s24
	s_addc_u32 s45, s45, s25
	s_mov_b32 m0, s61
	v_lshl_add_u64 v[238:239], s[44:45], 0, v[192:193]
	ds_read_b128 v[160:163], v228 offset:32768
	ds_read_b128 v[164:167], v228 offset:33792
	ds_read_b128 v[168:171], v228 offset:34816
	ds_read_b128 v[172:175], v228 offset:35840
	ds_read_b128 v[198:201], v228 offset:36864
	ds_read_b128 v[202:205], v228 offset:37888
	ds_read_b128 v[206:209], v228 offset:38912
	ds_read_b128 v[210:213], v228 offset:39936
	global_load_lds_dwordx4 v[238:239], off
	v_lshl_add_u64 v[238:239], s[44:45], 0, v[188:189]
	s_mov_b32 m0, s62
	s_nop 0
	global_load_lds_dwordx4 v[238:239], off
	s_waitcnt vmcnt(8)
	s_waitcnt lgkmcnt(0)
	s_barrier
	s_waitcnt lgkmcnt(0)
	v_mfma_f32_16x16x32_bf16 v[120:123], v[128:131], v[160:163], v[120:123]
	v_mfma_f32_16x16x32_bf16 v[116:119], v[136:139], v[160:163], v[116:119]
	v_mfma_f32_16x16x32_bf16 v[108:111], v[128:131], v[168:171], v[108:111]
	v_mfma_f32_16x16x32_bf16 v[100:103], v[136:139], v[168:171], v[100:103]
	v_mfma_f32_16x16x32_bf16 v[92:95], v[128:131], v[198:201], v[92:95]
	v_mfma_f32_16x16x32_bf16 v[84:87], v[136:139], v[198:201], v[84:87]
	v_mfma_f32_16x16x32_bf16 v[76:79], v[128:131], v[206:209], v[76:79]
	v_mfma_f32_16x16x32_bf16 v[68:71], v[136:139], v[206:209], v[68:71]
	v_mfma_f32_16x16x32_bf16 v[120:123], v[132:135], v[164:167], v[120:123]
	v_mfma_f32_16x16x32_bf16 v[116:119], v[140:143], v[164:167], v[116:119]
	v_mfma_f32_16x16x32_bf16 v[108:111], v[132:135], v[172:175], v[108:111]
	v_mfma_f32_16x16x32_bf16 v[100:103], v[140:143], v[172:175], v[100:103]
	v_mfma_f32_16x16x32_bf16 v[92:95], v[132:135], v[202:205], v[92:95]
	v_mfma_f32_16x16x32_bf16 v[84:87], v[140:143], v[202:205], v[84:87]
	v_mfma_f32_16x16x32_bf16 v[76:79], v[132:135], v[210:213], v[76:79]
	v_mfma_f32_16x16x32_bf16 v[68:71], v[140:143], v[210:213], v[68:71]
	v_mfma_f32_16x16x32_bf16 v[124:127], v[144:147], v[160:163], v[124:127]
	v_mfma_f32_16x16x32_bf16 v[112:115], v[152:155], v[160:163], v[112:115]
	v_mfma_f32_16x16x32_bf16 v[104:107], v[144:147], v[168:171], v[104:107]
	v_mfma_f32_16x16x32_bf16 v[96:99], v[152:155], v[168:171], v[96:99]
	v_mfma_f32_16x16x32_bf16 v[88:91], v[144:147], v[198:201], v[88:91]
	v_mfma_f32_16x16x32_bf16 v[80:83], v[152:155], v[198:201], v[80:83]
	v_mfma_f32_16x16x32_bf16 v[72:75], v[144:147], v[206:209], v[72:75]
	v_mfma_f32_16x16x32_bf16 v[64:67], v[152:155], v[206:209], v[64:67]
	v_mfma_f32_16x16x32_bf16 v[124:127], v[148:151], v[164:167], v[124:127]
	v_mfma_f32_16x16x32_bf16 v[112:115], v[156:159], v[164:167], v[112:115]
	v_mfma_f32_16x16x32_bf16 v[104:107], v[148:151], v[172:175], v[104:107]
	v_mfma_f32_16x16x32_bf16 v[96:99], v[156:159], v[172:175], v[96:99]
	v_mfma_f32_16x16x32_bf16 v[88:91], v[148:151], v[202:205], v[88:91]
	v_mfma_f32_16x16x32_bf16 v[80:83], v[156:159], v[202:205], v[80:83]
	v_mfma_f32_16x16x32_bf16 v[72:75], v[148:151], v[210:213], v[72:75]
	v_mfma_f32_16x16x32_bf16 v[64:67], v[156:159], v[210:213], v[64:67]
	s_barrier
	s_add_i32 s4, s4, s58
	v_lshl_add_u64 v[214:215], v[214:215], 0, s[14:15]
	s_mov_b32 m0, s4
	ds_read_b128 v[160:163], v228 offset:49152
	ds_read_b128 v[164:167], v228 offset:50176
	ds_read_b128 v[168:171], v228 offset:51200
	ds_read_b128 v[172:175], v228 offset:52224
	ds_read_b128 v[198:201], v228 offset:53248
	ds_read_b128 v[202:205], v228 offset:54272
	ds_read_b128 v[206:209], v228 offset:55296
	ds_read_b128 v[210:213], v228 offset:56320
	global_load_lds_dwordx4 v[214:215], off
	v_lshl_add_u64 v[214:215], v[216:217], 0, s[14:15]
	s_add_i32 m0, s4, 0x2000
	s_add_i32 s4, s5, s58
	global_load_lds_dwordx4 v[214:215], off
	v_lshl_add_u64 v[214:215], v[230:231], 0, s[14:15]
	s_mov_b32 m0, s4
	s_nop 0
	global_load_lds_dwordx4 v[214:215], off
	v_lshl_add_u64 v[214:215], v[232:233], 0, s[14:15]
	s_add_i32 m0, s4, 0x2000
	s_nop 0
	global_load_lds_dwordx4 v[214:215], off
	v_lshl_add_u64 v[214:215], v[234:235], 0, s[14:15]
	s_mov_b32 m0, s63
	s_nop 0
	global_load_lds_dwordx4 v[214:215], off
	v_lshl_add_u64 v[214:215], v[236:237], 0, s[14:15]
	s_mov_b32 m0, s66
	s_nop 0
	global_load_lds_dwordx4 v[214:215], off
	s_waitcnt vmcnt(8)
	s_waitcnt lgkmcnt(0)
	s_barrier
	s_waitcnt lgkmcnt(0)
	v_mfma_f32_16x16x32_bf16 v[60:63], v[128:131], v[160:163], v[60:63]
	s_add_u32 s42, s42, 0x100
	v_mfma_f32_16x16x32_bf16 v[52:55], v[136:139], v[160:163], v[52:55]
	s_addc_u32 s43, s43, 0
	v_mfma_f32_16x16x32_bf16 v[44:47], v[128:131], v[168:171], v[44:47]
	s_add_u32 s10, s10, 0x100
	v_mfma_f32_16x16x32_bf16 v[36:39], v[136:139], v[168:171], v[36:39]
	s_addc_u32 s11, s11, 0
	v_mfma_f32_16x16x32_bf16 v[28:31], v[128:131], v[198:201], v[28:31]
	s_mov_b32 s44, s47
	v_mfma_f32_16x16x32_bf16 v[20:23], v[136:139], v[198:201], v[20:23]
	s_cmp_ge_i32 s47, s67
	v_mfma_f32_16x16x32_bf16 v[12:15], v[128:131], v[206:209], v[12:15]
	s_cselect_b32 s99, 1, 0
	v_mfma_f32_16x16x32_bf16 v[4:7], v[136:139], v[206:209], v[4:7]
	s_add_i32 s47, s44, 2
	v_mfma_f32_16x16x32_bf16 v[60:63], v[132:135], v[164:167], v[60:63]
	s_add_u32 s4, s42, 0x80
	v_mfma_f32_16x16x32_bf16 v[52:55], v[140:143], v[164:167], v[52:55]
	s_addc_u32 s5, s43, 0
	v_mfma_f32_16x16x32_bf16 v[44:47], v[132:135], v[172:175], v[44:47]
	s_add_i32 s54, 0, 0x10000
	v_mfma_f32_16x16x32_bf16 v[36:39], v[140:143], v[172:175], v[36:39]
	s_cmp_eq_u32 s69, s44
	v_mfma_f32_16x16x32_bf16 v[28:31], v[132:135], v[202:205], v[28:31]
	s_cselect_b32 s45, s13, s5
	v_mfma_f32_16x16x32_bf16 v[20:23], v[140:143], v[202:205], v[20:23]
	s_cselect_b32 s44, s12, s4
	v_mfma_f32_16x16x32_bf16 v[12:15], v[132:135], v[210:213], v[12:15]
	s_cselect_b32 vcc_hi, s1, s11
	v_mfma_f32_16x16x32_bf16 v[4:7], v[140:143], v[210:213], v[4:7]
	s_cselect_b32 vcc_lo, s0, s10
	v_mfma_f32_16x16x32_bf16 v[56:59], v[144:147], v[160:163], v[56:59]
	s_add_i32 s4, 0, 0x14000
	v_mfma_f32_16x16x32_bf16 v[48:51], v[152:155], v[160:163], v[48:51]
	v_mfma_f32_16x16x32_bf16 v[40:43], v[144:147], v[168:171], v[40:43]
	v_mfma_f32_16x16x32_bf16 v[32:35], v[152:155], v[168:171], v[32:35]
	v_mfma_f32_16x16x32_bf16 v[24:27], v[144:147], v[198:201], v[24:27]
	v_mfma_f32_16x16x32_bf16 v[16:19], v[152:155], v[198:201], v[16:19]
	v_mfma_f32_16x16x32_bf16 v[8:11], v[144:147], v[206:209], v[8:11]
	v_mfma_f32_16x16x32_bf16 v[0:3], v[152:155], v[206:209], v[0:3]
	v_mfma_f32_16x16x32_bf16 v[56:59], v[148:151], v[164:167], v[56:59]
	v_mfma_f32_16x16x32_bf16 v[48:51], v[156:159], v[164:167], v[48:51]
	v_mfma_f32_16x16x32_bf16 v[40:43], v[148:151], v[172:175], v[40:43]
	v_mfma_f32_16x16x32_bf16 v[32:35], v[156:159], v[172:175], v[32:35]
	v_mfma_f32_16x16x32_bf16 v[24:27], v[148:151], v[202:205], v[24:27]
	v_mfma_f32_16x16x32_bf16 v[16:19], v[156:159], v[202:205], v[16:19]
	v_mfma_f32_16x16x32_bf16 v[8:11], v[148:151], v[210:213], v[8:11]
	v_mfma_f32_16x16x32_bf16 v[0:3], v[156:159], v[210:213], v[0:3]
	s_barrier
	s_cmp_lg_u32 s99, 0
	s_cbranch_scc1 .Lpeelx_4
.LBB0_155:
	v_add_u32_e32 v140, s54, v223
	v_add_u32_e32 v156, s4, v223
	s_waitcnt lgkmcnt(0)
	ds_read_b128 v[128:131], v140
	ds_read_b128 v[132:135], v140 offset:1024
	ds_read_b128 v[136:139], v140 offset:2048
	ds_read_b128 v[140:143], v140 offset:3072
	ds_read_b128 v[144:147], v156
	ds_read_b128 v[148:151], v156 offset:1024
	ds_read_b128 v[152:155], v156 offset:2048
	ds_read_b128 v[156:159], v156 offset:3072
	v_lshl_add_u64 v[214:215], s[42:43], 0, v[194:195]
	s_add_i32 m0, s59, 0xc000
	ds_read_b128 v[160:163], v228
	ds_read_b128 v[164:167], v228 offset:1024
	ds_read_b128 v[168:171], v228 offset:2048
	ds_read_b128 v[172:175], v228 offset:3072
	ds_read_b128 v[198:201], v228 offset:4096
	ds_read_b128 v[202:205], v228 offset:5120
	ds_read_b128 v[206:209], v228 offset:6144
	ds_read_b128 v[210:213], v228 offset:7168
	global_load_lds_dwordx4 v[214:215], off
	v_lshl_add_u64 v[214:215], s[42:43], 0, v[196:197]
	s_add_i32 m0, s59, 0xe000
	s_nop 0
	global_load_lds_dwordx4 v[214:215], off
	s_waitcnt vmcnt(8)
	s_waitcnt lgkmcnt(0)
	s_barrier
	s_waitcnt lgkmcnt(0)
	v_mfma_f32_16x16x32_bf16 v[120:123], v[128:131], v[160:163], v[120:123]
	v_mfma_f32_16x16x32_bf16 v[116:119], v[136:139], v[160:163], v[116:119]
	v_mfma_f32_16x16x32_bf16 v[108:111], v[128:131], v[168:171], v[108:111]
	v_mfma_f32_16x16x32_bf16 v[100:103], v[136:139], v[168:171], v[100:103]
	v_mfma_f32_16x16x32_bf16 v[92:95], v[128:131], v[198:201], v[92:95]
	v_mfma_f32_16x16x32_bf16 v[84:87], v[136:139], v[198:201], v[84:87]
	v_mfma_f32_16x16x32_bf16 v[76:79], v[128:131], v[206:209], v[76:79]
	v_mfma_f32_16x16x32_bf16 v[68:71], v[136:139], v[206:209], v[68:71]
	v_mfma_f32_16x16x32_bf16 v[120:123], v[132:135], v[164:167], v[120:123]
	v_mfma_f32_16x16x32_bf16 v[116:119], v[140:143], v[164:167], v[116:119]
	v_mfma_f32_16x16x32_bf16 v[108:111], v[132:135], v[172:175], v[108:111]
	v_mfma_f32_16x16x32_bf16 v[100:103], v[140:143], v[172:175], v[100:103]
	v_mfma_f32_16x16x32_bf16 v[92:95], v[132:135], v[202:205], v[92:95]
	v_mfma_f32_16x16x32_bf16 v[84:87], v[140:143], v[202:205], v[84:87]
	v_mfma_f32_16x16x32_bf16 v[76:79], v[132:135], v[210:213], v[76:79]
	v_mfma_f32_16x16x32_bf16 v[68:71], v[140:143], v[210:213], v[68:71]
	v_mfma_f32_16x16x32_bf16 v[124:127], v[144:147], v[160:163], v[124:127]
	v_mfma_f32_16x16x32_bf16 v[112:115], v[152:155], v[160:163], v[112:115]
	v_mfma_f32_16x16x32_bf16 v[104:107], v[144:147], v[168:171], v[104:107]
	v_mfma_f32_16x16x32_bf16 v[96:99], v[152:155], v[168:171], v[96:99]
	v_mfma_f32_16x16x32_bf16 v[88:91], v[144:147], v[198:201], v[88:91]
	v_mfma_f32_16x16x32_bf16 v[80:83], v[152:155], v[198:201], v[80:83]
	v_mfma_f32_16x16x32_bf16 v[72:75], v[144:147], v[206:209], v[72:75]
	v_mfma_f32_16x16x32_bf16 v[64:67], v[152:155], v[206:209], v[64:67]
	v_mfma_f32_16x16x32_bf16 v[124:127], v[148:151], v[164:167], v[124:127]
	v_mfma_f32_16x16x32_bf16 v[112:115], v[156:159], v[164:167], v[112:115]
	v_mfma_f32_16x16x32_bf16 v[104:107], v[148:151], v[172:175], v[104:107]
	v_mfma_f32_16x16x32_bf16 v[96:99], v[156:159], v[172:175], v[96:99]
	v_mfma_f32_16x16x32_bf16 v[88:91], v[148:151], v[202:205], v[88:91]
	v_mfma_f32_16x16x32_bf16 v[80:83], v[156:159], v[202:205], v[80:83]
	v_mfma_f32_16x16x32_bf16 v[72:75], v[148:151], v[210:213], v[72:75]
	v_mfma_f32_16x16x32_bf16 v[64:67], v[156:159], v[210:213], v[64:67]
	s_barrier
	s_add_i32 s5, s54, s58
	v_lshl_add_u64 v[214:215], vcc, 0, v[190:191]
	s_mov_b32 m0, s5
	ds_read_b128 v[160:163], v228 offset:16384
	ds_read_b128 v[164:167], v228 offset:17408
	ds_read_b128 v[168:171], v228 offset:18432
	ds_read_b128 v[172:175], v228 offset:19456
	ds_read_b128 v[198:201], v228 offset:20480
	ds_read_b128 v[202:205], v228 offset:21504
	ds_read_b128 v[206:209], v228 offset:22528
	ds_read_b128 v[210:213], v228 offset:23552
	global_load_lds_dwordx4 v[214:215], off
	s_add_i32 m0, s5, 0x2000
	v_lshl_add_u64 v[216:217], vcc, 0, v[186:187]
	s_add_u32 vcc_lo, vcc_lo, s24
	s_addc_u32 vcc_hi, vcc_hi, s25
	s_add_i32 s4, s4, s58
	global_load_lds_dwordx4 v[216:217], off
	v_lshl_add_u64 v[230:231], vcc, 0, v[190:191]
	s_mov_b32 m0, s4
	v_lshl_add_u64 v[232:233], vcc, 0, v[186:187]
	global_load_lds_dwordx4 v[230:231], off
	s_add_i32 m0, s4, 0x2000
	v_lshl_add_u64 v[234:235], s[44:45], 0, v[192:193]
	global_load_lds_dwordx4 v[232:233], off
	s_mov_b32 m0, s59
	v_lshl_add_u64 v[236:237], s[44:45], 0, v[188:189]
	global_load_lds_dwordx4 v[234:235], off
	s_mov_b32 m0, s60
	s_nop 0
	global_load_lds_dwordx4 v[236:237], off
	s_waitcnt vmcnt(8)
	s_waitcnt lgkmcnt(0)
	s_barrier
	s_waitcnt lgkmcnt(0)
	v_mfma_f32_16x16x32_bf16 v[60:63], v[128:131], v[160:163], v[60:63]
	v_mfma_f32_16x16x32_bf16 v[52:55], v[136:139], v[160:163], v[52:55]
	v_mfma_f32_16x16x32_bf16 v[44:47], v[128:131], v[168:171], v[44:47]
	v_mfma_f32_16x16x32_bf16 v[36:39], v[136:139], v[168:171], v[36:39]
	v_mfma_f32_16x16x32_bf16 v[28:31], v[128:131], v[198:201], v[28:31]
	v_mfma_f32_16x16x32_bf16 v[20:23], v[136:139], v[198:201], v[20:23]
	v_mfma_f32_16x16x32_bf16 v[12:15], v[128:131], v[206:209], v[12:15]
	v_mfma_f32_16x16x32_bf16 v[4:7], v[136:139], v[206:209], v[4:7]
	v_mfma_f32_16x16x32_bf16 v[60:63], v[132:135], v[164:167], v[60:63]
	v_mfma_f32_16x16x32_bf16 v[52:55], v[140:143], v[164:167], v[52:55]
	v_mfma_f32_16x16x32_bf16 v[44:47], v[132:135], v[172:175], v[44:47]
	v_mfma_f32_16x16x32_bf16 v[36:39], v[140:143], v[172:175], v[36:39]
	v_mfma_f32_16x16x32_bf16 v[28:31], v[132:135], v[202:205], v[28:31]
	v_mfma_f32_16x16x32_bf16 v[20:23], v[140:143], v[202:205], v[20:23]
	v_mfma_f32_16x16x32_bf16 v[12:15], v[132:135], v[210:213], v[12:15]
	v_mfma_f32_16x16x32_bf16 v[4:7], v[140:143], v[210:213], v[4:7]
	v_mfma_f32_16x16x32_bf16 v[56:59], v[144:147], v[160:163], v[56:59]
	v_mfma_f32_16x16x32_bf16 v[48:51], v[152:155], v[160:163], v[48:51]
	v_mfma_f32_16x16x32_bf16 v[40:43], v[144:147], v[168:171], v[40:43]
	v_mfma_f32_16x16x32_bf16 v[32:35], v[152:155], v[168:171], v[32:35]
	v_mfma_f32_16x16x32_bf16 v[24:27], v[144:147], v[198:201], v[24:27]
	v_mfma_f32_16x16x32_bf16 v[16:19], v[152:155], v[198:201], v[16:19]
	v_mfma_f32_16x16x32_bf16 v[8:11], v[144:147], v[206:209], v[8:11]
	v_mfma_f32_16x16x32_bf16 v[0:3], v[152:155], v[206:209], v[0:3]
	v_mfma_f32_16x16x32_bf16 v[56:59], v[148:151], v[164:167], v[56:59]
	v_mfma_f32_16x16x32_bf16 v[48:51], v[156:159], v[164:167], v[48:51]
	v_mfma_f32_16x16x32_bf16 v[40:43], v[148:151], v[172:175], v[40:43]
	v_mfma_f32_16x16x32_bf16 v[32:35], v[156:159], v[172:175], v[32:35]
	v_mfma_f32_16x16x32_bf16 v[24:27], v[148:151], v[202:205], v[24:27]
	v_mfma_f32_16x16x32_bf16 v[16:19], v[156:159], v[202:205], v[16:19]
	v_mfma_f32_16x16x32_bf16 v[8:11], v[148:151], v[210:213], v[8:11]
	v_mfma_f32_16x16x32_bf16 v[0:3], v[156:159], v[210:213], v[0:3]
	s_barrier
	s_add_i32 s4, 0, 0x18000
	s_add_i32 s5, 0, 0x1c000
	v_add_u32_e32 v140, s4, v223
	v_add_u32_e32 v156, s5, v223
	ds_read_b128 v[128:131], v140
	ds_read_b128 v[132:135], v140 offset:1024
	ds_read_b128 v[136:139], v140 offset:2048
	ds_read_b128 v[140:143], v140 offset:3072
	ds_read_b128 v[144:147], v156
	ds_read_b128 v[148:151], v156 offset:1024
	ds_read_b128 v[152:155], v156 offset:2048
	ds_read_b128 v[156:159], v156 offset:3072
	s_add_u32 s44, s44, s24
	s_addc_u32 s45, s45, s25
	s_mov_b32 m0, s61
	v_lshl_add_u64 v[238:239], s[44:45], 0, v[192:193]
	ds_read_b128 v[160:163], v228 offset:32768
	ds_read_b128 v[164:167], v228 offset:33792
	ds_read_b128 v[168:171], v228 offset:34816
	ds_read_b128 v[172:175], v228 offset:35840
	ds_read_b128 v[198:201], v228 offset:36864
	ds_read_b128 v[202:205], v228 offset:37888
	ds_read_b128 v[206:209], v228 offset:38912
	ds_read_b128 v[210:213], v228 offset:39936
	global_load_lds_dwordx4 v[238:239], off
	v_lshl_add_u64 v[238:239], s[44:45], 0, v[188:189]
	s_mov_b32 m0, s62
	s_nop 0
	global_load_lds_dwordx4 v[238:239], off
	s_waitcnt vmcnt(8)
	s_waitcnt lgkmcnt(0)
	s_barrier
	s_waitcnt lgkmcnt(0)
	v_mfma_f32_16x16x32_bf16 v[120:123], v[128:131], v[160:163], v[120:123]
	v_mfma_f32_16x16x32_bf16 v[116:119], v[136:139], v[160:163], v[116:119]
	v_mfma_f32_16x16x32_bf16 v[108:111], v[128:131], v[168:171], v[108:111]
	v_mfma_f32_16x16x32_bf16 v[100:103], v[136:139], v[168:171], v[100:103]
	v_mfma_f32_16x16x32_bf16 v[92:95], v[128:131], v[198:201], v[92:95]
	v_mfma_f32_16x16x32_bf16 v[84:87], v[136:139], v[198:201], v[84:87]
	v_mfma_f32_16x16x32_bf16 v[76:79], v[128:131], v[206:209], v[76:79]
	v_mfma_f32_16x16x32_bf16 v[68:71], v[136:139], v[206:209], v[68:71]
	v_mfma_f32_16x16x32_bf16 v[120:123], v[132:135], v[164:167], v[120:123]
	v_mfma_f32_16x16x32_bf16 v[116:119], v[140:143], v[164:167], v[116:119]
	v_mfma_f32_16x16x32_bf16 v[108:111], v[132:135], v[172:175], v[108:111]
	v_mfma_f32_16x16x32_bf16 v[100:103], v[140:143], v[172:175], v[100:103]
	v_mfma_f32_16x16x32_bf16 v[92:95], v[132:135], v[202:205], v[92:95]
	v_mfma_f32_16x16x32_bf16 v[84:87], v[140:143], v[202:205], v[84:87]
	v_mfma_f32_16x16x32_bf16 v[76:79], v[132:135], v[210:213], v[76:79]
	v_mfma_f32_16x16x32_bf16 v[68:71], v[140:143], v[210:213], v[68:71]
	v_mfma_f32_16x16x32_bf16 v[124:127], v[144:147], v[160:163], v[124:127]
	v_mfma_f32_16x16x32_bf16 v[112:115], v[152:155], v[160:163], v[112:115]
	v_mfma_f32_16x16x32_bf16 v[104:107], v[144:147], v[168:171], v[104:107]
	v_mfma_f32_16x16x32_bf16 v[96:99], v[152:155], v[168:171], v[96:99]
	v_mfma_f32_16x16x32_bf16 v[88:91], v[144:147], v[198:201], v[88:91]
	v_mfma_f32_16x16x32_bf16 v[80:83], v[152:155], v[198:201], v[80:83]
	v_mfma_f32_16x16x32_bf16 v[72:75], v[144:147], v[206:209], v[72:75]
	v_mfma_f32_16x16x32_bf16 v[64:67], v[152:155], v[206:209], v[64:67]
	v_mfma_f32_16x16x32_bf16 v[124:127], v[148:151], v[164:167], v[124:127]
	v_mfma_f32_16x16x32_bf16 v[112:115], v[156:159], v[164:167], v[112:115]
	v_mfma_f32_16x16x32_bf16 v[104:107], v[148:151], v[172:175], v[104:107]
	v_mfma_f32_16x16x32_bf16 v[96:99], v[156:159], v[172:175], v[96:99]
	v_mfma_f32_16x16x32_bf16 v[88:91], v[148:151], v[202:205], v[88:91]
	v_mfma_f32_16x16x32_bf16 v[80:83], v[156:159], v[202:205], v[80:83]
	v_mfma_f32_16x16x32_bf16 v[72:75], v[148:151], v[210:213], v[72:75]
	v_mfma_f32_16x16x32_bf16 v[64:67], v[156:159], v[210:213], v[64:67]
	s_barrier
	s_add_i32 s4, s4, s58
	v_lshl_add_u64 v[214:215], v[214:215], 0, s[14:15]
	s_mov_b32 m0, s4
	ds_read_b128 v[160:163], v228 offset:49152
	ds_read_b128 v[164:167], v228 offset:50176
	ds_read_b128 v[168:171], v228 offset:51200
	ds_read_b128 v[172:175], v228 offset:52224
	ds_read_b128 v[198:201], v228 offset:53248
	ds_read_b128 v[202:205], v228 offset:54272
	ds_read_b128 v[206:209], v228 offset:55296
	ds_read_b128 v[210:213], v228 offset:56320
	global_load_lds_dwordx4 v[214:215], off
	v_lshl_add_u64 v[214:215], v[216:217], 0, s[14:15]
	s_add_i32 m0, s4, 0x2000
	s_add_i32 s4, s5, s58
	global_load_lds_dwordx4 v[214:215], off
	v_lshl_add_u64 v[214:215], v[230:231], 0, s[14:15]
	s_mov_b32 m0, s4
	s_nop 0
	global_load_lds_dwordx4 v[214:215], off
	v_lshl_add_u64 v[214:215], v[232:233], 0, s[14:15]
	s_add_i32 m0, s4, 0x2000
	s_nop 0
	global_load_lds_dwordx4 v[214:215], off
	v_lshl_add_u64 v[214:215], v[234:235], 0, s[14:15]
	s_mov_b32 m0, s63
	s_nop 0
	global_load_lds_dwordx4 v[214:215], off
	v_lshl_add_u64 v[214:215], v[236:237], 0, s[14:15]
	s_mov_b32 m0, s66
	s_nop 0
	global_load_lds_dwordx4 v[214:215], off
	s_waitcnt vmcnt(8)
	s_waitcnt lgkmcnt(0)
	s_barrier
	s_waitcnt lgkmcnt(0)
	v_mfma_f32_16x16x32_bf16 v[60:63], v[128:131], v[160:163], v[60:63]
	s_add_u32 s42, s42, 0x100
	v_mfma_f32_16x16x32_bf16 v[52:55], v[136:139], v[160:163], v[52:55]
	s_addc_u32 s43, s43, 0
	v_mfma_f32_16x16x32_bf16 v[44:47], v[128:131], v[168:171], v[44:47]
	s_add_u32 s10, s10, 0x100
	v_mfma_f32_16x16x32_bf16 v[36:39], v[136:139], v[168:171], v[36:39]
	s_addc_u32 s11, s11, 0
	v_mfma_f32_16x16x32_bf16 v[28:31], v[128:131], v[198:201], v[28:31]
	s_mov_b32 s44, s47
	v_mfma_f32_16x16x32_bf16 v[20:23], v[136:139], v[198:201], v[20:23]
	s_cmp_ge_i32 s47, s67
	v_mfma_f32_16x16x32_bf16 v[12:15], v[128:131], v[206:209], v[12:15]
	s_cselect_b32 s99, 1, 0
	v_mfma_f32_16x16x32_bf16 v[4:7], v[136:139], v[206:209], v[4:7]
	s_add_i32 s47, s44, 2
	v_mfma_f32_16x16x32_bf16 v[60:63], v[132:135], v[164:167], v[60:63]
	s_add_u32 s4, s42, 0x80
	v_mfma_f32_16x16x32_bf16 v[52:55], v[140:143], v[164:167], v[52:55]
	s_addc_u32 s5, s43, 0
	v_mfma_f32_16x16x32_bf16 v[44:47], v[132:135], v[172:175], v[44:47]
	s_add_i32 s54, 0, 0x10000
	v_mfma_f32_16x16x32_bf16 v[36:39], v[140:143], v[172:175], v[36:39]
	s_cmp_eq_u32 s69, s44
	v_mfma_f32_16x16x32_bf16 v[28:31], v[132:135], v[202:205], v[28:31]
	s_cselect_b32 s45, s13, s5
	v_mfma_f32_16x16x32_bf16 v[20:23], v[140:143], v[202:205], v[20:23]
	s_cselect_b32 s44, s12, s4
	v_mfma_f32_16x16x32_bf16 v[12:15], v[132:135], v[210:213], v[12:15]
	s_cselect_b32 vcc_hi, s1, s11
	v_mfma_f32_16x16x32_bf16 v[4:7], v[140:143], v[210:213], v[4:7]
	s_cselect_b32 vcc_lo, s0, s10
	v_mfma_f32_16x16x32_bf16 v[56:59], v[144:147], v[160:163], v[56:59]
	s_add_i32 s4, 0, 0x14000
	v_mfma_f32_16x16x32_bf16 v[48:51], v[152:155], v[160:163], v[48:51]
	v_mfma_f32_16x16x32_bf16 v[40:43], v[144:147], v[168:171], v[40:43]
	v_mfma_f32_16x16x32_bf16 v[32:35], v[152:155], v[168:171], v[32:35]
	v_mfma_f32_16x16x32_bf16 v[24:27], v[144:147], v[198:201], v[24:27]
	v_mfma_f32_16x16x32_bf16 v[16:19], v[152:155], v[198:201], v[16:19]
	v_mfma_f32_16x16x32_bf16 v[8:11], v[144:147], v[206:209], v[8:11]
	v_mfma_f32_16x16x32_bf16 v[0:3], v[152:155], v[206:209], v[0:3]
	v_mfma_f32_16x16x32_bf16 v[56:59], v[148:151], v[164:167], v[56:59]
	v_mfma_f32_16x16x32_bf16 v[48:51], v[156:159], v[164:167], v[48:51]
	v_mfma_f32_16x16x32_bf16 v[40:43], v[148:151], v[172:175], v[40:43]
	v_mfma_f32_16x16x32_bf16 v[32:35], v[156:159], v[172:175], v[32:35]
	v_mfma_f32_16x16x32_bf16 v[24:27], v[148:151], v[202:205], v[24:27]
	v_mfma_f32_16x16x32_bf16 v[16:19], v[156:159], v[202:205], v[16:19]
	v_mfma_f32_16x16x32_bf16 v[8:11], v[148:151], v[210:213], v[8:11]
	v_mfma_f32_16x16x32_bf16 v[0:3], v[156:159], v[210:213], v[0:3]
	s_barrier
	s_cmp_lg_u32 s99, 0
	s_cbranch_scc0 .LBB0_155

.Llbb_1:
	s_add_i32 s44, s34, 2
	s_add_u32 s4, s30, 0x80
	s_addc_u32 s5, s31, 0
	s_add_i32 s45, 0, 0x10000
	s_cmp_eq_u32 s62, s34
	s_cselect_b32 s35, s27, s5
	s_cselect_b32 s34, s26, s4
	s_cselect_b32 s5, s29, s11
	s_cselect_b32 s4, s28, s10
	s_add_i32 s54, 0, 0x14000
	v_add_u32_e32 v140, s45, v195
	v_add_u32_e32 v166, s54, v195
	ds_read_b128 v[128:131], v140
	ds_read_b128 v[132:135], v140 offset:1024
	ds_read_b128 v[136:139], v140 offset:2048
	ds_read_b128 v[140:143], v140 offset:3072
	ds_read_b128 v[144:147], v166
	ds_read_b128 v[148:151], v166 offset:1024
	ds_read_b128 v[152:155], v166 offset:2048
	ds_read_b128 v[166:169], v166 offset:3072
	v_lshl_add_u64 v[174:175], s[30:31], 0, v[162:163]
	s_add_i32 m0, s38, 0xc000
	ds_read_b128 v[170:173], v197
	ds_read_b128 v[186:189], v197 offset:1024
	ds_read_b128 v[190:193], v197 offset:2048
	ds_read_b128 v[198:201], v197 offset:3072
	ds_read_b128 v[202:205], v197 offset:4096
	ds_read_b128 v[206:209], v197 offset:5120
	ds_read_b128 v[210:213], v197 offset:6144
	ds_read_b128 v[214:217], v197 offset:7168
	global_load_lds_dwordx4 v[174:175], off
	v_lshl_add_u64 v[174:175], s[30:31], 0, v[164:165]
	s_add_i32 m0, s38, 0xe000
	s_nop 0
	global_load_lds_dwordx4 v[174:175], off
	s_waitcnt vmcnt(8)
	s_waitcnt lgkmcnt(0)
	s_barrier
	s_waitcnt lgkmcnt(0)
	v_mfma_f32_16x16x32_bf16 v[120:123], v[128:131], v[170:173], 0
	v_mfma_f32_16x16x32_bf16 v[124:127], v[136:139], v[170:173], 0
	v_mfma_f32_16x16x32_bf16 v[108:111], v[128:131], v[190:193], 0
	v_mfma_f32_16x16x32_bf16 v[104:107], v[136:139], v[190:193], 0
	v_mfma_f32_16x16x32_bf16 v[92:95], v[128:131], v[202:205], 0
	v_mfma_f32_16x16x32_bf16 v[88:91], v[136:139], v[202:205], 0
	v_mfma_f32_16x16x32_bf16 v[76:79], v[128:131], v[210:213], 0
	v_mfma_f32_16x16x32_bf16 v[72:75], v[136:139], v[210:213], 0
	v_mfma_f32_16x16x32_bf16 v[120:123], v[132:135], v[186:189], v[120:123]
	v_mfma_f32_16x16x32_bf16 v[124:127], v[140:143], v[186:189], v[124:127]
	v_mfma_f32_16x16x32_bf16 v[108:111], v[132:135], v[198:201], v[108:111]
	v_mfma_f32_16x16x32_bf16 v[104:107], v[140:143], v[198:201], v[104:107]
	v_mfma_f32_16x16x32_bf16 v[92:95], v[132:135], v[206:209], v[92:95]
	v_mfma_f32_16x16x32_bf16 v[88:91], v[140:143], v[206:209], v[88:91]
	v_mfma_f32_16x16x32_bf16 v[76:79], v[132:135], v[214:217], v[76:79]
	v_mfma_f32_16x16x32_bf16 v[72:75], v[140:143], v[214:217], v[72:75]
	v_mfma_f32_16x16x32_bf16 v[116:119], v[144:147], v[170:173], 0
	v_mfma_f32_16x16x32_bf16 v[112:115], v[152:155], v[170:173], 0
	v_mfma_f32_16x16x32_bf16 v[100:103], v[144:147], v[190:193], 0
	v_mfma_f32_16x16x32_bf16 v[96:99], v[152:155], v[190:193], 0
	v_mfma_f32_16x16x32_bf16 v[84:87], v[144:147], v[202:205], 0
	v_mfma_f32_16x16x32_bf16 v[80:83], v[152:155], v[202:205], 0
	v_mfma_f32_16x16x32_bf16 v[68:71], v[144:147], v[210:213], 0
	v_mfma_f32_16x16x32_bf16 v[64:67], v[152:155], v[210:213], 0
	v_mfma_f32_16x16x32_bf16 v[116:119], v[148:151], v[186:189], v[116:119]
	v_mfma_f32_16x16x32_bf16 v[112:115], v[166:169], v[186:189], v[112:115]
	v_mfma_f32_16x16x32_bf16 v[100:103], v[148:151], v[198:201], v[100:103]
	v_mfma_f32_16x16x32_bf16 v[96:99], v[166:169], v[198:201], v[96:99]
	v_mfma_f32_16x16x32_bf16 v[84:87], v[148:151], v[206:209], v[84:87]
	v_mfma_f32_16x16x32_bf16 v[80:83], v[166:169], v[206:209], v[80:83]
	v_mfma_f32_16x16x32_bf16 v[68:71], v[148:151], v[214:217], v[68:71]
	v_mfma_f32_16x16x32_bf16 v[64:67], v[166:169], v[214:217], v[64:67]
	s_barrier
	s_add_i32 s45, s45, s37
	v_lshl_add_u64 v[174:175], s[4:5], 0, v[176:177]
	s_mov_b32 m0, s45
	ds_read_b128 v[170:173], v197 offset:16384
	ds_read_b128 v[186:189], v197 offset:17408
	ds_read_b128 v[190:193], v197 offset:18432
	ds_read_b128 v[198:201], v197 offset:19456
	ds_read_b128 v[202:205], v197 offset:20480
	ds_read_b128 v[206:209], v197 offset:21504
	ds_read_b128 v[210:213], v197 offset:22528
	ds_read_b128 v[214:217], v197 offset:23552
	global_load_lds_dwordx4 v[174:175], off
	s_add_i32 m0, s45, 0x2000
	v_lshl_add_u64 v[222:223], s[4:5], 0, v[156:157]
	s_add_u32 s4, s4, s0
	s_addc_u32 s5, s5, s1
	s_add_i32 s45, s54, s37
	global_load_lds_dwordx4 v[222:223], off
	v_lshl_add_u64 v[224:225], s[4:5], 0, v[176:177]
	s_mov_b32 m0, s45
	v_lshl_add_u64 v[226:227], s[4:5], 0, v[156:157]
	global_load_lds_dwordx4 v[224:225], off
	s_add_i32 m0, s45, 0x2000
	v_lshl_add_u64 v[228:229], s[34:35], 0, v[160:161]
	global_load_lds_dwordx4 v[226:227], off
	s_mov_b32 m0, s38
	v_lshl_add_u64 v[230:231], s[34:35], 0, v[158:159]
	global_load_lds_dwordx4 v[228:229], off
	s_mov_b32 m0, s39
	s_nop 0
	global_load_lds_dwordx4 v[230:231], off
	s_waitcnt vmcnt(8)
	s_waitcnt lgkmcnt(0)
	s_barrier
	s_waitcnt lgkmcnt(0)
	v_mfma_f32_16x16x32_bf16 v[60:63], v[128:131], v[170:173], 0
	v_mfma_f32_16x16x32_bf16 v[56:59], v[136:139], v[170:173], 0
	v_mfma_f32_16x16x32_bf16 v[44:47], v[128:131], v[190:193], 0
	v_mfma_f32_16x16x32_bf16 v[40:43], v[136:139], v[190:193], 0
	v_mfma_f32_16x16x32_bf16 v[28:31], v[128:131], v[202:205], 0
	v_mfma_f32_16x16x32_bf16 v[24:27], v[136:139], v[202:205], 0
	v_mfma_f32_16x16x32_bf16 v[12:15], v[128:131], v[210:213], 0
	v_mfma_f32_16x16x32_bf16 v[8:11], v[136:139], v[210:213], 0
	v_mfma_f32_16x16x32_bf16 v[60:63], v[132:135], v[186:189], v[60:63]
	v_mfma_f32_16x16x32_bf16 v[56:59], v[140:143], v[186:189], v[56:59]
	v_mfma_f32_16x16x32_bf16 v[44:47], v[132:135], v[198:201], v[44:47]
	v_mfma_f32_16x16x32_bf16 v[40:43], v[140:143], v[198:201], v[40:43]
	v_mfma_f32_16x16x32_bf16 v[28:31], v[132:135], v[206:209], v[28:31]
	v_mfma_f32_16x16x32_bf16 v[24:27], v[140:143], v[206:209], v[24:27]
	v_mfma_f32_16x16x32_bf16 v[12:15], v[132:135], v[214:217], v[12:15]
	v_mfma_f32_16x16x32_bf16 v[8:11], v[140:143], v[214:217], v[8:11]
	v_mfma_f32_16x16x32_bf16 v[52:55], v[144:147], v[170:173], 0
	v_mfma_f32_16x16x32_bf16 v[48:51], v[152:155], v[170:173], 0
	v_mfma_f32_16x16x32_bf16 v[36:39], v[144:147], v[190:193], 0
	v_mfma_f32_16x16x32_bf16 v[32:35], v[152:155], v[190:193], 0
	v_mfma_f32_16x16x32_bf16 v[20:23], v[144:147], v[202:205], 0
	v_mfma_f32_16x16x32_bf16 v[16:19], v[152:155], v[202:205], 0
	v_mfma_f32_16x16x32_bf16 v[4:7], v[144:147], v[210:213], 0
	v_mfma_f32_16x16x32_bf16 v[0:3], v[152:155], v[210:213], 0
	v_mfma_f32_16x16x32_bf16 v[52:55], v[148:151], v[186:189], v[52:55]
	v_mfma_f32_16x16x32_bf16 v[48:51], v[166:169], v[186:189], v[48:51]
	v_mfma_f32_16x16x32_bf16 v[36:39], v[148:151], v[198:201], v[36:39]
	v_mfma_f32_16x16x32_bf16 v[32:35], v[166:169], v[198:201], v[32:35]
	v_mfma_f32_16x16x32_bf16 v[20:23], v[148:151], v[206:209], v[20:23]
	v_mfma_f32_16x16x32_bf16 v[16:19], v[166:169], v[206:209], v[16:19]
	v_mfma_f32_16x16x32_bf16 v[4:7], v[148:151], v[214:217], v[4:7]
	v_mfma_f32_16x16x32_bf16 v[0:3], v[166:169], v[214:217], v[0:3]
	s_barrier
	s_add_i32 s45, 0, 0x18000
	s_add_i32 s54, 0, 0x1c000
	v_add_u32_e32 v140, s45, v195
	v_add_u32_e32 v166, s54, v195
	ds_read_b128 v[128:131], v140
	ds_read_b128 v[132:135], v140 offset:1024
	ds_read_b128 v[136:139], v140 offset:2048
	ds_read_b128 v[140:143], v140 offset:3072
	ds_read_b128 v[144:147], v166
	ds_read_b128 v[148:151], v166 offset:1024
	ds_read_b128 v[152:155], v166 offset:2048
	ds_read_b128 v[166:169], v166 offset:3072
	s_add_u32 s4, s34, s0
	s_addc_u32 s5, s35, s1
	s_mov_b32 m0, s48
	v_lshl_add_u64 v[232:233], s[4:5], 0, v[160:161]
	ds_read_b128 v[170:173], v197 offset:32768
	ds_read_b128 v[186:189], v197 offset:33792
	ds_read_b128 v[190:193], v197 offset:34816
	ds_read_b128 v[198:201], v197 offset:35840
	ds_read_b128 v[202:205], v197 offset:36864
	ds_read_b128 v[206:209], v197 offset:37888
	ds_read_b128 v[210:213], v197 offset:38912
	ds_read_b128 v[214:217], v197 offset:39936
	global_load_lds_dwordx4 v[232:233], off
	v_lshl_add_u64 v[232:233], s[4:5], 0, v[158:159]
	s_mov_b32 m0, s49
	s_nop 0
	global_load_lds_dwordx4 v[232:233], off
	s_waitcnt vmcnt(8)
	s_waitcnt lgkmcnt(0)
	s_barrier
	s_waitcnt lgkmcnt(0)
	v_mfma_f32_16x16x32_bf16 v[120:123], v[128:131], v[170:173], v[120:123]
	v_mfma_f32_16x16x32_bf16 v[124:127], v[136:139], v[170:173], v[124:127]
	v_mfma_f32_16x16x32_bf16 v[108:111], v[128:131], v[190:193], v[108:111]
	v_mfma_f32_16x16x32_bf16 v[104:107], v[136:139], v[190:193], v[104:107]
	v_mfma_f32_16x16x32_bf16 v[92:95], v[128:131], v[202:205], v[92:95]
	v_mfma_f32_16x16x32_bf16 v[88:91], v[136:139], v[202:205], v[88:91]
	v_mfma_f32_16x16x32_bf16 v[76:79], v[128:131], v[210:213], v[76:79]
	v_mfma_f32_16x16x32_bf16 v[72:75], v[136:139], v[210:213], v[72:75]
	v_mfma_f32_16x16x32_bf16 v[120:123], v[132:135], v[186:189], v[120:123]
	v_mfma_f32_16x16x32_bf16 v[124:127], v[140:143], v[186:189], v[124:127]
	v_mfma_f32_16x16x32_bf16 v[108:111], v[132:135], v[198:201], v[108:111]
	v_mfma_f32_16x16x32_bf16 v[104:107], v[140:143], v[198:201], v[104:107]
	v_mfma_f32_16x16x32_bf16 v[92:95], v[132:135], v[206:209], v[92:95]
	v_mfma_f32_16x16x32_bf16 v[88:91], v[140:143], v[206:209], v[88:91]
	v_mfma_f32_16x16x32_bf16 v[76:79], v[132:135], v[214:217], v[76:79]
	v_mfma_f32_16x16x32_bf16 v[72:75], v[140:143], v[214:217], v[72:75]
	v_mfma_f32_16x16x32_bf16 v[116:119], v[144:147], v[170:173], v[116:119]
	v_mfma_f32_16x16x32_bf16 v[112:115], v[152:155], v[170:173], v[112:115]
	v_mfma_f32_16x16x32_bf16 v[100:103], v[144:147], v[190:193], v[100:103]
	v_mfma_f32_16x16x32_bf16 v[96:99], v[152:155], v[190:193], v[96:99]
	v_mfma_f32_16x16x32_bf16 v[84:87], v[144:147], v[202:205], v[84:87]
	v_mfma_f32_16x16x32_bf16 v[80:83], v[152:155], v[202:205], v[80:83]
	v_mfma_f32_16x16x32_bf16 v[68:71], v[144:147], v[210:213], v[68:71]
	v_mfma_f32_16x16x32_bf16 v[64:67], v[152:155], v[210:213], v[64:67]
	v_mfma_f32_16x16x32_bf16 v[116:119], v[148:151], v[186:189], v[116:119]
	v_mfma_f32_16x16x32_bf16 v[112:115], v[166:169], v[186:189], v[112:115]
	v_mfma_f32_16x16x32_bf16 v[100:103], v[148:151], v[198:201], v[100:103]
	v_mfma_f32_16x16x32_bf16 v[96:99], v[166:169], v[198:201], v[96:99]
	v_mfma_f32_16x16x32_bf16 v[84:87], v[148:151], v[206:209], v[84:87]
	v_mfma_f32_16x16x32_bf16 v[80:83], v[166:169], v[206:209], v[80:83]
	v_mfma_f32_16x16x32_bf16 v[68:71], v[148:151], v[214:217], v[68:71]
	v_mfma_f32_16x16x32_bf16 v[64:67], v[166:169], v[214:217], v[64:67]
	s_barrier
	s_add_i32 s4, s45, s37
	v_lshl_add_u64 v[174:175], v[174:175], 0, s[14:15]
	s_mov_b32 m0, s4
	ds_read_b128 v[170:173], v197 offset:49152
	ds_read_b128 v[186:189], v197 offset:50176
	ds_read_b128 v[190:193], v197 offset:51200
	ds_read_b128 v[198:201], v197 offset:52224
	ds_read_b128 v[202:205], v197 offset:53248
	ds_read_b128 v[206:209], v197 offset:54272
	ds_read_b128 v[210:213], v197 offset:55296
	ds_read_b128 v[214:217], v197 offset:56320
	global_load_lds_dwordx4 v[174:175], off
	v_lshl_add_u64 v[174:175], v[222:223], 0, s[14:15]
	s_add_i32 m0, s4, 0x2000
	s_add_i32 s4, s54, s37
	global_load_lds_dwordx4 v[174:175], off
	v_lshl_add_u64 v[174:175], v[224:225], 0, s[14:15]
	s_mov_b32 m0, s4
	s_nop 0
	global_load_lds_dwordx4 v[174:175], off
	v_lshl_add_u64 v[174:175], v[226:227], 0, s[14:15]
	s_add_i32 m0, s4, 0x2000
	s_nop 0
	global_load_lds_dwordx4 v[174:175], off
	v_lshl_add_u64 v[174:175], v[228:229], 0, s[14:15]
	s_mov_b32 m0, s60
	s_nop 0
	global_load_lds_dwordx4 v[174:175], off
	v_lshl_add_u64 v[174:175], v[230:231], 0, s[14:15]
	s_mov_b32 m0, s61
	s_nop 0
	global_load_lds_dwordx4 v[174:175], off
	s_waitcnt vmcnt(8)
	s_waitcnt lgkmcnt(0)
	s_barrier
	s_waitcnt lgkmcnt(0)
	v_mfma_f32_16x16x32_bf16 v[60:63], v[128:131], v[170:173], v[60:63]
	s_add_u32 s30, s30, 0x100
	v_mfma_f32_16x16x32_bf16 v[56:59], v[136:139], v[170:173], v[56:59]
	s_addc_u32 s31, s31, 0
	v_mfma_f32_16x16x32_bf16 v[44:47], v[128:131], v[190:193], v[44:47]
	s_add_u32 s10, s10, 0x100
	v_mfma_f32_16x16x32_bf16 v[40:43], v[136:139], v[190:193], v[40:43]
	s_addc_u32 s11, s11, 0
	v_mfma_f32_16x16x32_bf16 v[28:31], v[128:131], v[202:205], v[28:31]
	s_mov_b32 s34, s44
	v_mfma_f32_16x16x32_bf16 v[24:27], v[136:139], v[202:205], v[24:27]
	s_cmp_ge_i32 s44, s59
	v_mfma_f32_16x16x32_bf16 v[12:15], v[128:131], v[210:213], v[12:15]
	s_cselect_b32 s99, 1, 0
	v_mfma_f32_16x16x32_bf16 v[8:11], v[136:139], v[210:213], v[8:11]
	s_add_i32 s44, s34, 2
	v_mfma_f32_16x16x32_bf16 v[60:63], v[132:135], v[186:189], v[60:63]
	s_add_u32 s4, s30, 0x80
	v_mfma_f32_16x16x32_bf16 v[56:59], v[140:143], v[186:189], v[56:59]
	s_addc_u32 s5, s31, 0
	v_mfma_f32_16x16x32_bf16 v[44:47], v[132:135], v[198:201], v[44:47]
	s_add_i32 s45, 0, 0x10000
	v_mfma_f32_16x16x32_bf16 v[40:43], v[140:143], v[198:201], v[40:43]
	s_cmp_eq_u32 s62, s34
	v_mfma_f32_16x16x32_bf16 v[28:31], v[132:135], v[206:209], v[28:31]
	s_cselect_b32 s35, s27, s5
	v_mfma_f32_16x16x32_bf16 v[24:27], v[140:143], v[206:209], v[24:27]
	s_cselect_b32 s34, s26, s4
	v_mfma_f32_16x16x32_bf16 v[12:15], v[132:135], v[214:217], v[12:15]
	s_cselect_b32 s5, s29, s11
	v_mfma_f32_16x16x32_bf16 v[8:11], v[140:143], v[214:217], v[8:11]
	s_cselect_b32 s4, s28, s10
	v_mfma_f32_16x16x32_bf16 v[52:55], v[144:147], v[170:173], v[52:55]
	s_add_i32 s54, 0, 0x14000
	v_mfma_f32_16x16x32_bf16 v[48:51], v[152:155], v[170:173], v[48:51]
	v_mfma_f32_16x16x32_bf16 v[36:39], v[144:147], v[190:193], v[36:39]
	v_mfma_f32_16x16x32_bf16 v[32:35], v[152:155], v[190:193], v[32:35]
	v_mfma_f32_16x16x32_bf16 v[20:23], v[144:147], v[202:205], v[20:23]
	v_mfma_f32_16x16x32_bf16 v[16:19], v[152:155], v[202:205], v[16:19]
	v_mfma_f32_16x16x32_bf16 v[4:7], v[144:147], v[210:213], v[4:7]
	v_mfma_f32_16x16x32_bf16 v[0:3], v[152:155], v[210:213], v[0:3]
	v_mfma_f32_16x16x32_bf16 v[52:55], v[148:151], v[186:189], v[52:55]
	v_mfma_f32_16x16x32_bf16 v[48:51], v[166:169], v[186:189], v[48:51]
	v_mfma_f32_16x16x32_bf16 v[36:39], v[148:151], v[198:201], v[36:39]
	v_mfma_f32_16x16x32_bf16 v[32:35], v[166:169], v[198:201], v[32:35]
	v_mfma_f32_16x16x32_bf16 v[20:23], v[148:151], v[206:209], v[20:23]
	v_mfma_f32_16x16x32_bf16 v[16:19], v[166:169], v[206:209], v[16:19]
	v_mfma_f32_16x16x32_bf16 v[4:7], v[148:151], v[214:217], v[4:7]
	v_mfma_f32_16x16x32_bf16 v[0:3], v[166:169], v[214:217], v[0:3]
	s_barrier
	s_cmp_lg_u32 s99, 0
	s_cbranch_scc1 .Lpeelx_5
.LBB0_262:
	v_add_u32_e32 v140, s45, v195
	v_add_u32_e32 v166, s54, v195
	ds_read_b128 v[128:131], v140
	ds_read_b128 v[132:135], v140 offset:1024
	ds_read_b128 v[136:139], v140 offset:2048
	ds_read_b128 v[140:143], v140 offset:3072
	ds_read_b128 v[144:147], v166
	ds_read_b128 v[148:151], v166 offset:1024
	ds_read_b128 v[152:155], v166 offset:2048
	ds_read_b128 v[166:169], v166 offset:3072
	v_lshl_add_u64 v[174:175], s[30:31], 0, v[162:163]
	s_add_i32 m0, s38, 0xc000
	ds_read_b128 v[170:173], v197
	ds_read_b128 v[186:189], v197 offset:1024
	ds_read_b128 v[190:193], v197 offset:2048
	ds_read_b128 v[198:201], v197 offset:3072
	ds_read_b128 v[202:205], v197 offset:4096
	ds_read_b128 v[206:209], v197 offset:5120
	ds_read_b128 v[210:213], v197 offset:6144
	ds_read_b128 v[214:217], v197 offset:7168
	global_load_lds_dwordx4 v[174:175], off
	v_lshl_add_u64 v[174:175], s[30:31], 0, v[164:165]
	s_add_i32 m0, s38, 0xe000
	s_nop 0
	global_load_lds_dwordx4 v[174:175], off
	s_waitcnt vmcnt(8)
	s_waitcnt lgkmcnt(0)
	s_barrier
	s_waitcnt lgkmcnt(0)
	v_mfma_f32_16x16x32_bf16 v[120:123], v[128:131], v[170:173], v[120:123]
	v_mfma_f32_16x16x32_bf16 v[124:127], v[136:139], v[170:173], v[124:127]
	v_mfma_f32_16x16x32_bf16 v[108:111], v[128:131], v[190:193], v[108:111]
	v_mfma_f32_16x16x32_bf16 v[104:107], v[136:139], v[190:193], v[104:107]
	v_mfma_f32_16x16x32_bf16 v[92:95], v[128:131], v[202:205], v[92:95]
	v_mfma_f32_16x16x32_bf16 v[88:91], v[136:139], v[202:205], v[88:91]
	v_mfma_f32_16x16x32_bf16 v[76:79], v[128:131], v[210:213], v[76:79]
	v_mfma_f32_16x16x32_bf16 v[72:75], v[136:139], v[210:213], v[72:75]
	v_mfma_f32_16x16x32_bf16 v[120:123], v[132:135], v[186:189], v[120:123]
	v_mfma_f32_16x16x32_bf16 v[124:127], v[140:143], v[186:189], v[124:127]
	v_mfma_f32_16x16x32_bf16 v[108:111], v[132:135], v[198:201], v[108:111]
	v_mfma_f32_16x16x32_bf16 v[104:107], v[140:143], v[198:201], v[104:107]
	v_mfma_f32_16x16x32_bf16 v[92:95], v[132:135], v[206:209], v[92:95]
	v_mfma_f32_16x16x32_bf16 v[88:91], v[140:143], v[206:209], v[88:91]
	v_mfma_f32_16x16x32_bf16 v[76:79], v[132:135], v[214:217], v[76:79]
	v_mfma_f32_16x16x32_bf16 v[72:75], v[140:143], v[214:217], v[72:75]
	v_mfma_f32_16x16x32_bf16 v[116:119], v[144:147], v[170:173], v[116:119]
	v_mfma_f32_16x16x32_bf16 v[112:115], v[152:155], v[170:173], v[112:115]
	v_mfma_f32_16x16x32_bf16 v[100:103], v[144:147], v[190:193], v[100:103]
	v_mfma_f32_16x16x32_bf16 v[96:99], v[152:155], v[190:193], v[96:99]
	v_mfma_f32_16x16x32_bf16 v[84:87], v[144:147], v[202:205], v[84:87]
	v_mfma_f32_16x16x32_bf16 v[80:83], v[152:155], v[202:205], v[80:83]
	v_mfma_f32_16x16x32_bf16 v[68:71], v[144:147], v[210:213], v[68:71]
	v_mfma_f32_16x16x32_bf16 v[64:67], v[152:155], v[210:213], v[64:67]
	v_mfma_f32_16x16x32_bf16 v[116:119], v[148:151], v[186:189], v[116:119]
	v_mfma_f32_16x16x32_bf16 v[112:115], v[166:169], v[186:189], v[112:115]
	v_mfma_f32_16x16x32_bf16 v[100:103], v[148:151], v[198:201], v[100:103]
	v_mfma_f32_16x16x32_bf16 v[96:99], v[166:169], v[198:201], v[96:99]
	v_mfma_f32_16x16x32_bf16 v[84:87], v[148:151], v[206:209], v[84:87]
	v_mfma_f32_16x16x32_bf16 v[80:83], v[166:169], v[206:209], v[80:83]
	v_mfma_f32_16x16x32_bf16 v[68:71], v[148:151], v[214:217], v[68:71]
	v_mfma_f32_16x16x32_bf16 v[64:67], v[166:169], v[214:217], v[64:67]
	s_barrier
	s_add_i32 s45, s45, s37
	v_lshl_add_u64 v[174:175], s[4:5], 0, v[176:177]
	s_mov_b32 m0, s45
	ds_read_b128 v[170:173], v197 offset:16384
	ds_read_b128 v[186:189], v197 offset:17408
	ds_read_b128 v[190:193], v197 offset:18432
	ds_read_b128 v[198:201], v197 offset:19456
	ds_read_b128 v[202:205], v197 offset:20480
	ds_read_b128 v[206:209], v197 offset:21504
	ds_read_b128 v[210:213], v197 offset:22528
	ds_read_b128 v[214:217], v197 offset:23552
	global_load_lds_dwordx4 v[174:175], off
	s_add_i32 m0, s45, 0x2000
	v_lshl_add_u64 v[222:223], s[4:5], 0, v[156:157]
	s_add_u32 s4, s4, s0
	s_addc_u32 s5, s5, s1
	s_add_i32 s45, s54, s37
	global_load_lds_dwordx4 v[222:223], off
	v_lshl_add_u64 v[224:225], s[4:5], 0, v[176:177]
	s_mov_b32 m0, s45
	v_lshl_add_u64 v[226:227], s[4:5], 0, v[156:157]
	global_load_lds_dwordx4 v[224:225], off
	s_add_i32 m0, s45, 0x2000
	v_lshl_add_u64 v[228:229], s[34:35], 0, v[160:161]
	global_load_lds_dwordx4 v[226:227], off
	s_mov_b32 m0, s38
	v_lshl_add_u64 v[230:231], s[34:35], 0, v[158:159]
	global_load_lds_dwordx4 v[228:229], off
	s_mov_b32 m0, s39
	s_nop 0
	global_load_lds_dwordx4 v[230:231], off
	s_waitcnt vmcnt(8)
	s_waitcnt lgkmcnt(0)
	s_barrier
	s_waitcnt lgkmcnt(0)
	v_mfma_f32_16x16x32_bf16 v[60:63], v[128:131], v[170:173], v[60:63]
	v_mfma_f32_16x16x32_bf16 v[56:59], v[136:139], v[170:173], v[56:59]
	v_mfma_f32_16x16x32_bf16 v[44:47], v[128:131], v[190:193], v[44:47]
	v_mfma_f32_16x16x32_bf16 v[40:43], v[136:139], v[190:193], v[40:43]
	v_mfma_f32_16x16x32_bf16 v[28:31], v[128:131], v[202:205], v[28:31]
	v_mfma_f32_16x16x32_bf16 v[24:27], v[136:139], v[202:205], v[24:27]
	v_mfma_f32_16x16x32_bf16 v[12:15], v[128:131], v[210:213], v[12:15]
	v_mfma_f32_16x16x32_bf16 v[8:11], v[136:139], v[210:213], v[8:11]
	v_mfma_f32_16x16x32_bf16 v[60:63], v[132:135], v[186:189], v[60:63]
	v_mfma_f32_16x16x32_bf16 v[56:59], v[140:143], v[186:189], v[56:59]
	v_mfma_f32_16x16x32_bf16 v[44:47], v[132:135], v[198:201], v[44:47]
	v_mfma_f32_16x16x32_bf16 v[40:43], v[140:143], v[198:201], v[40:43]
	v_mfma_f32_16x16x32_bf16 v[28:31], v[132:135], v[206:209], v[28:31]
	v_mfma_f32_16x16x32_bf16 v[24:27], v[140:143], v[206:209], v[24:27]
	v_mfma_f32_16x16x32_bf16 v[12:15], v[132:135], v[214:217], v[12:15]
	v_mfma_f32_16x16x32_bf16 v[8:11], v[140:143], v[214:217], v[8:11]
	v_mfma_f32_16x16x32_bf16 v[52:55], v[144:147], v[170:173], v[52:55]
	v_mfma_f32_16x16x32_bf16 v[48:51], v[152:155], v[170:173], v[48:51]
	v_mfma_f32_16x16x32_bf16 v[36:39], v[144:147], v[190:193], v[36:39]
	v_mfma_f32_16x16x32_bf16 v[32:35], v[152:155], v[190:193], v[32:35]
	v_mfma_f32_16x16x32_bf16 v[20:23], v[144:147], v[202:205], v[20:23]
	v_mfma_f32_16x16x32_bf16 v[16:19], v[152:155], v[202:205], v[16:19]
	v_mfma_f32_16x16x32_bf16 v[4:7], v[144:147], v[210:213], v[4:7]
	v_mfma_f32_16x16x32_bf16 v[0:3], v[152:155], v[210:213], v[0:3]
	v_mfma_f32_16x16x32_bf16 v[52:55], v[148:151], v[186:189], v[52:55]
	v_mfma_f32_16x16x32_bf16 v[48:51], v[166:169], v[186:189], v[48:51]
	v_mfma_f32_16x16x32_bf16 v[36:39], v[148:151], v[198:201], v[36:39]
	v_mfma_f32_16x16x32_bf16 v[32:35], v[166:169], v[198:201], v[32:35]
	v_mfma_f32_16x16x32_bf16 v[20:23], v[148:151], v[206:209], v[20:23]
	v_mfma_f32_16x16x32_bf16 v[16:19], v[166:169], v[206:209], v[16:19]
	v_mfma_f32_16x16x32_bf16 v[4:7], v[148:151], v[214:217], v[4:7]
	v_mfma_f32_16x16x32_bf16 v[0:3], v[166:169], v[214:217], v[0:3]
	s_barrier
	s_add_i32 s45, 0, 0x18000
	s_add_i32 s54, 0, 0x1c000
	v_add_u32_e32 v140, s45, v195
	v_add_u32_e32 v166, s54, v195
	ds_read_b128 v[128:131], v140
	ds_read_b128 v[132:135], v140 offset:1024
	ds_read_b128 v[136:139], v140 offset:2048
	ds_read_b128 v[140:143], v140 offset:3072
	ds_read_b128 v[144:147], v166
	ds_read_b128 v[148:151], v166 offset:1024
	ds_read_b128 v[152:155], v166 offset:2048
	ds_read_b128 v[166:169], v166 offset:3072
	s_add_u32 s4, s34, s0
	s_addc_u32 s5, s35, s1
	s_mov_b32 m0, s48
	v_lshl_add_u64 v[232:233], s[4:5], 0, v[160:161]
	ds_read_b128 v[170:173], v197 offset:32768
	ds_read_b128 v[186:189], v197 offset:33792
	ds_read_b128 v[190:193], v197 offset:34816
	ds_read_b128 v[198:201], v197 offset:35840
	ds_read_b128 v[202:205], v197 offset:36864
	ds_read_b128 v[206:209], v197 offset:37888
	ds_read_b128 v[210:213], v197 offset:38912
	ds_read_b128 v[214:217], v197 offset:39936
	global_load_lds_dwordx4 v[232:233], off
	v_lshl_add_u64 v[232:233], s[4:5], 0, v[158:159]
	s_mov_b32 m0, s49
	s_nop 0
	global_load_lds_dwordx4 v[232:233], off
	s_waitcnt vmcnt(8)
	s_waitcnt lgkmcnt(0)
	s_barrier
	s_waitcnt lgkmcnt(0)
	v_mfma_f32_16x16x32_bf16 v[120:123], v[128:131], v[170:173], v[120:123]
	v_mfma_f32_16x16x32_bf16 v[124:127], v[136:139], v[170:173], v[124:127]
	v_mfma_f32_16x16x32_bf16 v[108:111], v[128:131], v[190:193], v[108:111]
	v_mfma_f32_16x16x32_bf16 v[104:107], v[136:139], v[190:193], v[104:107]
	v_mfma_f32_16x16x32_bf16 v[92:95], v[128:131], v[202:205], v[92:95]
	v_mfma_f32_16x16x32_bf16 v[88:91], v[136:139], v[202:205], v[88:91]
	v_mfma_f32_16x16x32_bf16 v[76:79], v[128:131], v[210:213], v[76:79]
	v_mfma_f32_16x16x32_bf16 v[72:75], v[136:139], v[210:213], v[72:75]
	v_mfma_f32_16x16x32_bf16 v[120:123], v[132:135], v[186:189], v[120:123]
	v_mfma_f32_16x16x32_bf16 v[124:127], v[140:143], v[186:189], v[124:127]
	v_mfma_f32_16x16x32_bf16 v[108:111], v[132:135], v[198:201], v[108:111]
	v_mfma_f32_16x16x32_bf16 v[104:107], v[140:143], v[198:201], v[104:107]
	v_mfma_f32_16x16x32_bf16 v[92:95], v[132:135], v[206:209], v[92:95]
	v_mfma_f32_16x16x32_bf16 v[88:91], v[140:143], v[206:209], v[88:91]
	v_mfma_f32_16x16x32_bf16 v[76:79], v[132:135], v[214:217], v[76:79]
	v_mfma_f32_16x16x32_bf16 v[72:75], v[140:143], v[214:217], v[72:75]
	v_mfma_f32_16x16x32_bf16 v[116:119], v[144:147], v[170:173], v[116:119]
	v_mfma_f32_16x16x32_bf16 v[112:115], v[152:155], v[170:173], v[112:115]
	v_mfma_f32_16x16x32_bf16 v[100:103], v[144:147], v[190:193], v[100:103]
	v_mfma_f32_16x16x32_bf16 v[96:99], v[152:155], v[190:193], v[96:99]
	v_mfma_f32_16x16x32_bf16 v[84:87], v[144:147], v[202:205], v[84:87]
	v_mfma_f32_16x16x32_bf16 v[80:83], v[152:155], v[202:205], v[80:83]
	v_mfma_f32_16x16x32_bf16 v[68:71], v[144:147], v[210:213], v[68:71]
	v_mfma_f32_16x16x32_bf16 v[64:67], v[152:155], v[210:213], v[64:67]
	v_mfma_f32_16x16x32_bf16 v[116:119], v[148:151], v[186:189], v[116:119]
	v_mfma_f32_16x16x32_bf16 v[112:115], v[166:169], v[186:189], v[112:115]
	v_mfma_f32_16x16x32_bf16 v[100:103], v[148:151], v[198:201], v[100:103]
	v_mfma_f32_16x16x32_bf16 v[96:99], v[166:169], v[198:201], v[96:99]
	v_mfma_f32_16x16x32_bf16 v[84:87], v[148:151], v[206:209], v[84:87]
	v_mfma_f32_16x16x32_bf16 v[80:83], v[166:169], v[206:209], v[80:83]
	v_mfma_f32_16x16x32_bf16 v[68:71], v[148:151], v[214:217], v[68:71]
	v_mfma_f32_16x16x32_bf16 v[64:67], v[166:169], v[214:217], v[64:67]
	s_barrier
	s_add_i32 s4, s45, s37
	v_lshl_add_u64 v[174:175], v[174:175], 0, s[14:15]
	s_mov_b32 m0, s4
	ds_read_b128 v[170:173], v197 offset:49152
	ds_read_b128 v[186:189], v197 offset:50176
	ds_read_b128 v[190:193], v197 offset:51200
	ds_read_b128 v[198:201], v197 offset:52224
	ds_read_b128 v[202:205], v197 offset:53248
	ds_read_b128 v[206:209], v197 offset:54272
	ds_read_b128 v[210:213], v197 offset:55296
	ds_read_b128 v[214:217], v197 offset:56320
	global_load_lds_dwordx4 v[174:175], off
	v_lshl_add_u64 v[174:175], v[222:223], 0, s[14:15]
	s_add_i32 m0, s4, 0x2000
	s_add_i32 s4, s54, s37
	global_load_lds_dwordx4 v[174:175], off
	v_lshl_add_u64 v[174:175], v[224:225], 0, s[14:15]
	s_mov_b32 m0, s4
	s_nop 0
	global_load_lds_dwordx4 v[174:175], off
	v_lshl_add_u64 v[174:175], v[226:227], 0, s[14:15]
	s_add_i32 m0, s4, 0x2000
	s_nop 0
	global_load_lds_dwordx4 v[174:175], off
	v_lshl_add_u64 v[174:175], v[228:229], 0, s[14:15]
	s_mov_b32 m0, s60
	s_nop 0
	global_load_lds_dwordx4 v[174:175], off
	v_lshl_add_u64 v[174:175], v[230:231], 0, s[14:15]
	s_mov_b32 m0, s61
	s_nop 0
	global_load_lds_dwordx4 v[174:175], off
	s_waitcnt vmcnt(8)
	s_waitcnt lgkmcnt(0)
	s_barrier
	s_waitcnt lgkmcnt(0)
	v_mfma_f32_16x16x32_bf16 v[60:63], v[128:131], v[170:173], v[60:63]
	s_add_u32 s30, s30, 0x100
	v_mfma_f32_16x16x32_bf16 v[56:59], v[136:139], v[170:173], v[56:59]
	s_addc_u32 s31, s31, 0
	v_mfma_f32_16x16x32_bf16 v[44:47], v[128:131], v[190:193], v[44:47]
	s_add_u32 s10, s10, 0x100
	v_mfma_f32_16x16x32_bf16 v[40:43], v[136:139], v[190:193], v[40:43]
	s_addc_u32 s11, s11, 0
	v_mfma_f32_16x16x32_bf16 v[28:31], v[128:131], v[202:205], v[28:31]
	s_mov_b32 s34, s44
	v_mfma_f32_16x16x32_bf16 v[24:27], v[136:139], v[202:205], v[24:27]
	s_cmp_ge_i32 s44, s59
	v_mfma_f32_16x16x32_bf16 v[12:15], v[128:131], v[210:213], v[12:15]
	s_cselect_b32 s99, 1, 0
	v_mfma_f32_16x16x32_bf16 v[8:11], v[136:139], v[210:213], v[8:11]
	s_add_i32 s44, s34, 2
	v_mfma_f32_16x16x32_bf16 v[60:63], v[132:135], v[186:189], v[60:63]
	s_add_u32 s4, s30, 0x80
	v_mfma_f32_16x16x32_bf16 v[56:59], v[140:143], v[186:189], v[56:59]
	s_addc_u32 s5, s31, 0
	v_mfma_f32_16x16x32_bf16 v[44:47], v[132:135], v[198:201], v[44:47]
	s_add_i32 s45, 0, 0x10000
	v_mfma_f32_16x16x32_bf16 v[40:43], v[140:143], v[198:201], v[40:43]
	s_cmp_eq_u32 s62, s34
	v_mfma_f32_16x16x32_bf16 v[28:31], v[132:135], v[206:209], v[28:31]
	s_cselect_b32 s35, s27, s5
	v_mfma_f32_16x16x32_bf16 v[24:27], v[140:143], v[206:209], v[24:27]
	s_cselect_b32 s34, s26, s4
	v_mfma_f32_16x16x32_bf16 v[12:15], v[132:135], v[214:217], v[12:15]
	s_cselect_b32 s5, s29, s11
	v_mfma_f32_16x16x32_bf16 v[8:11], v[140:143], v[214:217], v[8:11]
	s_cselect_b32 s4, s28, s10
	v_mfma_f32_16x16x32_bf16 v[52:55], v[144:147], v[170:173], v[52:55]
	s_add_i32 s54, 0, 0x14000
	v_mfma_f32_16x16x32_bf16 v[48:51], v[152:155], v[170:173], v[48:51]
	v_mfma_f32_16x16x32_bf16 v[36:39], v[144:147], v[190:193], v[36:39]
	v_mfma_f32_16x16x32_bf16 v[32:35], v[152:155], v[190:193], v[32:35]
	v_mfma_f32_16x16x32_bf16 v[20:23], v[144:147], v[202:205], v[20:23]
	v_mfma_f32_16x16x32_bf16 v[16:19], v[152:155], v[202:205], v[16:19]
	v_mfma_f32_16x16x32_bf16 v[4:7], v[144:147], v[210:213], v[4:7]
	v_mfma_f32_16x16x32_bf16 v[0:3], v[152:155], v[210:213], v[0:3]
	v_mfma_f32_16x16x32_bf16 v[52:55], v[148:151], v[186:189], v[52:55]
	v_mfma_f32_16x16x32_bf16 v[48:51], v[166:169], v[186:189], v[48:51]
	v_mfma_f32_16x16x32_bf16 v[36:39], v[148:151], v[198:201], v[36:39]
	v_mfma_f32_16x16x32_bf16 v[32:35], v[166:169], v[198:201], v[32:35]
	v_mfma_f32_16x16x32_bf16 v[20:23], v[148:151], v[206:209], v[20:23]
	v_mfma_f32_16x16x32_bf16 v[16:19], v[166:169], v[206:209], v[16:19]
	v_mfma_f32_16x16x32_bf16 v[4:7], v[148:151], v[214:217], v[4:7]
	v_mfma_f32_16x16x32_bf16 v[0:3], v[166:169], v[214:217], v[0:3]
	s_barrier
	s_cmp_lg_u32 s99, 0
	s_cbranch_scc0 .LBB0_262

.Llbb_2:
	s_add_i32 s44, s34, 2
	s_add_u32 s4, s30, 0x80
	s_addc_u32 s5, s31, 0
	s_add_i32 s45, 0, 0x10000
	s_cmp_eq_u32 s62, s34
	s_cselect_b32 s35, s27, s5
	s_cselect_b32 s34, s26, s4
	s_cselect_b32 s5, s29, s11
	s_cselect_b32 s4, s28, s10
	s_add_i32 s54, 0, 0x14000
	v_add_u32_e32 v140, s45, v163
	v_add_u32_e32 v170, s54, v163
	ds_read_b128 v[128:131], v140
	ds_read_b128 v[132:135], v140 offset:1024
	ds_read_b128 v[136:139], v140 offset:2048
	ds_read_b128 v[140:143], v140 offset:3072
	ds_read_b128 v[154:157], v170
	ds_read_b128 v[158:161], v170 offset:1024
	ds_read_b128 v[166:169], v170 offset:2048
	ds_read_b128 v[170:173], v170 offset:3072
	v_lshl_add_u64 v[174:175], s[30:31], 0, v[150:151]
	s_add_i32 m0, s38, 0xc000
	ds_read_b128 v[186:189], v165
	ds_read_b128 v[190:193], v165 offset:1024
	ds_read_b128 v[194:197], v165 offset:2048
	ds_read_b128 v[198:201], v165 offset:3072
	ds_read_b128 v[202:205], v165 offset:4096
	ds_read_b128 v[206:209], v165 offset:5120
	ds_read_b128 v[210:213], v165 offset:6144
	ds_read_b128 v[214:217], v165 offset:7168
	global_load_lds_dwordx4 v[174:175], off
	v_lshl_add_u64 v[174:175], s[30:31], 0, v[152:153]
	s_add_i32 m0, s38, 0xe000
	s_nop 0
	global_load_lds_dwordx4 v[174:175], off
	s_waitcnt vmcnt(8)
	s_waitcnt lgkmcnt(0)
	s_barrier
	s_waitcnt lgkmcnt(0)
	v_mfma_f32_16x16x32_bf16 v[124:127], v[128:131], v[186:189], 0
	v_mfma_f32_16x16x32_bf16 v[120:123], v[136:139], v[186:189], 0
	v_mfma_f32_16x16x32_bf16 v[108:111], v[128:131], v[194:197], 0
	v_mfma_f32_16x16x32_bf16 v[104:107], v[136:139], v[194:197], 0
	v_mfma_f32_16x16x32_bf16 v[92:95], v[128:131], v[202:205], 0
	v_mfma_f32_16x16x32_bf16 v[88:91], v[136:139], v[202:205], 0
	v_mfma_f32_16x16x32_bf16 v[76:79], v[128:131], v[210:213], 0
	v_mfma_f32_16x16x32_bf16 v[72:75], v[136:139], v[210:213], 0
	v_mfma_f32_16x16x32_bf16 v[124:127], v[132:135], v[190:193], v[124:127]
	v_mfma_f32_16x16x32_bf16 v[120:123], v[140:143], v[190:193], v[120:123]
	v_mfma_f32_16x16x32_bf16 v[108:111], v[132:135], v[198:201], v[108:111]
	v_mfma_f32_16x16x32_bf16 v[104:107], v[140:143], v[198:201], v[104:107]
	v_mfma_f32_16x16x32_bf16 v[92:95], v[132:135], v[206:209], v[92:95]
	v_mfma_f32_16x16x32_bf16 v[88:91], v[140:143], v[206:209], v[88:91]
	v_mfma_f32_16x16x32_bf16 v[76:79], v[132:135], v[214:217], v[76:79]
	v_mfma_f32_16x16x32_bf16 v[72:75], v[140:143], v[214:217], v[72:75]
	v_mfma_f32_16x16x32_bf16 v[116:119], v[154:157], v[186:189], 0
	v_mfma_f32_16x16x32_bf16 v[112:115], v[166:169], v[186:189], 0
	v_mfma_f32_16x16x32_bf16 v[100:103], v[154:157], v[194:197], 0
	v_mfma_f32_16x16x32_bf16 v[96:99], v[166:169], v[194:197], 0
	v_mfma_f32_16x16x32_bf16 v[84:87], v[154:157], v[202:205], 0
	v_mfma_f32_16x16x32_bf16 v[80:83], v[166:169], v[202:205], 0
	v_mfma_f32_16x16x32_bf16 v[68:71], v[154:157], v[210:213], 0
	v_mfma_f32_16x16x32_bf16 v[64:67], v[166:169], v[210:213], 0
	v_mfma_f32_16x16x32_bf16 v[116:119], v[158:161], v[190:193], v[116:119]
	v_mfma_f32_16x16x32_bf16 v[112:115], v[170:173], v[190:193], v[112:115]
	v_mfma_f32_16x16x32_bf16 v[100:103], v[158:161], v[198:201], v[100:103]
	v_mfma_f32_16x16x32_bf16 v[96:99], v[170:173], v[198:201], v[96:99]
	v_mfma_f32_16x16x32_bf16 v[84:87], v[158:161], v[206:209], v[84:87]
	v_mfma_f32_16x16x32_bf16 v[80:83], v[170:173], v[206:209], v[80:83]
	v_mfma_f32_16x16x32_bf16 v[68:71], v[158:161], v[214:217], v[68:71]
	v_mfma_f32_16x16x32_bf16 v[64:67], v[170:173], v[214:217], v[64:67]
	s_barrier
	s_add_i32 s45, s45, s37
	v_lshl_add_u64 v[174:175], s[4:5], 0, v[176:177]
	s_mov_b32 m0, s45
	ds_read_b128 v[186:189], v165 offset:16384
	ds_read_b128 v[190:193], v165 offset:17408
	ds_read_b128 v[194:197], v165 offset:18432
	ds_read_b128 v[198:201], v165 offset:19456
	ds_read_b128 v[202:205], v165 offset:20480
	ds_read_b128 v[206:209], v165 offset:21504
	ds_read_b128 v[210:213], v165 offset:22528
	ds_read_b128 v[214:217], v165 offset:23552
	global_load_lds_dwordx4 v[174:175], off
	s_add_i32 m0, s45, 0x2000
	v_lshl_add_u64 v[222:223], s[4:5], 0, v[144:145]
	s_add_u32 s4, s4, s0
	s_addc_u32 s5, s5, s1
	s_add_i32 s45, s54, s37
	global_load_lds_dwordx4 v[222:223], off
	v_lshl_add_u64 v[224:225], s[4:5], 0, v[176:177]
	s_mov_b32 m0, s45
	v_lshl_add_u64 v[226:227], s[4:5], 0, v[144:145]
	global_load_lds_dwordx4 v[224:225], off
	s_add_i32 m0, s45, 0x2000
	v_lshl_add_u64 v[228:229], s[34:35], 0, v[148:149]
	global_load_lds_dwordx4 v[226:227], off
	s_mov_b32 m0, s38
	v_lshl_add_u64 v[230:231], s[34:35], 0, v[146:147]
	global_load_lds_dwordx4 v[228:229], off
	s_mov_b32 m0, s39
	s_nop 0
	global_load_lds_dwordx4 v[230:231], off
	s_waitcnt vmcnt(8)
	s_waitcnt lgkmcnt(0)
	s_barrier
	s_waitcnt lgkmcnt(0)
	v_mfma_f32_16x16x32_bf16 v[60:63], v[128:131], v[186:189], 0
	v_mfma_f32_16x16x32_bf16 v[56:59], v[136:139], v[186:189], 0
	v_mfma_f32_16x16x32_bf16 v[44:47], v[128:131], v[194:197], 0
	v_mfma_f32_16x16x32_bf16 v[40:43], v[136:139], v[194:197], 0
	v_mfma_f32_16x16x32_bf16 v[28:31], v[128:131], v[202:205], 0
	v_mfma_f32_16x16x32_bf16 v[24:27], v[136:139], v[202:205], 0
	v_mfma_f32_16x16x32_bf16 v[12:15], v[128:131], v[210:213], 0
	v_mfma_f32_16x16x32_bf16 v[8:11], v[136:139], v[210:213], 0
	v_mfma_f32_16x16x32_bf16 v[60:63], v[132:135], v[190:193], v[60:63]
	v_mfma_f32_16x16x32_bf16 v[56:59], v[140:143], v[190:193], v[56:59]
	v_mfma_f32_16x16x32_bf16 v[44:47], v[132:135], v[198:201], v[44:47]
	v_mfma_f32_16x16x32_bf16 v[40:43], v[140:143], v[198:201], v[40:43]
	v_mfma_f32_16x16x32_bf16 v[28:31], v[132:135], v[206:209], v[28:31]
	v_mfma_f32_16x16x32_bf16 v[24:27], v[140:143], v[206:209], v[24:27]
	v_mfma_f32_16x16x32_bf16 v[12:15], v[132:135], v[214:217], v[12:15]
	v_mfma_f32_16x16x32_bf16 v[8:11], v[140:143], v[214:217], v[8:11]
	v_mfma_f32_16x16x32_bf16 v[52:55], v[154:157], v[186:189], 0
	v_mfma_f32_16x16x32_bf16 v[48:51], v[166:169], v[186:189], 0
	v_mfma_f32_16x16x32_bf16 v[36:39], v[154:157], v[194:197], 0
	v_mfma_f32_16x16x32_bf16 v[32:35], v[166:169], v[194:197], 0
	v_mfma_f32_16x16x32_bf16 v[20:23], v[154:157], v[202:205], 0
	v_mfma_f32_16x16x32_bf16 v[16:19], v[166:169], v[202:205], 0
	v_mfma_f32_16x16x32_bf16 v[4:7], v[154:157], v[210:213], 0
	v_mfma_f32_16x16x32_bf16 v[0:3], v[166:169], v[210:213], 0
	v_mfma_f32_16x16x32_bf16 v[52:55], v[158:161], v[190:193], v[52:55]
	v_mfma_f32_16x16x32_bf16 v[48:51], v[170:173], v[190:193], v[48:51]
	v_mfma_f32_16x16x32_bf16 v[36:39], v[158:161], v[198:201], v[36:39]
	v_mfma_f32_16x16x32_bf16 v[32:35], v[170:173], v[198:201], v[32:35]
	v_mfma_f32_16x16x32_bf16 v[20:23], v[158:161], v[206:209], v[20:23]
	v_mfma_f32_16x16x32_bf16 v[16:19], v[170:173], v[206:209], v[16:19]
	v_mfma_f32_16x16x32_bf16 v[4:7], v[158:161], v[214:217], v[4:7]
	v_mfma_f32_16x16x32_bf16 v[0:3], v[170:173], v[214:217], v[0:3]
	s_barrier
	s_add_i32 s45, 0, 0x18000
	s_add_i32 s54, 0, 0x1c000
	v_add_u32_e32 v140, s45, v163
	v_add_u32_e32 v170, s54, v163
	ds_read_b128 v[128:131], v140
	ds_read_b128 v[132:135], v140 offset:1024
	ds_read_b128 v[136:139], v140 offset:2048
	ds_read_b128 v[140:143], v140 offset:3072
	ds_read_b128 v[154:157], v170
	ds_read_b128 v[158:161], v170 offset:1024
	ds_read_b128 v[166:169], v170 offset:2048
	ds_read_b128 v[170:173], v170 offset:3072
	s_add_u32 s4, s34, s0
	s_addc_u32 s5, s35, s1
	s_mov_b32 m0, s48
	v_lshl_add_u64 v[232:233], s[4:5], 0, v[148:149]
	ds_read_b128 v[186:189], v165 offset:32768
	ds_read_b128 v[190:193], v165 offset:33792
	ds_read_b128 v[194:197], v165 offset:34816
	ds_read_b128 v[198:201], v165 offset:35840
	ds_read_b128 v[202:205], v165 offset:36864
	ds_read_b128 v[206:209], v165 offset:37888
	ds_read_b128 v[210:213], v165 offset:38912
	ds_read_b128 v[214:217], v165 offset:39936
	global_load_lds_dwordx4 v[232:233], off
	v_lshl_add_u64 v[232:233], s[4:5], 0, v[146:147]
	s_mov_b32 m0, s49
	s_nop 0
	global_load_lds_dwordx4 v[232:233], off
	s_waitcnt vmcnt(8)
	s_waitcnt lgkmcnt(0)
	s_barrier
	s_waitcnt lgkmcnt(0)
	v_mfma_f32_16x16x32_bf16 v[124:127], v[128:131], v[186:189], v[124:127]
	v_mfma_f32_16x16x32_bf16 v[120:123], v[136:139], v[186:189], v[120:123]
	v_mfma_f32_16x16x32_bf16 v[108:111], v[128:131], v[194:197], v[108:111]
	v_mfma_f32_16x16x32_bf16 v[104:107], v[136:139], v[194:197], v[104:107]
	v_mfma_f32_16x16x32_bf16 v[92:95], v[128:131], v[202:205], v[92:95]
	v_mfma_f32_16x16x32_bf16 v[88:91], v[136:139], v[202:205], v[88:91]
	v_mfma_f32_16x16x32_bf16 v[76:79], v[128:131], v[210:213], v[76:79]
	v_mfma_f32_16x16x32_bf16 v[72:75], v[136:139], v[210:213], v[72:75]
	v_mfma_f32_16x16x32_bf16 v[124:127], v[132:135], v[190:193], v[124:127]
	v_mfma_f32_16x16x32_bf16 v[120:123], v[140:143], v[190:193], v[120:123]
	v_mfma_f32_16x16x32_bf16 v[108:111], v[132:135], v[198:201], v[108:111]
	v_mfma_f32_16x16x32_bf16 v[104:107], v[140:143], v[198:201], v[104:107]
	v_mfma_f32_16x16x32_bf16 v[92:95], v[132:135], v[206:209], v[92:95]
	v_mfma_f32_16x16x32_bf16 v[88:91], v[140:143], v[206:209], v[88:91]
	v_mfma_f32_16x16x32_bf16 v[76:79], v[132:135], v[214:217], v[76:79]
	v_mfma_f32_16x16x32_bf16 v[72:75], v[140:143], v[214:217], v[72:75]
	v_mfma_f32_16x16x32_bf16 v[116:119], v[154:157], v[186:189], v[116:119]
	v_mfma_f32_16x16x32_bf16 v[112:115], v[166:169], v[186:189], v[112:115]
	v_mfma_f32_16x16x32_bf16 v[100:103], v[154:157], v[194:197], v[100:103]
	v_mfma_f32_16x16x32_bf16 v[96:99], v[166:169], v[194:197], v[96:99]
	v_mfma_f32_16x16x32_bf16 v[84:87], v[154:157], v[202:205], v[84:87]
	v_mfma_f32_16x16x32_bf16 v[80:83], v[166:169], v[202:205], v[80:83]
	v_mfma_f32_16x16x32_bf16 v[68:71], v[154:157], v[210:213], v[68:71]
	v_mfma_f32_16x16x32_bf16 v[64:67], v[166:169], v[210:213], v[64:67]
	v_mfma_f32_16x16x32_bf16 v[116:119], v[158:161], v[190:193], v[116:119]
	v_mfma_f32_16x16x32_bf16 v[112:115], v[170:173], v[190:193], v[112:115]
	v_mfma_f32_16x16x32_bf16 v[100:103], v[158:161], v[198:201], v[100:103]
	v_mfma_f32_16x16x32_bf16 v[96:99], v[170:173], v[198:201], v[96:99]
	v_mfma_f32_16x16x32_bf16 v[84:87], v[158:161], v[206:209], v[84:87]
	v_mfma_f32_16x16x32_bf16 v[80:83], v[170:173], v[206:209], v[80:83]
	v_mfma_f32_16x16x32_bf16 v[68:71], v[158:161], v[214:217], v[68:71]
	v_mfma_f32_16x16x32_bf16 v[64:67], v[170:173], v[214:217], v[64:67]
	s_barrier
	s_add_i32 s4, s45, s37
	v_lshl_add_u64 v[174:175], v[174:175], 0, s[14:15]
	s_mov_b32 m0, s4
	ds_read_b128 v[186:189], v165 offset:49152
	ds_read_b128 v[190:193], v165 offset:50176
	ds_read_b128 v[194:197], v165 offset:51200
	ds_read_b128 v[198:201], v165 offset:52224
	ds_read_b128 v[202:205], v165 offset:53248
	ds_read_b128 v[206:209], v165 offset:54272
	ds_read_b128 v[210:213], v165 offset:55296
	ds_read_b128 v[214:217], v165 offset:56320
	global_load_lds_dwordx4 v[174:175], off
	v_lshl_add_u64 v[174:175], v[222:223], 0, s[14:15]
	s_add_i32 m0, s4, 0x2000
	s_add_i32 s4, s54, s37
	global_load_lds_dwordx4 v[174:175], off
	v_lshl_add_u64 v[174:175], v[224:225], 0, s[14:15]
	s_mov_b32 m0, s4
	s_nop 0
	global_load_lds_dwordx4 v[174:175], off
	v_lshl_add_u64 v[174:175], v[226:227], 0, s[14:15]
	s_add_i32 m0, s4, 0x2000
	s_nop 0
	global_load_lds_dwordx4 v[174:175], off
	v_lshl_add_u64 v[174:175], v[228:229], 0, s[14:15]
	s_mov_b32 m0, s60
	s_nop 0
	global_load_lds_dwordx4 v[174:175], off
	v_lshl_add_u64 v[174:175], v[230:231], 0, s[14:15]
	s_mov_b32 m0, s61
	s_nop 0
	global_load_lds_dwordx4 v[174:175], off
	s_waitcnt vmcnt(8)
	s_waitcnt lgkmcnt(0)
	s_barrier
	s_waitcnt lgkmcnt(0)
	v_mfma_f32_16x16x32_bf16 v[60:63], v[128:131], v[186:189], v[60:63]
	s_add_u32 s30, s30, 0x100
	v_mfma_f32_16x16x32_bf16 v[56:59], v[136:139], v[186:189], v[56:59]
	s_addc_u32 s31, s31, 0
	v_mfma_f32_16x16x32_bf16 v[44:47], v[128:131], v[194:197], v[44:47]
	s_add_u32 s10, s10, 0x100
	v_mfma_f32_16x16x32_bf16 v[40:43], v[136:139], v[194:197], v[40:43]
	s_addc_u32 s11, s11, 0
	v_mfma_f32_16x16x32_bf16 v[28:31], v[128:131], v[202:205], v[28:31]
	s_mov_b32 s34, s44
	v_mfma_f32_16x16x32_bf16 v[24:27], v[136:139], v[202:205], v[24:27]
	s_cmp_ge_i32 s44, s59
	v_mfma_f32_16x16x32_bf16 v[12:15], v[128:131], v[210:213], v[12:15]
	s_cselect_b32 s99, 1, 0
	v_mfma_f32_16x16x32_bf16 v[8:11], v[136:139], v[210:213], v[8:11]
	s_add_i32 s44, s34, 2
	v_mfma_f32_16x16x32_bf16 v[60:63], v[132:135], v[190:193], v[60:63]
	s_add_u32 s4, s30, 0x80
	v_mfma_f32_16x16x32_bf16 v[56:59], v[140:143], v[190:193], v[56:59]
	s_addc_u32 s5, s31, 0
	v_mfma_f32_16x16x32_bf16 v[44:47], v[132:135], v[198:201], v[44:47]
	s_add_i32 s45, 0, 0x10000
	v_mfma_f32_16x16x32_bf16 v[40:43], v[140:143], v[198:201], v[40:43]
	s_cmp_eq_u32 s62, s34
	v_mfma_f32_16x16x32_bf16 v[28:31], v[132:135], v[206:209], v[28:31]
	s_cselect_b32 s35, s27, s5
	v_mfma_f32_16x16x32_bf16 v[24:27], v[140:143], v[206:209], v[24:27]
	s_cselect_b32 s34, s26, s4
	v_mfma_f32_16x16x32_bf16 v[12:15], v[132:135], v[214:217], v[12:15]
	s_cselect_b32 s5, s29, s11
	v_mfma_f32_16x16x32_bf16 v[8:11], v[140:143], v[214:217], v[8:11]
	s_cselect_b32 s4, s28, s10
	v_mfma_f32_16x16x32_bf16 v[52:55], v[154:157], v[186:189], v[52:55]
	s_add_i32 s54, 0, 0x14000
	v_mfma_f32_16x16x32_bf16 v[48:51], v[166:169], v[186:189], v[48:51]
	v_mfma_f32_16x16x32_bf16 v[36:39], v[154:157], v[194:197], v[36:39]
	v_mfma_f32_16x16x32_bf16 v[32:35], v[166:169], v[194:197], v[32:35]
	v_mfma_f32_16x16x32_bf16 v[20:23], v[154:157], v[202:205], v[20:23]
	v_mfma_f32_16x16x32_bf16 v[16:19], v[166:169], v[202:205], v[16:19]
	v_mfma_f32_16x16x32_bf16 v[4:7], v[154:157], v[210:213], v[4:7]
	v_mfma_f32_16x16x32_bf16 v[0:3], v[166:169], v[210:213], v[0:3]
	v_mfma_f32_16x16x32_bf16 v[52:55], v[158:161], v[190:193], v[52:55]
	v_mfma_f32_16x16x32_bf16 v[48:51], v[170:173], v[190:193], v[48:51]
	v_mfma_f32_16x16x32_bf16 v[36:39], v[158:161], v[198:201], v[36:39]
	v_mfma_f32_16x16x32_bf16 v[32:35], v[170:173], v[198:201], v[32:35]
	v_mfma_f32_16x16x32_bf16 v[20:23], v[158:161], v[206:209], v[20:23]
	v_mfma_f32_16x16x32_bf16 v[16:19], v[170:173], v[206:209], v[16:19]
	v_mfma_f32_16x16x32_bf16 v[4:7], v[158:161], v[214:217], v[4:7]
	v_mfma_f32_16x16x32_bf16 v[0:3], v[170:173], v[214:217], v[0:3]
	s_barrier
	s_cmp_lg_u32 s99, 0
	s_cbranch_scc1 .Lpeelx_6
.LBB0_305:
	v_add_u32_e32 v140, s45, v163
	v_add_u32_e32 v170, s54, v163
	ds_read_b128 v[128:131], v140
	ds_read_b128 v[132:135], v140 offset:1024
	ds_read_b128 v[136:139], v140 offset:2048
	ds_read_b128 v[140:143], v140 offset:3072
	ds_read_b128 v[154:157], v170
	ds_read_b128 v[158:161], v170 offset:1024
	ds_read_b128 v[166:169], v170 offset:2048
	ds_read_b128 v[170:173], v170 offset:3072
	v_lshl_add_u64 v[174:175], s[30:31], 0, v[150:151]
	s_add_i32 m0, s38, 0xc000
	ds_read_b128 v[186:189], v165
	ds_read_b128 v[190:193], v165 offset:1024
	ds_read_b128 v[194:197], v165 offset:2048
	ds_read_b128 v[198:201], v165 offset:3072
	ds_read_b128 v[202:205], v165 offset:4096
	ds_read_b128 v[206:209], v165 offset:5120
	ds_read_b128 v[210:213], v165 offset:6144
	ds_read_b128 v[214:217], v165 offset:7168
	global_load_lds_dwordx4 v[174:175], off
	v_lshl_add_u64 v[174:175], s[30:31], 0, v[152:153]
	s_add_i32 m0, s38, 0xe000
	s_nop 0
	global_load_lds_dwordx4 v[174:175], off
	s_waitcnt vmcnt(8)
	s_waitcnt lgkmcnt(0)
	s_barrier
	s_waitcnt lgkmcnt(0)
	v_mfma_f32_16x16x32_bf16 v[124:127], v[128:131], v[186:189], v[124:127]
	v_mfma_f32_16x16x32_bf16 v[120:123], v[136:139], v[186:189], v[120:123]
	v_mfma_f32_16x16x32_bf16 v[108:111], v[128:131], v[194:197], v[108:111]
	v_mfma_f32_16x16x32_bf16 v[104:107], v[136:139], v[194:197], v[104:107]
	v_mfma_f32_16x16x32_bf16 v[92:95], v[128:131], v[202:205], v[92:95]
	v_mfma_f32_16x16x32_bf16 v[88:91], v[136:139], v[202:205], v[88:91]
	v_mfma_f32_16x16x32_bf16 v[76:79], v[128:131], v[210:213], v[76:79]
	v_mfma_f32_16x16x32_bf16 v[72:75], v[136:139], v[210:213], v[72:75]
	v_mfma_f32_16x16x32_bf16 v[124:127], v[132:135], v[190:193], v[124:127]
	v_mfma_f32_16x16x32_bf16 v[120:123], v[140:143], v[190:193], v[120:123]
	v_mfma_f32_16x16x32_bf16 v[108:111], v[132:135], v[198:201], v[108:111]
	v_mfma_f32_16x16x32_bf16 v[104:107], v[140:143], v[198:201], v[104:107]
	v_mfma_f32_16x16x32_bf16 v[92:95], v[132:135], v[206:209], v[92:95]
	v_mfma_f32_16x16x32_bf16 v[88:91], v[140:143], v[206:209], v[88:91]
	v_mfma_f32_16x16x32_bf16 v[76:79], v[132:135], v[214:217], v[76:79]
	v_mfma_f32_16x16x32_bf16 v[72:75], v[140:143], v[214:217], v[72:75]
	v_mfma_f32_16x16x32_bf16 v[116:119], v[154:157], v[186:189], v[116:119]
	v_mfma_f32_16x16x32_bf16 v[112:115], v[166:169], v[186:189], v[112:115]
	v_mfma_f32_16x16x32_bf16 v[100:103], v[154:157], v[194:197], v[100:103]
	v_mfma_f32_16x16x32_bf16 v[96:99], v[166:169], v[194:197], v[96:99]
	v_mfma_f32_16x16x32_bf16 v[84:87], v[154:157], v[202:205], v[84:87]
	v_mfma_f32_16x16x32_bf16 v[80:83], v[166:169], v[202:205], v[80:83]
	v_mfma_f32_16x16x32_bf16 v[68:71], v[154:157], v[210:213], v[68:71]
	v_mfma_f32_16x16x32_bf16 v[64:67], v[166:169], v[210:213], v[64:67]
	v_mfma_f32_16x16x32_bf16 v[116:119], v[158:161], v[190:193], v[116:119]
	v_mfma_f32_16x16x32_bf16 v[112:115], v[170:173], v[190:193], v[112:115]
	v_mfma_f32_16x16x32_bf16 v[100:103], v[158:161], v[198:201], v[100:103]
	v_mfma_f32_16x16x32_bf16 v[96:99], v[170:173], v[198:201], v[96:99]
	v_mfma_f32_16x16x32_bf16 v[84:87], v[158:161], v[206:209], v[84:87]
	v_mfma_f32_16x16x32_bf16 v[80:83], v[170:173], v[206:209], v[80:83]
	v_mfma_f32_16x16x32_bf16 v[68:71], v[158:161], v[214:217], v[68:71]
	v_mfma_f32_16x16x32_bf16 v[64:67], v[170:173], v[214:217], v[64:67]
	s_barrier
	s_add_i32 s45, s45, s37
	v_lshl_add_u64 v[174:175], s[4:5], 0, v[176:177]
	s_mov_b32 m0, s45
	ds_read_b128 v[186:189], v165 offset:16384
	ds_read_b128 v[190:193], v165 offset:17408
	ds_read_b128 v[194:197], v165 offset:18432
	ds_read_b128 v[198:201], v165 offset:19456
	ds_read_b128 v[202:205], v165 offset:20480
	ds_read_b128 v[206:209], v165 offset:21504
	ds_read_b128 v[210:213], v165 offset:22528
	ds_read_b128 v[214:217], v165 offset:23552
	global_load_lds_dwordx4 v[174:175], off
	s_add_i32 m0, s45, 0x2000
	v_lshl_add_u64 v[222:223], s[4:5], 0, v[144:145]
	s_add_u32 s4, s4, s0
	s_addc_u32 s5, s5, s1
	s_add_i32 s45, s54, s37
	global_load_lds_dwordx4 v[222:223], off
	v_lshl_add_u64 v[224:225], s[4:5], 0, v[176:177]
	s_mov_b32 m0, s45
	v_lshl_add_u64 v[226:227], s[4:5], 0, v[144:145]
	global_load_lds_dwordx4 v[224:225], off
	s_add_i32 m0, s45, 0x2000
	v_lshl_add_u64 v[228:229], s[34:35], 0, v[148:149]
	global_load_lds_dwordx4 v[226:227], off
	s_mov_b32 m0, s38
	v_lshl_add_u64 v[230:231], s[34:35], 0, v[146:147]
	global_load_lds_dwordx4 v[228:229], off
	s_mov_b32 m0, s39
	s_nop 0
	global_load_lds_dwordx4 v[230:231], off
	s_waitcnt vmcnt(8)
	s_waitcnt lgkmcnt(0)
	s_barrier
	s_waitcnt lgkmcnt(0)
	v_mfma_f32_16x16x32_bf16 v[60:63], v[128:131], v[186:189], v[60:63]
	v_mfma_f32_16x16x32_bf16 v[56:59], v[136:139], v[186:189], v[56:59]
	v_mfma_f32_16x16x32_bf16 v[44:47], v[128:131], v[194:197], v[44:47]
	v_mfma_f32_16x16x32_bf16 v[40:43], v[136:139], v[194:197], v[40:43]
	v_mfma_f32_16x16x32_bf16 v[28:31], v[128:131], v[202:205], v[28:31]
	v_mfma_f32_16x16x32_bf16 v[24:27], v[136:139], v[202:205], v[24:27]
	v_mfma_f32_16x16x32_bf16 v[12:15], v[128:131], v[210:213], v[12:15]
	v_mfma_f32_16x16x32_bf16 v[8:11], v[136:139], v[210:213], v[8:11]
	v_mfma_f32_16x16x32_bf16 v[60:63], v[132:135], v[190:193], v[60:63]
	v_mfma_f32_16x16x32_bf16 v[56:59], v[140:143], v[190:193], v[56:59]
	v_mfma_f32_16x16x32_bf16 v[44:47], v[132:135], v[198:201], v[44:47]
	v_mfma_f32_16x16x32_bf16 v[40:43], v[140:143], v[198:201], v[40:43]
	v_mfma_f32_16x16x32_bf16 v[28:31], v[132:135], v[206:209], v[28:31]
	v_mfma_f32_16x16x32_bf16 v[24:27], v[140:143], v[206:209], v[24:27]
	v_mfma_f32_16x16x32_bf16 v[12:15], v[132:135], v[214:217], v[12:15]
	v_mfma_f32_16x16x32_bf16 v[8:11], v[140:143], v[214:217], v[8:11]
	v_mfma_f32_16x16x32_bf16 v[52:55], v[154:157], v[186:189], v[52:55]
	v_mfma_f32_16x16x32_bf16 v[48:51], v[166:169], v[186:189], v[48:51]
	v_mfma_f32_16x16x32_bf16 v[36:39], v[154:157], v[194:197], v[36:39]
	v_mfma_f32_16x16x32_bf16 v[32:35], v[166:169], v[194:197], v[32:35]
	v_mfma_f32_16x16x32_bf16 v[20:23], v[154:157], v[202:205], v[20:23]
	v_mfma_f32_16x16x32_bf16 v[16:19], v[166:169], v[202:205], v[16:19]
	v_mfma_f32_16x16x32_bf16 v[4:7], v[154:157], v[210:213], v[4:7]
	v_mfma_f32_16x16x32_bf16 v[0:3], v[166:169], v[210:213], v[0:3]
	v_mfma_f32_16x16x32_bf16 v[52:55], v[158:161], v[190:193], v[52:55]
	v_mfma_f32_16x16x32_bf16 v[48:51], v[170:173], v[190:193], v[48:51]
	v_mfma_f32_16x16x32_bf16 v[36:39], v[158:161], v[198:201], v[36:39]
	v_mfma_f32_16x16x32_bf16 v[32:35], v[170:173], v[198:201], v[32:35]
	v_mfma_f32_16x16x32_bf16 v[20:23], v[158:161], v[206:209], v[20:23]
	v_mfma_f32_16x16x32_bf16 v[16:19], v[170:173], v[206:209], v[16:19]
	v_mfma_f32_16x16x32_bf16 v[4:7], v[158:161], v[214:217], v[4:7]
	v_mfma_f32_16x16x32_bf16 v[0:3], v[170:173], v[214:217], v[0:3]
	s_barrier
	s_add_i32 s45, 0, 0x18000
	s_add_i32 s54, 0, 0x1c000
	v_add_u32_e32 v140, s45, v163
	v_add_u32_e32 v170, s54, v163
	ds_read_b128 v[128:131], v140
	ds_read_b128 v[132:135], v140 offset:1024
	ds_read_b128 v[136:139], v140 offset:2048
	ds_read_b128 v[140:143], v140 offset:3072
	ds_read_b128 v[154:157], v170
	ds_read_b128 v[158:161], v170 offset:1024
	ds_read_b128 v[166:169], v170 offset:2048
	ds_read_b128 v[170:173], v170 offset:3072
	s_add_u32 s4, s34, s0
	s_addc_u32 s5, s35, s1
	s_mov_b32 m0, s48
	v_lshl_add_u64 v[232:233], s[4:5], 0, v[148:149]
	ds_read_b128 v[186:189], v165 offset:32768
	ds_read_b128 v[190:193], v165 offset:33792
	ds_read_b128 v[194:197], v165 offset:34816
	ds_read_b128 v[198:201], v165 offset:35840
	ds_read_b128 v[202:205], v165 offset:36864
	ds_read_b128 v[206:209], v165 offset:37888
	ds_read_b128 v[210:213], v165 offset:38912
	ds_read_b128 v[214:217], v165 offset:39936
	global_load_lds_dwordx4 v[232:233], off
	v_lshl_add_u64 v[232:233], s[4:5], 0, v[146:147]
	s_mov_b32 m0, s49
	s_nop 0
	global_load_lds_dwordx4 v[232:233], off
	s_waitcnt vmcnt(8)
	s_waitcnt lgkmcnt(0)
	s_barrier
	s_waitcnt lgkmcnt(0)
	v_mfma_f32_16x16x32_bf16 v[124:127], v[128:131], v[186:189], v[124:127]
	v_mfma_f32_16x16x32_bf16 v[120:123], v[136:139], v[186:189], v[120:123]
	v_mfma_f32_16x16x32_bf16 v[108:111], v[128:131], v[194:197], v[108:111]
	v_mfma_f32_16x16x32_bf16 v[104:107], v[136:139], v[194:197], v[104:107]
	v_mfma_f32_16x16x32_bf16 v[92:95], v[128:131], v[202:205], v[92:95]
	v_mfma_f32_16x16x32_bf16 v[88:91], v[136:139], v[202:205], v[88:91]
	v_mfma_f32_16x16x32_bf16 v[76:79], v[128:131], v[210:213], v[76:79]
	v_mfma_f32_16x16x32_bf16 v[72:75], v[136:139], v[210:213], v[72:75]
	v_mfma_f32_16x16x32_bf16 v[124:127], v[132:135], v[190:193], v[124:127]
	v_mfma_f32_16x16x32_bf16 v[120:123], v[140:143], v[190:193], v[120:123]
	v_mfma_f32_16x16x32_bf16 v[108:111], v[132:135], v[198:201], v[108:111]
	v_mfma_f32_16x16x32_bf16 v[104:107], v[140:143], v[198:201], v[104:107]
	v_mfma_f32_16x16x32_bf16 v[92:95], v[132:135], v[206:209], v[92:95]
	v_mfma_f32_16x16x32_bf16 v[88:91], v[140:143], v[206:209], v[88:91]
	v_mfma_f32_16x16x32_bf16 v[76:79], v[132:135], v[214:217], v[76:79]
	v_mfma_f32_16x16x32_bf16 v[72:75], v[140:143], v[214:217], v[72:75]
	v_mfma_f32_16x16x32_bf16 v[116:119], v[154:157], v[186:189], v[116:119]
	v_mfma_f32_16x16x32_bf16 v[112:115], v[166:169], v[186:189], v[112:115]
	v_mfma_f32_16x16x32_bf16 v[100:103], v[154:157], v[194:197], v[100:103]
	v_mfma_f32_16x16x32_bf16 v[96:99], v[166:169], v[194:197], v[96:99]
	v_mfma_f32_16x16x32_bf16 v[84:87], v[154:157], v[202:205], v[84:87]
	v_mfma_f32_16x16x32_bf16 v[80:83], v[166:169], v[202:205], v[80:83]
	v_mfma_f32_16x16x32_bf16 v[68:71], v[154:157], v[210:213], v[68:71]
	v_mfma_f32_16x16x32_bf16 v[64:67], v[166:169], v[210:213], v[64:67]
	v_mfma_f32_16x16x32_bf16 v[116:119], v[158:161], v[190:193], v[116:119]
	v_mfma_f32_16x16x32_bf16 v[112:115], v[170:173], v[190:193], v[112:115]
	v_mfma_f32_16x16x32_bf16 v[100:103], v[158:161], v[198:201], v[100:103]
	v_mfma_f32_16x16x32_bf16 v[96:99], v[170:173], v[198:201], v[96:99]
	v_mfma_f32_16x16x32_bf16 v[84:87], v[158:161], v[206:209], v[84:87]
	v_mfma_f32_16x16x32_bf16 v[80:83], v[170:173], v[206:209], v[80:83]
	v_mfma_f32_16x16x32_bf16 v[68:71], v[158:161], v[214:217], v[68:71]
	v_mfma_f32_16x16x32_bf16 v[64:67], v[170:173], v[214:217], v[64:67]
	s_barrier
	s_add_i32 s4, s45, s37
	v_lshl_add_u64 v[174:175], v[174:175], 0, s[14:15]
	s_mov_b32 m0, s4
	ds_read_b128 v[186:189], v165 offset:49152
	ds_read_b128 v[190:193], v165 offset:50176
	ds_read_b128 v[194:197], v165 offset:51200
	ds_read_b128 v[198:201], v165 offset:52224
	ds_read_b128 v[202:205], v165 offset:53248
	ds_read_b128 v[206:209], v165 offset:54272
	ds_read_b128 v[210:213], v165 offset:55296
	ds_read_b128 v[214:217], v165 offset:56320
	global_load_lds_dwordx4 v[174:175], off
	v_lshl_add_u64 v[174:175], v[222:223], 0, s[14:15]
	s_add_i32 m0, s4, 0x2000
	s_add_i32 s4, s54, s37
	global_load_lds_dwordx4 v[174:175], off
	v_lshl_add_u64 v[174:175], v[224:225], 0, s[14:15]
	s_mov_b32 m0, s4
	s_nop 0
	global_load_lds_dwordx4 v[174:175], off
	v_lshl_add_u64 v[174:175], v[226:227], 0, s[14:15]
	s_add_i32 m0, s4, 0x2000
	s_nop 0
	global_load_lds_dwordx4 v[174:175], off
	v_lshl_add_u64 v[174:175], v[228:229], 0, s[14:15]
	s_mov_b32 m0, s60
	s_nop 0
	global_load_lds_dwordx4 v[174:175], off
	v_lshl_add_u64 v[174:175], v[230:231], 0, s[14:15]
	s_mov_b32 m0, s61
	s_nop 0
	global_load_lds_dwordx4 v[174:175], off
	s_waitcnt vmcnt(8)
	s_waitcnt lgkmcnt(0)
	s_barrier
	s_waitcnt lgkmcnt(0)
	v_mfma_f32_16x16x32_bf16 v[60:63], v[128:131], v[186:189], v[60:63]
	s_add_u32 s30, s30, 0x100
	v_mfma_f32_16x16x32_bf16 v[56:59], v[136:139], v[186:189], v[56:59]
	s_addc_u32 s31, s31, 0
	v_mfma_f32_16x16x32_bf16 v[44:47], v[128:131], v[194:197], v[44:47]
	s_add_u32 s10, s10, 0x100
	v_mfma_f32_16x16x32_bf16 v[40:43], v[136:139], v[194:197], v[40:43]
	s_addc_u32 s11, s11, 0
	v_mfma_f32_16x16x32_bf16 v[28:31], v[128:131], v[202:205], v[28:31]
	s_mov_b32 s34, s44
	v_mfma_f32_16x16x32_bf16 v[24:27], v[136:139], v[202:205], v[24:27]
	s_cmp_ge_i32 s44, s59
	v_mfma_f32_16x16x32_bf16 v[12:15], v[128:131], v[210:213], v[12:15]
	s_cselect_b32 s99, 1, 0
	v_mfma_f32_16x16x32_bf16 v[8:11], v[136:139], v[210:213], v[8:11]
	s_add_i32 s44, s34, 2
	v_mfma_f32_16x16x32_bf16 v[60:63], v[132:135], v[190:193], v[60:63]
	s_add_u32 s4, s30, 0x80
	v_mfma_f32_16x16x32_bf16 v[56:59], v[140:143], v[190:193], v[56:59]
	s_addc_u32 s5, s31, 0
	v_mfma_f32_16x16x32_bf16 v[44:47], v[132:135], v[198:201], v[44:47]
	s_add_i32 s45, 0, 0x10000
	v_mfma_f32_16x16x32_bf16 v[40:43], v[140:143], v[198:201], v[40:43]
	s_cmp_eq_u32 s62, s34
	v_mfma_f32_16x16x32_bf16 v[28:31], v[132:135], v[206:209], v[28:31]
	s_cselect_b32 s35, s27, s5
	v_mfma_f32_16x16x32_bf16 v[24:27], v[140:143], v[206:209], v[24:27]
	s_cselect_b32 s34, s26, s4
	v_mfma_f32_16x16x32_bf16 v[12:15], v[132:135], v[214:217], v[12:15]
	s_cselect_b32 s5, s29, s11
	v_mfma_f32_16x16x32_bf16 v[8:11], v[140:143], v[214:217], v[8:11]
	s_cselect_b32 s4, s28, s10
	v_mfma_f32_16x16x32_bf16 v[52:55], v[154:157], v[186:189], v[52:55]
	s_add_i32 s54, 0, 0x14000
	v_mfma_f32_16x16x32_bf16 v[48:51], v[166:169], v[186:189], v[48:51]
	v_mfma_f32_16x16x32_bf16 v[36:39], v[154:157], v[194:197], v[36:39]
	v_mfma_f32_16x16x32_bf16 v[32:35], v[166:169], v[194:197], v[32:35]
	v_mfma_f32_16x16x32_bf16 v[20:23], v[154:157], v[202:205], v[20:23]
	v_mfma_f32_16x16x32_bf16 v[16:19], v[166:169], v[202:205], v[16:19]
	v_mfma_f32_16x16x32_bf16 v[4:7], v[154:157], v[210:213], v[4:7]
	v_mfma_f32_16x16x32_bf16 v[0:3], v[166:169], v[210:213], v[0:3]
	v_mfma_f32_16x16x32_bf16 v[52:55], v[158:161], v[190:193], v[52:55]
	v_mfma_f32_16x16x32_bf16 v[48:51], v[170:173], v[190:193], v[48:51]
	v_mfma_f32_16x16x32_bf16 v[36:39], v[158:161], v[198:201], v[36:39]
	v_mfma_f32_16x16x32_bf16 v[32:35], v[170:173], v[198:201], v[32:35]
	v_mfma_f32_16x16x32_bf16 v[20:23], v[158:161], v[206:209], v[20:23]
	v_mfma_f32_16x16x32_bf16 v[16:19], v[170:173], v[206:209], v[16:19]
	v_mfma_f32_16x16x32_bf16 v[4:7], v[158:161], v[214:217], v[4:7]
	v_mfma_f32_16x16x32_bf16 v[0:3], v[170:173], v[214:217], v[0:3]
	s_barrier
	s_cmp_lg_u32 s99, 0
	s_cbranch_scc0 .LBB0_305

.Llbb_3:
	s_add_i32 s44, s30, 2
	s_add_u32 s4, s28, 0x80
	s_addc_u32 s5, s29, 0
	s_add_i32 s45, 0, 0x10000
	s_cmp_eq_u32 s61, s30
	s_cselect_b32 s31, s25, s5
	s_cselect_b32 s30, s24, s4
	s_cselect_b32 s5, s27, s11
	s_cselect_b32 s4, s26, s10
	s_add_i32 s54, 0, 0x14000
	v_add_u32_e32 v156, s45, v151
	v_add_u32_e32 v172, s54, v151
	ds_read_b128 v[128:131], v156
	ds_read_b128 v[142:145], v156 offset:1024
	ds_read_b128 v[146:149], v156 offset:2048
	ds_read_b128 v[156:159], v156 offset:3072
	ds_read_b128 v[160:163], v172
	ds_read_b128 v[164:167], v172 offset:1024
	ds_read_b128 v[168:171], v172 offset:2048
	ds_read_b128 v[172:175], v172 offset:3072
	v_lshl_add_u64 v[222:223], s[28:29], 0, v[138:139]
	s_add_i32 m0, s37, 0xc000
	ds_read_b128 v[186:189], v155
	ds_read_b128 v[190:193], v155 offset:1024
	ds_read_b128 v[194:197], v155 offset:2048
	ds_read_b128 v[198:201], v155 offset:3072
	ds_read_b128 v[202:205], v155 offset:4096
	ds_read_b128 v[206:209], v155 offset:5120
	ds_read_b128 v[210:213], v155 offset:6144
	ds_read_b128 v[214:217], v155 offset:7168
	global_load_lds_dwordx4 v[222:223], off
	v_lshl_add_u64 v[222:223], s[28:29], 0, v[140:141]
	s_add_i32 m0, s37, 0xe000
	s_nop 0
	global_load_lds_dwordx4 v[222:223], off
	s_waitcnt vmcnt(8)
	s_waitcnt lgkmcnt(0)
	s_barrier
	s_waitcnt lgkmcnt(0)
	v_mfma_f32_16x16x32_bf16 v[120:123], v[128:131], v[186:189], 0
	v_mfma_f32_16x16x32_bf16 v[116:119], v[146:149], v[186:189], 0
	v_mfma_f32_16x16x32_bf16 v[108:111], v[128:131], v[194:197], 0
	v_mfma_f32_16x16x32_bf16 v[100:103], v[146:149], v[194:197], 0
	v_mfma_f32_16x16x32_bf16 v[92:95], v[128:131], v[202:205], 0
	v_mfma_f32_16x16x32_bf16 v[84:87], v[146:149], v[202:205], 0
	v_mfma_f32_16x16x32_bf16 v[76:79], v[128:131], v[210:213], 0
	v_mfma_f32_16x16x32_bf16 v[68:71], v[146:149], v[210:213], 0
	v_mfma_f32_16x16x32_bf16 v[120:123], v[142:145], v[190:193], v[120:123]
	v_mfma_f32_16x16x32_bf16 v[116:119], v[156:159], v[190:193], v[116:119]
	v_mfma_f32_16x16x32_bf16 v[108:111], v[142:145], v[198:201], v[108:111]
	v_mfma_f32_16x16x32_bf16 v[100:103], v[156:159], v[198:201], v[100:103]
	v_mfma_f32_16x16x32_bf16 v[92:95], v[142:145], v[206:209], v[92:95]
	v_mfma_f32_16x16x32_bf16 v[84:87], v[156:159], v[206:209], v[84:87]
	v_mfma_f32_16x16x32_bf16 v[76:79], v[142:145], v[214:217], v[76:79]
	v_mfma_f32_16x16x32_bf16 v[68:71], v[156:159], v[214:217], v[68:71]
	v_mfma_f32_16x16x32_bf16 v[124:127], v[160:163], v[186:189], 0
	v_mfma_f32_16x16x32_bf16 v[112:115], v[168:171], v[186:189], 0
	v_mfma_f32_16x16x32_bf16 v[104:107], v[160:163], v[194:197], 0
	v_mfma_f32_16x16x32_bf16 v[96:99], v[168:171], v[194:197], 0
	v_mfma_f32_16x16x32_bf16 v[88:91], v[160:163], v[202:205], 0
	v_mfma_f32_16x16x32_bf16 v[80:83], v[168:171], v[202:205], 0
	v_mfma_f32_16x16x32_bf16 v[72:75], v[160:163], v[210:213], 0
	v_mfma_f32_16x16x32_bf16 v[64:67], v[168:171], v[210:213], 0
	v_mfma_f32_16x16x32_bf16 v[124:127], v[164:167], v[190:193], v[124:127]
	v_mfma_f32_16x16x32_bf16 v[112:115], v[172:175], v[190:193], v[112:115]
	v_mfma_f32_16x16x32_bf16 v[104:107], v[164:167], v[198:201], v[104:107]
	v_mfma_f32_16x16x32_bf16 v[96:99], v[172:175], v[198:201], v[96:99]
	v_mfma_f32_16x16x32_bf16 v[88:91], v[164:167], v[206:209], v[88:91]
	v_mfma_f32_16x16x32_bf16 v[80:83], v[172:175], v[206:209], v[80:83]
	v_mfma_f32_16x16x32_bf16 v[72:75], v[164:167], v[214:217], v[72:75]
	v_mfma_f32_16x16x32_bf16 v[64:67], v[172:175], v[214:217], v[64:67]
	s_barrier
	s_add_i32 s45, s45, s36
	v_lshl_add_u64 v[222:223], s[4:5], 0, v[176:177]
	s_mov_b32 m0, s45
	ds_read_b128 v[186:189], v155 offset:16384
	ds_read_b128 v[190:193], v155 offset:17408
	ds_read_b128 v[194:197], v155 offset:18432
	ds_read_b128 v[198:201], v155 offset:19456
	ds_read_b128 v[202:205], v155 offset:20480
	ds_read_b128 v[206:209], v155 offset:21504
	ds_read_b128 v[210:213], v155 offset:22528
	ds_read_b128 v[214:217], v155 offset:23552
	global_load_lds_dwordx4 v[222:223], off
	s_add_i32 m0, s45, 0x2000
	v_lshl_add_u64 v[224:225], s[4:5], 0, v[132:133]
	s_add_u32 s4, s4, s6
	s_addc_u32 s5, s5, s7
	s_add_i32 s45, s54, s36
	global_load_lds_dwordx4 v[224:225], off
	v_lshl_add_u64 v[226:227], s[4:5], 0, v[176:177]
	s_mov_b32 m0, s45
	v_lshl_add_u64 v[228:229], s[4:5], 0, v[132:133]
	global_load_lds_dwordx4 v[226:227], off
	s_add_i32 m0, s45, 0x2000
	v_lshl_add_u64 v[230:231], s[30:31], 0, v[136:137]
	global_load_lds_dwordx4 v[228:229], off
	s_mov_b32 m0, s37
	v_lshl_add_u64 v[232:233], s[30:31], 0, v[134:135]
	global_load_lds_dwordx4 v[230:231], off
	s_mov_b32 m0, s38
	s_nop 0
	global_load_lds_dwordx4 v[232:233], off
	s_waitcnt vmcnt(8)
	s_waitcnt lgkmcnt(0)
	s_barrier
	s_waitcnt lgkmcnt(0)
	v_mfma_f32_16x16x32_bf16 v[60:63], v[128:131], v[186:189], 0
	v_mfma_f32_16x16x32_bf16 v[52:55], v[146:149], v[186:189], 0
	v_mfma_f32_16x16x32_bf16 v[44:47], v[128:131], v[194:197], 0
	v_mfma_f32_16x16x32_bf16 v[36:39], v[146:149], v[194:197], 0
	v_mfma_f32_16x16x32_bf16 v[28:31], v[128:131], v[202:205], 0
	v_mfma_f32_16x16x32_bf16 v[20:23], v[146:149], v[202:205], 0
	v_mfma_f32_16x16x32_bf16 v[12:15], v[128:131], v[210:213], 0
	v_mfma_f32_16x16x32_bf16 v[4:7], v[146:149], v[210:213], 0
	v_mfma_f32_16x16x32_bf16 v[60:63], v[142:145], v[190:193], v[60:63]
	v_mfma_f32_16x16x32_bf16 v[52:55], v[156:159], v[190:193], v[52:55]
	v_mfma_f32_16x16x32_bf16 v[44:47], v[142:145], v[198:201], v[44:47]
	v_mfma_f32_16x16x32_bf16 v[36:39], v[156:159], v[198:201], v[36:39]
	v_mfma_f32_16x16x32_bf16 v[28:31], v[142:145], v[206:209], v[28:31]
	v_mfma_f32_16x16x32_bf16 v[20:23], v[156:159], v[206:209], v[20:23]
	v_mfma_f32_16x16x32_bf16 v[12:15], v[142:145], v[214:217], v[12:15]
	v_mfma_f32_16x16x32_bf16 v[4:7], v[156:159], v[214:217], v[4:7]
	v_mfma_f32_16x16x32_bf16 v[56:59], v[160:163], v[186:189], 0
	v_mfma_f32_16x16x32_bf16 v[48:51], v[168:171], v[186:189], 0
	v_mfma_f32_16x16x32_bf16 v[40:43], v[160:163], v[194:197], 0
	v_mfma_f32_16x16x32_bf16 v[32:35], v[168:171], v[194:197], 0
	v_mfma_f32_16x16x32_bf16 v[24:27], v[160:163], v[202:205], 0
	v_mfma_f32_16x16x32_bf16 v[16:19], v[168:171], v[202:205], 0
	v_mfma_f32_16x16x32_bf16 v[8:11], v[160:163], v[210:213], 0
	v_mfma_f32_16x16x32_bf16 v[0:3], v[168:171], v[210:213], 0
	v_mfma_f32_16x16x32_bf16 v[56:59], v[164:167], v[190:193], v[56:59]
	v_mfma_f32_16x16x32_bf16 v[48:51], v[172:175], v[190:193], v[48:51]
	v_mfma_f32_16x16x32_bf16 v[40:43], v[164:167], v[198:201], v[40:43]
	v_mfma_f32_16x16x32_bf16 v[32:35], v[172:175], v[198:201], v[32:35]
	v_mfma_f32_16x16x32_bf16 v[24:27], v[164:167], v[206:209], v[24:27]
	v_mfma_f32_16x16x32_bf16 v[16:19], v[172:175], v[206:209], v[16:19]
	v_mfma_f32_16x16x32_bf16 v[8:11], v[164:167], v[214:217], v[8:11]
	v_mfma_f32_16x16x32_bf16 v[0:3], v[172:175], v[214:217], v[0:3]
	s_barrier
	s_add_i32 s45, 0, 0x18000
	s_add_i32 s54, 0, 0x1c000
	v_add_u32_e32 v156, s45, v151
	v_add_u32_e32 v172, s54, v151
	ds_read_b128 v[128:131], v156
	ds_read_b128 v[142:145], v156 offset:1024
	ds_read_b128 v[146:149], v156 offset:2048
	ds_read_b128 v[156:159], v156 offset:3072
	ds_read_b128 v[160:163], v172
	ds_read_b128 v[164:167], v172 offset:1024
	ds_read_b128 v[168:171], v172 offset:2048
	ds_read_b128 v[172:175], v172 offset:3072
	s_add_u32 s4, s30, s6
	s_addc_u32 s5, s31, s7
	s_mov_b32 m0, s39
	v_lshl_add_u64 v[234:235], s[4:5], 0, v[136:137]
	ds_read_b128 v[186:189], v155 offset:32768
	ds_read_b128 v[190:193], v155 offset:33792
	ds_read_b128 v[194:197], v155 offset:34816
	ds_read_b128 v[198:201], v155 offset:35840
	ds_read_b128 v[202:205], v155 offset:36864
	ds_read_b128 v[206:209], v155 offset:37888
	ds_read_b128 v[210:213], v155 offset:38912
	ds_read_b128 v[214:217], v155 offset:39936
	global_load_lds_dwordx4 v[234:235], off
	v_lshl_add_u64 v[234:235], s[4:5], 0, v[134:135]
	s_mov_b32 m0, s48
	s_nop 0
	global_load_lds_dwordx4 v[234:235], off
	s_waitcnt vmcnt(8)
	s_waitcnt lgkmcnt(0)
	s_barrier
	s_waitcnt lgkmcnt(0)
	v_mfma_f32_16x16x32_bf16 v[120:123], v[128:131], v[186:189], v[120:123]
	v_mfma_f32_16x16x32_bf16 v[116:119], v[146:149], v[186:189], v[116:119]
	v_mfma_f32_16x16x32_bf16 v[108:111], v[128:131], v[194:197], v[108:111]
	v_mfma_f32_16x16x32_bf16 v[100:103], v[146:149], v[194:197], v[100:103]
	v_mfma_f32_16x16x32_bf16 v[92:95], v[128:131], v[202:205], v[92:95]
	v_mfma_f32_16x16x32_bf16 v[84:87], v[146:149], v[202:205], v[84:87]
	v_mfma_f32_16x16x32_bf16 v[76:79], v[128:131], v[210:213], v[76:79]
	v_mfma_f32_16x16x32_bf16 v[68:71], v[146:149], v[210:213], v[68:71]
	v_mfma_f32_16x16x32_bf16 v[120:123], v[142:145], v[190:193], v[120:123]
	v_mfma_f32_16x16x32_bf16 v[116:119], v[156:159], v[190:193], v[116:119]
	v_mfma_f32_16x16x32_bf16 v[108:111], v[142:145], v[198:201], v[108:111]
	v_mfma_f32_16x16x32_bf16 v[100:103], v[156:159], v[198:201], v[100:103]
	v_mfma_f32_16x16x32_bf16 v[92:95], v[142:145], v[206:209], v[92:95]
	v_mfma_f32_16x16x32_bf16 v[84:87], v[156:159], v[206:209], v[84:87]
	v_mfma_f32_16x16x32_bf16 v[76:79], v[142:145], v[214:217], v[76:79]
	v_mfma_f32_16x16x32_bf16 v[68:71], v[156:159], v[214:217], v[68:71]
	v_mfma_f32_16x16x32_bf16 v[124:127], v[160:163], v[186:189], v[124:127]
	v_mfma_f32_16x16x32_bf16 v[112:115], v[168:171], v[186:189], v[112:115]
	v_mfma_f32_16x16x32_bf16 v[104:107], v[160:163], v[194:197], v[104:107]
	v_mfma_f32_16x16x32_bf16 v[96:99], v[168:171], v[194:197], v[96:99]
	v_mfma_f32_16x16x32_bf16 v[88:91], v[160:163], v[202:205], v[88:91]
	v_mfma_f32_16x16x32_bf16 v[80:83], v[168:171], v[202:205], v[80:83]
	v_mfma_f32_16x16x32_bf16 v[72:75], v[160:163], v[210:213], v[72:75]
	v_mfma_f32_16x16x32_bf16 v[64:67], v[168:171], v[210:213], v[64:67]
	v_mfma_f32_16x16x32_bf16 v[124:127], v[164:167], v[190:193], v[124:127]
	v_mfma_f32_16x16x32_bf16 v[112:115], v[172:175], v[190:193], v[112:115]
	v_mfma_f32_16x16x32_bf16 v[104:107], v[164:167], v[198:201], v[104:107]
	v_mfma_f32_16x16x32_bf16 v[96:99], v[172:175], v[198:201], v[96:99]
	v_mfma_f32_16x16x32_bf16 v[88:91], v[164:167], v[206:209], v[88:91]
	v_mfma_f32_16x16x32_bf16 v[80:83], v[172:175], v[206:209], v[80:83]
	v_mfma_f32_16x16x32_bf16 v[72:75], v[164:167], v[214:217], v[72:75]
	v_mfma_f32_16x16x32_bf16 v[64:67], v[172:175], v[214:217], v[64:67]
	s_barrier
	s_add_i32 s4, s45, s36
	v_lshl_add_u64 v[222:223], v[222:223], 0, s[14:15]
	s_mov_b32 m0, s4
	ds_read_b128 v[186:189], v155 offset:49152
	ds_read_b128 v[190:193], v155 offset:50176
	ds_read_b128 v[194:197], v155 offset:51200
	ds_read_b128 v[198:201], v155 offset:52224
	ds_read_b128 v[202:205], v155 offset:53248
	ds_read_b128 v[206:209], v155 offset:54272
	ds_read_b128 v[210:213], v155 offset:55296
	ds_read_b128 v[214:217], v155 offset:56320
	global_load_lds_dwordx4 v[222:223], off
	v_lshl_add_u64 v[222:223], v[224:225], 0, s[14:15]
	s_add_i32 m0, s4, 0x2000
	s_add_i32 s4, s54, s36
	global_load_lds_dwordx4 v[222:223], off
	v_lshl_add_u64 v[222:223], v[226:227], 0, s[14:15]
	s_mov_b32 m0, s4
	s_nop 0
	global_load_lds_dwordx4 v[222:223], off
	v_lshl_add_u64 v[222:223], v[228:229], 0, s[14:15]
	s_add_i32 m0, s4, 0x2000
	s_nop 0
	global_load_lds_dwordx4 v[222:223], off
	v_lshl_add_u64 v[222:223], v[230:231], 0, s[14:15]
	s_mov_b32 m0, s59
	s_nop 0
	global_load_lds_dwordx4 v[222:223], off
	v_lshl_add_u64 v[222:223], v[232:233], 0, s[14:15]
	s_mov_b32 m0, s60
	s_nop 0
	global_load_lds_dwordx4 v[222:223], off
	s_waitcnt vmcnt(8)
	s_waitcnt lgkmcnt(0)
	s_barrier
	s_waitcnt lgkmcnt(0)
	v_mfma_f32_16x16x32_bf16 v[60:63], v[128:131], v[186:189], v[60:63]
	s_add_u32 s28, s28, 0x100
	v_mfma_f32_16x16x32_bf16 v[52:55], v[146:149], v[186:189], v[52:55]
	s_addc_u32 s29, s29, 0
	v_mfma_f32_16x16x32_bf16 v[44:47], v[128:131], v[194:197], v[44:47]
	s_add_u32 s10, s10, 0x100
	v_mfma_f32_16x16x32_bf16 v[36:39], v[146:149], v[194:197], v[36:39]
	s_addc_u32 s11, s11, 0
	v_mfma_f32_16x16x32_bf16 v[28:31], v[128:131], v[202:205], v[28:31]
	s_mov_b32 s30, s44
	v_mfma_f32_16x16x32_bf16 v[20:23], v[146:149], v[202:205], v[20:23]
	s_cmp_ge_i32 s44, s49
	v_mfma_f32_16x16x32_bf16 v[12:15], v[128:131], v[210:213], v[12:15]
	s_cselect_b32 s99, 1, 0
	v_mfma_f32_16x16x32_bf16 v[4:7], v[146:149], v[210:213], v[4:7]
	s_add_i32 s44, s30, 2
	v_mfma_f32_16x16x32_bf16 v[60:63], v[142:145], v[190:193], v[60:63]
	s_add_u32 s4, s28, 0x80
	v_mfma_f32_16x16x32_bf16 v[52:55], v[156:159], v[190:193], v[52:55]
	s_addc_u32 s5, s29, 0
	v_mfma_f32_16x16x32_bf16 v[44:47], v[142:145], v[198:201], v[44:47]
	s_add_i32 s45, 0, 0x10000
	v_mfma_f32_16x16x32_bf16 v[36:39], v[156:159], v[198:201], v[36:39]
	s_cmp_eq_u32 s61, s30
	v_mfma_f32_16x16x32_bf16 v[28:31], v[142:145], v[206:209], v[28:31]
	s_cselect_b32 s31, s25, s5
	v_mfma_f32_16x16x32_bf16 v[20:23], v[156:159], v[206:209], v[20:23]
	s_cselect_b32 s30, s24, s4
	v_mfma_f32_16x16x32_bf16 v[12:15], v[142:145], v[214:217], v[12:15]
	s_cselect_b32 s5, s27, s11
	v_mfma_f32_16x16x32_bf16 v[4:7], v[156:159], v[214:217], v[4:7]
	s_cselect_b32 s4, s26, s10
	v_mfma_f32_16x16x32_bf16 v[56:59], v[160:163], v[186:189], v[56:59]
	s_add_i32 s54, 0, 0x14000
	v_mfma_f32_16x16x32_bf16 v[48:51], v[168:171], v[186:189], v[48:51]
	v_mfma_f32_16x16x32_bf16 v[40:43], v[160:163], v[194:197], v[40:43]
	v_mfma_f32_16x16x32_bf16 v[32:35], v[168:171], v[194:197], v[32:35]
	v_mfma_f32_16x16x32_bf16 v[24:27], v[160:163], v[202:205], v[24:27]
	v_mfma_f32_16x16x32_bf16 v[16:19], v[168:171], v[202:205], v[16:19]
	v_mfma_f32_16x16x32_bf16 v[8:11], v[160:163], v[210:213], v[8:11]
	v_mfma_f32_16x16x32_bf16 v[0:3], v[168:171], v[210:213], v[0:3]
	v_mfma_f32_16x16x32_bf16 v[56:59], v[164:167], v[190:193], v[56:59]
	v_mfma_f32_16x16x32_bf16 v[48:51], v[172:175], v[190:193], v[48:51]
	v_mfma_f32_16x16x32_bf16 v[40:43], v[164:167], v[198:201], v[40:43]
	v_mfma_f32_16x16x32_bf16 v[32:35], v[172:175], v[198:201], v[32:35]
	v_mfma_f32_16x16x32_bf16 v[24:27], v[164:167], v[206:209], v[24:27]
	v_mfma_f32_16x16x32_bf16 v[16:19], v[172:175], v[206:209], v[16:19]
	v_mfma_f32_16x16x32_bf16 v[8:11], v[164:167], v[214:217], v[8:11]
	v_mfma_f32_16x16x32_bf16 v[0:3], v[172:175], v[214:217], v[0:3]
	s_barrier
	s_cmp_lg_u32 s99, 0
	s_cbranch_scc1 .Lpeelx_7
.LBB0_394:
	v_add_u32_e32 v156, s45, v151
	v_add_u32_e32 v172, s54, v151
	ds_read_b128 v[128:131], v156
	ds_read_b128 v[142:145], v156 offset:1024
	ds_read_b128 v[146:149], v156 offset:2048
	ds_read_b128 v[156:159], v156 offset:3072
	ds_read_b128 v[160:163], v172
	ds_read_b128 v[164:167], v172 offset:1024
	ds_read_b128 v[168:171], v172 offset:2048
	ds_read_b128 v[172:175], v172 offset:3072
	v_lshl_add_u64 v[222:223], s[28:29], 0, v[138:139]
	s_add_i32 m0, s37, 0xc000
	ds_read_b128 v[186:189], v155
	ds_read_b128 v[190:193], v155 offset:1024
	ds_read_b128 v[194:197], v155 offset:2048
	ds_read_b128 v[198:201], v155 offset:3072
	ds_read_b128 v[202:205], v155 offset:4096
	ds_read_b128 v[206:209], v155 offset:5120
	ds_read_b128 v[210:213], v155 offset:6144
	ds_read_b128 v[214:217], v155 offset:7168
	global_load_lds_dwordx4 v[222:223], off
	v_lshl_add_u64 v[222:223], s[28:29], 0, v[140:141]
	s_add_i32 m0, s37, 0xe000
	s_nop 0
	global_load_lds_dwordx4 v[222:223], off
	s_waitcnt vmcnt(8)
	s_waitcnt lgkmcnt(0)
	s_barrier
	s_waitcnt lgkmcnt(0)
	v_mfma_f32_16x16x32_bf16 v[120:123], v[128:131], v[186:189], v[120:123]
	v_mfma_f32_16x16x32_bf16 v[116:119], v[146:149], v[186:189], v[116:119]
	v_mfma_f32_16x16x32_bf16 v[108:111], v[128:131], v[194:197], v[108:111]
	v_mfma_f32_16x16x32_bf16 v[100:103], v[146:149], v[194:197], v[100:103]
	v_mfma_f32_16x16x32_bf16 v[92:95], v[128:131], v[202:205], v[92:95]
	v_mfma_f32_16x16x32_bf16 v[84:87], v[146:149], v[202:205], v[84:87]
	v_mfma_f32_16x16x32_bf16 v[76:79], v[128:131], v[210:213], v[76:79]
	v_mfma_f32_16x16x32_bf16 v[68:71], v[146:149], v[210:213], v[68:71]
	v_mfma_f32_16x16x32_bf16 v[120:123], v[142:145], v[190:193], v[120:123]
	v_mfma_f32_16x16x32_bf16 v[116:119], v[156:159], v[190:193], v[116:119]
	v_mfma_f32_16x16x32_bf16 v[108:111], v[142:145], v[198:201], v[108:111]
	v_mfma_f32_16x16x32_bf16 v[100:103], v[156:159], v[198:201], v[100:103]
	v_mfma_f32_16x16x32_bf16 v[92:95], v[142:145], v[206:209], v[92:95]
	v_mfma_f32_16x16x32_bf16 v[84:87], v[156:159], v[206:209], v[84:87]
	v_mfma_f32_16x16x32_bf16 v[76:79], v[142:145], v[214:217], v[76:79]
	v_mfma_f32_16x16x32_bf16 v[68:71], v[156:159], v[214:217], v[68:71]
	v_mfma_f32_16x16x32_bf16 v[124:127], v[160:163], v[186:189], v[124:127]
	v_mfma_f32_16x16x32_bf16 v[112:115], v[168:171], v[186:189], v[112:115]
	v_mfma_f32_16x16x32_bf16 v[104:107], v[160:163], v[194:197], v[104:107]
	v_mfma_f32_16x16x32_bf16 v[96:99], v[168:171], v[194:197], v[96:99]
	v_mfma_f32_16x16x32_bf16 v[88:91], v[160:163], v[202:205], v[88:91]
	v_mfma_f32_16x16x32_bf16 v[80:83], v[168:171], v[202:205], v[80:83]
	v_mfma_f32_16x16x32_bf16 v[72:75], v[160:163], v[210:213], v[72:75]
	v_mfma_f32_16x16x32_bf16 v[64:67], v[168:171], v[210:213], v[64:67]
	v_mfma_f32_16x16x32_bf16 v[124:127], v[164:167], v[190:193], v[124:127]
	v_mfma_f32_16x16x32_bf16 v[112:115], v[172:175], v[190:193], v[112:115]
	v_mfma_f32_16x16x32_bf16 v[104:107], v[164:167], v[198:201], v[104:107]
	v_mfma_f32_16x16x32_bf16 v[96:99], v[172:175], v[198:201], v[96:99]
	v_mfma_f32_16x16x32_bf16 v[88:91], v[164:167], v[206:209], v[88:91]
	v_mfma_f32_16x16x32_bf16 v[80:83], v[172:175], v[206:209], v[80:83]
	v_mfma_f32_16x16x32_bf16 v[72:75], v[164:167], v[214:217], v[72:75]
	v_mfma_f32_16x16x32_bf16 v[64:67], v[172:175], v[214:217], v[64:67]
	s_barrier
	s_add_i32 s45, s45, s36
	v_lshl_add_u64 v[222:223], s[4:5], 0, v[176:177]
	s_mov_b32 m0, s45
	ds_read_b128 v[186:189], v155 offset:16384
	ds_read_b128 v[190:193], v155 offset:17408
	ds_read_b128 v[194:197], v155 offset:18432
	ds_read_b128 v[198:201], v155 offset:19456
	ds_read_b128 v[202:205], v155 offset:20480
	ds_read_b128 v[206:209], v155 offset:21504
	ds_read_b128 v[210:213], v155 offset:22528
	ds_read_b128 v[214:217], v155 offset:23552
	global_load_lds_dwordx4 v[222:223], off
	s_add_i32 m0, s45, 0x2000
	v_lshl_add_u64 v[224:225], s[4:5], 0, v[132:133]
	s_add_u32 s4, s4, s6
	s_addc_u32 s5, s5, s7
	s_add_i32 s45, s54, s36
	global_load_lds_dwordx4 v[224:225], off
	v_lshl_add_u64 v[226:227], s[4:5], 0, v[176:177]
	s_mov_b32 m0, s45
	v_lshl_add_u64 v[228:229], s[4:5], 0, v[132:133]
	global_load_lds_dwordx4 v[226:227], off
	s_add_i32 m0, s45, 0x2000
	v_lshl_add_u64 v[230:231], s[30:31], 0, v[136:137]
	global_load_lds_dwordx4 v[228:229], off
	s_mov_b32 m0, s37
	v_lshl_add_u64 v[232:233], s[30:31], 0, v[134:135]
	global_load_lds_dwordx4 v[230:231], off
	s_mov_b32 m0, s38
	s_nop 0
	global_load_lds_dwordx4 v[232:233], off
	s_waitcnt vmcnt(8)
	s_waitcnt lgkmcnt(0)
	s_barrier
	s_waitcnt lgkmcnt(0)
	v_mfma_f32_16x16x32_bf16 v[60:63], v[128:131], v[186:189], v[60:63]
	v_mfma_f32_16x16x32_bf16 v[52:55], v[146:149], v[186:189], v[52:55]
	v_mfma_f32_16x16x32_bf16 v[44:47], v[128:131], v[194:197], v[44:47]
	v_mfma_f32_16x16x32_bf16 v[36:39], v[146:149], v[194:197], v[36:39]
	v_mfma_f32_16x16x32_bf16 v[28:31], v[128:131], v[202:205], v[28:31]
	v_mfma_f32_16x16x32_bf16 v[20:23], v[146:149], v[202:205], v[20:23]
	v_mfma_f32_16x16x32_bf16 v[12:15], v[128:131], v[210:213], v[12:15]
	v_mfma_f32_16x16x32_bf16 v[4:7], v[146:149], v[210:213], v[4:7]
	v_mfma_f32_16x16x32_bf16 v[60:63], v[142:145], v[190:193], v[60:63]
	v_mfma_f32_16x16x32_bf16 v[52:55], v[156:159], v[190:193], v[52:55]
	v_mfma_f32_16x16x32_bf16 v[44:47], v[142:145], v[198:201], v[44:47]
	v_mfma_f32_16x16x32_bf16 v[36:39], v[156:159], v[198:201], v[36:39]
	v_mfma_f32_16x16x32_bf16 v[28:31], v[142:145], v[206:209], v[28:31]
	v_mfma_f32_16x16x32_bf16 v[20:23], v[156:159], v[206:209], v[20:23]
	v_mfma_f32_16x16x32_bf16 v[12:15], v[142:145], v[214:217], v[12:15]
	v_mfma_f32_16x16x32_bf16 v[4:7], v[156:159], v[214:217], v[4:7]
	v_mfma_f32_16x16x32_bf16 v[56:59], v[160:163], v[186:189], v[56:59]
	v_mfma_f32_16x16x32_bf16 v[48:51], v[168:171], v[186:189], v[48:51]
	v_mfma_f32_16x16x32_bf16 v[40:43], v[160:163], v[194:197], v[40:43]
	v_mfma_f32_16x16x32_bf16 v[32:35], v[168:171], v[194:197], v[32:35]
	v_mfma_f32_16x16x32_bf16 v[24:27], v[160:163], v[202:205], v[24:27]
	v_mfma_f32_16x16x32_bf16 v[16:19], v[168:171], v[202:205], v[16:19]
	v_mfma_f32_16x16x32_bf16 v[8:11], v[160:163], v[210:213], v[8:11]
	v_mfma_f32_16x16x32_bf16 v[0:3], v[168:171], v[210:213], v[0:3]
	v_mfma_f32_16x16x32_bf16 v[56:59], v[164:167], v[190:193], v[56:59]
	v_mfma_f32_16x16x32_bf16 v[48:51], v[172:175], v[190:193], v[48:51]
	v_mfma_f32_16x16x32_bf16 v[40:43], v[164:167], v[198:201], v[40:43]
	v_mfma_f32_16x16x32_bf16 v[32:35], v[172:175], v[198:201], v[32:35]
	v_mfma_f32_16x16x32_bf16 v[24:27], v[164:167], v[206:209], v[24:27]
	v_mfma_f32_16x16x32_bf16 v[16:19], v[172:175], v[206:209], v[16:19]
	v_mfma_f32_16x16x32_bf16 v[8:11], v[164:167], v[214:217], v[8:11]
	v_mfma_f32_16x16x32_bf16 v[0:3], v[172:175], v[214:217], v[0:3]
	s_barrier
	s_add_i32 s45, 0, 0x18000
	s_add_i32 s54, 0, 0x1c000
	v_add_u32_e32 v156, s45, v151
	v_add_u32_e32 v172, s54, v151
	ds_read_b128 v[128:131], v156
	ds_read_b128 v[142:145], v156 offset:1024
	ds_read_b128 v[146:149], v156 offset:2048
	ds_read_b128 v[156:159], v156 offset:3072
	ds_read_b128 v[160:163], v172
	ds_read_b128 v[164:167], v172 offset:1024
	ds_read_b128 v[168:171], v172 offset:2048
	ds_read_b128 v[172:175], v172 offset:3072
	s_add_u32 s4, s30, s6
	s_addc_u32 s5, s31, s7
	s_mov_b32 m0, s39
	v_lshl_add_u64 v[234:235], s[4:5], 0, v[136:137]
	ds_read_b128 v[186:189], v155 offset:32768
	ds_read_b128 v[190:193], v155 offset:33792
	ds_read_b128 v[194:197], v155 offset:34816
	ds_read_b128 v[198:201], v155 offset:35840
	ds_read_b128 v[202:205], v155 offset:36864
	ds_read_b128 v[206:209], v155 offset:37888
	ds_read_b128 v[210:213], v155 offset:38912
	ds_read_b128 v[214:217], v155 offset:39936
	global_load_lds_dwordx4 v[234:235], off
	v_lshl_add_u64 v[234:235], s[4:5], 0, v[134:135]
	s_mov_b32 m0, s48
	s_nop 0
	global_load_lds_dwordx4 v[234:235], off
	s_waitcnt vmcnt(8)
	s_waitcnt lgkmcnt(0)
	s_barrier
	s_waitcnt lgkmcnt(0)
	v_mfma_f32_16x16x32_bf16 v[120:123], v[128:131], v[186:189], v[120:123]
	v_mfma_f32_16x16x32_bf16 v[116:119], v[146:149], v[186:189], v[116:119]
	v_mfma_f32_16x16x32_bf16 v[108:111], v[128:131], v[194:197], v[108:111]
	v_mfma_f32_16x16x32_bf16 v[100:103], v[146:149], v[194:197], v[100:103]
	v_mfma_f32_16x16x32_bf16 v[92:95], v[128:131], v[202:205], v[92:95]
	v_mfma_f32_16x16x32_bf16 v[84:87], v[146:149], v[202:205], v[84:87]
	v_mfma_f32_16x16x32_bf16 v[76:79], v[128:131], v[210:213], v[76:79]
	v_mfma_f32_16x16x32_bf16 v[68:71], v[146:149], v[210:213], v[68:71]
	v_mfma_f32_16x16x32_bf16 v[120:123], v[142:145], v[190:193], v[120:123]
	v_mfma_f32_16x16x32_bf16 v[116:119], v[156:159], v[190:193], v[116:119]
	v_mfma_f32_16x16x32_bf16 v[108:111], v[142:145], v[198:201], v[108:111]
	v_mfma_f32_16x16x32_bf16 v[100:103], v[156:159], v[198:201], v[100:103]
	v_mfma_f32_16x16x32_bf16 v[92:95], v[142:145], v[206:209], v[92:95]
	v_mfma_f32_16x16x32_bf16 v[84:87], v[156:159], v[206:209], v[84:87]
	v_mfma_f32_16x16x32_bf16 v[76:79], v[142:145], v[214:217], v[76:79]
	v_mfma_f32_16x16x32_bf16 v[68:71], v[156:159], v[214:217], v[68:71]
	v_mfma_f32_16x16x32_bf16 v[124:127], v[160:163], v[186:189], v[124:127]
	v_mfma_f32_16x16x32_bf16 v[112:115], v[168:171], v[186:189], v[112:115]
	v_mfma_f32_16x16x32_bf16 v[104:107], v[160:163], v[194:197], v[104:107]
	v_mfma_f32_16x16x32_bf16 v[96:99], v[168:171], v[194:197], v[96:99]
	v_mfma_f32_16x16x32_bf16 v[88:91], v[160:163], v[202:205], v[88:91]
	v_mfma_f32_16x16x32_bf16 v[80:83], v[168:171], v[202:205], v[80:83]
	v_mfma_f32_16x16x32_bf16 v[72:75], v[160:163], v[210:213], v[72:75]
	v_mfma_f32_16x16x32_bf16 v[64:67], v[168:171], v[210:213], v[64:67]
	v_mfma_f32_16x16x32_bf16 v[124:127], v[164:167], v[190:193], v[124:127]
	v_mfma_f32_16x16x32_bf16 v[112:115], v[172:175], v[190:193], v[112:115]
	v_mfma_f32_16x16x32_bf16 v[104:107], v[164:167], v[198:201], v[104:107]
	v_mfma_f32_16x16x32_bf16 v[96:99], v[172:175], v[198:201], v[96:99]
	v_mfma_f32_16x16x32_bf16 v[88:91], v[164:167], v[206:209], v[88:91]
	v_mfma_f32_16x16x32_bf16 v[80:83], v[172:175], v[206:209], v[80:83]
	v_mfma_f32_16x16x32_bf16 v[72:75], v[164:167], v[214:217], v[72:75]
	v_mfma_f32_16x16x32_bf16 v[64:67], v[172:175], v[214:217], v[64:67]
	s_barrier
	s_add_i32 s4, s45, s36
	v_lshl_add_u64 v[222:223], v[222:223], 0, s[14:15]
	s_mov_b32 m0, s4
	ds_read_b128 v[186:189], v155 offset:49152
	ds_read_b128 v[190:193], v155 offset:50176
	ds_read_b128 v[194:197], v155 offset:51200
	ds_read_b128 v[198:201], v155 offset:52224
	ds_read_b128 v[202:205], v155 offset:53248
	ds_read_b128 v[206:209], v155 offset:54272
	ds_read_b128 v[210:213], v155 offset:55296
	ds_read_b128 v[214:217], v155 offset:56320
	global_load_lds_dwordx4 v[222:223], off
	v_lshl_add_u64 v[222:223], v[224:225], 0, s[14:15]
	s_add_i32 m0, s4, 0x2000
	s_add_i32 s4, s54, s36
	global_load_lds_dwordx4 v[222:223], off
	v_lshl_add_u64 v[222:223], v[226:227], 0, s[14:15]
	s_mov_b32 m0, s4
	s_nop 0
	global_load_lds_dwordx4 v[222:223], off
	v_lshl_add_u64 v[222:223], v[228:229], 0, s[14:15]
	s_add_i32 m0, s4, 0x2000
	s_nop 0
	global_load_lds_dwordx4 v[222:223], off
	v_lshl_add_u64 v[222:223], v[230:231], 0, s[14:15]
	s_mov_b32 m0, s59
	s_nop 0
	global_load_lds_dwordx4 v[222:223], off
	v_lshl_add_u64 v[222:223], v[232:233], 0, s[14:15]
	s_mov_b32 m0, s60
	s_nop 0
	global_load_lds_dwordx4 v[222:223], off
	s_waitcnt vmcnt(8)
	s_waitcnt lgkmcnt(0)
	s_barrier
	s_waitcnt lgkmcnt(0)
	v_mfma_f32_16x16x32_bf16 v[60:63], v[128:131], v[186:189], v[60:63]
	s_add_u32 s28, s28, 0x100
	v_mfma_f32_16x16x32_bf16 v[52:55], v[146:149], v[186:189], v[52:55]
	s_addc_u32 s29, s29, 0
	v_mfma_f32_16x16x32_bf16 v[44:47], v[128:131], v[194:197], v[44:47]
	s_add_u32 s10, s10, 0x100
	v_mfma_f32_16x16x32_bf16 v[36:39], v[146:149], v[194:197], v[36:39]
	s_addc_u32 s11, s11, 0
	v_mfma_f32_16x16x32_bf16 v[28:31], v[128:131], v[202:205], v[28:31]
	s_mov_b32 s30, s44
	v_mfma_f32_16x16x32_bf16 v[20:23], v[146:149], v[202:205], v[20:23]
	s_cmp_ge_i32 s44, s49
	v_mfma_f32_16x16x32_bf16 v[12:15], v[128:131], v[210:213], v[12:15]
	s_cselect_b32 s99, 1, 0
	v_mfma_f32_16x16x32_bf16 v[4:7], v[146:149], v[210:213], v[4:7]
	s_add_i32 s44, s30, 2
	v_mfma_f32_16x16x32_bf16 v[60:63], v[142:145], v[190:193], v[60:63]
	s_add_u32 s4, s28, 0x80
	v_mfma_f32_16x16x32_bf16 v[52:55], v[156:159], v[190:193], v[52:55]
	s_addc_u32 s5, s29, 0
	v_mfma_f32_16x16x32_bf16 v[44:47], v[142:145], v[198:201], v[44:47]
	s_add_i32 s45, 0, 0x10000
	v_mfma_f32_16x16x32_bf16 v[36:39], v[156:159], v[198:201], v[36:39]
	s_cmp_eq_u32 s61, s30
	v_mfma_f32_16x16x32_bf16 v[28:31], v[142:145], v[206:209], v[28:31]
	s_cselect_b32 s31, s25, s5
	v_mfma_f32_16x16x32_bf16 v[20:23], v[156:159], v[206:209], v[20:23]
	s_cselect_b32 s30, s24, s4
	v_mfma_f32_16x16x32_bf16 v[12:15], v[142:145], v[214:217], v[12:15]
	s_cselect_b32 s5, s27, s11
	v_mfma_f32_16x16x32_bf16 v[4:7], v[156:159], v[214:217], v[4:7]
	s_cselect_b32 s4, s26, s10
	v_mfma_f32_16x16x32_bf16 v[56:59], v[160:163], v[186:189], v[56:59]
	s_add_i32 s54, 0, 0x14000
	v_mfma_f32_16x16x32_bf16 v[48:51], v[168:171], v[186:189], v[48:51]
	v_mfma_f32_16x16x32_bf16 v[40:43], v[160:163], v[194:197], v[40:43]
	v_mfma_f32_16x16x32_bf16 v[32:35], v[168:171], v[194:197], v[32:35]
	v_mfma_f32_16x16x32_bf16 v[24:27], v[160:163], v[202:205], v[24:27]
	v_mfma_f32_16x16x32_bf16 v[16:19], v[168:171], v[202:205], v[16:19]
	v_mfma_f32_16x16x32_bf16 v[8:11], v[160:163], v[210:213], v[8:11]
	v_mfma_f32_16x16x32_bf16 v[0:3], v[168:171], v[210:213], v[0:3]
	v_mfma_f32_16x16x32_bf16 v[56:59], v[164:167], v[190:193], v[56:59]
	v_mfma_f32_16x16x32_bf16 v[48:51], v[172:175], v[190:193], v[48:51]
	v_mfma_f32_16x16x32_bf16 v[40:43], v[164:167], v[198:201], v[40:43]
	v_mfma_f32_16x16x32_bf16 v[32:35], v[172:175], v[198:201], v[32:35]
	v_mfma_f32_16x16x32_bf16 v[24:27], v[164:167], v[206:209], v[24:27]
	v_mfma_f32_16x16x32_bf16 v[16:19], v[172:175], v[206:209], v[16:19]
	v_mfma_f32_16x16x32_bf16 v[8:11], v[164:167], v[214:217], v[8:11]
	v_mfma_f32_16x16x32_bf16 v[0:3], v[172:175], v[214:217], v[0:3]
	s_barrier
	s_cmp_lg_u32 s99, 0
	s_cbranch_scc0 .LBB0_394

.Llbb_4:
	s_add_i32 s44, s30, 2
	s_add_u32 s4, s28, 0x80
	s_addc_u32 s5, s29, 0
	s_add_i32 s45, 0, 0x10000
	s_cmp_eq_u32 s61, s30
	s_cselect_b32 s31, s25, s5
	s_cselect_b32 s30, s24, s4
	s_cselect_b32 s5, s27, s11
	s_cselect_b32 s4, s26, s10
	s_add_i32 s54, 0, 0x14000
	v_add_u32_e32 v140, s45, v195
	v_add_u32_e32 v166, s54, v195
	ds_read_b128 v[128:131], v140
	ds_read_b128 v[132:135], v140 offset:1024
	ds_read_b128 v[136:139], v140 offset:2048
	ds_read_b128 v[140:143], v140 offset:3072
	ds_read_b128 v[144:147], v166
	ds_read_b128 v[148:151], v166 offset:1024
	ds_read_b128 v[152:155], v166 offset:2048
	ds_read_b128 v[166:169], v166 offset:3072
	v_lshl_add_u64 v[174:175], s[28:29], 0, v[162:163]
	s_add_i32 m0, s38, 0xc000
	ds_read_b128 v[170:173], v197
	ds_read_b128 v[186:189], v197 offset:1024
	ds_read_b128 v[190:193], v197 offset:2048
	ds_read_b128 v[198:201], v197 offset:3072
	ds_read_b128 v[202:205], v197 offset:4096
	ds_read_b128 v[206:209], v197 offset:5120
	ds_read_b128 v[210:213], v197 offset:6144
	ds_read_b128 v[214:217], v197 offset:7168
	global_load_lds_dwordx4 v[174:175], off
	v_lshl_add_u64 v[174:175], s[28:29], 0, v[164:165]
	s_add_i32 m0, s38, 0xe000
	s_nop 0
	global_load_lds_dwordx4 v[174:175], off
	s_waitcnt vmcnt(8)
	s_waitcnt lgkmcnt(0)
	s_barrier
	s_waitcnt lgkmcnt(0)
	v_mfma_f32_16x16x32_bf16 v[120:123], v[128:131], v[170:173], 0
	v_mfma_f32_16x16x32_bf16 v[124:127], v[136:139], v[170:173], 0
	v_mfma_f32_16x16x32_bf16 v[108:111], v[128:131], v[190:193], 0
	v_mfma_f32_16x16x32_bf16 v[104:107], v[136:139], v[190:193], 0
	v_mfma_f32_16x16x32_bf16 v[92:95], v[128:131], v[202:205], 0
	v_mfma_f32_16x16x32_bf16 v[88:91], v[136:139], v[202:205], 0
	v_mfma_f32_16x16x32_bf16 v[76:79], v[128:131], v[210:213], 0
	v_mfma_f32_16x16x32_bf16 v[72:75], v[136:139], v[210:213], 0
	v_mfma_f32_16x16x32_bf16 v[120:123], v[132:135], v[186:189], v[120:123]
	v_mfma_f32_16x16x32_bf16 v[124:127], v[140:143], v[186:189], v[124:127]
	v_mfma_f32_16x16x32_bf16 v[108:111], v[132:135], v[198:201], v[108:111]
	v_mfma_f32_16x16x32_bf16 v[104:107], v[140:143], v[198:201], v[104:107]
	v_mfma_f32_16x16x32_bf16 v[92:95], v[132:135], v[206:209], v[92:95]
	v_mfma_f32_16x16x32_bf16 v[88:91], v[140:143], v[206:209], v[88:91]
	v_mfma_f32_16x16x32_bf16 v[76:79], v[132:135], v[214:217], v[76:79]
	v_mfma_f32_16x16x32_bf16 v[72:75], v[140:143], v[214:217], v[72:75]
	v_mfma_f32_16x16x32_bf16 v[116:119], v[144:147], v[170:173], 0
	v_mfma_f32_16x16x32_bf16 v[112:115], v[152:155], v[170:173], 0
	v_mfma_f32_16x16x32_bf16 v[100:103], v[144:147], v[190:193], 0
	v_mfma_f32_16x16x32_bf16 v[96:99], v[152:155], v[190:193], 0
	v_mfma_f32_16x16x32_bf16 v[84:87], v[144:147], v[202:205], 0
	v_mfma_f32_16x16x32_bf16 v[80:83], v[152:155], v[202:205], 0
	v_mfma_f32_16x16x32_bf16 v[68:71], v[144:147], v[210:213], 0
	v_mfma_f32_16x16x32_bf16 v[64:67], v[152:155], v[210:213], 0
	v_mfma_f32_16x16x32_bf16 v[116:119], v[148:151], v[186:189], v[116:119]
	v_mfma_f32_16x16x32_bf16 v[112:115], v[166:169], v[186:189], v[112:115]
	v_mfma_f32_16x16x32_bf16 v[100:103], v[148:151], v[198:201], v[100:103]
	v_mfma_f32_16x16x32_bf16 v[96:99], v[166:169], v[198:201], v[96:99]
	v_mfma_f32_16x16x32_bf16 v[84:87], v[148:151], v[206:209], v[84:87]
	v_mfma_f32_16x16x32_bf16 v[80:83], v[166:169], v[206:209], v[80:83]
	v_mfma_f32_16x16x32_bf16 v[68:71], v[148:151], v[214:217], v[68:71]
	v_mfma_f32_16x16x32_bf16 v[64:67], v[166:169], v[214:217], v[64:67]
	s_barrier
	s_add_i32 s45, s45, s37
	v_lshl_add_u64 v[174:175], s[4:5], 0, v[176:177]
	s_mov_b32 m0, s45
	ds_read_b128 v[170:173], v197 offset:16384
	ds_read_b128 v[186:189], v197 offset:17408
	ds_read_b128 v[190:193], v197 offset:18432
	ds_read_b128 v[198:201], v197 offset:19456
	ds_read_b128 v[202:205], v197 offset:20480
	ds_read_b128 v[206:209], v197 offset:21504
	ds_read_b128 v[210:213], v197 offset:22528
	ds_read_b128 v[214:217], v197 offset:23552
	global_load_lds_dwordx4 v[174:175], off
	s_add_i32 m0, s45, 0x2000
	v_lshl_add_u64 v[222:223], s[4:5], 0, v[156:157]
	s_add_u32 s4, s4, s6
	s_addc_u32 s5, s5, s7
	s_add_i32 s45, s54, s37
	global_load_lds_dwordx4 v[222:223], off
	v_lshl_add_u64 v[224:225], s[4:5], 0, v[176:177]
	s_mov_b32 m0, s45
	v_lshl_add_u64 v[226:227], s[4:5], 0, v[156:157]
	global_load_lds_dwordx4 v[224:225], off
	s_add_i32 m0, s45, 0x2000
	v_lshl_add_u64 v[228:229], s[30:31], 0, v[160:161]
	global_load_lds_dwordx4 v[226:227], off
	s_mov_b32 m0, s38
	v_lshl_add_u64 v[230:231], s[30:31], 0, v[158:159]
	global_load_lds_dwordx4 v[228:229], off
	s_mov_b32 m0, s39
	s_nop 0
	global_load_lds_dwordx4 v[230:231], off
	s_waitcnt vmcnt(8)
	s_waitcnt lgkmcnt(0)
	s_barrier
	s_waitcnt lgkmcnt(0)
	v_mfma_f32_16x16x32_bf16 v[60:63], v[128:131], v[170:173], 0
	v_mfma_f32_16x16x32_bf16 v[56:59], v[136:139], v[170:173], 0
	v_mfma_f32_16x16x32_bf16 v[44:47], v[128:131], v[190:193], 0
	v_mfma_f32_16x16x32_bf16 v[40:43], v[136:139], v[190:193], 0
	v_mfma_f32_16x16x32_bf16 v[28:31], v[128:131], v[202:205], 0
	v_mfma_f32_16x16x32_bf16 v[24:27], v[136:139], v[202:205], 0
	v_mfma_f32_16x16x32_bf16 v[12:15], v[128:131], v[210:213], 0
	v_mfma_f32_16x16x32_bf16 v[8:11], v[136:139], v[210:213], 0
	v_mfma_f32_16x16x32_bf16 v[60:63], v[132:135], v[186:189], v[60:63]
	v_mfma_f32_16x16x32_bf16 v[56:59], v[140:143], v[186:189], v[56:59]
	v_mfma_f32_16x16x32_bf16 v[44:47], v[132:135], v[198:201], v[44:47]
	v_mfma_f32_16x16x32_bf16 v[40:43], v[140:143], v[198:201], v[40:43]
	v_mfma_f32_16x16x32_bf16 v[28:31], v[132:135], v[206:209], v[28:31]
	v_mfma_f32_16x16x32_bf16 v[24:27], v[140:143], v[206:209], v[24:27]
	v_mfma_f32_16x16x32_bf16 v[12:15], v[132:135], v[214:217], v[12:15]
	v_mfma_f32_16x16x32_bf16 v[8:11], v[140:143], v[214:217], v[8:11]
	v_mfma_f32_16x16x32_bf16 v[52:55], v[144:147], v[170:173], 0
	v_mfma_f32_16x16x32_bf16 v[48:51], v[152:155], v[170:173], 0
	v_mfma_f32_16x16x32_bf16 v[36:39], v[144:147], v[190:193], 0
	v_mfma_f32_16x16x32_bf16 v[32:35], v[152:155], v[190:193], 0
	v_mfma_f32_16x16x32_bf16 v[20:23], v[144:147], v[202:205], 0
	v_mfma_f32_16x16x32_bf16 v[16:19], v[152:155], v[202:205], 0
	v_mfma_f32_16x16x32_bf16 v[4:7], v[144:147], v[210:213], 0
	v_mfma_f32_16x16x32_bf16 v[0:3], v[152:155], v[210:213], 0
	v_mfma_f32_16x16x32_bf16 v[52:55], v[148:151], v[186:189], v[52:55]
	v_mfma_f32_16x16x32_bf16 v[48:51], v[166:169], v[186:189], v[48:51]
	v_mfma_f32_16x16x32_bf16 v[36:39], v[148:151], v[198:201], v[36:39]
	v_mfma_f32_16x16x32_bf16 v[32:35], v[166:169], v[198:201], v[32:35]
	v_mfma_f32_16x16x32_bf16 v[20:23], v[148:151], v[206:209], v[20:23]
	v_mfma_f32_16x16x32_bf16 v[16:19], v[166:169], v[206:209], v[16:19]
	v_mfma_f32_16x16x32_bf16 v[4:7], v[148:151], v[214:217], v[4:7]
	v_mfma_f32_16x16x32_bf16 v[0:3], v[166:169], v[214:217], v[0:3]
	s_barrier
	s_add_i32 s45, 0, 0x18000
	s_add_i32 s54, 0, 0x1c000
	v_add_u32_e32 v140, s45, v195
	v_add_u32_e32 v166, s54, v195
	ds_read_b128 v[128:131], v140
	ds_read_b128 v[132:135], v140 offset:1024
	ds_read_b128 v[136:139], v140 offset:2048
	ds_read_b128 v[140:143], v140 offset:3072
	ds_read_b128 v[144:147], v166
	ds_read_b128 v[148:151], v166 offset:1024
	ds_read_b128 v[152:155], v166 offset:2048
	ds_read_b128 v[166:169], v166 offset:3072
	s_add_u32 s4, s30, s6
	s_addc_u32 s5, s31, s7
	s_mov_b32 m0, s48
	v_lshl_add_u64 v[232:233], s[4:5], 0, v[160:161]
	ds_read_b128 v[170:173], v197 offset:32768
	ds_read_b128 v[186:189], v197 offset:33792
	ds_read_b128 v[190:193], v197 offset:34816
	ds_read_b128 v[198:201], v197 offset:35840
	ds_read_b128 v[202:205], v197 offset:36864
	ds_read_b128 v[206:209], v197 offset:37888
	ds_read_b128 v[210:213], v197 offset:38912
	ds_read_b128 v[214:217], v197 offset:39936
	global_load_lds_dwordx4 v[232:233], off
	v_lshl_add_u64 v[232:233], s[4:5], 0, v[158:159]
	s_mov_b32 m0, s49
	s_nop 0
	global_load_lds_dwordx4 v[232:233], off
	s_waitcnt vmcnt(8)
	s_waitcnt lgkmcnt(0)
	s_barrier
	s_waitcnt lgkmcnt(0)
	v_mfma_f32_16x16x32_bf16 v[120:123], v[128:131], v[170:173], v[120:123]
	v_mfma_f32_16x16x32_bf16 v[124:127], v[136:139], v[170:173], v[124:127]
	v_mfma_f32_16x16x32_bf16 v[108:111], v[128:131], v[190:193], v[108:111]
	v_mfma_f32_16x16x32_bf16 v[104:107], v[136:139], v[190:193], v[104:107]
	v_mfma_f32_16x16x32_bf16 v[92:95], v[128:131], v[202:205], v[92:95]
	v_mfma_f32_16x16x32_bf16 v[88:91], v[136:139], v[202:205], v[88:91]
	v_mfma_f32_16x16x32_bf16 v[76:79], v[128:131], v[210:213], v[76:79]
	v_mfma_f32_16x16x32_bf16 v[72:75], v[136:139], v[210:213], v[72:75]
	v_mfma_f32_16x16x32_bf16 v[120:123], v[132:135], v[186:189], v[120:123]
	v_mfma_f32_16x16x32_bf16 v[124:127], v[140:143], v[186:189], v[124:127]
	v_mfma_f32_16x16x32_bf16 v[108:111], v[132:135], v[198:201], v[108:111]
	v_mfma_f32_16x16x32_bf16 v[104:107], v[140:143], v[198:201], v[104:107]
	v_mfma_f32_16x16x32_bf16 v[92:95], v[132:135], v[206:209], v[92:95]
	v_mfma_f32_16x16x32_bf16 v[88:91], v[140:143], v[206:209], v[88:91]
	v_mfma_f32_16x16x32_bf16 v[76:79], v[132:135], v[214:217], v[76:79]
	v_mfma_f32_16x16x32_bf16 v[72:75], v[140:143], v[214:217], v[72:75]
	v_mfma_f32_16x16x32_bf16 v[116:119], v[144:147], v[170:173], v[116:119]
	v_mfma_f32_16x16x32_bf16 v[112:115], v[152:155], v[170:173], v[112:115]
	v_mfma_f32_16x16x32_bf16 v[100:103], v[144:147], v[190:193], v[100:103]
	v_mfma_f32_16x16x32_bf16 v[96:99], v[152:155], v[190:193], v[96:99]
	v_mfma_f32_16x16x32_bf16 v[84:87], v[144:147], v[202:205], v[84:87]
	v_mfma_f32_16x16x32_bf16 v[80:83], v[152:155], v[202:205], v[80:83]
	v_mfma_f32_16x16x32_bf16 v[68:71], v[144:147], v[210:213], v[68:71]
	v_mfma_f32_16x16x32_bf16 v[64:67], v[152:155], v[210:213], v[64:67]
	v_mfma_f32_16x16x32_bf16 v[116:119], v[148:151], v[186:189], v[116:119]
	v_mfma_f32_16x16x32_bf16 v[112:115], v[166:169], v[186:189], v[112:115]
	v_mfma_f32_16x16x32_bf16 v[100:103], v[148:151], v[198:201], v[100:103]
	v_mfma_f32_16x16x32_bf16 v[96:99], v[166:169], v[198:201], v[96:99]
	v_mfma_f32_16x16x32_bf16 v[84:87], v[148:151], v[206:209], v[84:87]
	v_mfma_f32_16x16x32_bf16 v[80:83], v[166:169], v[206:209], v[80:83]
	v_mfma_f32_16x16x32_bf16 v[68:71], v[148:151], v[214:217], v[68:71]
	v_mfma_f32_16x16x32_bf16 v[64:67], v[166:169], v[214:217], v[64:67]
	s_barrier
	s_add_i32 s4, s45, s37
	v_lshl_add_u64 v[174:175], v[174:175], 0, s[14:15]
	s_mov_b32 m0, s4
	ds_read_b128 v[170:173], v197 offset:49152
	ds_read_b128 v[186:189], v197 offset:50176
	ds_read_b128 v[190:193], v197 offset:51200
	ds_read_b128 v[198:201], v197 offset:52224
	ds_read_b128 v[202:205], v197 offset:53248
	ds_read_b128 v[206:209], v197 offset:54272
	ds_read_b128 v[210:213], v197 offset:55296
	ds_read_b128 v[214:217], v197 offset:56320
	global_load_lds_dwordx4 v[174:175], off
	v_lshl_add_u64 v[174:175], v[222:223], 0, s[14:15]
	s_add_i32 m0, s4, 0x2000
	s_add_i32 s4, s54, s37
	global_load_lds_dwordx4 v[174:175], off
	v_lshl_add_u64 v[174:175], v[224:225], 0, s[14:15]
	s_mov_b32 m0, s4
	s_nop 0
	global_load_lds_dwordx4 v[174:175], off
	v_lshl_add_u64 v[174:175], v[226:227], 0, s[14:15]
	s_add_i32 m0, s4, 0x2000
	s_nop 0
	global_load_lds_dwordx4 v[174:175], off
	v_lshl_add_u64 v[174:175], v[228:229], 0, s[14:15]
	s_mov_b32 m0, s59
	s_nop 0
	global_load_lds_dwordx4 v[174:175], off
	v_lshl_add_u64 v[174:175], v[230:231], 0, s[14:15]
	s_mov_b32 m0, s60
	s_nop 0
	global_load_lds_dwordx4 v[174:175], off
	s_waitcnt vmcnt(8)
	s_waitcnt lgkmcnt(0)
	s_barrier
	s_waitcnt lgkmcnt(0)
	v_mfma_f32_16x16x32_bf16 v[60:63], v[128:131], v[170:173], v[60:63]
	s_add_u32 s28, s28, 0x100
	v_mfma_f32_16x16x32_bf16 v[56:59], v[136:139], v[170:173], v[56:59]
	s_addc_u32 s29, s29, 0
	v_mfma_f32_16x16x32_bf16 v[44:47], v[128:131], v[190:193], v[44:47]
	s_add_u32 s10, s10, 0x100
	v_mfma_f32_16x16x32_bf16 v[40:43], v[136:139], v[190:193], v[40:43]
	s_addc_u32 s11, s11, 0
	v_mfma_f32_16x16x32_bf16 v[28:31], v[128:131], v[202:205], v[28:31]
	s_mov_b32 s30, s44
	v_mfma_f32_16x16x32_bf16 v[24:27], v[136:139], v[202:205], v[24:27]
	s_cmp_ge_i32 s44, s58
	v_mfma_f32_16x16x32_bf16 v[12:15], v[128:131], v[210:213], v[12:15]
	s_cselect_b32 s99, 1, 0
	v_mfma_f32_16x16x32_bf16 v[8:11], v[136:139], v[210:213], v[8:11]
	s_add_i32 s44, s30, 2
	v_mfma_f32_16x16x32_bf16 v[60:63], v[132:135], v[186:189], v[60:63]
	s_add_u32 s4, s28, 0x80
	v_mfma_f32_16x16x32_bf16 v[56:59], v[140:143], v[186:189], v[56:59]
	s_addc_u32 s5, s29, 0
	v_mfma_f32_16x16x32_bf16 v[44:47], v[132:135], v[198:201], v[44:47]
	s_add_i32 s45, 0, 0x10000
	v_mfma_f32_16x16x32_bf16 v[40:43], v[140:143], v[198:201], v[40:43]
	s_cmp_eq_u32 s61, s30
	v_mfma_f32_16x16x32_bf16 v[28:31], v[132:135], v[206:209], v[28:31]
	s_cselect_b32 s31, s25, s5
	v_mfma_f32_16x16x32_bf16 v[24:27], v[140:143], v[206:209], v[24:27]
	s_cselect_b32 s30, s24, s4
	v_mfma_f32_16x16x32_bf16 v[12:15], v[132:135], v[214:217], v[12:15]
	s_cselect_b32 s5, s27, s11
	v_mfma_f32_16x16x32_bf16 v[8:11], v[140:143], v[214:217], v[8:11]
	s_cselect_b32 s4, s26, s10
	v_mfma_f32_16x16x32_bf16 v[52:55], v[144:147], v[170:173], v[52:55]
	s_add_i32 s54, 0, 0x14000
	v_mfma_f32_16x16x32_bf16 v[48:51], v[152:155], v[170:173], v[48:51]
	v_mfma_f32_16x16x32_bf16 v[36:39], v[144:147], v[190:193], v[36:39]
	v_mfma_f32_16x16x32_bf16 v[32:35], v[152:155], v[190:193], v[32:35]
	v_mfma_f32_16x16x32_bf16 v[20:23], v[144:147], v[202:205], v[20:23]
	v_mfma_f32_16x16x32_bf16 v[16:19], v[152:155], v[202:205], v[16:19]
	v_mfma_f32_16x16x32_bf16 v[4:7], v[144:147], v[210:213], v[4:7]
	v_mfma_f32_16x16x32_bf16 v[0:3], v[152:155], v[210:213], v[0:3]
	v_mfma_f32_16x16x32_bf16 v[52:55], v[148:151], v[186:189], v[52:55]
	v_mfma_f32_16x16x32_bf16 v[48:51], v[166:169], v[186:189], v[48:51]
	v_mfma_f32_16x16x32_bf16 v[36:39], v[148:151], v[198:201], v[36:39]
	v_mfma_f32_16x16x32_bf16 v[32:35], v[166:169], v[198:201], v[32:35]
	v_mfma_f32_16x16x32_bf16 v[20:23], v[148:151], v[206:209], v[20:23]
	v_mfma_f32_16x16x32_bf16 v[16:19], v[166:169], v[206:209], v[16:19]
	v_mfma_f32_16x16x32_bf16 v[4:7], v[148:151], v[214:217], v[4:7]
	v_mfma_f32_16x16x32_bf16 v[0:3], v[166:169], v[214:217], v[0:3]
	s_barrier
	s_cmp_lg_u32 s99, 0
	s_cbranch_scc1 .Lpeelx_8
.LBB0_475:
	v_add_u32_e32 v140, s45, v195
	v_add_u32_e32 v166, s54, v195
	ds_read_b128 v[128:131], v140
	ds_read_b128 v[132:135], v140 offset:1024
	ds_read_b128 v[136:139], v140 offset:2048
	ds_read_b128 v[140:143], v140 offset:3072
	ds_read_b128 v[144:147], v166
	ds_read_b128 v[148:151], v166 offset:1024
	ds_read_b128 v[152:155], v166 offset:2048
	ds_read_b128 v[166:169], v166 offset:3072
	v_lshl_add_u64 v[174:175], s[28:29], 0, v[162:163]
	s_add_i32 m0, s38, 0xc000
	ds_read_b128 v[170:173], v197
	ds_read_b128 v[186:189], v197 offset:1024
	ds_read_b128 v[190:193], v197 offset:2048
	ds_read_b128 v[198:201], v197 offset:3072
	ds_read_b128 v[202:205], v197 offset:4096
	ds_read_b128 v[206:209], v197 offset:5120
	ds_read_b128 v[210:213], v197 offset:6144
	ds_read_b128 v[214:217], v197 offset:7168
	global_load_lds_dwordx4 v[174:175], off
	v_lshl_add_u64 v[174:175], s[28:29], 0, v[164:165]
	s_add_i32 m0, s38, 0xe000
	s_nop 0
	global_load_lds_dwordx4 v[174:175], off
	s_waitcnt vmcnt(8)
	s_waitcnt lgkmcnt(0)
	s_barrier
	s_waitcnt lgkmcnt(0)
	v_mfma_f32_16x16x32_bf16 v[120:123], v[128:131], v[170:173], v[120:123]
	v_mfma_f32_16x16x32_bf16 v[124:127], v[136:139], v[170:173], v[124:127]
	v_mfma_f32_16x16x32_bf16 v[108:111], v[128:131], v[190:193], v[108:111]
	v_mfma_f32_16x16x32_bf16 v[104:107], v[136:139], v[190:193], v[104:107]
	v_mfma_f32_16x16x32_bf16 v[92:95], v[128:131], v[202:205], v[92:95]
	v_mfma_f32_16x16x32_bf16 v[88:91], v[136:139], v[202:205], v[88:91]
	v_mfma_f32_16x16x32_bf16 v[76:79], v[128:131], v[210:213], v[76:79]
	v_mfma_f32_16x16x32_bf16 v[72:75], v[136:139], v[210:213], v[72:75]
	v_mfma_f32_16x16x32_bf16 v[120:123], v[132:135], v[186:189], v[120:123]
	v_mfma_f32_16x16x32_bf16 v[124:127], v[140:143], v[186:189], v[124:127]
	v_mfma_f32_16x16x32_bf16 v[108:111], v[132:135], v[198:201], v[108:111]
	v_mfma_f32_16x16x32_bf16 v[104:107], v[140:143], v[198:201], v[104:107]
	v_mfma_f32_16x16x32_bf16 v[92:95], v[132:135], v[206:209], v[92:95]
	v_mfma_f32_16x16x32_bf16 v[88:91], v[140:143], v[206:209], v[88:91]
	v_mfma_f32_16x16x32_bf16 v[76:79], v[132:135], v[214:217], v[76:79]
	v_mfma_f32_16x16x32_bf16 v[72:75], v[140:143], v[214:217], v[72:75]
	v_mfma_f32_16x16x32_bf16 v[116:119], v[144:147], v[170:173], v[116:119]
	v_mfma_f32_16x16x32_bf16 v[112:115], v[152:155], v[170:173], v[112:115]
	v_mfma_f32_16x16x32_bf16 v[100:103], v[144:147], v[190:193], v[100:103]
	v_mfma_f32_16x16x32_bf16 v[96:99], v[152:155], v[190:193], v[96:99]
	v_mfma_f32_16x16x32_bf16 v[84:87], v[144:147], v[202:205], v[84:87]
	v_mfma_f32_16x16x32_bf16 v[80:83], v[152:155], v[202:205], v[80:83]
	v_mfma_f32_16x16x32_bf16 v[68:71], v[144:147], v[210:213], v[68:71]
	v_mfma_f32_16x16x32_bf16 v[64:67], v[152:155], v[210:213], v[64:67]
	v_mfma_f32_16x16x32_bf16 v[116:119], v[148:151], v[186:189], v[116:119]
	v_mfma_f32_16x16x32_bf16 v[112:115], v[166:169], v[186:189], v[112:115]
	v_mfma_f32_16x16x32_bf16 v[100:103], v[148:151], v[198:201], v[100:103]
	v_mfma_f32_16x16x32_bf16 v[96:99], v[166:169], v[198:201], v[96:99]
	v_mfma_f32_16x16x32_bf16 v[84:87], v[148:151], v[206:209], v[84:87]
	v_mfma_f32_16x16x32_bf16 v[80:83], v[166:169], v[206:209], v[80:83]
	v_mfma_f32_16x16x32_bf16 v[68:71], v[148:151], v[214:217], v[68:71]
	v_mfma_f32_16x16x32_bf16 v[64:67], v[166:169], v[214:217], v[64:67]
	s_barrier
	s_add_i32 s45, s45, s37
	v_lshl_add_u64 v[174:175], s[4:5], 0, v[176:177]
	s_mov_b32 m0, s45
	ds_read_b128 v[170:173], v197 offset:16384
	ds_read_b128 v[186:189], v197 offset:17408
	ds_read_b128 v[190:193], v197 offset:18432
	ds_read_b128 v[198:201], v197 offset:19456
	ds_read_b128 v[202:205], v197 offset:20480
	ds_read_b128 v[206:209], v197 offset:21504
	ds_read_b128 v[210:213], v197 offset:22528
	ds_read_b128 v[214:217], v197 offset:23552
	global_load_lds_dwordx4 v[174:175], off
	s_add_i32 m0, s45, 0x2000
	v_lshl_add_u64 v[222:223], s[4:5], 0, v[156:157]
	s_add_u32 s4, s4, s6
	s_addc_u32 s5, s5, s7
	s_add_i32 s45, s54, s37
	global_load_lds_dwordx4 v[222:223], off
	v_lshl_add_u64 v[224:225], s[4:5], 0, v[176:177]
	s_mov_b32 m0, s45
	v_lshl_add_u64 v[226:227], s[4:5], 0, v[156:157]
	global_load_lds_dwordx4 v[224:225], off
	s_add_i32 m0, s45, 0x2000
	v_lshl_add_u64 v[228:229], s[30:31], 0, v[160:161]
	global_load_lds_dwordx4 v[226:227], off
	s_mov_b32 m0, s38
	v_lshl_add_u64 v[230:231], s[30:31], 0, v[158:159]
	global_load_lds_dwordx4 v[228:229], off
	s_mov_b32 m0, s39
	s_nop 0
	global_load_lds_dwordx4 v[230:231], off
	s_waitcnt vmcnt(8)
	s_waitcnt lgkmcnt(0)
	s_barrier
	s_waitcnt lgkmcnt(0)
	v_mfma_f32_16x16x32_bf16 v[60:63], v[128:131], v[170:173], v[60:63]
	v_mfma_f32_16x16x32_bf16 v[56:59], v[136:139], v[170:173], v[56:59]
	v_mfma_f32_16x16x32_bf16 v[44:47], v[128:131], v[190:193], v[44:47]
	v_mfma_f32_16x16x32_bf16 v[40:43], v[136:139], v[190:193], v[40:43]
	v_mfma_f32_16x16x32_bf16 v[28:31], v[128:131], v[202:205], v[28:31]
	v_mfma_f32_16x16x32_bf16 v[24:27], v[136:139], v[202:205], v[24:27]
	v_mfma_f32_16x16x32_bf16 v[12:15], v[128:131], v[210:213], v[12:15]
	v_mfma_f32_16x16x32_bf16 v[8:11], v[136:139], v[210:213], v[8:11]
	v_mfma_f32_16x16x32_bf16 v[60:63], v[132:135], v[186:189], v[60:63]
	v_mfma_f32_16x16x32_bf16 v[56:59], v[140:143], v[186:189], v[56:59]
	v_mfma_f32_16x16x32_bf16 v[44:47], v[132:135], v[198:201], v[44:47]
	v_mfma_f32_16x16x32_bf16 v[40:43], v[140:143], v[198:201], v[40:43]
	v_mfma_f32_16x16x32_bf16 v[28:31], v[132:135], v[206:209], v[28:31]
	v_mfma_f32_16x16x32_bf16 v[24:27], v[140:143], v[206:209], v[24:27]
	v_mfma_f32_16x16x32_bf16 v[12:15], v[132:135], v[214:217], v[12:15]
	v_mfma_f32_16x16x32_bf16 v[8:11], v[140:143], v[214:217], v[8:11]
	v_mfma_f32_16x16x32_bf16 v[52:55], v[144:147], v[170:173], v[52:55]
	v_mfma_f32_16x16x32_bf16 v[48:51], v[152:155], v[170:173], v[48:51]
	v_mfma_f32_16x16x32_bf16 v[36:39], v[144:147], v[190:193], v[36:39]
	v_mfma_f32_16x16x32_bf16 v[32:35], v[152:155], v[190:193], v[32:35]
	v_mfma_f32_16x16x32_bf16 v[20:23], v[144:147], v[202:205], v[20:23]
	v_mfma_f32_16x16x32_bf16 v[16:19], v[152:155], v[202:205], v[16:19]
	v_mfma_f32_16x16x32_bf16 v[4:7], v[144:147], v[210:213], v[4:7]
	v_mfma_f32_16x16x32_bf16 v[0:3], v[152:155], v[210:213], v[0:3]
	v_mfma_f32_16x16x32_bf16 v[52:55], v[148:151], v[186:189], v[52:55]
	v_mfma_f32_16x16x32_bf16 v[48:51], v[166:169], v[186:189], v[48:51]
	v_mfma_f32_16x16x32_bf16 v[36:39], v[148:151], v[198:201], v[36:39]
	v_mfma_f32_16x16x32_bf16 v[32:35], v[166:169], v[198:201], v[32:35]
	v_mfma_f32_16x16x32_bf16 v[20:23], v[148:151], v[206:209], v[20:23]
	v_mfma_f32_16x16x32_bf16 v[16:19], v[166:169], v[206:209], v[16:19]
	v_mfma_f32_16x16x32_bf16 v[4:7], v[148:151], v[214:217], v[4:7]
	v_mfma_f32_16x16x32_bf16 v[0:3], v[166:169], v[214:217], v[0:3]
	s_barrier
	s_add_i32 s45, 0, 0x18000
	s_add_i32 s54, 0, 0x1c000
	v_add_u32_e32 v140, s45, v195
	v_add_u32_e32 v166, s54, v195
	ds_read_b128 v[128:131], v140
	ds_read_b128 v[132:135], v140 offset:1024
	ds_read_b128 v[136:139], v140 offset:2048
	ds_read_b128 v[140:143], v140 offset:3072
	ds_read_b128 v[144:147], v166
	ds_read_b128 v[148:151], v166 offset:1024
	ds_read_b128 v[152:155], v166 offset:2048
	ds_read_b128 v[166:169], v166 offset:3072
	s_add_u32 s4, s30, s6
	s_addc_u32 s5, s31, s7
	s_mov_b32 m0, s48
	v_lshl_add_u64 v[232:233], s[4:5], 0, v[160:161]
	ds_read_b128 v[170:173], v197 offset:32768
	ds_read_b128 v[186:189], v197 offset:33792
	ds_read_b128 v[190:193], v197 offset:34816
	ds_read_b128 v[198:201], v197 offset:35840
	ds_read_b128 v[202:205], v197 offset:36864
	ds_read_b128 v[206:209], v197 offset:37888
	ds_read_b128 v[210:213], v197 offset:38912
	ds_read_b128 v[214:217], v197 offset:39936
	global_load_lds_dwordx4 v[232:233], off
	v_lshl_add_u64 v[232:233], s[4:5], 0, v[158:159]
	s_mov_b32 m0, s49
	s_nop 0
	global_load_lds_dwordx4 v[232:233], off
	s_waitcnt vmcnt(8)
	s_waitcnt lgkmcnt(0)
	s_barrier
	s_waitcnt lgkmcnt(0)
	v_mfma_f32_16x16x32_bf16 v[120:123], v[128:131], v[170:173], v[120:123]
	v_mfma_f32_16x16x32_bf16 v[124:127], v[136:139], v[170:173], v[124:127]
	v_mfma_f32_16x16x32_bf16 v[108:111], v[128:131], v[190:193], v[108:111]
	v_mfma_f32_16x16x32_bf16 v[104:107], v[136:139], v[190:193], v[104:107]
	v_mfma_f32_16x16x32_bf16 v[92:95], v[128:131], v[202:205], v[92:95]
	v_mfma_f32_16x16x32_bf16 v[88:91], v[136:139], v[202:205], v[88:91]
	v_mfma_f32_16x16x32_bf16 v[76:79], v[128:131], v[210:213], v[76:79]
	v_mfma_f32_16x16x32_bf16 v[72:75], v[136:139], v[210:213], v[72:75]
	v_mfma_f32_16x16x32_bf16 v[120:123], v[132:135], v[186:189], v[120:123]
	v_mfma_f32_16x16x32_bf16 v[124:127], v[140:143], v[186:189], v[124:127]
	v_mfma_f32_16x16x32_bf16 v[108:111], v[132:135], v[198:201], v[108:111]
	v_mfma_f32_16x16x32_bf16 v[104:107], v[140:143], v[198:201], v[104:107]
	v_mfma_f32_16x16x32_bf16 v[92:95], v[132:135], v[206:209], v[92:95]
	v_mfma_f32_16x16x32_bf16 v[88:91], v[140:143], v[206:209], v[88:91]
	v_mfma_f32_16x16x32_bf16 v[76:79], v[132:135], v[214:217], v[76:79]
	v_mfma_f32_16x16x32_bf16 v[72:75], v[140:143], v[214:217], v[72:75]
	v_mfma_f32_16x16x32_bf16 v[116:119], v[144:147], v[170:173], v[116:119]
	v_mfma_f32_16x16x32_bf16 v[112:115], v[152:155], v[170:173], v[112:115]
	v_mfma_f32_16x16x32_bf16 v[100:103], v[144:147], v[190:193], v[100:103]
	v_mfma_f32_16x16x32_bf16 v[96:99], v[152:155], v[190:193], v[96:99]
	v_mfma_f32_16x16x32_bf16 v[84:87], v[144:147], v[202:205], v[84:87]
	v_mfma_f32_16x16x32_bf16 v[80:83], v[152:155], v[202:205], v[80:83]
	v_mfma_f32_16x16x32_bf16 v[68:71], v[144:147], v[210:213], v[68:71]
	v_mfma_f32_16x16x32_bf16 v[64:67], v[152:155], v[210:213], v[64:67]
	v_mfma_f32_16x16x32_bf16 v[116:119], v[148:151], v[186:189], v[116:119]
	v_mfma_f32_16x16x32_bf16 v[112:115], v[166:169], v[186:189], v[112:115]
	v_mfma_f32_16x16x32_bf16 v[100:103], v[148:151], v[198:201], v[100:103]
	v_mfma_f32_16x16x32_bf16 v[96:99], v[166:169], v[198:201], v[96:99]
	v_mfma_f32_16x16x32_bf16 v[84:87], v[148:151], v[206:209], v[84:87]
	v_mfma_f32_16x16x32_bf16 v[80:83], v[166:169], v[206:209], v[80:83]
	v_mfma_f32_16x16x32_bf16 v[68:71], v[148:151], v[214:217], v[68:71]
	v_mfma_f32_16x16x32_bf16 v[64:67], v[166:169], v[214:217], v[64:67]
	s_barrier
	s_add_i32 s4, s45, s37
	v_lshl_add_u64 v[174:175], v[174:175], 0, s[14:15]
	s_mov_b32 m0, s4
	ds_read_b128 v[170:173], v197 offset:49152
	ds_read_b128 v[186:189], v197 offset:50176
	ds_read_b128 v[190:193], v197 offset:51200
	ds_read_b128 v[198:201], v197 offset:52224
	ds_read_b128 v[202:205], v197 offset:53248
	ds_read_b128 v[206:209], v197 offset:54272
	ds_read_b128 v[210:213], v197 offset:55296
	ds_read_b128 v[214:217], v197 offset:56320
	global_load_lds_dwordx4 v[174:175], off
	v_lshl_add_u64 v[174:175], v[222:223], 0, s[14:15]
	s_add_i32 m0, s4, 0x2000
	s_add_i32 s4, s54, s37
	global_load_lds_dwordx4 v[174:175], off
	v_lshl_add_u64 v[174:175], v[224:225], 0, s[14:15]
	s_mov_b32 m0, s4
	s_nop 0
	global_load_lds_dwordx4 v[174:175], off
	v_lshl_add_u64 v[174:175], v[226:227], 0, s[14:15]
	s_add_i32 m0, s4, 0x2000
	s_nop 0
	global_load_lds_dwordx4 v[174:175], off
	v_lshl_add_u64 v[174:175], v[228:229], 0, s[14:15]
	s_mov_b32 m0, s59
	s_nop 0
	global_load_lds_dwordx4 v[174:175], off
	v_lshl_add_u64 v[174:175], v[230:231], 0, s[14:15]
	s_mov_b32 m0, s60
	s_nop 0
	global_load_lds_dwordx4 v[174:175], off
	s_waitcnt vmcnt(8)
	s_waitcnt lgkmcnt(0)
	s_barrier
	s_waitcnt lgkmcnt(0)
	v_mfma_f32_16x16x32_bf16 v[60:63], v[128:131], v[170:173], v[60:63]
	s_add_u32 s28, s28, 0x100
	v_mfma_f32_16x16x32_bf16 v[56:59], v[136:139], v[170:173], v[56:59]
	s_addc_u32 s29, s29, 0
	v_mfma_f32_16x16x32_bf16 v[44:47], v[128:131], v[190:193], v[44:47]
	s_add_u32 s10, s10, 0x100
	v_mfma_f32_16x16x32_bf16 v[40:43], v[136:139], v[190:193], v[40:43]
	s_addc_u32 s11, s11, 0
	v_mfma_f32_16x16x32_bf16 v[28:31], v[128:131], v[202:205], v[28:31]
	s_mov_b32 s30, s44
	v_mfma_f32_16x16x32_bf16 v[24:27], v[136:139], v[202:205], v[24:27]
	s_cmp_ge_i32 s44, s58
	v_mfma_f32_16x16x32_bf16 v[12:15], v[128:131], v[210:213], v[12:15]
	s_cselect_b32 s99, 1, 0
	v_mfma_f32_16x16x32_bf16 v[8:11], v[136:139], v[210:213], v[8:11]
	s_add_i32 s44, s30, 2
	v_mfma_f32_16x16x32_bf16 v[60:63], v[132:135], v[186:189], v[60:63]
	s_add_u32 s4, s28, 0x80
	v_mfma_f32_16x16x32_bf16 v[56:59], v[140:143], v[186:189], v[56:59]
	s_addc_u32 s5, s29, 0
	v_mfma_f32_16x16x32_bf16 v[44:47], v[132:135], v[198:201], v[44:47]
	s_add_i32 s45, 0, 0x10000
	v_mfma_f32_16x16x32_bf16 v[40:43], v[140:143], v[198:201], v[40:43]
	s_cmp_eq_u32 s61, s30
	v_mfma_f32_16x16x32_bf16 v[28:31], v[132:135], v[206:209], v[28:31]
	s_cselect_b32 s31, s25, s5
	v_mfma_f32_16x16x32_bf16 v[24:27], v[140:143], v[206:209], v[24:27]
	s_cselect_b32 s30, s24, s4
	v_mfma_f32_16x16x32_bf16 v[12:15], v[132:135], v[214:217], v[12:15]
	s_cselect_b32 s5, s27, s11
	v_mfma_f32_16x16x32_bf16 v[8:11], v[140:143], v[214:217], v[8:11]
	s_cselect_b32 s4, s26, s10
	v_mfma_f32_16x16x32_bf16 v[52:55], v[144:147], v[170:173], v[52:55]
	s_add_i32 s54, 0, 0x14000
	v_mfma_f32_16x16x32_bf16 v[48:51], v[152:155], v[170:173], v[48:51]
	v_mfma_f32_16x16x32_bf16 v[36:39], v[144:147], v[190:193], v[36:39]
	v_mfma_f32_16x16x32_bf16 v[32:35], v[152:155], v[190:193], v[32:35]
	v_mfma_f32_16x16x32_bf16 v[20:23], v[144:147], v[202:205], v[20:23]
	v_mfma_f32_16x16x32_bf16 v[16:19], v[152:155], v[202:205], v[16:19]
	v_mfma_f32_16x16x32_bf16 v[4:7], v[144:147], v[210:213], v[4:7]
	v_mfma_f32_16x16x32_bf16 v[0:3], v[152:155], v[210:213], v[0:3]
	v_mfma_f32_16x16x32_bf16 v[52:55], v[148:151], v[186:189], v[52:55]
	v_mfma_f32_16x16x32_bf16 v[48:51], v[166:169], v[186:189], v[48:51]
	v_mfma_f32_16x16x32_bf16 v[36:39], v[148:151], v[198:201], v[36:39]
	v_mfma_f32_16x16x32_bf16 v[32:35], v[166:169], v[198:201], v[32:35]
	v_mfma_f32_16x16x32_bf16 v[20:23], v[148:151], v[206:209], v[20:23]
	v_mfma_f32_16x16x32_bf16 v[16:19], v[166:169], v[206:209], v[16:19]
	v_mfma_f32_16x16x32_bf16 v[4:7], v[148:151], v[214:217], v[4:7]
	v_mfma_f32_16x16x32_bf16 v[0:3], v[166:169], v[214:217], v[0:3]
	s_barrier
	s_cmp_lg_u32 s99, 0
	s_cbranch_scc0 .LBB0_475

.Llbb_5:
	s_add_i32 s44, s16, 2
	s_add_u32 s45, s0, 0x80
	s_addc_u32 s17, s1, 0
	s_add_i32 s64, 0, 0x10000
	s_cmp_eq_u32 s63, s16
	s_cselect_b32 s17, s57, s17
	s_cselect_b32 s16, s56, s45
	v_add_u32_e32 v152, s64, v153
	s_cselect_b32 s47, s9, s39
	s_cselect_b32 s46, s8, s38
	s_add_i32 s45, 0, 0x14000
	ds_read_b128 v[128:131], v152
	ds_read_b128 v[158:161], v152 offset:1024
	ds_read_b128 v[162:165], v152 offset:2048
	ds_read_b128 v[166:169], v152 offset:3072
	v_add_u32_e32 v152, s45, v153
	ds_read_b128 v[170:173], v152
	ds_read_b128 v[174:177], v152 offset:1024
	ds_read_b128 v[194:197], v152 offset:2048
	ds_read_b128 v[206:209], v152 offset:3072
	v_lshl_add_u64 v[178:179], s[0:1], 0, v[148:149]
	s_add_i32 m0, s52, 0xc000
	ds_read_b128 v[210:213], v157
	ds_read_b128 v[214:217], v157 offset:1024
	ds_read_b128 v[220:223], v157 offset:2048
	ds_read_b128 v[224:227], v157 offset:3072
	ds_read_b128 v[228:231], v157 offset:4096
	ds_read_b128 v[232:235], v157 offset:5120
	ds_read_b128 v[236:239], v157 offset:6144
	ds_read_b128 v[240:243], v157 offset:7168
	global_load_lds_dwordx4 v[178:179], off
	v_lshl_add_u64 v[178:179], s[0:1], 0, v[150:151]
	s_add_i32 m0, s52, 0xe000
	s_nop 0
	global_load_lds_dwordx4 v[178:179], off
	s_waitcnt vmcnt(8)
	s_waitcnt lgkmcnt(0)
	s_barrier
	s_waitcnt lgkmcnt(0)
	v_mfma_f32_16x16x32_bf16 v[124:127], v[128:131], v[210:213], 0
	v_mfma_f32_16x16x32_bf16 v[120:123], v[162:165], v[210:213], 0
	v_mfma_f32_16x16x32_bf16 v[108:111], v[128:131], v[220:223], 0
	v_mfma_f32_16x16x32_bf16 v[104:107], v[162:165], v[220:223], 0
	v_mfma_f32_16x16x32_bf16 v[92:95], v[128:131], v[228:231], 0
	v_mfma_f32_16x16x32_bf16 v[88:91], v[162:165], v[228:231], 0
	v_mfma_f32_16x16x32_bf16 v[76:79], v[128:131], v[236:239], 0
	v_mfma_f32_16x16x32_bf16 v[72:75], v[162:165], v[236:239], 0
	v_mfma_f32_16x16x32_bf16 v[124:127], v[158:161], v[214:217], v[124:127]
	v_mfma_f32_16x16x32_bf16 v[120:123], v[166:169], v[214:217], v[120:123]
	v_mfma_f32_16x16x32_bf16 v[108:111], v[158:161], v[224:227], v[108:111]
	v_mfma_f32_16x16x32_bf16 v[104:107], v[166:169], v[224:227], v[104:107]
	v_mfma_f32_16x16x32_bf16 v[92:95], v[158:161], v[232:235], v[92:95]
	v_mfma_f32_16x16x32_bf16 v[88:91], v[166:169], v[232:235], v[88:91]
	v_mfma_f32_16x16x32_bf16 v[76:79], v[158:161], v[240:243], v[76:79]
	v_mfma_f32_16x16x32_bf16 v[72:75], v[166:169], v[240:243], v[72:75]
	v_mfma_f32_16x16x32_bf16 v[116:119], v[170:173], v[210:213], 0
	v_mfma_f32_16x16x32_bf16 v[112:115], v[194:197], v[210:213], 0
	v_mfma_f32_16x16x32_bf16 v[100:103], v[170:173], v[220:223], 0
	v_mfma_f32_16x16x32_bf16 v[96:99], v[194:197], v[220:223], 0
	v_mfma_f32_16x16x32_bf16 v[84:87], v[170:173], v[228:231], 0
	v_mfma_f32_16x16x32_bf16 v[80:83], v[194:197], v[228:231], 0
	v_mfma_f32_16x16x32_bf16 v[68:71], v[170:173], v[236:239], 0
	v_mfma_f32_16x16x32_bf16 v[64:67], v[194:197], v[236:239], 0
	v_mfma_f32_16x16x32_bf16 v[116:119], v[174:177], v[214:217], v[116:119]
	v_mfma_f32_16x16x32_bf16 v[112:115], v[206:209], v[214:217], v[112:115]
	v_mfma_f32_16x16x32_bf16 v[100:103], v[174:177], v[224:227], v[100:103]
	v_mfma_f32_16x16x32_bf16 v[96:99], v[206:209], v[224:227], v[96:99]
	v_mfma_f32_16x16x32_bf16 v[84:87], v[174:177], v[232:235], v[84:87]
	v_mfma_f32_16x16x32_bf16 v[80:83], v[206:209], v[232:235], v[80:83]
	v_mfma_f32_16x16x32_bf16 v[68:71], v[174:177], v[240:243], v[68:71]
	v_mfma_f32_16x16x32_bf16 v[64:67], v[206:209], v[240:243], v[64:67]
	s_barrier
	s_add_i32 s64, s64, s4
	v_lshl_add_u64 v[178:179], s[46:47], 0, v[134:135]
	s_mov_b32 m0, s64
	ds_read_b128 v[210:213], v157 offset:16384
	ds_read_b128 v[214:217], v157 offset:17408
	ds_read_b128 v[220:223], v157 offset:18432
	ds_read_b128 v[224:227], v157 offset:19456
	ds_read_b128 v[228:231], v157 offset:20480
	ds_read_b128 v[232:235], v157 offset:21504
	ds_read_b128 v[236:239], v157 offset:22528
	ds_read_b128 v[240:243], v157 offset:23552
	global_load_lds_dwordx4 v[178:179], off
	s_add_i32 m0, s64, 0x2000
	v_lshl_add_u64 v[198:199], s[46:47], 0, v[138:139]
	s_add_u32 s46, s46, s24
	s_addc_u32 s47, s47, s25
	s_add_i32 s45, s45, s4
	global_load_lds_dwordx4 v[198:199], off
	v_lshl_add_u64 v[244:245], s[46:47], 0, v[134:135]
	s_mov_b32 m0, s45
	v_lshl_add_u64 v[246:247], s[46:47], 0, v[138:139]
	global_load_lds_dwordx4 v[244:245], off
	s_add_i32 m0, s45, 0x2000
	v_lshl_add_u64 v[248:249], s[16:17], 0, v[132:133]
	global_load_lds_dwordx4 v[246:247], off
	s_mov_b32 m0, s52
	v_lshl_add_u64 v[250:251], s[16:17], 0, v[136:137]
	global_load_lds_dwordx4 v[248:249], off
	s_mov_b32 m0, s18
	s_nop 0
	global_load_lds_dwordx4 v[250:251], off
	s_waitcnt vmcnt(8)
	s_waitcnt lgkmcnt(0)
	s_barrier
	s_waitcnt lgkmcnt(0)
	v_mfma_f32_16x16x32_bf16 v[60:63], v[128:131], v[210:213], 0
	v_mfma_f32_16x16x32_bf16 v[56:59], v[162:165], v[210:213], 0
	v_mfma_f32_16x16x32_bf16 v[44:47], v[128:131], v[220:223], 0
	v_mfma_f32_16x16x32_bf16 v[40:43], v[162:165], v[220:223], 0
	v_mfma_f32_16x16x32_bf16 v[28:31], v[128:131], v[228:231], 0
	v_mfma_f32_16x16x32_bf16 v[24:27], v[162:165], v[228:231], 0
	v_mfma_f32_16x16x32_bf16 v[12:15], v[128:131], v[236:239], 0
	v_mfma_f32_16x16x32_bf16 v[8:11], v[162:165], v[236:239], 0
	v_mfma_f32_16x16x32_bf16 v[60:63], v[158:161], v[214:217], v[60:63]
	v_mfma_f32_16x16x32_bf16 v[56:59], v[166:169], v[214:217], v[56:59]
	v_mfma_f32_16x16x32_bf16 v[44:47], v[158:161], v[224:227], v[44:47]
	v_mfma_f32_16x16x32_bf16 v[40:43], v[166:169], v[224:227], v[40:43]
	v_mfma_f32_16x16x32_bf16 v[28:31], v[158:161], v[232:235], v[28:31]
	v_mfma_f32_16x16x32_bf16 v[24:27], v[166:169], v[232:235], v[24:27]
	v_mfma_f32_16x16x32_bf16 v[12:15], v[158:161], v[240:243], v[12:15]
	v_mfma_f32_16x16x32_bf16 v[8:11], v[166:169], v[240:243], v[8:11]
	v_mfma_f32_16x16x32_bf16 v[52:55], v[170:173], v[210:213], 0
	v_mfma_f32_16x16x32_bf16 v[48:51], v[194:197], v[210:213], 0
	v_mfma_f32_16x16x32_bf16 v[36:39], v[170:173], v[220:223], 0
	v_mfma_f32_16x16x32_bf16 v[32:35], v[194:197], v[220:223], 0
	v_mfma_f32_16x16x32_bf16 v[20:23], v[170:173], v[228:231], 0
	v_mfma_f32_16x16x32_bf16 v[16:19], v[194:197], v[228:231], 0
	v_mfma_f32_16x16x32_bf16 v[4:7], v[170:173], v[236:239], 0
	v_mfma_f32_16x16x32_bf16 v[0:3], v[194:197], v[236:239], 0
	v_mfma_f32_16x16x32_bf16 v[52:55], v[174:177], v[214:217], v[52:55]
	v_mfma_f32_16x16x32_bf16 v[48:51], v[206:209], v[214:217], v[48:51]
	v_mfma_f32_16x16x32_bf16 v[36:39], v[174:177], v[224:227], v[36:39]
	v_mfma_f32_16x16x32_bf16 v[32:35], v[206:209], v[224:227], v[32:35]
	v_mfma_f32_16x16x32_bf16 v[20:23], v[174:177], v[232:235], v[20:23]
	v_mfma_f32_16x16x32_bf16 v[16:19], v[206:209], v[232:235], v[16:19]
	v_mfma_f32_16x16x32_bf16 v[4:7], v[174:177], v[240:243], v[4:7]
	v_mfma_f32_16x16x32_bf16 v[0:3], v[206:209], v[240:243], v[0:3]
	s_barrier
	s_add_i32 s45, 0, 0x18000
	v_add_u32_e32 v152, s45, v153
	s_add_i32 s46, 0, 0x1c000
	ds_read_b128 v[128:131], v152
	ds_read_b128 v[158:161], v152 offset:1024
	ds_read_b128 v[162:165], v152 offset:2048
	ds_read_b128 v[166:169], v152 offset:3072
	v_add_u32_e32 v152, s46, v153
	ds_read_b128 v[170:173], v152
	ds_read_b128 v[174:177], v152 offset:1024
	ds_read_b128 v[194:197], v152 offset:2048
	ds_read_b128 v[206:209], v152 offset:3072
	s_add_u32 s16, s16, s24
	s_addc_u32 s17, s17, s25
	s_mov_b32 m0, s19
	v_lshl_add_u64 v[202:203], s[16:17], 0, v[132:133]
	ds_read_b128 v[210:213], v157 offset:32768
	ds_read_b128 v[214:217], v157 offset:33792
	ds_read_b128 v[220:223], v157 offset:34816
	ds_read_b128 v[224:227], v157 offset:35840
	ds_read_b128 v[228:231], v157 offset:36864
	ds_read_b128 v[232:235], v157 offset:37888
	ds_read_b128 v[236:239], v157 offset:38912
	ds_read_b128 v[240:243], v157 offset:39936
	global_load_lds_dwordx4 v[202:203], off
	v_lshl_add_u64 v[202:203], s[16:17], 0, v[136:137]
	s_mov_b32 m0, s33
	s_nop 0
	global_load_lds_dwordx4 v[202:203], off
	s_waitcnt vmcnt(8)
	s_waitcnt lgkmcnt(0)
	s_barrier
	s_waitcnt lgkmcnt(0)
	v_mfma_f32_16x16x32_bf16 v[124:127], v[128:131], v[210:213], v[124:127]
	v_mfma_f32_16x16x32_bf16 v[120:123], v[162:165], v[210:213], v[120:123]
	v_mfma_f32_16x16x32_bf16 v[108:111], v[128:131], v[220:223], v[108:111]
	v_mfma_f32_16x16x32_bf16 v[104:107], v[162:165], v[220:223], v[104:107]
	v_mfma_f32_16x16x32_bf16 v[92:95], v[128:131], v[228:231], v[92:95]
	v_mfma_f32_16x16x32_bf16 v[88:91], v[162:165], v[228:231], v[88:91]
	v_mfma_f32_16x16x32_bf16 v[76:79], v[128:131], v[236:239], v[76:79]
	v_mfma_f32_16x16x32_bf16 v[72:75], v[162:165], v[236:239], v[72:75]
	v_mfma_f32_16x16x32_bf16 v[124:127], v[158:161], v[214:217], v[124:127]
	v_mfma_f32_16x16x32_bf16 v[120:123], v[166:169], v[214:217], v[120:123]
	v_mfma_f32_16x16x32_bf16 v[108:111], v[158:161], v[224:227], v[108:111]
	v_mfma_f32_16x16x32_bf16 v[104:107], v[166:169], v[224:227], v[104:107]
	v_mfma_f32_16x16x32_bf16 v[92:95], v[158:161], v[232:235], v[92:95]
	v_mfma_f32_16x16x32_bf16 v[88:91], v[166:169], v[232:235], v[88:91]
	v_mfma_f32_16x16x32_bf16 v[76:79], v[158:161], v[240:243], v[76:79]
	v_mfma_f32_16x16x32_bf16 v[72:75], v[166:169], v[240:243], v[72:75]
	v_mfma_f32_16x16x32_bf16 v[116:119], v[170:173], v[210:213], v[116:119]
	v_mfma_f32_16x16x32_bf16 v[112:115], v[194:197], v[210:213], v[112:115]
	v_mfma_f32_16x16x32_bf16 v[100:103], v[170:173], v[220:223], v[100:103]
	v_mfma_f32_16x16x32_bf16 v[96:99], v[194:197], v[220:223], v[96:99]
	v_mfma_f32_16x16x32_bf16 v[84:87], v[170:173], v[228:231], v[84:87]
	v_mfma_f32_16x16x32_bf16 v[80:83], v[194:197], v[228:231], v[80:83]
	v_mfma_f32_16x16x32_bf16 v[68:71], v[170:173], v[236:239], v[68:71]
	v_mfma_f32_16x16x32_bf16 v[64:67], v[194:197], v[236:239], v[64:67]
	v_mfma_f32_16x16x32_bf16 v[116:119], v[174:177], v[214:217], v[116:119]
	v_mfma_f32_16x16x32_bf16 v[112:115], v[206:209], v[214:217], v[112:115]
	v_mfma_f32_16x16x32_bf16 v[100:103], v[174:177], v[224:227], v[100:103]
	v_mfma_f32_16x16x32_bf16 v[96:99], v[206:209], v[224:227], v[96:99]
	v_mfma_f32_16x16x32_bf16 v[84:87], v[174:177], v[232:235], v[84:87]
	v_mfma_f32_16x16x32_bf16 v[80:83], v[206:209], v[232:235], v[80:83]
	v_mfma_f32_16x16x32_bf16 v[68:71], v[174:177], v[240:243], v[68:71]
	v_mfma_f32_16x16x32_bf16 v[64:67], v[206:209], v[240:243], v[64:67]
	s_barrier
	s_add_i32 s16, s45, s4
	v_lshl_add_u64 v[178:179], v[178:179], 0, s[12:13]
	s_mov_b32 m0, s16
	ds_read_b128 v[210:213], v157 offset:49152
	ds_read_b128 v[214:217], v157 offset:50176
	ds_read_b128 v[220:223], v157 offset:51200
	ds_read_b128 v[224:227], v157 offset:52224
	ds_read_b128 v[228:231], v157 offset:53248
	ds_read_b128 v[232:235], v157 offset:54272
	ds_read_b128 v[236:239], v157 offset:55296
	ds_read_b128 v[240:243], v157 offset:56320
	global_load_lds_dwordx4 v[178:179], off
	v_lshl_add_u64 v[178:179], v[198:199], 0, s[12:13]
	s_add_i32 m0, s16, 0x2000
	s_add_i32 s16, s46, s4
	global_load_lds_dwordx4 v[178:179], off
	v_lshl_add_u64 v[178:179], v[244:245], 0, s[12:13]
	s_mov_b32 m0, s16
	s_nop 0
	global_load_lds_dwordx4 v[178:179], off
	v_lshl_add_u64 v[178:179], v[246:247], 0, s[12:13]
	s_add_i32 m0, s16, 0x2000
	s_nop 0
	global_load_lds_dwordx4 v[178:179], off
	v_lshl_add_u64 v[178:179], v[248:249], 0, s[12:13]
	s_mov_b32 m0, s59
	s_nop 0
	global_load_lds_dwordx4 v[178:179], off
	v_lshl_add_u64 v[178:179], v[250:251], 0, s[12:13]
	s_mov_b32 m0, s60
	s_nop 0
	global_load_lds_dwordx4 v[178:179], off
	s_waitcnt vmcnt(8)
	s_waitcnt lgkmcnt(0)
	s_barrier
	s_waitcnt lgkmcnt(0)
	v_mfma_f32_16x16x32_bf16 v[60:63], v[128:131], v[210:213], v[60:63]
	s_add_u32 s0, s0, 0x100
	v_mfma_f32_16x16x32_bf16 v[56:59], v[162:165], v[210:213], v[56:59]
	s_addc_u32 s1, s1, 0
	v_mfma_f32_16x16x32_bf16 v[44:47], v[128:131], v[220:223], v[44:47]
	s_add_u32 s38, s38, 0x100
	v_mfma_f32_16x16x32_bf16 v[40:43], v[162:165], v[220:223], v[40:43]
	s_addc_u32 s39, s39, 0
	v_mfma_f32_16x16x32_bf16 v[28:31], v[128:131], v[228:231], v[28:31]
	s_mov_b32 s16, s44
	v_mfma_f32_16x16x32_bf16 v[24:27], v[162:165], v[228:231], v[24:27]
	s_cmp_ge_i32 s44, s68
	v_mfma_f32_16x16x32_bf16 v[12:15], v[128:131], v[236:239], v[12:15]
	s_cselect_b32 s99, 1, 0
	v_mfma_f32_16x16x32_bf16 v[8:11], v[162:165], v[236:239], v[8:11]
	s_add_i32 s44, s16, 2
	v_mfma_f32_16x16x32_bf16 v[60:63], v[158:161], v[214:217], v[60:63]
	s_add_u32 s45, s0, 0x80
	v_mfma_f32_16x16x32_bf16 v[56:59], v[166:169], v[214:217], v[56:59]
	s_addc_u32 s17, s1, 0
	v_mfma_f32_16x16x32_bf16 v[44:47], v[158:161], v[224:227], v[44:47]
	s_add_i32 s64, 0, 0x10000
	v_mfma_f32_16x16x32_bf16 v[40:43], v[166:169], v[224:227], v[40:43]
	s_cmp_eq_u32 s63, s16
	v_mfma_f32_16x16x32_bf16 v[28:31], v[158:161], v[232:235], v[28:31]
	s_cselect_b32 s17, s57, s17
	v_mfma_f32_16x16x32_bf16 v[24:27], v[166:169], v[232:235], v[24:27]
	s_cselect_b32 s16, s56, s45
	v_mfma_f32_16x16x32_bf16 v[12:15], v[158:161], v[240:243], v[12:15]
	s_cselect_b32 s47, s9, s39
	v_mfma_f32_16x16x32_bf16 v[8:11], v[166:169], v[240:243], v[8:11]
	s_cselect_b32 s46, s8, s38
	v_mfma_f32_16x16x32_bf16 v[52:55], v[170:173], v[210:213], v[52:55]
	s_add_i32 s45, 0, 0x14000
	v_mfma_f32_16x16x32_bf16 v[48:51], v[194:197], v[210:213], v[48:51]
	v_mfma_f32_16x16x32_bf16 v[36:39], v[170:173], v[220:223], v[36:39]
	v_mfma_f32_16x16x32_bf16 v[32:35], v[194:197], v[220:223], v[32:35]
	v_mfma_f32_16x16x32_bf16 v[20:23], v[170:173], v[228:231], v[20:23]
	v_mfma_f32_16x16x32_bf16 v[16:19], v[194:197], v[228:231], v[16:19]
	v_mfma_f32_16x16x32_bf16 v[4:7], v[170:173], v[236:239], v[4:7]
	v_mfma_f32_16x16x32_bf16 v[0:3], v[194:197], v[236:239], v[0:3]
	v_mfma_f32_16x16x32_bf16 v[52:55], v[174:177], v[214:217], v[52:55]
	v_mfma_f32_16x16x32_bf16 v[48:51], v[206:209], v[214:217], v[48:51]
	v_mfma_f32_16x16x32_bf16 v[36:39], v[174:177], v[224:227], v[36:39]
	v_mfma_f32_16x16x32_bf16 v[32:35], v[206:209], v[224:227], v[32:35]
	v_mfma_f32_16x16x32_bf16 v[20:23], v[174:177], v[232:235], v[20:23]
	v_mfma_f32_16x16x32_bf16 v[16:19], v[206:209], v[232:235], v[16:19]
	v_mfma_f32_16x16x32_bf16 v[4:7], v[174:177], v[240:243], v[4:7]
	v_mfma_f32_16x16x32_bf16 v[0:3], v[206:209], v[240:243], v[0:3]
	s_barrier
	s_cmp_lg_u32 s99, 0
	s_cbranch_scc1 .Lpeelx_9
.LBB0_576:
	v_add_u32_e32 v152, s64, v153
	ds_read_b128 v[128:131], v152
	ds_read_b128 v[158:161], v152 offset:1024
	ds_read_b128 v[162:165], v152 offset:2048
	ds_read_b128 v[166:169], v152 offset:3072
	v_add_u32_e32 v152, s45, v153
	ds_read_b128 v[170:173], v152
	ds_read_b128 v[174:177], v152 offset:1024
	ds_read_b128 v[194:197], v152 offset:2048
	ds_read_b128 v[206:209], v152 offset:3072
	v_lshl_add_u64 v[178:179], s[0:1], 0, v[148:149]
	s_add_i32 m0, s52, 0xc000
	ds_read_b128 v[210:213], v157
	ds_read_b128 v[214:217], v157 offset:1024
	ds_read_b128 v[220:223], v157 offset:2048
	ds_read_b128 v[224:227], v157 offset:3072
	ds_read_b128 v[228:231], v157 offset:4096
	ds_read_b128 v[232:235], v157 offset:5120
	ds_read_b128 v[236:239], v157 offset:6144
	ds_read_b128 v[240:243], v157 offset:7168
	global_load_lds_dwordx4 v[178:179], off
	v_lshl_add_u64 v[178:179], s[0:1], 0, v[150:151]
	s_add_i32 m0, s52, 0xe000
	s_nop 0
	global_load_lds_dwordx4 v[178:179], off
	s_waitcnt vmcnt(8)
	s_waitcnt lgkmcnt(0)
	s_barrier
	s_waitcnt lgkmcnt(0)
	v_mfma_f32_16x16x32_bf16 v[124:127], v[128:131], v[210:213], v[124:127]
	v_mfma_f32_16x16x32_bf16 v[120:123], v[162:165], v[210:213], v[120:123]
	v_mfma_f32_16x16x32_bf16 v[108:111], v[128:131], v[220:223], v[108:111]
	v_mfma_f32_16x16x32_bf16 v[104:107], v[162:165], v[220:223], v[104:107]
	v_mfma_f32_16x16x32_bf16 v[92:95], v[128:131], v[228:231], v[92:95]
	v_mfma_f32_16x16x32_bf16 v[88:91], v[162:165], v[228:231], v[88:91]
	v_mfma_f32_16x16x32_bf16 v[76:79], v[128:131], v[236:239], v[76:79]
	v_mfma_f32_16x16x32_bf16 v[72:75], v[162:165], v[236:239], v[72:75]
	v_mfma_f32_16x16x32_bf16 v[124:127], v[158:161], v[214:217], v[124:127]
	v_mfma_f32_16x16x32_bf16 v[120:123], v[166:169], v[214:217], v[120:123]
	v_mfma_f32_16x16x32_bf16 v[108:111], v[158:161], v[224:227], v[108:111]
	v_mfma_f32_16x16x32_bf16 v[104:107], v[166:169], v[224:227], v[104:107]
	v_mfma_f32_16x16x32_bf16 v[92:95], v[158:161], v[232:235], v[92:95]
	v_mfma_f32_16x16x32_bf16 v[88:91], v[166:169], v[232:235], v[88:91]
	v_mfma_f32_16x16x32_bf16 v[76:79], v[158:161], v[240:243], v[76:79]
	v_mfma_f32_16x16x32_bf16 v[72:75], v[166:169], v[240:243], v[72:75]
	v_mfma_f32_16x16x32_bf16 v[116:119], v[170:173], v[210:213], v[116:119]
	v_mfma_f32_16x16x32_bf16 v[112:115], v[194:197], v[210:213], v[112:115]
	v_mfma_f32_16x16x32_bf16 v[100:103], v[170:173], v[220:223], v[100:103]
	v_mfma_f32_16x16x32_bf16 v[96:99], v[194:197], v[220:223], v[96:99]
	v_mfma_f32_16x16x32_bf16 v[84:87], v[170:173], v[228:231], v[84:87]
	v_mfma_f32_16x16x32_bf16 v[80:83], v[194:197], v[228:231], v[80:83]
	v_mfma_f32_16x16x32_bf16 v[68:71], v[170:173], v[236:239], v[68:71]
	v_mfma_f32_16x16x32_bf16 v[64:67], v[194:197], v[236:239], v[64:67]
	v_mfma_f32_16x16x32_bf16 v[116:119], v[174:177], v[214:217], v[116:119]
	v_mfma_f32_16x16x32_bf16 v[112:115], v[206:209], v[214:217], v[112:115]
	v_mfma_f32_16x16x32_bf16 v[100:103], v[174:177], v[224:227], v[100:103]
	v_mfma_f32_16x16x32_bf16 v[96:99], v[206:209], v[224:227], v[96:99]
	v_mfma_f32_16x16x32_bf16 v[84:87], v[174:177], v[232:235], v[84:87]
	v_mfma_f32_16x16x32_bf16 v[80:83], v[206:209], v[232:235], v[80:83]
	v_mfma_f32_16x16x32_bf16 v[68:71], v[174:177], v[240:243], v[68:71]
	v_mfma_f32_16x16x32_bf16 v[64:67], v[206:209], v[240:243], v[64:67]
	s_barrier
	s_add_i32 s64, s64, s4
	v_lshl_add_u64 v[178:179], s[46:47], 0, v[134:135]
	s_mov_b32 m0, s64
	ds_read_b128 v[210:213], v157 offset:16384
	ds_read_b128 v[214:217], v157 offset:17408
	ds_read_b128 v[220:223], v157 offset:18432
	ds_read_b128 v[224:227], v157 offset:19456
	ds_read_b128 v[228:231], v157 offset:20480
	ds_read_b128 v[232:235], v157 offset:21504
	ds_read_b128 v[236:239], v157 offset:22528
	ds_read_b128 v[240:243], v157 offset:23552
	global_load_lds_dwordx4 v[178:179], off
	s_add_i32 m0, s64, 0x2000
	v_lshl_add_u64 v[198:199], s[46:47], 0, v[138:139]
	s_add_u32 s46, s46, s24
	s_addc_u32 s47, s47, s25
	s_add_i32 s45, s45, s4
	global_load_lds_dwordx4 v[198:199], off
	v_lshl_add_u64 v[244:245], s[46:47], 0, v[134:135]
	s_mov_b32 m0, s45
	v_lshl_add_u64 v[246:247], s[46:47], 0, v[138:139]
	global_load_lds_dwordx4 v[244:245], off
	s_add_i32 m0, s45, 0x2000
	v_lshl_add_u64 v[248:249], s[16:17], 0, v[132:133]
	global_load_lds_dwordx4 v[246:247], off
	s_mov_b32 m0, s52
	v_lshl_add_u64 v[250:251], s[16:17], 0, v[136:137]
	global_load_lds_dwordx4 v[248:249], off
	s_mov_b32 m0, s18
	s_nop 0
	global_load_lds_dwordx4 v[250:251], off
	s_waitcnt vmcnt(8)
	s_waitcnt lgkmcnt(0)
	s_barrier
	s_waitcnt lgkmcnt(0)
	v_mfma_f32_16x16x32_bf16 v[60:63], v[128:131], v[210:213], v[60:63]
	v_mfma_f32_16x16x32_bf16 v[56:59], v[162:165], v[210:213], v[56:59]
	v_mfma_f32_16x16x32_bf16 v[44:47], v[128:131], v[220:223], v[44:47]
	v_mfma_f32_16x16x32_bf16 v[40:43], v[162:165], v[220:223], v[40:43]
	v_mfma_f32_16x16x32_bf16 v[28:31], v[128:131], v[228:231], v[28:31]
	v_mfma_f32_16x16x32_bf16 v[24:27], v[162:165], v[228:231], v[24:27]
	v_mfma_f32_16x16x32_bf16 v[12:15], v[128:131], v[236:239], v[12:15]
	v_mfma_f32_16x16x32_bf16 v[8:11], v[162:165], v[236:239], v[8:11]
	v_mfma_f32_16x16x32_bf16 v[60:63], v[158:161], v[214:217], v[60:63]
	v_mfma_f32_16x16x32_bf16 v[56:59], v[166:169], v[214:217], v[56:59]
	v_mfma_f32_16x16x32_bf16 v[44:47], v[158:161], v[224:227], v[44:47]
	v_mfma_f32_16x16x32_bf16 v[40:43], v[166:169], v[224:227], v[40:43]
	v_mfma_f32_16x16x32_bf16 v[28:31], v[158:161], v[232:235], v[28:31]
	v_mfma_f32_16x16x32_bf16 v[24:27], v[166:169], v[232:235], v[24:27]
	v_mfma_f32_16x16x32_bf16 v[12:15], v[158:161], v[240:243], v[12:15]
	v_mfma_f32_16x16x32_bf16 v[8:11], v[166:169], v[240:243], v[8:11]
	v_mfma_f32_16x16x32_bf16 v[52:55], v[170:173], v[210:213], v[52:55]
	v_mfma_f32_16x16x32_bf16 v[48:51], v[194:197], v[210:213], v[48:51]
	v_mfma_f32_16x16x32_bf16 v[36:39], v[170:173], v[220:223], v[36:39]
	v_mfma_f32_16x16x32_bf16 v[32:35], v[194:197], v[220:223], v[32:35]
	v_mfma_f32_16x16x32_bf16 v[20:23], v[170:173], v[228:231], v[20:23]
	v_mfma_f32_16x16x32_bf16 v[16:19], v[194:197], v[228:231], v[16:19]
	v_mfma_f32_16x16x32_bf16 v[4:7], v[170:173], v[236:239], v[4:7]
	v_mfma_f32_16x16x32_bf16 v[0:3], v[194:197], v[236:239], v[0:3]
	v_mfma_f32_16x16x32_bf16 v[52:55], v[174:177], v[214:217], v[52:55]
	v_mfma_f32_16x16x32_bf16 v[48:51], v[206:209], v[214:217], v[48:51]
	v_mfma_f32_16x16x32_bf16 v[36:39], v[174:177], v[224:227], v[36:39]
	v_mfma_f32_16x16x32_bf16 v[32:35], v[206:209], v[224:227], v[32:35]
	v_mfma_f32_16x16x32_bf16 v[20:23], v[174:177], v[232:235], v[20:23]
	v_mfma_f32_16x16x32_bf16 v[16:19], v[206:209], v[232:235], v[16:19]
	v_mfma_f32_16x16x32_bf16 v[4:7], v[174:177], v[240:243], v[4:7]
	v_mfma_f32_16x16x32_bf16 v[0:3], v[206:209], v[240:243], v[0:3]
	s_barrier
	s_add_i32 s45, 0, 0x18000
	v_add_u32_e32 v152, s45, v153
	s_add_i32 s46, 0, 0x1c000
	ds_read_b128 v[128:131], v152
	ds_read_b128 v[158:161], v152 offset:1024
	ds_read_b128 v[162:165], v152 offset:2048
	ds_read_b128 v[166:169], v152 offset:3072
	v_add_u32_e32 v152, s46, v153
	ds_read_b128 v[170:173], v152
	ds_read_b128 v[174:177], v152 offset:1024
	ds_read_b128 v[194:197], v152 offset:2048
	ds_read_b128 v[206:209], v152 offset:3072
	s_add_u32 s16, s16, s24
	s_addc_u32 s17, s17, s25
	s_mov_b32 m0, s19
	v_lshl_add_u64 v[202:203], s[16:17], 0, v[132:133]
	ds_read_b128 v[210:213], v157 offset:32768
	ds_read_b128 v[214:217], v157 offset:33792
	ds_read_b128 v[220:223], v157 offset:34816
	ds_read_b128 v[224:227], v157 offset:35840
	ds_read_b128 v[228:231], v157 offset:36864
	ds_read_b128 v[232:235], v157 offset:37888
	ds_read_b128 v[236:239], v157 offset:38912
	ds_read_b128 v[240:243], v157 offset:39936
	global_load_lds_dwordx4 v[202:203], off
	v_lshl_add_u64 v[202:203], s[16:17], 0, v[136:137]
	s_mov_b32 m0, s33
	s_nop 0
	global_load_lds_dwordx4 v[202:203], off
	s_waitcnt vmcnt(8)
	s_waitcnt lgkmcnt(0)
	s_barrier
	s_waitcnt lgkmcnt(0)
	v_mfma_f32_16x16x32_bf16 v[124:127], v[128:131], v[210:213], v[124:127]
	v_mfma_f32_16x16x32_bf16 v[120:123], v[162:165], v[210:213], v[120:123]
	v_mfma_f32_16x16x32_bf16 v[108:111], v[128:131], v[220:223], v[108:111]
	v_mfma_f32_16x16x32_bf16 v[104:107], v[162:165], v[220:223], v[104:107]
	v_mfma_f32_16x16x32_bf16 v[92:95], v[128:131], v[228:231], v[92:95]
	v_mfma_f32_16x16x32_bf16 v[88:91], v[162:165], v[228:231], v[88:91]
	v_mfma_f32_16x16x32_bf16 v[76:79], v[128:131], v[236:239], v[76:79]
	v_mfma_f32_16x16x32_bf16 v[72:75], v[162:165], v[236:239], v[72:75]
	v_mfma_f32_16x16x32_bf16 v[124:127], v[158:161], v[214:217], v[124:127]
	v_mfma_f32_16x16x32_bf16 v[120:123], v[166:169], v[214:217], v[120:123]
	v_mfma_f32_16x16x32_bf16 v[108:111], v[158:161], v[224:227], v[108:111]
	v_mfma_f32_16x16x32_bf16 v[104:107], v[166:169], v[224:227], v[104:107]
	v_mfma_f32_16x16x32_bf16 v[92:95], v[158:161], v[232:235], v[92:95]
	v_mfma_f32_16x16x32_bf16 v[88:91], v[166:169], v[232:235], v[88:91]
	v_mfma_f32_16x16x32_bf16 v[76:79], v[158:161], v[240:243], v[76:79]
	v_mfma_f32_16x16x32_bf16 v[72:75], v[166:169], v[240:243], v[72:75]
	v_mfma_f32_16x16x32_bf16 v[116:119], v[170:173], v[210:213], v[116:119]
	v_mfma_f32_16x16x32_bf16 v[112:115], v[194:197], v[210:213], v[112:115]
	v_mfma_f32_16x16x32_bf16 v[100:103], v[170:173], v[220:223], v[100:103]
	v_mfma_f32_16x16x32_bf16 v[96:99], v[194:197], v[220:223], v[96:99]
	v_mfma_f32_16x16x32_bf16 v[84:87], v[170:173], v[228:231], v[84:87]
	v_mfma_f32_16x16x32_bf16 v[80:83], v[194:197], v[228:231], v[80:83]
	v_mfma_f32_16x16x32_bf16 v[68:71], v[170:173], v[236:239], v[68:71]
	v_mfma_f32_16x16x32_bf16 v[64:67], v[194:197], v[236:239], v[64:67]
	v_mfma_f32_16x16x32_bf16 v[116:119], v[174:177], v[214:217], v[116:119]
	v_mfma_f32_16x16x32_bf16 v[112:115], v[206:209], v[214:217], v[112:115]
	v_mfma_f32_16x16x32_bf16 v[100:103], v[174:177], v[224:227], v[100:103]
	v_mfma_f32_16x16x32_bf16 v[96:99], v[206:209], v[224:227], v[96:99]
	v_mfma_f32_16x16x32_bf16 v[84:87], v[174:177], v[232:235], v[84:87]
	v_mfma_f32_16x16x32_bf16 v[80:83], v[206:209], v[232:235], v[80:83]
	v_mfma_f32_16x16x32_bf16 v[68:71], v[174:177], v[240:243], v[68:71]
	v_mfma_f32_16x16x32_bf16 v[64:67], v[206:209], v[240:243], v[64:67]
	s_barrier
	s_add_i32 s16, s45, s4
	v_lshl_add_u64 v[178:179], v[178:179], 0, s[12:13]
	s_mov_b32 m0, s16
	ds_read_b128 v[210:213], v157 offset:49152
	ds_read_b128 v[214:217], v157 offset:50176
	ds_read_b128 v[220:223], v157 offset:51200
	ds_read_b128 v[224:227], v157 offset:52224
	ds_read_b128 v[228:231], v157 offset:53248
	ds_read_b128 v[232:235], v157 offset:54272
	ds_read_b128 v[236:239], v157 offset:55296
	ds_read_b128 v[240:243], v157 offset:56320
	global_load_lds_dwordx4 v[178:179], off
	v_lshl_add_u64 v[178:179], v[198:199], 0, s[12:13]
	s_add_i32 m0, s16, 0x2000
	s_add_i32 s16, s46, s4
	global_load_lds_dwordx4 v[178:179], off
	v_lshl_add_u64 v[178:179], v[244:245], 0, s[12:13]
	s_mov_b32 m0, s16
	s_nop 0
	global_load_lds_dwordx4 v[178:179], off
	v_lshl_add_u64 v[178:179], v[246:247], 0, s[12:13]
	s_add_i32 m0, s16, 0x2000
	s_nop 0
	global_load_lds_dwordx4 v[178:179], off
	v_lshl_add_u64 v[178:179], v[248:249], 0, s[12:13]
	s_mov_b32 m0, s59
	s_nop 0
	global_load_lds_dwordx4 v[178:179], off
	v_lshl_add_u64 v[178:179], v[250:251], 0, s[12:13]
	s_mov_b32 m0, s60
	s_nop 0
	global_load_lds_dwordx4 v[178:179], off
	s_waitcnt vmcnt(8)
	s_waitcnt lgkmcnt(0)
	s_barrier
	s_waitcnt lgkmcnt(0)
	v_mfma_f32_16x16x32_bf16 v[60:63], v[128:131], v[210:213], v[60:63]
	s_add_u32 s0, s0, 0x100
	v_mfma_f32_16x16x32_bf16 v[56:59], v[162:165], v[210:213], v[56:59]
	s_addc_u32 s1, s1, 0
	v_mfma_f32_16x16x32_bf16 v[44:47], v[128:131], v[220:223], v[44:47]
	s_add_u32 s38, s38, 0x100
	v_mfma_f32_16x16x32_bf16 v[40:43], v[162:165], v[220:223], v[40:43]
	s_addc_u32 s39, s39, 0
	v_mfma_f32_16x16x32_bf16 v[28:31], v[128:131], v[228:231], v[28:31]
	s_mov_b32 s16, s44
	v_mfma_f32_16x16x32_bf16 v[24:27], v[162:165], v[228:231], v[24:27]
	s_cmp_ge_i32 s44, s68
	v_mfma_f32_16x16x32_bf16 v[12:15], v[128:131], v[236:239], v[12:15]
	s_cselect_b32 s99, 1, 0
	v_mfma_f32_16x16x32_bf16 v[8:11], v[162:165], v[236:239], v[8:11]
	s_add_i32 s44, s16, 2
	v_mfma_f32_16x16x32_bf16 v[60:63], v[158:161], v[214:217], v[60:63]
	s_add_u32 s45, s0, 0x80
	v_mfma_f32_16x16x32_bf16 v[56:59], v[166:169], v[214:217], v[56:59]
	s_addc_u32 s17, s1, 0
	v_mfma_f32_16x16x32_bf16 v[44:47], v[158:161], v[224:227], v[44:47]
	s_add_i32 s64, 0, 0x10000
	v_mfma_f32_16x16x32_bf16 v[40:43], v[166:169], v[224:227], v[40:43]
	s_cmp_eq_u32 s63, s16
	v_mfma_f32_16x16x32_bf16 v[28:31], v[158:161], v[232:235], v[28:31]
	s_cselect_b32 s17, s57, s17
	v_mfma_f32_16x16x32_bf16 v[24:27], v[166:169], v[232:235], v[24:27]
	s_cselect_b32 s16, s56, s45
	v_mfma_f32_16x16x32_bf16 v[12:15], v[158:161], v[240:243], v[12:15]
	s_cselect_b32 s47, s9, s39
	v_mfma_f32_16x16x32_bf16 v[8:11], v[166:169], v[240:243], v[8:11]
	s_cselect_b32 s46, s8, s38
	v_mfma_f32_16x16x32_bf16 v[52:55], v[170:173], v[210:213], v[52:55]
	s_add_i32 s45, 0, 0x14000
	v_mfma_f32_16x16x32_bf16 v[48:51], v[194:197], v[210:213], v[48:51]
	v_mfma_f32_16x16x32_bf16 v[36:39], v[170:173], v[220:223], v[36:39]
	v_mfma_f32_16x16x32_bf16 v[32:35], v[194:197], v[220:223], v[32:35]
	v_mfma_f32_16x16x32_bf16 v[20:23], v[170:173], v[228:231], v[20:23]
	v_mfma_f32_16x16x32_bf16 v[16:19], v[194:197], v[228:231], v[16:19]
	v_mfma_f32_16x16x32_bf16 v[4:7], v[170:173], v[236:239], v[4:7]
	v_mfma_f32_16x16x32_bf16 v[0:3], v[194:197], v[236:239], v[0:3]
	v_mfma_f32_16x16x32_bf16 v[52:55], v[174:177], v[214:217], v[52:55]
	v_mfma_f32_16x16x32_bf16 v[48:51], v[206:209], v[214:217], v[48:51]
	v_mfma_f32_16x16x32_bf16 v[36:39], v[174:177], v[224:227], v[36:39]
	v_mfma_f32_16x16x32_bf16 v[32:35], v[206:209], v[224:227], v[32:35]
	v_mfma_f32_16x16x32_bf16 v[20:23], v[174:177], v[232:235], v[20:23]
	v_mfma_f32_16x16x32_bf16 v[16:19], v[206:209], v[232:235], v[16:19]
	v_mfma_f32_16x16x32_bf16 v[4:7], v[174:177], v[240:243], v[4:7]
	v_mfma_f32_16x16x32_bf16 v[0:3], v[206:209], v[240:243], v[0:3]
	s_barrier
	s_cmp_lg_u32 s99, 0
	s_cbranch_scc0 .LBB0_576

.Llbb_6:
	s_add_i32 s30, s16, 2
	s_add_u32 s31, s28, 0x80
	s_addc_u32 s17, s29, 0
	s_add_i32 s59, 0, 0x10000
	s_cmp_eq_u32 s48, s16
	s_cselect_b32 s17, s25, s17
	s_cselect_b32 s16, s24, s31
	v_add_u32_e32 v140, s59, v143
	s_cselect_b32 s43, s27, s11
	s_cselect_b32 s42, s26, s10
	s_add_i32 s31, 0, 0x14000
	ds_read_b128 v[146:149], v140
	ds_read_b128 v[150:153], v140 offset:1024
	ds_read_b128 v[154:157], v140 offset:2048
	ds_read_b128 v[158:161], v140 offset:3072
	v_add_u32_e32 v140, s31, v143
	ds_read_b128 v[162:165], v140
	ds_read_b128 v[166:169], v140 offset:1024
	ds_read_b128 v[170:173], v140 offset:2048
	ds_read_b128 v[174:177], v140 offset:3072
	v_lshl_add_u64 v[178:179], s[28:29], 0, v[136:137]
	s_add_i32 m0, s37, 0xc000
	ds_read_b128 v[194:197], v145
	ds_read_b128 v[206:209], v145 offset:1024
	ds_read_b128 v[210:213], v145 offset:2048
	ds_read_b128 v[214:217], v145 offset:3072
	ds_read_b128 v[220:223], v145 offset:4096
	ds_read_b128 v[224:227], v145 offset:5120
	ds_read_b128 v[228:231], v145 offset:6144
	ds_read_b128 v[232:235], v145 offset:7168
	global_load_lds_dwordx4 v[178:179], off
	v_lshl_add_u64 v[178:179], s[28:29], 0, v[138:139]
	s_add_i32 m0, s37, 0xe000
	s_nop 0
	global_load_lds_dwordx4 v[178:179], off
	s_waitcnt vmcnt(8)
	s_waitcnt lgkmcnt(0)
	s_barrier
	s_waitcnt lgkmcnt(0)
	v_mfma_f32_16x16x32_bf16 v[124:127], v[146:149], v[194:197], 0
	v_mfma_f32_16x16x32_bf16 v[120:123], v[154:157], v[194:197], 0
	v_mfma_f32_16x16x32_bf16 v[108:111], v[146:149], v[210:213], 0
	v_mfma_f32_16x16x32_bf16 v[104:107], v[154:157], v[210:213], 0
	v_mfma_f32_16x16x32_bf16 v[92:95], v[146:149], v[220:223], 0
	v_mfma_f32_16x16x32_bf16 v[88:91], v[154:157], v[220:223], 0
	v_mfma_f32_16x16x32_bf16 v[76:79], v[146:149], v[228:231], 0
	v_mfma_f32_16x16x32_bf16 v[72:75], v[154:157], v[228:231], 0
	v_mfma_f32_16x16x32_bf16 v[124:127], v[150:153], v[206:209], v[124:127]
	v_mfma_f32_16x16x32_bf16 v[120:123], v[158:161], v[206:209], v[120:123]
	v_mfma_f32_16x16x32_bf16 v[108:111], v[150:153], v[214:217], v[108:111]
	v_mfma_f32_16x16x32_bf16 v[104:107], v[158:161], v[214:217], v[104:107]
	v_mfma_f32_16x16x32_bf16 v[92:95], v[150:153], v[224:227], v[92:95]
	v_mfma_f32_16x16x32_bf16 v[88:91], v[158:161], v[224:227], v[88:91]
	v_mfma_f32_16x16x32_bf16 v[76:79], v[150:153], v[232:235], v[76:79]
	v_mfma_f32_16x16x32_bf16 v[72:75], v[158:161], v[232:235], v[72:75]
	v_mfma_f32_16x16x32_bf16 v[116:119], v[162:165], v[194:197], 0
	v_mfma_f32_16x16x32_bf16 v[112:115], v[170:173], v[194:197], 0
	v_mfma_f32_16x16x32_bf16 v[100:103], v[162:165], v[210:213], 0
	v_mfma_f32_16x16x32_bf16 v[96:99], v[170:173], v[210:213], 0
	v_mfma_f32_16x16x32_bf16 v[84:87], v[162:165], v[220:223], 0
	v_mfma_f32_16x16x32_bf16 v[80:83], v[170:173], v[220:223], 0
	v_mfma_f32_16x16x32_bf16 v[68:71], v[162:165], v[228:231], 0
	v_mfma_f32_16x16x32_bf16 v[64:67], v[170:173], v[228:231], 0
	v_mfma_f32_16x16x32_bf16 v[116:119], v[166:169], v[206:209], v[116:119]
	v_mfma_f32_16x16x32_bf16 v[112:115], v[174:177], v[206:209], v[112:115]
	v_mfma_f32_16x16x32_bf16 v[100:103], v[166:169], v[214:217], v[100:103]
	v_mfma_f32_16x16x32_bf16 v[96:99], v[174:177], v[214:217], v[96:99]
	v_mfma_f32_16x16x32_bf16 v[84:87], v[166:169], v[224:227], v[84:87]
	v_mfma_f32_16x16x32_bf16 v[80:83], v[174:177], v[224:227], v[80:83]
	v_mfma_f32_16x16x32_bf16 v[68:71], v[166:169], v[232:235], v[68:71]
	v_mfma_f32_16x16x32_bf16 v[64:67], v[174:177], v[232:235], v[64:67]
	s_barrier
	s_add_i32 s59, s59, s36
	v_lshl_add_u64 v[178:179], s[42:43], 0, v[132:133]
	s_mov_b32 m0, s59
	ds_read_b128 v[194:197], v145 offset:16384
	ds_read_b128 v[206:209], v145 offset:17408
	ds_read_b128 v[210:213], v145 offset:18432
	ds_read_b128 v[214:217], v145 offset:19456
	ds_read_b128 v[220:223], v145 offset:20480
	ds_read_b128 v[224:227], v145 offset:21504
	ds_read_b128 v[228:231], v145 offset:22528
	ds_read_b128 v[232:235], v145 offset:23552
	global_load_lds_dwordx4 v[178:179], off
	s_add_i32 m0, s59, 0x2000
	v_lshl_add_u64 v[198:199], s[42:43], 0, v[128:129]
	s_add_u32 s42, s42, s0
	s_addc_u32 s43, s43, s1
	s_add_i32 s31, s31, s36
	global_load_lds_dwordx4 v[198:199], off
	v_lshl_add_u64 v[202:203], s[42:43], 0, v[132:133]
	s_mov_b32 m0, s31
	v_lshl_add_u64 v[236:237], s[42:43], 0, v[128:129]
	global_load_lds_dwordx4 v[202:203], off
	s_add_i32 m0, s31, 0x2000
	v_lshl_add_u64 v[238:239], s[16:17], 0, v[134:135]
	global_load_lds_dwordx4 v[236:237], off
	s_mov_b32 m0, s37
	v_lshl_add_u64 v[240:241], s[16:17], 0, v[130:131]
	global_load_lds_dwordx4 v[238:239], off
	s_mov_b32 m0, s38
	s_nop 0
	global_load_lds_dwordx4 v[240:241], off
	s_waitcnt vmcnt(8)
	s_waitcnt lgkmcnt(0)
	s_barrier
	s_waitcnt lgkmcnt(0)
	v_mfma_f32_16x16x32_bf16 v[60:63], v[146:149], v[194:197], 0
	v_mfma_f32_16x16x32_bf16 v[56:59], v[154:157], v[194:197], 0
	v_mfma_f32_16x16x32_bf16 v[44:47], v[146:149], v[210:213], 0
	v_mfma_f32_16x16x32_bf16 v[40:43], v[154:157], v[210:213], 0
	v_mfma_f32_16x16x32_bf16 v[28:31], v[146:149], v[220:223], 0
	v_mfma_f32_16x16x32_bf16 v[24:27], v[154:157], v[220:223], 0
	v_mfma_f32_16x16x32_bf16 v[12:15], v[146:149], v[228:231], 0
	v_mfma_f32_16x16x32_bf16 v[8:11], v[154:157], v[228:231], 0
	v_mfma_f32_16x16x32_bf16 v[60:63], v[150:153], v[206:209], v[60:63]
	v_mfma_f32_16x16x32_bf16 v[56:59], v[158:161], v[206:209], v[56:59]
	v_mfma_f32_16x16x32_bf16 v[44:47], v[150:153], v[214:217], v[44:47]
	v_mfma_f32_16x16x32_bf16 v[40:43], v[158:161], v[214:217], v[40:43]
	v_mfma_f32_16x16x32_bf16 v[28:31], v[150:153], v[224:227], v[28:31]
	v_mfma_f32_16x16x32_bf16 v[24:27], v[158:161], v[224:227], v[24:27]
	v_mfma_f32_16x16x32_bf16 v[12:15], v[150:153], v[232:235], v[12:15]
	v_mfma_f32_16x16x32_bf16 v[8:11], v[158:161], v[232:235], v[8:11]
	v_mfma_f32_16x16x32_bf16 v[52:55], v[162:165], v[194:197], 0
	v_mfma_f32_16x16x32_bf16 v[48:51], v[170:173], v[194:197], 0
	v_mfma_f32_16x16x32_bf16 v[36:39], v[162:165], v[210:213], 0
	v_mfma_f32_16x16x32_bf16 v[32:35], v[170:173], v[210:213], 0
	v_mfma_f32_16x16x32_bf16 v[20:23], v[162:165], v[220:223], 0
	v_mfma_f32_16x16x32_bf16 v[16:19], v[170:173], v[220:223], 0
	v_mfma_f32_16x16x32_bf16 v[4:7], v[162:165], v[228:231], 0
	v_mfma_f32_16x16x32_bf16 v[0:3], v[170:173], v[228:231], 0
	v_mfma_f32_16x16x32_bf16 v[52:55], v[166:169], v[206:209], v[52:55]
	v_mfma_f32_16x16x32_bf16 v[48:51], v[174:177], v[206:209], v[48:51]
	v_mfma_f32_16x16x32_bf16 v[36:39], v[166:169], v[214:217], v[36:39]
	v_mfma_f32_16x16x32_bf16 v[32:35], v[174:177], v[214:217], v[32:35]
	v_mfma_f32_16x16x32_bf16 v[20:23], v[166:169], v[224:227], v[20:23]
	v_mfma_f32_16x16x32_bf16 v[16:19], v[174:177], v[224:227], v[16:19]
	v_mfma_f32_16x16x32_bf16 v[4:7], v[166:169], v[232:235], v[4:7]
	v_mfma_f32_16x16x32_bf16 v[0:3], v[174:177], v[232:235], v[0:3]
	s_barrier
	s_add_i32 s31, 0, 0x18000
	v_add_u32_e32 v140, s31, v143
	s_add_i32 s42, 0, 0x1c000
	ds_read_b128 v[146:149], v140
	ds_read_b128 v[150:153], v140 offset:1024
	ds_read_b128 v[154:157], v140 offset:2048
	ds_read_b128 v[158:161], v140 offset:3072
	v_add_u32_e32 v140, s42, v143
	ds_read_b128 v[162:165], v140
	ds_read_b128 v[166:169], v140 offset:1024
	ds_read_b128 v[170:173], v140 offset:2048
	ds_read_b128 v[174:177], v140 offset:3072
	s_add_u32 s16, s16, s0
	s_addc_u32 s17, s17, s1
	s_mov_b32 m0, s39
	v_lshl_add_u64 v[242:243], s[16:17], 0, v[134:135]
	ds_read_b128 v[194:197], v145 offset:32768
	ds_read_b128 v[206:209], v145 offset:33792
	ds_read_b128 v[210:213], v145 offset:34816
	ds_read_b128 v[214:217], v145 offset:35840
	ds_read_b128 v[220:223], v145 offset:36864
	ds_read_b128 v[224:227], v145 offset:37888
	ds_read_b128 v[228:231], v145 offset:38912
	ds_read_b128 v[232:235], v145 offset:39936
	global_load_lds_dwordx4 v[242:243], off
	v_lshl_add_u64 v[242:243], s[16:17], 0, v[130:131]
	s_mov_b32 m0, s44
	s_nop 0
	global_load_lds_dwordx4 v[242:243], off
	s_waitcnt vmcnt(8)
	s_waitcnt lgkmcnt(0)
	s_barrier
	s_waitcnt lgkmcnt(0)
	v_mfma_f32_16x16x32_bf16 v[124:127], v[146:149], v[194:197], v[124:127]
	v_mfma_f32_16x16x32_bf16 v[120:123], v[154:157], v[194:197], v[120:123]
	v_mfma_f32_16x16x32_bf16 v[108:111], v[146:149], v[210:213], v[108:111]
	v_mfma_f32_16x16x32_bf16 v[104:107], v[154:157], v[210:213], v[104:107]
	v_mfma_f32_16x16x32_bf16 v[92:95], v[146:149], v[220:223], v[92:95]
	v_mfma_f32_16x16x32_bf16 v[88:91], v[154:157], v[220:223], v[88:91]
	v_mfma_f32_16x16x32_bf16 v[76:79], v[146:149], v[228:231], v[76:79]
	v_mfma_f32_16x16x32_bf16 v[72:75], v[154:157], v[228:231], v[72:75]
	v_mfma_f32_16x16x32_bf16 v[124:127], v[150:153], v[206:209], v[124:127]
	v_mfma_f32_16x16x32_bf16 v[120:123], v[158:161], v[206:209], v[120:123]
	v_mfma_f32_16x16x32_bf16 v[108:111], v[150:153], v[214:217], v[108:111]
	v_mfma_f32_16x16x32_bf16 v[104:107], v[158:161], v[214:217], v[104:107]
	v_mfma_f32_16x16x32_bf16 v[92:95], v[150:153], v[224:227], v[92:95]
	v_mfma_f32_16x16x32_bf16 v[88:91], v[158:161], v[224:227], v[88:91]
	v_mfma_f32_16x16x32_bf16 v[76:79], v[150:153], v[232:235], v[76:79]
	v_mfma_f32_16x16x32_bf16 v[72:75], v[158:161], v[232:235], v[72:75]
	v_mfma_f32_16x16x32_bf16 v[116:119], v[162:165], v[194:197], v[116:119]
	v_mfma_f32_16x16x32_bf16 v[112:115], v[170:173], v[194:197], v[112:115]
	v_mfma_f32_16x16x32_bf16 v[100:103], v[162:165], v[210:213], v[100:103]
	v_mfma_f32_16x16x32_bf16 v[96:99], v[170:173], v[210:213], v[96:99]
	v_mfma_f32_16x16x32_bf16 v[84:87], v[162:165], v[220:223], v[84:87]
	v_mfma_f32_16x16x32_bf16 v[80:83], v[170:173], v[220:223], v[80:83]
	v_mfma_f32_16x16x32_bf16 v[68:71], v[162:165], v[228:231], v[68:71]
	v_mfma_f32_16x16x32_bf16 v[64:67], v[170:173], v[228:231], v[64:67]
	v_mfma_f32_16x16x32_bf16 v[116:119], v[166:169], v[206:209], v[116:119]
	v_mfma_f32_16x16x32_bf16 v[112:115], v[174:177], v[206:209], v[112:115]
	v_mfma_f32_16x16x32_bf16 v[100:103], v[166:169], v[214:217], v[100:103]
	v_mfma_f32_16x16x32_bf16 v[96:99], v[174:177], v[214:217], v[96:99]
	v_mfma_f32_16x16x32_bf16 v[84:87], v[166:169], v[224:227], v[84:87]
	v_mfma_f32_16x16x32_bf16 v[80:83], v[174:177], v[224:227], v[80:83]
	v_mfma_f32_16x16x32_bf16 v[68:71], v[166:169], v[232:235], v[68:71]
	v_mfma_f32_16x16x32_bf16 v[64:67], v[174:177], v[232:235], v[64:67]
	s_barrier
	s_add_i32 s16, s31, s36
	v_lshl_add_u64 v[178:179], v[178:179], 0, s[12:13]
	s_mov_b32 m0, s16
	ds_read_b128 v[194:197], v145 offset:49152
	ds_read_b128 v[206:209], v145 offset:50176
	ds_read_b128 v[210:213], v145 offset:51200
	ds_read_b128 v[214:217], v145 offset:52224
	ds_read_b128 v[220:223], v145 offset:53248
	ds_read_b128 v[224:227], v145 offset:54272
	ds_read_b128 v[228:231], v145 offset:55296
	ds_read_b128 v[232:235], v145 offset:56320
	global_load_lds_dwordx4 v[178:179], off
	v_lshl_add_u64 v[178:179], v[198:199], 0, s[12:13]
	s_add_i32 m0, s16, 0x2000
	s_add_i32 s16, s42, s36
	global_load_lds_dwordx4 v[178:179], off
	v_lshl_add_u64 v[178:179], v[202:203], 0, s[12:13]
	s_mov_b32 m0, s16
	s_nop 0
	global_load_lds_dwordx4 v[178:179], off
	v_lshl_add_u64 v[178:179], v[236:237], 0, s[12:13]
	s_add_i32 m0, s16, 0x2000
	s_nop 0
	global_load_lds_dwordx4 v[178:179], off
	v_lshl_add_u64 v[178:179], v[238:239], 0, s[12:13]
	s_mov_b32 m0, s45
	s_nop 0
	global_load_lds_dwordx4 v[178:179], off
	v_lshl_add_u64 v[178:179], v[240:241], 0, s[12:13]
	s_mov_b32 m0, s46
	s_nop 0
	global_load_lds_dwordx4 v[178:179], off
	s_waitcnt vmcnt(8)
	s_waitcnt lgkmcnt(0)
	s_barrier
	s_waitcnt lgkmcnt(0)
	v_mfma_f32_16x16x32_bf16 v[60:63], v[146:149], v[194:197], v[60:63]
	s_add_u32 s28, s28, 0x100
	v_mfma_f32_16x16x32_bf16 v[56:59], v[154:157], v[194:197], v[56:59]
	s_addc_u32 s29, s29, 0
	v_mfma_f32_16x16x32_bf16 v[44:47], v[146:149], v[210:213], v[44:47]
	s_add_u32 s10, s10, 0x100
	v_mfma_f32_16x16x32_bf16 v[40:43], v[154:157], v[210:213], v[40:43]
	s_addc_u32 s11, s11, 0
	v_mfma_f32_16x16x32_bf16 v[28:31], v[146:149], v[220:223], v[28:31]
	s_mov_b32 s16, s30
	v_mfma_f32_16x16x32_bf16 v[24:27], v[154:157], v[220:223], v[24:27]
	s_cmp_ge_i32 s30, s47
	v_mfma_f32_16x16x32_bf16 v[12:15], v[146:149], v[228:231], v[12:15]
	s_cselect_b32 s99, 1, 0
	v_mfma_f32_16x16x32_bf16 v[8:11], v[154:157], v[228:231], v[8:11]
	s_add_i32 s30, s16, 2
	v_mfma_f32_16x16x32_bf16 v[60:63], v[150:153], v[206:209], v[60:63]
	s_add_u32 s31, s28, 0x80
	v_mfma_f32_16x16x32_bf16 v[56:59], v[158:161], v[206:209], v[56:59]
	s_addc_u32 s17, s29, 0
	v_mfma_f32_16x16x32_bf16 v[44:47], v[150:153], v[214:217], v[44:47]
	s_add_i32 s59, 0, 0x10000
	v_mfma_f32_16x16x32_bf16 v[40:43], v[158:161], v[214:217], v[40:43]
	s_cmp_eq_u32 s48, s16
	v_mfma_f32_16x16x32_bf16 v[28:31], v[150:153], v[224:227], v[28:31]
	s_cselect_b32 s17, s25, s17
	v_mfma_f32_16x16x32_bf16 v[24:27], v[158:161], v[224:227], v[24:27]
	s_cselect_b32 s16, s24, s31
	v_mfma_f32_16x16x32_bf16 v[12:15], v[150:153], v[232:235], v[12:15]
	s_cselect_b32 s43, s27, s11
	v_mfma_f32_16x16x32_bf16 v[8:11], v[158:161], v[232:235], v[8:11]
	s_cselect_b32 s42, s26, s10
	v_mfma_f32_16x16x32_bf16 v[52:55], v[162:165], v[194:197], v[52:55]
	s_add_i32 s31, 0, 0x14000
	v_mfma_f32_16x16x32_bf16 v[48:51], v[170:173], v[194:197], v[48:51]
	v_mfma_f32_16x16x32_bf16 v[36:39], v[162:165], v[210:213], v[36:39]
	v_mfma_f32_16x16x32_bf16 v[32:35], v[170:173], v[210:213], v[32:35]
	v_mfma_f32_16x16x32_bf16 v[20:23], v[162:165], v[220:223], v[20:23]
	v_mfma_f32_16x16x32_bf16 v[16:19], v[170:173], v[220:223], v[16:19]
	v_mfma_f32_16x16x32_bf16 v[4:7], v[162:165], v[228:231], v[4:7]
	v_mfma_f32_16x16x32_bf16 v[0:3], v[170:173], v[228:231], v[0:3]
	v_mfma_f32_16x16x32_bf16 v[52:55], v[166:169], v[206:209], v[52:55]
	v_mfma_f32_16x16x32_bf16 v[48:51], v[174:177], v[206:209], v[48:51]
	v_mfma_f32_16x16x32_bf16 v[36:39], v[166:169], v[214:217], v[36:39]
	v_mfma_f32_16x16x32_bf16 v[32:35], v[174:177], v[214:217], v[32:35]
	v_mfma_f32_16x16x32_bf16 v[20:23], v[166:169], v[224:227], v[20:23]
	v_mfma_f32_16x16x32_bf16 v[16:19], v[174:177], v[224:227], v[16:19]
	v_mfma_f32_16x16x32_bf16 v[4:7], v[166:169], v[232:235], v[4:7]
	v_mfma_f32_16x16x32_bf16 v[0:3], v[174:177], v[232:235], v[0:3]
	s_barrier
	s_cmp_lg_u32 s99, 0
	s_cbranch_scc1 .Lpeelx_10
.LBB0_798:
	v_add_u32_e32 v140, s59, v143
	ds_read_b128 v[146:149], v140
	ds_read_b128 v[150:153], v140 offset:1024
	ds_read_b128 v[154:157], v140 offset:2048
	ds_read_b128 v[158:161], v140 offset:3072
	v_add_u32_e32 v140, s31, v143
	ds_read_b128 v[162:165], v140
	ds_read_b128 v[166:169], v140 offset:1024
	ds_read_b128 v[170:173], v140 offset:2048
	ds_read_b128 v[174:177], v140 offset:3072
	v_lshl_add_u64 v[178:179], s[28:29], 0, v[136:137]
	s_add_i32 m0, s37, 0xc000
	ds_read_b128 v[194:197], v145
	ds_read_b128 v[206:209], v145 offset:1024
	ds_read_b128 v[210:213], v145 offset:2048
	ds_read_b128 v[214:217], v145 offset:3072
	ds_read_b128 v[220:223], v145 offset:4096
	ds_read_b128 v[224:227], v145 offset:5120
	ds_read_b128 v[228:231], v145 offset:6144
	ds_read_b128 v[232:235], v145 offset:7168
	global_load_lds_dwordx4 v[178:179], off
	v_lshl_add_u64 v[178:179], s[28:29], 0, v[138:139]
	s_add_i32 m0, s37, 0xe000
	s_nop 0
	global_load_lds_dwordx4 v[178:179], off
	s_waitcnt vmcnt(8)
	s_waitcnt lgkmcnt(0)
	s_barrier
	s_waitcnt lgkmcnt(0)
	v_mfma_f32_16x16x32_bf16 v[124:127], v[146:149], v[194:197], v[124:127]
	v_mfma_f32_16x16x32_bf16 v[120:123], v[154:157], v[194:197], v[120:123]
	v_mfma_f32_16x16x32_bf16 v[108:111], v[146:149], v[210:213], v[108:111]
	v_mfma_f32_16x16x32_bf16 v[104:107], v[154:157], v[210:213], v[104:107]
	v_mfma_f32_16x16x32_bf16 v[92:95], v[146:149], v[220:223], v[92:95]
	v_mfma_f32_16x16x32_bf16 v[88:91], v[154:157], v[220:223], v[88:91]
	v_mfma_f32_16x16x32_bf16 v[76:79], v[146:149], v[228:231], v[76:79]
	v_mfma_f32_16x16x32_bf16 v[72:75], v[154:157], v[228:231], v[72:75]
	v_mfma_f32_16x16x32_bf16 v[124:127], v[150:153], v[206:209], v[124:127]
	v_mfma_f32_16x16x32_bf16 v[120:123], v[158:161], v[206:209], v[120:123]
	v_mfma_f32_16x16x32_bf16 v[108:111], v[150:153], v[214:217], v[108:111]
	v_mfma_f32_16x16x32_bf16 v[104:107], v[158:161], v[214:217], v[104:107]
	v_mfma_f32_16x16x32_bf16 v[92:95], v[150:153], v[224:227], v[92:95]
	v_mfma_f32_16x16x32_bf16 v[88:91], v[158:161], v[224:227], v[88:91]
	v_mfma_f32_16x16x32_bf16 v[76:79], v[150:153], v[232:235], v[76:79]
	v_mfma_f32_16x16x32_bf16 v[72:75], v[158:161], v[232:235], v[72:75]
	v_mfma_f32_16x16x32_bf16 v[116:119], v[162:165], v[194:197], v[116:119]
	v_mfma_f32_16x16x32_bf16 v[112:115], v[170:173], v[194:197], v[112:115]
	v_mfma_f32_16x16x32_bf16 v[100:103], v[162:165], v[210:213], v[100:103]
	v_mfma_f32_16x16x32_bf16 v[96:99], v[170:173], v[210:213], v[96:99]
	v_mfma_f32_16x16x32_bf16 v[84:87], v[162:165], v[220:223], v[84:87]
	v_mfma_f32_16x16x32_bf16 v[80:83], v[170:173], v[220:223], v[80:83]
	v_mfma_f32_16x16x32_bf16 v[68:71], v[162:165], v[228:231], v[68:71]
	v_mfma_f32_16x16x32_bf16 v[64:67], v[170:173], v[228:231], v[64:67]
	v_mfma_f32_16x16x32_bf16 v[116:119], v[166:169], v[206:209], v[116:119]
	v_mfma_f32_16x16x32_bf16 v[112:115], v[174:177], v[206:209], v[112:115]
	v_mfma_f32_16x16x32_bf16 v[100:103], v[166:169], v[214:217], v[100:103]
	v_mfma_f32_16x16x32_bf16 v[96:99], v[174:177], v[214:217], v[96:99]
	v_mfma_f32_16x16x32_bf16 v[84:87], v[166:169], v[224:227], v[84:87]
	v_mfma_f32_16x16x32_bf16 v[80:83], v[174:177], v[224:227], v[80:83]
	v_mfma_f32_16x16x32_bf16 v[68:71], v[166:169], v[232:235], v[68:71]
	v_mfma_f32_16x16x32_bf16 v[64:67], v[174:177], v[232:235], v[64:67]
	s_barrier
	s_add_i32 s59, s59, s36
	v_lshl_add_u64 v[178:179], s[42:43], 0, v[132:133]
	s_mov_b32 m0, s59
	ds_read_b128 v[194:197], v145 offset:16384
	ds_read_b128 v[206:209], v145 offset:17408
	ds_read_b128 v[210:213], v145 offset:18432
	ds_read_b128 v[214:217], v145 offset:19456
	ds_read_b128 v[220:223], v145 offset:20480
	ds_read_b128 v[224:227], v145 offset:21504
	ds_read_b128 v[228:231], v145 offset:22528
	ds_read_b128 v[232:235], v145 offset:23552
	global_load_lds_dwordx4 v[178:179], off
	s_add_i32 m0, s59, 0x2000
	v_lshl_add_u64 v[198:199], s[42:43], 0, v[128:129]
	s_add_u32 s42, s42, s0
	s_addc_u32 s43, s43, s1
	s_add_i32 s31, s31, s36
	global_load_lds_dwordx4 v[198:199], off
	v_lshl_add_u64 v[202:203], s[42:43], 0, v[132:133]
	s_mov_b32 m0, s31
	v_lshl_add_u64 v[236:237], s[42:43], 0, v[128:129]
	global_load_lds_dwordx4 v[202:203], off
	s_add_i32 m0, s31, 0x2000
	v_lshl_add_u64 v[238:239], s[16:17], 0, v[134:135]
	global_load_lds_dwordx4 v[236:237], off
	s_mov_b32 m0, s37
	v_lshl_add_u64 v[240:241], s[16:17], 0, v[130:131]
	global_load_lds_dwordx4 v[238:239], off
	s_mov_b32 m0, s38
	s_nop 0
	global_load_lds_dwordx4 v[240:241], off
	s_waitcnt vmcnt(8)
	s_waitcnt lgkmcnt(0)
	s_barrier
	s_waitcnt lgkmcnt(0)
	v_mfma_f32_16x16x32_bf16 v[60:63], v[146:149], v[194:197], v[60:63]
	v_mfma_f32_16x16x32_bf16 v[56:59], v[154:157], v[194:197], v[56:59]
	v_mfma_f32_16x16x32_bf16 v[44:47], v[146:149], v[210:213], v[44:47]
	v_mfma_f32_16x16x32_bf16 v[40:43], v[154:157], v[210:213], v[40:43]
	v_mfma_f32_16x16x32_bf16 v[28:31], v[146:149], v[220:223], v[28:31]
	v_mfma_f32_16x16x32_bf16 v[24:27], v[154:157], v[220:223], v[24:27]
	v_mfma_f32_16x16x32_bf16 v[12:15], v[146:149], v[228:231], v[12:15]
	v_mfma_f32_16x16x32_bf16 v[8:11], v[154:157], v[228:231], v[8:11]
	v_mfma_f32_16x16x32_bf16 v[60:63], v[150:153], v[206:209], v[60:63]
	v_mfma_f32_16x16x32_bf16 v[56:59], v[158:161], v[206:209], v[56:59]
	v_mfma_f32_16x16x32_bf16 v[44:47], v[150:153], v[214:217], v[44:47]
	v_mfma_f32_16x16x32_bf16 v[40:43], v[158:161], v[214:217], v[40:43]
	v_mfma_f32_16x16x32_bf16 v[28:31], v[150:153], v[224:227], v[28:31]
	v_mfma_f32_16x16x32_bf16 v[24:27], v[158:161], v[224:227], v[24:27]
	v_mfma_f32_16x16x32_bf16 v[12:15], v[150:153], v[232:235], v[12:15]
	v_mfma_f32_16x16x32_bf16 v[8:11], v[158:161], v[232:235], v[8:11]
	v_mfma_f32_16x16x32_bf16 v[52:55], v[162:165], v[194:197], v[52:55]
	v_mfma_f32_16x16x32_bf16 v[48:51], v[170:173], v[194:197], v[48:51]
	v_mfma_f32_16x16x32_bf16 v[36:39], v[162:165], v[210:213], v[36:39]
	v_mfma_f32_16x16x32_bf16 v[32:35], v[170:173], v[210:213], v[32:35]
	v_mfma_f32_16x16x32_bf16 v[20:23], v[162:165], v[220:223], v[20:23]
	v_mfma_f32_16x16x32_bf16 v[16:19], v[170:173], v[220:223], v[16:19]
	v_mfma_f32_16x16x32_bf16 v[4:7], v[162:165], v[228:231], v[4:7]
	v_mfma_f32_16x16x32_bf16 v[0:3], v[170:173], v[228:231], v[0:3]
	v_mfma_f32_16x16x32_bf16 v[52:55], v[166:169], v[206:209], v[52:55]
	v_mfma_f32_16x16x32_bf16 v[48:51], v[174:177], v[206:209], v[48:51]
	v_mfma_f32_16x16x32_bf16 v[36:39], v[166:169], v[214:217], v[36:39]
	v_mfma_f32_16x16x32_bf16 v[32:35], v[174:177], v[214:217], v[32:35]
	v_mfma_f32_16x16x32_bf16 v[20:23], v[166:169], v[224:227], v[20:23]
	v_mfma_f32_16x16x32_bf16 v[16:19], v[174:177], v[224:227], v[16:19]
	v_mfma_f32_16x16x32_bf16 v[4:7], v[166:169], v[232:235], v[4:7]
	v_mfma_f32_16x16x32_bf16 v[0:3], v[174:177], v[232:235], v[0:3]
	s_barrier
	s_add_i32 s31, 0, 0x18000
	v_add_u32_e32 v140, s31, v143
	s_add_i32 s42, 0, 0x1c000
	ds_read_b128 v[146:149], v140
	ds_read_b128 v[150:153], v140 offset:1024
	ds_read_b128 v[154:157], v140 offset:2048
	ds_read_b128 v[158:161], v140 offset:3072
	v_add_u32_e32 v140, s42, v143
	ds_read_b128 v[162:165], v140
	ds_read_b128 v[166:169], v140 offset:1024
	ds_read_b128 v[170:173], v140 offset:2048
	ds_read_b128 v[174:177], v140 offset:3072
	s_add_u32 s16, s16, s0
	s_addc_u32 s17, s17, s1
	s_mov_b32 m0, s39
	v_lshl_add_u64 v[242:243], s[16:17], 0, v[134:135]
	ds_read_b128 v[194:197], v145 offset:32768
	ds_read_b128 v[206:209], v145 offset:33792
	ds_read_b128 v[210:213], v145 offset:34816
	ds_read_b128 v[214:217], v145 offset:35840
	ds_read_b128 v[220:223], v145 offset:36864
	ds_read_b128 v[224:227], v145 offset:37888
	ds_read_b128 v[228:231], v145 offset:38912
	ds_read_b128 v[232:235], v145 offset:39936
	global_load_lds_dwordx4 v[242:243], off
	v_lshl_add_u64 v[242:243], s[16:17], 0, v[130:131]
	s_mov_b32 m0, s44
	s_nop 0
	global_load_lds_dwordx4 v[242:243], off
	s_waitcnt vmcnt(8)
	s_waitcnt lgkmcnt(0)
	s_barrier
	s_waitcnt lgkmcnt(0)
	v_mfma_f32_16x16x32_bf16 v[124:127], v[146:149], v[194:197], v[124:127]
	v_mfma_f32_16x16x32_bf16 v[120:123], v[154:157], v[194:197], v[120:123]
	v_mfma_f32_16x16x32_bf16 v[108:111], v[146:149], v[210:213], v[108:111]
	v_mfma_f32_16x16x32_bf16 v[104:107], v[154:157], v[210:213], v[104:107]
	v_mfma_f32_16x16x32_bf16 v[92:95], v[146:149], v[220:223], v[92:95]
	v_mfma_f32_16x16x32_bf16 v[88:91], v[154:157], v[220:223], v[88:91]
	v_mfma_f32_16x16x32_bf16 v[76:79], v[146:149], v[228:231], v[76:79]
	v_mfma_f32_16x16x32_bf16 v[72:75], v[154:157], v[228:231], v[72:75]
	v_mfma_f32_16x16x32_bf16 v[124:127], v[150:153], v[206:209], v[124:127]
	v_mfma_f32_16x16x32_bf16 v[120:123], v[158:161], v[206:209], v[120:123]
	v_mfma_f32_16x16x32_bf16 v[108:111], v[150:153], v[214:217], v[108:111]
	v_mfma_f32_16x16x32_bf16 v[104:107], v[158:161], v[214:217], v[104:107]
	v_mfma_f32_16x16x32_bf16 v[92:95], v[150:153], v[224:227], v[92:95]
	v_mfma_f32_16x16x32_bf16 v[88:91], v[158:161], v[224:227], v[88:91]
	v_mfma_f32_16x16x32_bf16 v[76:79], v[150:153], v[232:235], v[76:79]
	v_mfma_f32_16x16x32_bf16 v[72:75], v[158:161], v[232:235], v[72:75]
	v_mfma_f32_16x16x32_bf16 v[116:119], v[162:165], v[194:197], v[116:119]
	v_mfma_f32_16x16x32_bf16 v[112:115], v[170:173], v[194:197], v[112:115]
	v_mfma_f32_16x16x32_bf16 v[100:103], v[162:165], v[210:213], v[100:103]
	v_mfma_f32_16x16x32_bf16 v[96:99], v[170:173], v[210:213], v[96:99]
	v_mfma_f32_16x16x32_bf16 v[84:87], v[162:165], v[220:223], v[84:87]
	v_mfma_f32_16x16x32_bf16 v[80:83], v[170:173], v[220:223], v[80:83]
	v_mfma_f32_16x16x32_bf16 v[68:71], v[162:165], v[228:231], v[68:71]
	v_mfma_f32_16x16x32_bf16 v[64:67], v[170:173], v[228:231], v[64:67]
	v_mfma_f32_16x16x32_bf16 v[116:119], v[166:169], v[206:209], v[116:119]
	v_mfma_f32_16x16x32_bf16 v[112:115], v[174:177], v[206:209], v[112:115]
	v_mfma_f32_16x16x32_bf16 v[100:103], v[166:169], v[214:217], v[100:103]
	v_mfma_f32_16x16x32_bf16 v[96:99], v[174:177], v[214:217], v[96:99]
	v_mfma_f32_16x16x32_bf16 v[84:87], v[166:169], v[224:227], v[84:87]
	v_mfma_f32_16x16x32_bf16 v[80:83], v[174:177], v[224:227], v[80:83]
	v_mfma_f32_16x16x32_bf16 v[68:71], v[166:169], v[232:235], v[68:71]
	v_mfma_f32_16x16x32_bf16 v[64:67], v[174:177], v[232:235], v[64:67]
	s_barrier
	s_add_i32 s16, s31, s36
	v_lshl_add_u64 v[178:179], v[178:179], 0, s[12:13]
	s_mov_b32 m0, s16
	ds_read_b128 v[194:197], v145 offset:49152
	ds_read_b128 v[206:209], v145 offset:50176
	ds_read_b128 v[210:213], v145 offset:51200
	ds_read_b128 v[214:217], v145 offset:52224
	ds_read_b128 v[220:223], v145 offset:53248
	ds_read_b128 v[224:227], v145 offset:54272
	ds_read_b128 v[228:231], v145 offset:55296
	ds_read_b128 v[232:235], v145 offset:56320
	global_load_lds_dwordx4 v[178:179], off
	v_lshl_add_u64 v[178:179], v[198:199], 0, s[12:13]
	s_add_i32 m0, s16, 0x2000
	s_add_i32 s16, s42, s36
	global_load_lds_dwordx4 v[178:179], off
	v_lshl_add_u64 v[178:179], v[202:203], 0, s[12:13]
	s_mov_b32 m0, s16
	s_nop 0
	global_load_lds_dwordx4 v[178:179], off
	v_lshl_add_u64 v[178:179], v[236:237], 0, s[12:13]
	s_add_i32 m0, s16, 0x2000
	s_nop 0
	global_load_lds_dwordx4 v[178:179], off
	v_lshl_add_u64 v[178:179], v[238:239], 0, s[12:13]
	s_mov_b32 m0, s45
	s_nop 0
	global_load_lds_dwordx4 v[178:179], off
	v_lshl_add_u64 v[178:179], v[240:241], 0, s[12:13]
	s_mov_b32 m0, s46
	s_nop 0
	global_load_lds_dwordx4 v[178:179], off
	s_waitcnt vmcnt(8)
	s_waitcnt lgkmcnt(0)
	s_barrier
	s_waitcnt lgkmcnt(0)
	v_mfma_f32_16x16x32_bf16 v[60:63], v[146:149], v[194:197], v[60:63]
	s_add_u32 s28, s28, 0x100
	v_mfma_f32_16x16x32_bf16 v[56:59], v[154:157], v[194:197], v[56:59]
	s_addc_u32 s29, s29, 0
	v_mfma_f32_16x16x32_bf16 v[44:47], v[146:149], v[210:213], v[44:47]
	s_add_u32 s10, s10, 0x100
	v_mfma_f32_16x16x32_bf16 v[40:43], v[154:157], v[210:213], v[40:43]
	s_addc_u32 s11, s11, 0
	v_mfma_f32_16x16x32_bf16 v[28:31], v[146:149], v[220:223], v[28:31]
	s_mov_b32 s16, s30
	v_mfma_f32_16x16x32_bf16 v[24:27], v[154:157], v[220:223], v[24:27]
	s_cmp_ge_i32 s30, s47
	v_mfma_f32_16x16x32_bf16 v[12:15], v[146:149], v[228:231], v[12:15]
	s_cselect_b32 s99, 1, 0
	v_mfma_f32_16x16x32_bf16 v[8:11], v[154:157], v[228:231], v[8:11]
	s_add_i32 s30, s16, 2
	v_mfma_f32_16x16x32_bf16 v[60:63], v[150:153], v[206:209], v[60:63]
	s_add_u32 s31, s28, 0x80
	v_mfma_f32_16x16x32_bf16 v[56:59], v[158:161], v[206:209], v[56:59]
	s_addc_u32 s17, s29, 0
	v_mfma_f32_16x16x32_bf16 v[44:47], v[150:153], v[214:217], v[44:47]
	s_add_i32 s59, 0, 0x10000
	v_mfma_f32_16x16x32_bf16 v[40:43], v[158:161], v[214:217], v[40:43]
	s_cmp_eq_u32 s48, s16
	v_mfma_f32_16x16x32_bf16 v[28:31], v[150:153], v[224:227], v[28:31]
	s_cselect_b32 s17, s25, s17
	v_mfma_f32_16x16x32_bf16 v[24:27], v[158:161], v[224:227], v[24:27]
	s_cselect_b32 s16, s24, s31
	v_mfma_f32_16x16x32_bf16 v[12:15], v[150:153], v[232:235], v[12:15]
	s_cselect_b32 s43, s27, s11
	v_mfma_f32_16x16x32_bf16 v[8:11], v[158:161], v[232:235], v[8:11]
	s_cselect_b32 s42, s26, s10
	v_mfma_f32_16x16x32_bf16 v[52:55], v[162:165], v[194:197], v[52:55]
	s_add_i32 s31, 0, 0x14000
	v_mfma_f32_16x16x32_bf16 v[48:51], v[170:173], v[194:197], v[48:51]
	v_mfma_f32_16x16x32_bf16 v[36:39], v[162:165], v[210:213], v[36:39]
	v_mfma_f32_16x16x32_bf16 v[32:35], v[170:173], v[210:213], v[32:35]
	v_mfma_f32_16x16x32_bf16 v[20:23], v[162:165], v[220:223], v[20:23]
	v_mfma_f32_16x16x32_bf16 v[16:19], v[170:173], v[220:223], v[16:19]
	v_mfma_f32_16x16x32_bf16 v[4:7], v[162:165], v[228:231], v[4:7]
	v_mfma_f32_16x16x32_bf16 v[0:3], v[170:173], v[228:231], v[0:3]
	v_mfma_f32_16x16x32_bf16 v[52:55], v[166:169], v[206:209], v[52:55]
	v_mfma_f32_16x16x32_bf16 v[48:51], v[174:177], v[206:209], v[48:51]
	v_mfma_f32_16x16x32_bf16 v[36:39], v[166:169], v[214:217], v[36:39]
	v_mfma_f32_16x16x32_bf16 v[32:35], v[174:177], v[214:217], v[32:35]
	v_mfma_f32_16x16x32_bf16 v[20:23], v[166:169], v[224:227], v[20:23]
	v_mfma_f32_16x16x32_bf16 v[16:19], v[174:177], v[224:227], v[16:19]
	v_mfma_f32_16x16x32_bf16 v[4:7], v[166:169], v[232:235], v[4:7]
	v_mfma_f32_16x16x32_bf16 v[0:3], v[174:177], v[232:235], v[0:3]
	s_barrier
	s_cmp_lg_u32 s99, 0
	s_cbranch_scc0 .LBB0_798

.Llbb_7:
	s_add_i32 s28, s16, 2
	s_add_u32 s29, s26, 0x80
	s_addc_u32 s17, s27, 0
	s_add_i32 s59, 0, 0x10000
	s_cmp_eq_u32 s48, s16
	s_cselect_b32 s17, s23, s17
	s_cselect_b32 s16, s22, s29
	v_add_u32_e32 v140, s59, v143
	s_cselect_b32 s43, s25, s11
	s_cselect_b32 s42, s24, s10
	s_add_i32 s29, 0, 0x14000
	ds_read_b128 v[146:149], v140
	ds_read_b128 v[150:153], v140 offset:1024
	ds_read_b128 v[154:157], v140 offset:2048
	ds_read_b128 v[158:161], v140 offset:3072
	v_add_u32_e32 v140, s29, v143
	ds_read_b128 v[162:165], v140
	ds_read_b128 v[166:169], v140 offset:1024
	ds_read_b128 v[170:173], v140 offset:2048
	ds_read_b128 v[174:177], v140 offset:3072
	v_lshl_add_u64 v[140:141], s[26:27], 0, v[136:137]
	s_add_i32 m0, s35, 0xc000
	ds_read_b128 v[194:197], v145
	ds_read_b128 v[206:209], v145 offset:1024
	ds_read_b128 v[210:213], v145 offset:2048
	ds_read_b128 v[214:217], v145 offset:3072
	ds_read_b128 v[220:223], v145 offset:4096
	ds_read_b128 v[224:227], v145 offset:5120
	ds_read_b128 v[228:231], v145 offset:6144
	ds_read_b128 v[232:235], v145 offset:7168
	global_load_lds_dwordx4 v[140:141], off
	v_lshl_add_u64 v[140:141], s[26:27], 0, v[138:139]
	s_add_i32 m0, s35, 0xe000
	s_nop 0
	global_load_lds_dwordx4 v[140:141], off
	s_waitcnt vmcnt(8)
	s_waitcnt lgkmcnt(0)
	s_barrier
	s_waitcnt lgkmcnt(0)
	v_mfma_f32_16x16x32_bf16 v[120:123], v[146:149], v[194:197], 0
	v_mfma_f32_16x16x32_bf16 v[124:127], v[154:157], v[194:197], 0
	v_mfma_f32_16x16x32_bf16 v[116:119], v[146:149], v[210:213], 0
	v_mfma_f32_16x16x32_bf16 v[112:115], v[154:157], v[210:213], 0
	v_mfma_f32_16x16x32_bf16 v[108:111], v[146:149], v[220:223], 0
	v_mfma_f32_16x16x32_bf16 v[104:107], v[154:157], v[220:223], 0
	v_mfma_f32_16x16x32_bf16 v[100:103], v[146:149], v[228:231], 0
	v_mfma_f32_16x16x32_bf16 v[96:99], v[154:157], v[228:231], 0
	v_mfma_f32_16x16x32_bf16 v[120:123], v[150:153], v[206:209], v[120:123]
	v_mfma_f32_16x16x32_bf16 v[124:127], v[158:161], v[206:209], v[124:127]
	v_mfma_f32_16x16x32_bf16 v[116:119], v[150:153], v[214:217], v[116:119]
	v_mfma_f32_16x16x32_bf16 v[112:115], v[158:161], v[214:217], v[112:115]
	v_mfma_f32_16x16x32_bf16 v[108:111], v[150:153], v[224:227], v[108:111]
	v_mfma_f32_16x16x32_bf16 v[104:107], v[158:161], v[224:227], v[104:107]
	v_mfma_f32_16x16x32_bf16 v[100:103], v[150:153], v[232:235], v[100:103]
	v_mfma_f32_16x16x32_bf16 v[96:99], v[158:161], v[232:235], v[96:99]
	v_mfma_f32_16x16x32_bf16 v[60:63], v[162:165], v[194:197], 0
	v_mfma_f32_16x16x32_bf16 v[56:59], v[170:173], v[194:197], 0
	v_mfma_f32_16x16x32_bf16 v[52:55], v[162:165], v[210:213], 0
	v_mfma_f32_16x16x32_bf16 v[48:51], v[170:173], v[210:213], 0
	v_mfma_f32_16x16x32_bf16 v[44:47], v[162:165], v[220:223], 0
	v_mfma_f32_16x16x32_bf16 v[40:43], v[170:173], v[220:223], 0
	v_mfma_f32_16x16x32_bf16 v[36:39], v[162:165], v[228:231], 0
	v_mfma_f32_16x16x32_bf16 v[32:35], v[170:173], v[228:231], 0
	v_mfma_f32_16x16x32_bf16 v[60:63], v[166:169], v[206:209], v[60:63]
	v_mfma_f32_16x16x32_bf16 v[56:59], v[174:177], v[206:209], v[56:59]
	v_mfma_f32_16x16x32_bf16 v[52:55], v[166:169], v[214:217], v[52:55]
	v_mfma_f32_16x16x32_bf16 v[48:51], v[174:177], v[214:217], v[48:51]
	v_mfma_f32_16x16x32_bf16 v[44:47], v[166:169], v[224:227], v[44:47]
	v_mfma_f32_16x16x32_bf16 v[40:43], v[174:177], v[224:227], v[40:43]
	v_mfma_f32_16x16x32_bf16 v[36:39], v[166:169], v[232:235], v[36:39]
	v_mfma_f32_16x16x32_bf16 v[32:35], v[174:177], v[232:235], v[32:35]
	s_barrier
	s_add_i32 s59, s59, s34
	v_lshl_add_u64 v[140:141], s[42:43], 0, v[132:133]
	s_mov_b32 m0, s59
	ds_read_b128 v[194:197], v145 offset:16384
	ds_read_b128 v[206:209], v145 offset:17408
	ds_read_b128 v[210:213], v145 offset:18432
	ds_read_b128 v[214:217], v145 offset:19456
	ds_read_b128 v[220:223], v145 offset:20480
	ds_read_b128 v[224:227], v145 offset:21504
	ds_read_b128 v[228:231], v145 offset:22528
	ds_read_b128 v[232:235], v145 offset:23552
	global_load_lds_dwordx4 v[140:141], off
	s_add_i32 m0, s59, 0x2000
	v_lshl_add_u64 v[178:179], s[42:43], 0, v[128:129]
	s_add_u32 s42, s42, s0
	s_addc_u32 s43, s43, s1
	s_add_i32 s29, s29, s34
	global_load_lds_dwordx4 v[178:179], off
	v_lshl_add_u64 v[198:199], s[42:43], 0, v[132:133]
	s_mov_b32 m0, s29
	v_lshl_add_u64 v[202:203], s[42:43], 0, v[128:129]
	global_load_lds_dwordx4 v[198:199], off
	s_add_i32 m0, s29, 0x2000
	v_lshl_add_u64 v[236:237], s[16:17], 0, v[134:135]
	global_load_lds_dwordx4 v[202:203], off
	s_mov_b32 m0, s35
	v_lshl_add_u64 v[238:239], s[16:17], 0, v[130:131]
	global_load_lds_dwordx4 v[236:237], off
	s_mov_b32 m0, s36
	s_nop 0
	global_load_lds_dwordx4 v[238:239], off
	s_waitcnt vmcnt(8)
	s_waitcnt lgkmcnt(0)
	s_barrier
	s_waitcnt lgkmcnt(0)
	v_mfma_f32_16x16x32_bf16 v[92:95], v[146:149], v[194:197], 0
	v_mfma_f32_16x16x32_bf16 v[88:91], v[154:157], v[194:197], 0
	v_mfma_f32_16x16x32_bf16 v[84:87], v[146:149], v[210:213], 0
	v_mfma_f32_16x16x32_bf16 v[80:83], v[154:157], v[210:213], 0
	v_mfma_f32_16x16x32_bf16 v[76:79], v[146:149], v[220:223], 0
	v_mfma_f32_16x16x32_bf16 v[72:75], v[154:157], v[220:223], 0
	v_mfma_f32_16x16x32_bf16 v[68:71], v[146:149], v[228:231], 0
	v_mfma_f32_16x16x32_bf16 v[64:67], v[154:157], v[228:231], 0
	v_mfma_f32_16x16x32_bf16 v[92:95], v[150:153], v[206:209], v[92:95]
	v_mfma_f32_16x16x32_bf16 v[88:91], v[158:161], v[206:209], v[88:91]
	v_mfma_f32_16x16x32_bf16 v[84:87], v[150:153], v[214:217], v[84:87]
	v_mfma_f32_16x16x32_bf16 v[80:83], v[158:161], v[214:217], v[80:83]
	v_mfma_f32_16x16x32_bf16 v[76:79], v[150:153], v[224:227], v[76:79]
	v_mfma_f32_16x16x32_bf16 v[72:75], v[158:161], v[224:227], v[72:75]
	v_mfma_f32_16x16x32_bf16 v[68:71], v[150:153], v[232:235], v[68:71]
	v_mfma_f32_16x16x32_bf16 v[64:67], v[158:161], v[232:235], v[64:67]
	v_mfma_f32_16x16x32_bf16 v[28:31], v[162:165], v[194:197], 0
	v_mfma_f32_16x16x32_bf16 v[24:27], v[170:173], v[194:197], 0
	v_mfma_f32_16x16x32_bf16 v[20:23], v[162:165], v[210:213], 0
	v_mfma_f32_16x16x32_bf16 v[16:19], v[170:173], v[210:213], 0
	v_mfma_f32_16x16x32_bf16 v[12:15], v[162:165], v[220:223], 0
	v_mfma_f32_16x16x32_bf16 v[8:11], v[170:173], v[220:223], 0
	v_mfma_f32_16x16x32_bf16 v[4:7], v[162:165], v[228:231], 0
	v_mfma_f32_16x16x32_bf16 v[0:3], v[170:173], v[228:231], 0
	v_mfma_f32_16x16x32_bf16 v[28:31], v[166:169], v[206:209], v[28:31]
	v_mfma_f32_16x16x32_bf16 v[24:27], v[174:177], v[206:209], v[24:27]
	v_mfma_f32_16x16x32_bf16 v[20:23], v[166:169], v[214:217], v[20:23]
	v_mfma_f32_16x16x32_bf16 v[16:19], v[174:177], v[214:217], v[16:19]
	v_mfma_f32_16x16x32_bf16 v[12:15], v[166:169], v[224:227], v[12:15]
	v_mfma_f32_16x16x32_bf16 v[8:11], v[174:177], v[224:227], v[8:11]
	v_mfma_f32_16x16x32_bf16 v[4:7], v[166:169], v[232:235], v[4:7]
	v_mfma_f32_16x16x32_bf16 v[0:3], v[174:177], v[232:235], v[0:3]
	s_barrier
	s_add_i32 s29, 0, 0x18000
	s_add_i32 s42, 0, 0x1c000
	v_add_u32_e32 v158, s29, v143
	v_add_u32_e32 v174, s42, v143
	ds_read_b128 v[146:149], v158
	ds_read_b128 v[150:153], v158 offset:1024
	ds_read_b128 v[154:157], v158 offset:2048
	ds_read_b128 v[158:161], v158 offset:3072
	ds_read_b128 v[162:165], v174
	ds_read_b128 v[166:169], v174 offset:1024
	ds_read_b128 v[170:173], v174 offset:2048
	ds_read_b128 v[174:177], v174 offset:3072
	s_add_u32 s16, s16, s0
	s_addc_u32 s17, s17, s1
	s_mov_b32 m0, s37
	v_lshl_add_u64 v[240:241], s[16:17], 0, v[134:135]
	ds_read_b128 v[194:197], v145 offset:32768
	ds_read_b128 v[206:209], v145 offset:33792
	ds_read_b128 v[210:213], v145 offset:34816
	ds_read_b128 v[214:217], v145 offset:35840
	ds_read_b128 v[220:223], v145 offset:36864
	ds_read_b128 v[224:227], v145 offset:37888
	ds_read_b128 v[228:231], v145 offset:38912
	ds_read_b128 v[232:235], v145 offset:39936
	global_load_lds_dwordx4 v[240:241], off
	v_lshl_add_u64 v[240:241], s[16:17], 0, v[130:131]
	s_mov_b32 m0, s38
	s_nop 0
	global_load_lds_dwordx4 v[240:241], off
	s_waitcnt vmcnt(8)
	s_waitcnt lgkmcnt(0)
	s_barrier
	s_waitcnt lgkmcnt(0)
	v_mfma_f32_16x16x32_bf16 v[120:123], v[146:149], v[194:197], v[120:123]
	v_mfma_f32_16x16x32_bf16 v[124:127], v[154:157], v[194:197], v[124:127]
	v_mfma_f32_16x16x32_bf16 v[116:119], v[146:149], v[210:213], v[116:119]
	v_mfma_f32_16x16x32_bf16 v[112:115], v[154:157], v[210:213], v[112:115]
	v_mfma_f32_16x16x32_bf16 v[108:111], v[146:149], v[220:223], v[108:111]
	v_mfma_f32_16x16x32_bf16 v[104:107], v[154:157], v[220:223], v[104:107]
	v_mfma_f32_16x16x32_bf16 v[100:103], v[146:149], v[228:231], v[100:103]
	v_mfma_f32_16x16x32_bf16 v[96:99], v[154:157], v[228:231], v[96:99]
	v_mfma_f32_16x16x32_bf16 v[120:123], v[150:153], v[206:209], v[120:123]
	v_mfma_f32_16x16x32_bf16 v[124:127], v[158:161], v[206:209], v[124:127]
	v_mfma_f32_16x16x32_bf16 v[116:119], v[150:153], v[214:217], v[116:119]
	v_mfma_f32_16x16x32_bf16 v[112:115], v[158:161], v[214:217], v[112:115]
	v_mfma_f32_16x16x32_bf16 v[108:111], v[150:153], v[224:227], v[108:111]
	v_mfma_f32_16x16x32_bf16 v[104:107], v[158:161], v[224:227], v[104:107]
	v_mfma_f32_16x16x32_bf16 v[100:103], v[150:153], v[232:235], v[100:103]
	v_mfma_f32_16x16x32_bf16 v[96:99], v[158:161], v[232:235], v[96:99]
	v_mfma_f32_16x16x32_bf16 v[60:63], v[162:165], v[194:197], v[60:63]
	v_mfma_f32_16x16x32_bf16 v[56:59], v[170:173], v[194:197], v[56:59]
	v_mfma_f32_16x16x32_bf16 v[52:55], v[162:165], v[210:213], v[52:55]
	v_mfma_f32_16x16x32_bf16 v[48:51], v[170:173], v[210:213], v[48:51]
	v_mfma_f32_16x16x32_bf16 v[44:47], v[162:165], v[220:223], v[44:47]
	v_mfma_f32_16x16x32_bf16 v[40:43], v[170:173], v[220:223], v[40:43]
	v_mfma_f32_16x16x32_bf16 v[36:39], v[162:165], v[228:231], v[36:39]
	v_mfma_f32_16x16x32_bf16 v[32:35], v[170:173], v[228:231], v[32:35]
	v_mfma_f32_16x16x32_bf16 v[60:63], v[166:169], v[206:209], v[60:63]
	v_mfma_f32_16x16x32_bf16 v[56:59], v[174:177], v[206:209], v[56:59]
	v_mfma_f32_16x16x32_bf16 v[52:55], v[166:169], v[214:217], v[52:55]
	v_mfma_f32_16x16x32_bf16 v[48:51], v[174:177], v[214:217], v[48:51]
	v_mfma_f32_16x16x32_bf16 v[44:47], v[166:169], v[224:227], v[44:47]
	v_mfma_f32_16x16x32_bf16 v[40:43], v[174:177], v[224:227], v[40:43]
	v_mfma_f32_16x16x32_bf16 v[36:39], v[166:169], v[232:235], v[36:39]
	v_mfma_f32_16x16x32_bf16 v[32:35], v[174:177], v[232:235], v[32:35]
	s_barrier
	s_add_i32 s16, s29, s34
	v_lshl_add_u64 v[140:141], v[140:141], 0, s[12:13]
	s_mov_b32 m0, s16
	ds_read_b128 v[194:197], v145 offset:49152
	ds_read_b128 v[206:209], v145 offset:50176
	ds_read_b128 v[210:213], v145 offset:51200
	ds_read_b128 v[214:217], v145 offset:52224
	ds_read_b128 v[220:223], v145 offset:53248
	ds_read_b128 v[224:227], v145 offset:54272
	ds_read_b128 v[228:231], v145 offset:55296
	ds_read_b128 v[232:235], v145 offset:56320
	global_load_lds_dwordx4 v[140:141], off
	v_lshl_add_u64 v[140:141], v[178:179], 0, s[12:13]
	s_add_i32 m0, s16, 0x2000
	s_add_i32 s16, s42, s34
	global_load_lds_dwordx4 v[140:141], off
	v_lshl_add_u64 v[140:141], v[198:199], 0, s[12:13]
	s_mov_b32 m0, s16
	s_nop 0
	global_load_lds_dwordx4 v[140:141], off
	v_lshl_add_u64 v[140:141], v[202:203], 0, s[12:13]
	s_add_i32 m0, s16, 0x2000
	s_nop 0
	global_load_lds_dwordx4 v[140:141], off
	v_lshl_add_u64 v[140:141], v[236:237], 0, s[12:13]
	s_mov_b32 m0, s46
	s_nop 0
	global_load_lds_dwordx4 v[140:141], off
	v_lshl_add_u64 v[140:141], v[238:239], 0, s[12:13]
	s_mov_b32 m0, s47
	s_nop 0
	global_load_lds_dwordx4 v[140:141], off
	s_waitcnt vmcnt(8)
	s_waitcnt lgkmcnt(0)
	s_barrier
	s_waitcnt lgkmcnt(0)
	v_mfma_f32_16x16x32_bf16 v[92:95], v[146:149], v[194:197], v[92:95]
	s_add_u32 s26, s26, 0x100
	v_mfma_f32_16x16x32_bf16 v[88:91], v[154:157], v[194:197], v[88:91]
	s_addc_u32 s27, s27, 0
	v_mfma_f32_16x16x32_bf16 v[84:87], v[146:149], v[210:213], v[84:87]
	s_add_u32 s10, s10, 0x100
	v_mfma_f32_16x16x32_bf16 v[80:83], v[154:157], v[210:213], v[80:83]
	s_addc_u32 s11, s11, 0
	v_mfma_f32_16x16x32_bf16 v[76:79], v[146:149], v[220:223], v[76:79]
	s_mov_b32 s16, s28
	v_mfma_f32_16x16x32_bf16 v[72:75], v[154:157], v[220:223], v[72:75]
	s_cmp_ge_i32 s28, s45
	v_mfma_f32_16x16x32_bf16 v[68:71], v[146:149], v[228:231], v[68:71]
	s_cselect_b32 s99, 1, 0
	v_mfma_f32_16x16x32_bf16 v[64:67], v[154:157], v[228:231], v[64:67]
	s_add_i32 s28, s16, 2
	v_mfma_f32_16x16x32_bf16 v[92:95], v[150:153], v[206:209], v[92:95]
	s_add_u32 s29, s26, 0x80
	v_mfma_f32_16x16x32_bf16 v[88:91], v[158:161], v[206:209], v[88:91]
	s_addc_u32 s17, s27, 0
	v_mfma_f32_16x16x32_bf16 v[84:87], v[150:153], v[214:217], v[84:87]
	s_add_i32 s59, 0, 0x10000
	v_mfma_f32_16x16x32_bf16 v[80:83], v[158:161], v[214:217], v[80:83]
	s_cmp_eq_u32 s48, s16
	v_mfma_f32_16x16x32_bf16 v[76:79], v[150:153], v[224:227], v[76:79]
	s_cselect_b32 s17, s23, s17
	v_mfma_f32_16x16x32_bf16 v[72:75], v[158:161], v[224:227], v[72:75]
	s_cselect_b32 s16, s22, s29
	v_mfma_f32_16x16x32_bf16 v[68:71], v[150:153], v[232:235], v[68:71]
	s_cselect_b32 s43, s25, s11
	v_mfma_f32_16x16x32_bf16 v[64:67], v[158:161], v[232:235], v[64:67]
	s_cselect_b32 s42, s24, s10
	v_mfma_f32_16x16x32_bf16 v[28:31], v[162:165], v[194:197], v[28:31]
	s_add_i32 s29, 0, 0x14000
	v_mfma_f32_16x16x32_bf16 v[24:27], v[170:173], v[194:197], v[24:27]
	v_mfma_f32_16x16x32_bf16 v[20:23], v[162:165], v[210:213], v[20:23]
	v_mfma_f32_16x16x32_bf16 v[16:19], v[170:173], v[210:213], v[16:19]
	v_mfma_f32_16x16x32_bf16 v[12:15], v[162:165], v[220:223], v[12:15]
	v_mfma_f32_16x16x32_bf16 v[8:11], v[170:173], v[220:223], v[8:11]
	v_mfma_f32_16x16x32_bf16 v[4:7], v[162:165], v[228:231], v[4:7]
	v_mfma_f32_16x16x32_bf16 v[0:3], v[170:173], v[228:231], v[0:3]
	v_mfma_f32_16x16x32_bf16 v[28:31], v[166:169], v[206:209], v[28:31]
	v_mfma_f32_16x16x32_bf16 v[24:27], v[174:177], v[206:209], v[24:27]
	v_mfma_f32_16x16x32_bf16 v[20:23], v[166:169], v[214:217], v[20:23]
	v_mfma_f32_16x16x32_bf16 v[16:19], v[174:177], v[214:217], v[16:19]
	v_mfma_f32_16x16x32_bf16 v[12:15], v[166:169], v[224:227], v[12:15]
	v_mfma_f32_16x16x32_bf16 v[8:11], v[174:177], v[224:227], v[8:11]
	v_mfma_f32_16x16x32_bf16 v[4:7], v[166:169], v[232:235], v[4:7]
	v_mfma_f32_16x16x32_bf16 v[0:3], v[174:177], v[232:235], v[0:3]
	s_barrier
	s_cmp_lg_u32 s99, 0
	s_cbranch_scc1 .Lpeelx_11
.LBB0_823:
	v_add_u32_e32 v140, s59, v143
	ds_read_b128 v[146:149], v140
	ds_read_b128 v[150:153], v140 offset:1024
	ds_read_b128 v[154:157], v140 offset:2048
	ds_read_b128 v[158:161], v140 offset:3072
	v_add_u32_e32 v140, s29, v143
	ds_read_b128 v[162:165], v140
	ds_read_b128 v[166:169], v140 offset:1024
	ds_read_b128 v[170:173], v140 offset:2048
	ds_read_b128 v[174:177], v140 offset:3072
	v_lshl_add_u64 v[140:141], s[26:27], 0, v[136:137]
	s_add_i32 m0, s35, 0xc000
	ds_read_b128 v[194:197], v145
	ds_read_b128 v[206:209], v145 offset:1024
	ds_read_b128 v[210:213], v145 offset:2048
	ds_read_b128 v[214:217], v145 offset:3072
	ds_read_b128 v[220:223], v145 offset:4096
	ds_read_b128 v[224:227], v145 offset:5120
	ds_read_b128 v[228:231], v145 offset:6144
	ds_read_b128 v[232:235], v145 offset:7168
	global_load_lds_dwordx4 v[140:141], off
	v_lshl_add_u64 v[140:141], s[26:27], 0, v[138:139]
	s_add_i32 m0, s35, 0xe000
	s_nop 0
	global_load_lds_dwordx4 v[140:141], off
	s_waitcnt vmcnt(8)
	s_waitcnt lgkmcnt(0)
	s_barrier
	s_waitcnt lgkmcnt(0)
	v_mfma_f32_16x16x32_bf16 v[120:123], v[146:149], v[194:197], v[120:123]
	v_mfma_f32_16x16x32_bf16 v[124:127], v[154:157], v[194:197], v[124:127]
	v_mfma_f32_16x16x32_bf16 v[116:119], v[146:149], v[210:213], v[116:119]
	v_mfma_f32_16x16x32_bf16 v[112:115], v[154:157], v[210:213], v[112:115]
	v_mfma_f32_16x16x32_bf16 v[108:111], v[146:149], v[220:223], v[108:111]
	v_mfma_f32_16x16x32_bf16 v[104:107], v[154:157], v[220:223], v[104:107]
	v_mfma_f32_16x16x32_bf16 v[100:103], v[146:149], v[228:231], v[100:103]
	v_mfma_f32_16x16x32_bf16 v[96:99], v[154:157], v[228:231], v[96:99]
	v_mfma_f32_16x16x32_bf16 v[120:123], v[150:153], v[206:209], v[120:123]
	v_mfma_f32_16x16x32_bf16 v[124:127], v[158:161], v[206:209], v[124:127]
	v_mfma_f32_16x16x32_bf16 v[116:119], v[150:153], v[214:217], v[116:119]
	v_mfma_f32_16x16x32_bf16 v[112:115], v[158:161], v[214:217], v[112:115]
	v_mfma_f32_16x16x32_bf16 v[108:111], v[150:153], v[224:227], v[108:111]
	v_mfma_f32_16x16x32_bf16 v[104:107], v[158:161], v[224:227], v[104:107]
	v_mfma_f32_16x16x32_bf16 v[100:103], v[150:153], v[232:235], v[100:103]
	v_mfma_f32_16x16x32_bf16 v[96:99], v[158:161], v[232:235], v[96:99]
	v_mfma_f32_16x16x32_bf16 v[60:63], v[162:165], v[194:197], v[60:63]
	v_mfma_f32_16x16x32_bf16 v[56:59], v[170:173], v[194:197], v[56:59]
	v_mfma_f32_16x16x32_bf16 v[52:55], v[162:165], v[210:213], v[52:55]
	v_mfma_f32_16x16x32_bf16 v[48:51], v[170:173], v[210:213], v[48:51]
	v_mfma_f32_16x16x32_bf16 v[44:47], v[162:165], v[220:223], v[44:47]
	v_mfma_f32_16x16x32_bf16 v[40:43], v[170:173], v[220:223], v[40:43]
	v_mfma_f32_16x16x32_bf16 v[36:39], v[162:165], v[228:231], v[36:39]
	v_mfma_f32_16x16x32_bf16 v[32:35], v[170:173], v[228:231], v[32:35]
	v_mfma_f32_16x16x32_bf16 v[60:63], v[166:169], v[206:209], v[60:63]
	v_mfma_f32_16x16x32_bf16 v[56:59], v[174:177], v[206:209], v[56:59]
	v_mfma_f32_16x16x32_bf16 v[52:55], v[166:169], v[214:217], v[52:55]
	v_mfma_f32_16x16x32_bf16 v[48:51], v[174:177], v[214:217], v[48:51]
	v_mfma_f32_16x16x32_bf16 v[44:47], v[166:169], v[224:227], v[44:47]
	v_mfma_f32_16x16x32_bf16 v[40:43], v[174:177], v[224:227], v[40:43]
	v_mfma_f32_16x16x32_bf16 v[36:39], v[166:169], v[232:235], v[36:39]
	v_mfma_f32_16x16x32_bf16 v[32:35], v[174:177], v[232:235], v[32:35]
	s_barrier
	s_add_i32 s59, s59, s34
	v_lshl_add_u64 v[140:141], s[42:43], 0, v[132:133]
	s_mov_b32 m0, s59
	ds_read_b128 v[194:197], v145 offset:16384
	ds_read_b128 v[206:209], v145 offset:17408
	ds_read_b128 v[210:213], v145 offset:18432
	ds_read_b128 v[214:217], v145 offset:19456
	ds_read_b128 v[220:223], v145 offset:20480
	ds_read_b128 v[224:227], v145 offset:21504
	ds_read_b128 v[228:231], v145 offset:22528
	ds_read_b128 v[232:235], v145 offset:23552
	global_load_lds_dwordx4 v[140:141], off
	s_add_i32 m0, s59, 0x2000
	v_lshl_add_u64 v[178:179], s[42:43], 0, v[128:129]
	s_add_u32 s42, s42, s0
	s_addc_u32 s43, s43, s1
	s_add_i32 s29, s29, s34
	global_load_lds_dwordx4 v[178:179], off
	v_lshl_add_u64 v[198:199], s[42:43], 0, v[132:133]
	s_mov_b32 m0, s29
	v_lshl_add_u64 v[202:203], s[42:43], 0, v[128:129]
	global_load_lds_dwordx4 v[198:199], off
	s_add_i32 m0, s29, 0x2000
	v_lshl_add_u64 v[236:237], s[16:17], 0, v[134:135]
	global_load_lds_dwordx4 v[202:203], off
	s_mov_b32 m0, s35
	v_lshl_add_u64 v[238:239], s[16:17], 0, v[130:131]
	global_load_lds_dwordx4 v[236:237], off
	s_mov_b32 m0, s36
	s_nop 0
	global_load_lds_dwordx4 v[238:239], off
	s_waitcnt vmcnt(8)
	s_waitcnt lgkmcnt(0)
	s_barrier
	s_waitcnt lgkmcnt(0)
	v_mfma_f32_16x16x32_bf16 v[92:95], v[146:149], v[194:197], v[92:95]
	v_mfma_f32_16x16x32_bf16 v[88:91], v[154:157], v[194:197], v[88:91]
	v_mfma_f32_16x16x32_bf16 v[84:87], v[146:149], v[210:213], v[84:87]
	v_mfma_f32_16x16x32_bf16 v[80:83], v[154:157], v[210:213], v[80:83]
	v_mfma_f32_16x16x32_bf16 v[76:79], v[146:149], v[220:223], v[76:79]
	v_mfma_f32_16x16x32_bf16 v[72:75], v[154:157], v[220:223], v[72:75]
	v_mfma_f32_16x16x32_bf16 v[68:71], v[146:149], v[228:231], v[68:71]
	v_mfma_f32_16x16x32_bf16 v[64:67], v[154:157], v[228:231], v[64:67]
	v_mfma_f32_16x16x32_bf16 v[92:95], v[150:153], v[206:209], v[92:95]
	v_mfma_f32_16x16x32_bf16 v[88:91], v[158:161], v[206:209], v[88:91]
	v_mfma_f32_16x16x32_bf16 v[84:87], v[150:153], v[214:217], v[84:87]
	v_mfma_f32_16x16x32_bf16 v[80:83], v[158:161], v[214:217], v[80:83]
	v_mfma_f32_16x16x32_bf16 v[76:79], v[150:153], v[224:227], v[76:79]
	v_mfma_f32_16x16x32_bf16 v[72:75], v[158:161], v[224:227], v[72:75]
	v_mfma_f32_16x16x32_bf16 v[68:71], v[150:153], v[232:235], v[68:71]
	v_mfma_f32_16x16x32_bf16 v[64:67], v[158:161], v[232:235], v[64:67]
	v_mfma_f32_16x16x32_bf16 v[28:31], v[162:165], v[194:197], v[28:31]
	v_mfma_f32_16x16x32_bf16 v[24:27], v[170:173], v[194:197], v[24:27]
	v_mfma_f32_16x16x32_bf16 v[20:23], v[162:165], v[210:213], v[20:23]
	v_mfma_f32_16x16x32_bf16 v[16:19], v[170:173], v[210:213], v[16:19]
	v_mfma_f32_16x16x32_bf16 v[12:15], v[162:165], v[220:223], v[12:15]
	v_mfma_f32_16x16x32_bf16 v[8:11], v[170:173], v[220:223], v[8:11]
	v_mfma_f32_16x16x32_bf16 v[4:7], v[162:165], v[228:231], v[4:7]
	v_mfma_f32_16x16x32_bf16 v[0:3], v[170:173], v[228:231], v[0:3]
	v_mfma_f32_16x16x32_bf16 v[28:31], v[166:169], v[206:209], v[28:31]
	v_mfma_f32_16x16x32_bf16 v[24:27], v[174:177], v[206:209], v[24:27]
	v_mfma_f32_16x16x32_bf16 v[20:23], v[166:169], v[214:217], v[20:23]
	v_mfma_f32_16x16x32_bf16 v[16:19], v[174:177], v[214:217], v[16:19]
	v_mfma_f32_16x16x32_bf16 v[12:15], v[166:169], v[224:227], v[12:15]
	v_mfma_f32_16x16x32_bf16 v[8:11], v[174:177], v[224:227], v[8:11]
	v_mfma_f32_16x16x32_bf16 v[4:7], v[166:169], v[232:235], v[4:7]
	v_mfma_f32_16x16x32_bf16 v[0:3], v[174:177], v[232:235], v[0:3]
	s_barrier
	s_add_i32 s29, 0, 0x18000
	s_add_i32 s42, 0, 0x1c000
	v_add_u32_e32 v158, s29, v143
	v_add_u32_e32 v174, s42, v143
	ds_read_b128 v[146:149], v158
	ds_read_b128 v[150:153], v158 offset:1024
	ds_read_b128 v[154:157], v158 offset:2048
	ds_read_b128 v[158:161], v158 offset:3072
	ds_read_b128 v[162:165], v174
	ds_read_b128 v[166:169], v174 offset:1024
	ds_read_b128 v[170:173], v174 offset:2048
	ds_read_b128 v[174:177], v174 offset:3072
	s_add_u32 s16, s16, s0
	s_addc_u32 s17, s17, s1
	s_mov_b32 m0, s37
	v_lshl_add_u64 v[240:241], s[16:17], 0, v[134:135]
	ds_read_b128 v[194:197], v145 offset:32768
	ds_read_b128 v[206:209], v145 offset:33792
	ds_read_b128 v[210:213], v145 offset:34816
	ds_read_b128 v[214:217], v145 offset:35840
	ds_read_b128 v[220:223], v145 offset:36864
	ds_read_b128 v[224:227], v145 offset:37888
	ds_read_b128 v[228:231], v145 offset:38912
	ds_read_b128 v[232:235], v145 offset:39936
	global_load_lds_dwordx4 v[240:241], off
	v_lshl_add_u64 v[240:241], s[16:17], 0, v[130:131]
	s_mov_b32 m0, s38
	s_nop 0
	global_load_lds_dwordx4 v[240:241], off
	s_waitcnt vmcnt(8)
	s_waitcnt lgkmcnt(0)
	s_barrier
	s_waitcnt lgkmcnt(0)
	v_mfma_f32_16x16x32_bf16 v[120:123], v[146:149], v[194:197], v[120:123]
	v_mfma_f32_16x16x32_bf16 v[124:127], v[154:157], v[194:197], v[124:127]
	v_mfma_f32_16x16x32_bf16 v[116:119], v[146:149], v[210:213], v[116:119]
	v_mfma_f32_16x16x32_bf16 v[112:115], v[154:157], v[210:213], v[112:115]
	v_mfma_f32_16x16x32_bf16 v[108:111], v[146:149], v[220:223], v[108:111]
	v_mfma_f32_16x16x32_bf16 v[104:107], v[154:157], v[220:223], v[104:107]
	v_mfma_f32_16x16x32_bf16 v[100:103], v[146:149], v[228:231], v[100:103]
	v_mfma_f32_16x16x32_bf16 v[96:99], v[154:157], v[228:231], v[96:99]
	v_mfma_f32_16x16x32_bf16 v[120:123], v[150:153], v[206:209], v[120:123]
	v_mfma_f32_16x16x32_bf16 v[124:127], v[158:161], v[206:209], v[124:127]
	v_mfma_f32_16x16x32_bf16 v[116:119], v[150:153], v[214:217], v[116:119]
	v_mfma_f32_16x16x32_bf16 v[112:115], v[158:161], v[214:217], v[112:115]
	v_mfma_f32_16x16x32_bf16 v[108:111], v[150:153], v[224:227], v[108:111]
	v_mfma_f32_16x16x32_bf16 v[104:107], v[158:161], v[224:227], v[104:107]
	v_mfma_f32_16x16x32_bf16 v[100:103], v[150:153], v[232:235], v[100:103]
	v_mfma_f32_16x16x32_bf16 v[96:99], v[158:161], v[232:235], v[96:99]
	v_mfma_f32_16x16x32_bf16 v[60:63], v[162:165], v[194:197], v[60:63]
	v_mfma_f32_16x16x32_bf16 v[56:59], v[170:173], v[194:197], v[56:59]
	v_mfma_f32_16x16x32_bf16 v[52:55], v[162:165], v[210:213], v[52:55]
	v_mfma_f32_16x16x32_bf16 v[48:51], v[170:173], v[210:213], v[48:51]
	v_mfma_f32_16x16x32_bf16 v[44:47], v[162:165], v[220:223], v[44:47]
	v_mfma_f32_16x16x32_bf16 v[40:43], v[170:173], v[220:223], v[40:43]
	v_mfma_f32_16x16x32_bf16 v[36:39], v[162:165], v[228:231], v[36:39]
	v_mfma_f32_16x16x32_bf16 v[32:35], v[170:173], v[228:231], v[32:35]
	v_mfma_f32_16x16x32_bf16 v[60:63], v[166:169], v[206:209], v[60:63]
	v_mfma_f32_16x16x32_bf16 v[56:59], v[174:177], v[206:209], v[56:59]
	v_mfma_f32_16x16x32_bf16 v[52:55], v[166:169], v[214:217], v[52:55]
	v_mfma_f32_16x16x32_bf16 v[48:51], v[174:177], v[214:217], v[48:51]
	v_mfma_f32_16x16x32_bf16 v[44:47], v[166:169], v[224:227], v[44:47]
	v_mfma_f32_16x16x32_bf16 v[40:43], v[174:177], v[224:227], v[40:43]
	v_mfma_f32_16x16x32_bf16 v[36:39], v[166:169], v[232:235], v[36:39]
	v_mfma_f32_16x16x32_bf16 v[32:35], v[174:177], v[232:235], v[32:35]
	s_barrier
	s_add_i32 s16, s29, s34
	v_lshl_add_u64 v[140:141], v[140:141], 0, s[12:13]
	s_mov_b32 m0, s16
	ds_read_b128 v[194:197], v145 offset:49152
	ds_read_b128 v[206:209], v145 offset:50176
	ds_read_b128 v[210:213], v145 offset:51200
	ds_read_b128 v[214:217], v145 offset:52224
	ds_read_b128 v[220:223], v145 offset:53248
	ds_read_b128 v[224:227], v145 offset:54272
	ds_read_b128 v[228:231], v145 offset:55296
	ds_read_b128 v[232:235], v145 offset:56320
	global_load_lds_dwordx4 v[140:141], off
	v_lshl_add_u64 v[140:141], v[178:179], 0, s[12:13]
	s_add_i32 m0, s16, 0x2000
	s_add_i32 s16, s42, s34
	global_load_lds_dwordx4 v[140:141], off
	v_lshl_add_u64 v[140:141], v[198:199], 0, s[12:13]
	s_mov_b32 m0, s16
	s_nop 0
	global_load_lds_dwordx4 v[140:141], off
	v_lshl_add_u64 v[140:141], v[202:203], 0, s[12:13]
	s_add_i32 m0, s16, 0x2000
	s_nop 0
	global_load_lds_dwordx4 v[140:141], off
	v_lshl_add_u64 v[140:141], v[236:237], 0, s[12:13]
	s_mov_b32 m0, s46
	s_nop 0
	global_load_lds_dwordx4 v[140:141], off
	v_lshl_add_u64 v[140:141], v[238:239], 0, s[12:13]
	s_mov_b32 m0, s47
	s_nop 0
	global_load_lds_dwordx4 v[140:141], off
	s_waitcnt vmcnt(8)
	s_waitcnt lgkmcnt(0)
	s_barrier
	s_waitcnt lgkmcnt(0)
	v_mfma_f32_16x16x32_bf16 v[92:95], v[146:149], v[194:197], v[92:95]
	s_add_u32 s26, s26, 0x100
	v_mfma_f32_16x16x32_bf16 v[88:91], v[154:157], v[194:197], v[88:91]
	s_addc_u32 s27, s27, 0
	v_mfma_f32_16x16x32_bf16 v[84:87], v[146:149], v[210:213], v[84:87]
	s_add_u32 s10, s10, 0x100
	v_mfma_f32_16x16x32_bf16 v[80:83], v[154:157], v[210:213], v[80:83]
	s_addc_u32 s11, s11, 0
	v_mfma_f32_16x16x32_bf16 v[76:79], v[146:149], v[220:223], v[76:79]
	s_mov_b32 s16, s28
	v_mfma_f32_16x16x32_bf16 v[72:75], v[154:157], v[220:223], v[72:75]
	s_cmp_ge_i32 s28, s45
	v_mfma_f32_16x16x32_bf16 v[68:71], v[146:149], v[228:231], v[68:71]
	s_cselect_b32 s99, 1, 0
	v_mfma_f32_16x16x32_bf16 v[64:67], v[154:157], v[228:231], v[64:67]
	s_add_i32 s28, s16, 2
	v_mfma_f32_16x16x32_bf16 v[92:95], v[150:153], v[206:209], v[92:95]
	s_add_u32 s29, s26, 0x80
	v_mfma_f32_16x16x32_bf16 v[88:91], v[158:161], v[206:209], v[88:91]
	s_addc_u32 s17, s27, 0
	v_mfma_f32_16x16x32_bf16 v[84:87], v[150:153], v[214:217], v[84:87]
	s_add_i32 s59, 0, 0x10000
	v_mfma_f32_16x16x32_bf16 v[80:83], v[158:161], v[214:217], v[80:83]
	s_cmp_eq_u32 s48, s16
	v_mfma_f32_16x16x32_bf16 v[76:79], v[150:153], v[224:227], v[76:79]
	s_cselect_b32 s17, s23, s17
	v_mfma_f32_16x16x32_bf16 v[72:75], v[158:161], v[224:227], v[72:75]
	s_cselect_b32 s16, s22, s29
	v_mfma_f32_16x16x32_bf16 v[68:71], v[150:153], v[232:235], v[68:71]
	s_cselect_b32 s43, s25, s11
	v_mfma_f32_16x16x32_bf16 v[64:67], v[158:161], v[232:235], v[64:67]
	s_cselect_b32 s42, s24, s10
	v_mfma_f32_16x16x32_bf16 v[28:31], v[162:165], v[194:197], v[28:31]
	s_add_i32 s29, 0, 0x14000
	v_mfma_f32_16x16x32_bf16 v[24:27], v[170:173], v[194:197], v[24:27]
	v_mfma_f32_16x16x32_bf16 v[20:23], v[162:165], v[210:213], v[20:23]
	v_mfma_f32_16x16x32_bf16 v[16:19], v[170:173], v[210:213], v[16:19]
	v_mfma_f32_16x16x32_bf16 v[12:15], v[162:165], v[220:223], v[12:15]
	v_mfma_f32_16x16x32_bf16 v[8:11], v[170:173], v[220:223], v[8:11]
	v_mfma_f32_16x16x32_bf16 v[4:7], v[162:165], v[228:231], v[4:7]
	v_mfma_f32_16x16x32_bf16 v[0:3], v[170:173], v[228:231], v[0:3]
	v_mfma_f32_16x16x32_bf16 v[28:31], v[166:169], v[206:209], v[28:31]
	v_mfma_f32_16x16x32_bf16 v[24:27], v[174:177], v[206:209], v[24:27]
	v_mfma_f32_16x16x32_bf16 v[20:23], v[166:169], v[214:217], v[20:23]
	v_mfma_f32_16x16x32_bf16 v[16:19], v[174:177], v[214:217], v[16:19]
	v_mfma_f32_16x16x32_bf16 v[12:15], v[166:169], v[224:227], v[12:15]
	v_mfma_f32_16x16x32_bf16 v[8:11], v[174:177], v[224:227], v[8:11]
	v_mfma_f32_16x16x32_bf16 v[4:7], v[166:169], v[232:235], v[4:7]
	v_mfma_f32_16x16x32_bf16 v[0:3], v[174:177], v[232:235], v[0:3]
	s_barrier
	s_cmp_lg_u32 s99, 0
	s_cbranch_scc0 .LBB0_823

.Llbb_8:
	s_add_i32 s30, s16, 2
	s_add_u32 s31, s0, 0x80
	s_addc_u32 s17, s1, 0
	s_add_i32 s35, 0, 0x10000
	s_cmp_eq_u32 s57, s16
	s_cselect_b32 s17, s27, s17
	s_cselect_b32 s16, s26, s31
	s_cselect_b32 s43, s29, s11
	s_cselect_b32 s42, s28, s10
	s_add_i32 s31, 0, 0x14000
	v_add_u32_e32 v156, s35, v164
	v_add_u32_e32 v167, s31, v164
	ds_read_b128 v[144:147], v156
	ds_read_b128 v[148:151], v156 offset:1024
	ds_read_b128 v[152:155], v156 offset:2048
	ds_read_b128 v[156:159], v156 offset:3072
	ds_read_b128 v[160:163], v167
	ds_read_b128 v[168:171], v167 offset:1024
	ds_read_b128 v[172:175], v167 offset:2048
	ds_read_b128 v[176:179], v167 offset:3072
	v_lshl_add_u64 v[198:199], s[0:1], 0, v[140:141]
	s_add_i32 m0, s39, 0xc000
	ds_read_b128 v[194:197], v166
	ds_read_b128 v[206:209], v166 offset:1024
	ds_read_b128 v[210:213], v166 offset:2048
	ds_read_b128 v[214:217], v166 offset:3072
	ds_read_b128 v[220:223], v166 offset:4096
	ds_read_b128 v[224:227], v166 offset:5120
	ds_read_b128 v[228:231], v166 offset:6144
	ds_read_b128 v[232:235], v166 offset:7168
	global_load_lds_dwordx4 v[198:199], off
	v_lshl_add_u64 v[198:199], s[0:1], 0, v[142:143]
	s_add_i32 m0, s39, 0xe000
	s_nop 0
	global_load_lds_dwordx4 v[198:199], off
	s_waitcnt vmcnt(8)
	s_waitcnt lgkmcnt(0)
	s_barrier
	s_waitcnt lgkmcnt(0)
	v_mfma_f32_16x16x32_bf16 v[124:127], v[144:147], v[194:197], 0
	v_mfma_f32_16x16x32_bf16 v[120:123], v[152:155], v[194:197], 0
	v_mfma_f32_16x16x32_bf16 v[108:111], v[144:147], v[210:213], 0
	v_mfma_f32_16x16x32_bf16 v[104:107], v[152:155], v[210:213], 0
	v_mfma_f32_16x16x32_bf16 v[92:95], v[144:147], v[220:223], 0
	v_mfma_f32_16x16x32_bf16 v[88:91], v[152:155], v[220:223], 0
	v_mfma_f32_16x16x32_bf16 v[76:79], v[144:147], v[228:231], 0
	v_mfma_f32_16x16x32_bf16 v[72:75], v[152:155], v[228:231], 0
	v_mfma_f32_16x16x32_bf16 v[124:127], v[148:151], v[206:209], v[124:127]
	v_mfma_f32_16x16x32_bf16 v[120:123], v[156:159], v[206:209], v[120:123]
	v_mfma_f32_16x16x32_bf16 v[108:111], v[148:151], v[214:217], v[108:111]
	v_mfma_f32_16x16x32_bf16 v[104:107], v[156:159], v[214:217], v[104:107]
	v_mfma_f32_16x16x32_bf16 v[92:95], v[148:151], v[224:227], v[92:95]
	v_mfma_f32_16x16x32_bf16 v[88:91], v[156:159], v[224:227], v[88:91]
	v_mfma_f32_16x16x32_bf16 v[76:79], v[148:151], v[232:235], v[76:79]
	v_mfma_f32_16x16x32_bf16 v[72:75], v[156:159], v[232:235], v[72:75]
	v_mfma_f32_16x16x32_bf16 v[116:119], v[160:163], v[194:197], 0
	v_mfma_f32_16x16x32_bf16 v[112:115], v[172:175], v[194:197], 0
	v_mfma_f32_16x16x32_bf16 v[100:103], v[160:163], v[210:213], 0
	v_mfma_f32_16x16x32_bf16 v[96:99], v[172:175], v[210:213], 0
	v_mfma_f32_16x16x32_bf16 v[84:87], v[160:163], v[220:223], 0
	v_mfma_f32_16x16x32_bf16 v[80:83], v[172:175], v[220:223], 0
	v_mfma_f32_16x16x32_bf16 v[68:71], v[160:163], v[228:231], 0
	v_mfma_f32_16x16x32_bf16 v[64:67], v[172:175], v[228:231], 0
	v_mfma_f32_16x16x32_bf16 v[116:119], v[168:171], v[206:209], v[116:119]
	v_mfma_f32_16x16x32_bf16 v[112:115], v[176:179], v[206:209], v[112:115]
	v_mfma_f32_16x16x32_bf16 v[100:103], v[168:171], v[214:217], v[100:103]
	v_mfma_f32_16x16x32_bf16 v[96:99], v[176:179], v[214:217], v[96:99]
	v_mfma_f32_16x16x32_bf16 v[84:87], v[168:171], v[224:227], v[84:87]
	v_mfma_f32_16x16x32_bf16 v[80:83], v[176:179], v[224:227], v[80:83]
	v_mfma_f32_16x16x32_bf16 v[68:71], v[168:171], v[232:235], v[68:71]
	v_mfma_f32_16x16x32_bf16 v[64:67], v[176:179], v[232:235], v[64:67]
	s_barrier
	s_add_i32 s35, s35, s38
	v_lshl_add_u64 v[198:199], s[42:43], 0, v[132:133]
	s_mov_b32 m0, s35
	ds_read_b128 v[194:197], v166 offset:16384
	ds_read_b128 v[206:209], v166 offset:17408
	ds_read_b128 v[210:213], v166 offset:18432
	ds_read_b128 v[214:217], v166 offset:19456
	ds_read_b128 v[220:223], v166 offset:20480
	ds_read_b128 v[224:227], v166 offset:21504
	ds_read_b128 v[228:231], v166 offset:22528
	ds_read_b128 v[232:235], v166 offset:23552
	global_load_lds_dwordx4 v[198:199], off
	s_add_i32 m0, s35, 0x2000
	v_lshl_add_u64 v[202:203], s[42:43], 0, v[128:129]
	s_add_u32 s42, s42, s6
	s_addc_u32 s43, s43, s7
	s_add_i32 s31, s31, s38
	global_load_lds_dwordx4 v[202:203], off
	v_lshl_add_u64 v[236:237], s[42:43], 0, v[132:133]
	s_mov_b32 m0, s31
	v_lshl_add_u64 v[238:239], s[42:43], 0, v[128:129]
	global_load_lds_dwordx4 v[236:237], off
	s_add_i32 m0, s31, 0x2000
	v_lshl_add_u64 v[240:241], s[16:17], 0, v[134:135]
	global_load_lds_dwordx4 v[238:239], off
	s_mov_b32 m0, s39
	v_lshl_add_u64 v[242:243], s[16:17], 0, v[130:131]
	global_load_lds_dwordx4 v[240:241], off
	s_mov_b32 m0, s44
	s_nop 0
	global_load_lds_dwordx4 v[242:243], off
	s_waitcnt vmcnt(8)
	s_waitcnt lgkmcnt(0)
	s_barrier
	s_waitcnt lgkmcnt(0)
	v_mfma_f32_16x16x32_bf16 v[60:63], v[144:147], v[194:197], 0
	v_mfma_f32_16x16x32_bf16 v[56:59], v[152:155], v[194:197], 0
	v_mfma_f32_16x16x32_bf16 v[44:47], v[144:147], v[210:213], 0
	v_mfma_f32_16x16x32_bf16 v[40:43], v[152:155], v[210:213], 0
	v_mfma_f32_16x16x32_bf16 v[28:31], v[144:147], v[220:223], 0
	v_mfma_f32_16x16x32_bf16 v[24:27], v[152:155], v[220:223], 0
	v_mfma_f32_16x16x32_bf16 v[12:15], v[144:147], v[228:231], 0
	v_mfma_f32_16x16x32_bf16 v[8:11], v[152:155], v[228:231], 0
	v_mfma_f32_16x16x32_bf16 v[60:63], v[148:151], v[206:209], v[60:63]
	v_mfma_f32_16x16x32_bf16 v[56:59], v[156:159], v[206:209], v[56:59]
	v_mfma_f32_16x16x32_bf16 v[44:47], v[148:151], v[214:217], v[44:47]
	v_mfma_f32_16x16x32_bf16 v[40:43], v[156:159], v[214:217], v[40:43]
	v_mfma_f32_16x16x32_bf16 v[28:31], v[148:151], v[224:227], v[28:31]
	v_mfma_f32_16x16x32_bf16 v[24:27], v[156:159], v[224:227], v[24:27]
	v_mfma_f32_16x16x32_bf16 v[12:15], v[148:151], v[232:235], v[12:15]
	v_mfma_f32_16x16x32_bf16 v[8:11], v[156:159], v[232:235], v[8:11]
	v_mfma_f32_16x16x32_bf16 v[52:55], v[160:163], v[194:197], 0
	v_mfma_f32_16x16x32_bf16 v[48:51], v[172:175], v[194:197], 0
	v_mfma_f32_16x16x32_bf16 v[36:39], v[160:163], v[210:213], 0
	v_mfma_f32_16x16x32_bf16 v[32:35], v[172:175], v[210:213], 0
	v_mfma_f32_16x16x32_bf16 v[20:23], v[160:163], v[220:223], 0
	v_mfma_f32_16x16x32_bf16 v[16:19], v[172:175], v[220:223], 0
	v_mfma_f32_16x16x32_bf16 v[4:7], v[160:163], v[228:231], 0
	v_mfma_f32_16x16x32_bf16 v[0:3], v[172:175], v[228:231], 0
	v_mfma_f32_16x16x32_bf16 v[52:55], v[168:171], v[206:209], v[52:55]
	v_mfma_f32_16x16x32_bf16 v[48:51], v[176:179], v[206:209], v[48:51]
	v_mfma_f32_16x16x32_bf16 v[36:39], v[168:171], v[214:217], v[36:39]
	v_mfma_f32_16x16x32_bf16 v[32:35], v[176:179], v[214:217], v[32:35]
	v_mfma_f32_16x16x32_bf16 v[20:23], v[168:171], v[224:227], v[20:23]
	v_mfma_f32_16x16x32_bf16 v[16:19], v[176:179], v[224:227], v[16:19]
	v_mfma_f32_16x16x32_bf16 v[4:7], v[168:171], v[232:235], v[4:7]
	v_mfma_f32_16x16x32_bf16 v[0:3], v[176:179], v[232:235], v[0:3]
	s_barrier
	s_add_i32 s31, 0, 0x18000
	s_add_i32 s35, 0, 0x1c000
	v_add_u32_e32 v156, s31, v164
	v_add_u32_e32 v167, s35, v164
	ds_read_b128 v[144:147], v156
	ds_read_b128 v[148:151], v156 offset:1024
	ds_read_b128 v[152:155], v156 offset:2048
	ds_read_b128 v[156:159], v156 offset:3072
	ds_read_b128 v[160:163], v167
	ds_read_b128 v[168:171], v167 offset:1024
	ds_read_b128 v[172:175], v167 offset:2048
	ds_read_b128 v[176:179], v167 offset:3072
	s_add_u32 s16, s16, s6
	s_addc_u32 s17, s17, s7
	s_mov_b32 m0, s45
	v_lshl_add_u64 v[244:245], s[16:17], 0, v[134:135]
	ds_read_b128 v[194:197], v166 offset:32768
	ds_read_b128 v[206:209], v166 offset:33792
	ds_read_b128 v[210:213], v166 offset:34816
	ds_read_b128 v[214:217], v166 offset:35840
	ds_read_b128 v[220:223], v166 offset:36864
	ds_read_b128 v[224:227], v166 offset:37888
	ds_read_b128 v[228:231], v166 offset:38912
	ds_read_b128 v[232:235], v166 offset:39936
	global_load_lds_dwordx4 v[244:245], off
	v_lshl_add_u64 v[244:245], s[16:17], 0, v[130:131]
	s_mov_b32 m0, s46
	s_nop 0
	global_load_lds_dwordx4 v[244:245], off
	s_waitcnt vmcnt(8)
	s_waitcnt lgkmcnt(0)
	s_barrier
	s_waitcnt lgkmcnt(0)
	v_mfma_f32_16x16x32_bf16 v[124:127], v[144:147], v[194:197], v[124:127]
	v_mfma_f32_16x16x32_bf16 v[120:123], v[152:155], v[194:197], v[120:123]
	v_mfma_f32_16x16x32_bf16 v[108:111], v[144:147], v[210:213], v[108:111]
	v_mfma_f32_16x16x32_bf16 v[104:107], v[152:155], v[210:213], v[104:107]
	v_mfma_f32_16x16x32_bf16 v[92:95], v[144:147], v[220:223], v[92:95]
	v_mfma_f32_16x16x32_bf16 v[88:91], v[152:155], v[220:223], v[88:91]
	v_mfma_f32_16x16x32_bf16 v[76:79], v[144:147], v[228:231], v[76:79]
	v_mfma_f32_16x16x32_bf16 v[72:75], v[152:155], v[228:231], v[72:75]
	v_mfma_f32_16x16x32_bf16 v[124:127], v[148:151], v[206:209], v[124:127]
	v_mfma_f32_16x16x32_bf16 v[120:123], v[156:159], v[206:209], v[120:123]
	v_mfma_f32_16x16x32_bf16 v[108:111], v[148:151], v[214:217], v[108:111]
	v_mfma_f32_16x16x32_bf16 v[104:107], v[156:159], v[214:217], v[104:107]
	v_mfma_f32_16x16x32_bf16 v[92:95], v[148:151], v[224:227], v[92:95]
	v_mfma_f32_16x16x32_bf16 v[88:91], v[156:159], v[224:227], v[88:91]
	v_mfma_f32_16x16x32_bf16 v[76:79], v[148:151], v[232:235], v[76:79]
	v_mfma_f32_16x16x32_bf16 v[72:75], v[156:159], v[232:235], v[72:75]
	v_mfma_f32_16x16x32_bf16 v[116:119], v[160:163], v[194:197], v[116:119]
	v_mfma_f32_16x16x32_bf16 v[112:115], v[172:175], v[194:197], v[112:115]
	v_mfma_f32_16x16x32_bf16 v[100:103], v[160:163], v[210:213], v[100:103]
	v_mfma_f32_16x16x32_bf16 v[96:99], v[172:175], v[210:213], v[96:99]
	v_mfma_f32_16x16x32_bf16 v[84:87], v[160:163], v[220:223], v[84:87]
	v_mfma_f32_16x16x32_bf16 v[80:83], v[172:175], v[220:223], v[80:83]
	v_mfma_f32_16x16x32_bf16 v[68:71], v[160:163], v[228:231], v[68:71]
	v_mfma_f32_16x16x32_bf16 v[64:67], v[172:175], v[228:231], v[64:67]
	v_mfma_f32_16x16x32_bf16 v[116:119], v[168:171], v[206:209], v[116:119]
	v_mfma_f32_16x16x32_bf16 v[112:115], v[176:179], v[206:209], v[112:115]
	v_mfma_f32_16x16x32_bf16 v[100:103], v[168:171], v[214:217], v[100:103]
	v_mfma_f32_16x16x32_bf16 v[96:99], v[176:179], v[214:217], v[96:99]
	v_mfma_f32_16x16x32_bf16 v[84:87], v[168:171], v[224:227], v[84:87]
	v_mfma_f32_16x16x32_bf16 v[80:83], v[176:179], v[224:227], v[80:83]
	v_mfma_f32_16x16x32_bf16 v[68:71], v[168:171], v[232:235], v[68:71]
	v_mfma_f32_16x16x32_bf16 v[64:67], v[176:179], v[232:235], v[64:67]
	s_barrier
	s_add_i32 s16, s31, s38
	v_lshl_add_u64 v[198:199], v[198:199], 0, s[12:13]
	s_mov_b32 m0, s16
	ds_read_b128 v[194:197], v166 offset:49152
	ds_read_b128 v[206:209], v166 offset:50176
	ds_read_b128 v[210:213], v166 offset:51200
	ds_read_b128 v[214:217], v166 offset:52224
	ds_read_b128 v[220:223], v166 offset:53248
	ds_read_b128 v[224:227], v166 offset:54272
	ds_read_b128 v[228:231], v166 offset:55296
	ds_read_b128 v[232:235], v166 offset:56320
	global_load_lds_dwordx4 v[198:199], off
	v_lshl_add_u64 v[198:199], v[202:203], 0, s[12:13]
	s_add_i32 m0, s16, 0x2000
	s_add_i32 s16, s35, s38
	global_load_lds_dwordx4 v[198:199], off
	v_lshl_add_u64 v[198:199], v[236:237], 0, s[12:13]
	s_mov_b32 m0, s16
	s_nop 0
	global_load_lds_dwordx4 v[198:199], off
	v_lshl_add_u64 v[198:199], v[238:239], 0, s[12:13]
	s_add_i32 m0, s16, 0x2000
	s_nop 0
	global_load_lds_dwordx4 v[198:199], off
	v_lshl_add_u64 v[198:199], v[240:241], 0, s[12:13]
	s_mov_b32 m0, s47
	s_nop 0
	global_load_lds_dwordx4 v[198:199], off
	v_lshl_add_u64 v[198:199], v[242:243], 0, s[12:13]
	s_mov_b32 m0, s48
	s_nop 0
	global_load_lds_dwordx4 v[198:199], off
	s_waitcnt vmcnt(8)
	s_waitcnt lgkmcnt(0)
	s_barrier
	s_waitcnt lgkmcnt(0)
	v_mfma_f32_16x16x32_bf16 v[60:63], v[144:147], v[194:197], v[60:63]
	s_add_u32 s0, s0, 0x100
	v_mfma_f32_16x16x32_bf16 v[56:59], v[152:155], v[194:197], v[56:59]
	s_addc_u32 s1, s1, 0
	v_mfma_f32_16x16x32_bf16 v[44:47], v[144:147], v[210:213], v[44:47]
	s_add_u32 s10, s10, 0x100
	v_mfma_f32_16x16x32_bf16 v[40:43], v[152:155], v[210:213], v[40:43]
	s_addc_u32 s11, s11, 0
	v_mfma_f32_16x16x32_bf16 v[28:31], v[144:147], v[220:223], v[28:31]
	s_mov_b32 s16, s30
	v_mfma_f32_16x16x32_bf16 v[24:27], v[152:155], v[220:223], v[24:27]
	s_cmp_ge_i32 s30, s49
	v_mfma_f32_16x16x32_bf16 v[12:15], v[144:147], v[228:231], v[12:15]
	s_cselect_b32 s99, 1, 0
	v_mfma_f32_16x16x32_bf16 v[8:11], v[152:155], v[228:231], v[8:11]
	s_add_i32 s30, s16, 2
	v_mfma_f32_16x16x32_bf16 v[60:63], v[148:151], v[206:209], v[60:63]
	s_add_u32 s31, s0, 0x80
	v_mfma_f32_16x16x32_bf16 v[56:59], v[156:159], v[206:209], v[56:59]
	s_addc_u32 s17, s1, 0
	v_mfma_f32_16x16x32_bf16 v[44:47], v[148:151], v[214:217], v[44:47]
	s_add_i32 s35, 0, 0x10000
	v_mfma_f32_16x16x32_bf16 v[40:43], v[156:159], v[214:217], v[40:43]
	s_cmp_eq_u32 s57, s16
	v_mfma_f32_16x16x32_bf16 v[28:31], v[148:151], v[224:227], v[28:31]
	s_cselect_b32 s17, s27, s17
	v_mfma_f32_16x16x32_bf16 v[24:27], v[156:159], v[224:227], v[24:27]
	s_cselect_b32 s16, s26, s31
	v_mfma_f32_16x16x32_bf16 v[12:15], v[148:151], v[232:235], v[12:15]
	s_cselect_b32 s43, s29, s11
	v_mfma_f32_16x16x32_bf16 v[8:11], v[156:159], v[232:235], v[8:11]
	s_cselect_b32 s42, s28, s10
	v_mfma_f32_16x16x32_bf16 v[52:55], v[160:163], v[194:197], v[52:55]
	s_add_i32 s31, 0, 0x14000
	v_mfma_f32_16x16x32_bf16 v[48:51], v[172:175], v[194:197], v[48:51]
	v_mfma_f32_16x16x32_bf16 v[36:39], v[160:163], v[210:213], v[36:39]
	v_mfma_f32_16x16x32_bf16 v[32:35], v[172:175], v[210:213], v[32:35]
	v_mfma_f32_16x16x32_bf16 v[20:23], v[160:163], v[220:223], v[20:23]
	v_mfma_f32_16x16x32_bf16 v[16:19], v[172:175], v[220:223], v[16:19]
	v_mfma_f32_16x16x32_bf16 v[4:7], v[160:163], v[228:231], v[4:7]
	v_mfma_f32_16x16x32_bf16 v[0:3], v[172:175], v[228:231], v[0:3]
	v_mfma_f32_16x16x32_bf16 v[52:55], v[168:171], v[206:209], v[52:55]
	v_mfma_f32_16x16x32_bf16 v[48:51], v[176:179], v[206:209], v[48:51]
	v_mfma_f32_16x16x32_bf16 v[36:39], v[168:171], v[214:217], v[36:39]
	v_mfma_f32_16x16x32_bf16 v[32:35], v[176:179], v[214:217], v[32:35]
	v_mfma_f32_16x16x32_bf16 v[20:23], v[168:171], v[224:227], v[20:23]
	v_mfma_f32_16x16x32_bf16 v[16:19], v[176:179], v[224:227], v[16:19]
	v_mfma_f32_16x16x32_bf16 v[4:7], v[168:171], v[232:235], v[4:7]
	v_mfma_f32_16x16x32_bf16 v[0:3], v[176:179], v[232:235], v[0:3]
	s_barrier
	s_cmp_lg_u32 s99, 0
	s_cbranch_scc1 .Lpeelx_12
.LBB0_844:
	v_add_u32_e32 v156, s35, v164
	v_add_u32_e32 v167, s31, v164
	ds_read_b128 v[144:147], v156
	ds_read_b128 v[148:151], v156 offset:1024
	ds_read_b128 v[152:155], v156 offset:2048
	ds_read_b128 v[156:159], v156 offset:3072
	ds_read_b128 v[160:163], v167
	ds_read_b128 v[168:171], v167 offset:1024
	ds_read_b128 v[172:175], v167 offset:2048
	ds_read_b128 v[176:179], v167 offset:3072
	v_lshl_add_u64 v[198:199], s[0:1], 0, v[140:141]
	s_add_i32 m0, s39, 0xc000
	ds_read_b128 v[194:197], v166
	ds_read_b128 v[206:209], v166 offset:1024
	ds_read_b128 v[210:213], v166 offset:2048
	ds_read_b128 v[214:217], v166 offset:3072
	ds_read_b128 v[220:223], v166 offset:4096
	ds_read_b128 v[224:227], v166 offset:5120
	ds_read_b128 v[228:231], v166 offset:6144
	ds_read_b128 v[232:235], v166 offset:7168
	global_load_lds_dwordx4 v[198:199], off
	v_lshl_add_u64 v[198:199], s[0:1], 0, v[142:143]
	s_add_i32 m0, s39, 0xe000
	s_nop 0
	global_load_lds_dwordx4 v[198:199], off
	s_waitcnt vmcnt(8)
	s_waitcnt lgkmcnt(0)
	s_barrier
	s_waitcnt lgkmcnt(0)
	v_mfma_f32_16x16x32_bf16 v[124:127], v[144:147], v[194:197], v[124:127]
	v_mfma_f32_16x16x32_bf16 v[120:123], v[152:155], v[194:197], v[120:123]
	v_mfma_f32_16x16x32_bf16 v[108:111], v[144:147], v[210:213], v[108:111]
	v_mfma_f32_16x16x32_bf16 v[104:107], v[152:155], v[210:213], v[104:107]
	v_mfma_f32_16x16x32_bf16 v[92:95], v[144:147], v[220:223], v[92:95]
	v_mfma_f32_16x16x32_bf16 v[88:91], v[152:155], v[220:223], v[88:91]
	v_mfma_f32_16x16x32_bf16 v[76:79], v[144:147], v[228:231], v[76:79]
	v_mfma_f32_16x16x32_bf16 v[72:75], v[152:155], v[228:231], v[72:75]
	v_mfma_f32_16x16x32_bf16 v[124:127], v[148:151], v[206:209], v[124:127]
	v_mfma_f32_16x16x32_bf16 v[120:123], v[156:159], v[206:209], v[120:123]
	v_mfma_f32_16x16x32_bf16 v[108:111], v[148:151], v[214:217], v[108:111]
	v_mfma_f32_16x16x32_bf16 v[104:107], v[156:159], v[214:217], v[104:107]
	v_mfma_f32_16x16x32_bf16 v[92:95], v[148:151], v[224:227], v[92:95]
	v_mfma_f32_16x16x32_bf16 v[88:91], v[156:159], v[224:227], v[88:91]
	v_mfma_f32_16x16x32_bf16 v[76:79], v[148:151], v[232:235], v[76:79]
	v_mfma_f32_16x16x32_bf16 v[72:75], v[156:159], v[232:235], v[72:75]
	v_mfma_f32_16x16x32_bf16 v[116:119], v[160:163], v[194:197], v[116:119]
	v_mfma_f32_16x16x32_bf16 v[112:115], v[172:175], v[194:197], v[112:115]
	v_mfma_f32_16x16x32_bf16 v[100:103], v[160:163], v[210:213], v[100:103]
	v_mfma_f32_16x16x32_bf16 v[96:99], v[172:175], v[210:213], v[96:99]
	v_mfma_f32_16x16x32_bf16 v[84:87], v[160:163], v[220:223], v[84:87]
	v_mfma_f32_16x16x32_bf16 v[80:83], v[172:175], v[220:223], v[80:83]
	v_mfma_f32_16x16x32_bf16 v[68:71], v[160:163], v[228:231], v[68:71]
	v_mfma_f32_16x16x32_bf16 v[64:67], v[172:175], v[228:231], v[64:67]
	v_mfma_f32_16x16x32_bf16 v[116:119], v[168:171], v[206:209], v[116:119]
	v_mfma_f32_16x16x32_bf16 v[112:115], v[176:179], v[206:209], v[112:115]
	v_mfma_f32_16x16x32_bf16 v[100:103], v[168:171], v[214:217], v[100:103]
	v_mfma_f32_16x16x32_bf16 v[96:99], v[176:179], v[214:217], v[96:99]
	v_mfma_f32_16x16x32_bf16 v[84:87], v[168:171], v[224:227], v[84:87]
	v_mfma_f32_16x16x32_bf16 v[80:83], v[176:179], v[224:227], v[80:83]
	v_mfma_f32_16x16x32_bf16 v[68:71], v[168:171], v[232:235], v[68:71]
	v_mfma_f32_16x16x32_bf16 v[64:67], v[176:179], v[232:235], v[64:67]
	s_barrier
	s_add_i32 s35, s35, s38
	v_lshl_add_u64 v[198:199], s[42:43], 0, v[132:133]
	s_mov_b32 m0, s35
	ds_read_b128 v[194:197], v166 offset:16384
	ds_read_b128 v[206:209], v166 offset:17408
	ds_read_b128 v[210:213], v166 offset:18432
	ds_read_b128 v[214:217], v166 offset:19456
	ds_read_b128 v[220:223], v166 offset:20480
	ds_read_b128 v[224:227], v166 offset:21504
	ds_read_b128 v[228:231], v166 offset:22528
	ds_read_b128 v[232:235], v166 offset:23552
	global_load_lds_dwordx4 v[198:199], off
	s_add_i32 m0, s35, 0x2000
	v_lshl_add_u64 v[202:203], s[42:43], 0, v[128:129]
	s_add_u32 s42, s42, s6
	s_addc_u32 s43, s43, s7
	s_add_i32 s31, s31, s38
	global_load_lds_dwordx4 v[202:203], off
	v_lshl_add_u64 v[236:237], s[42:43], 0, v[132:133]
	s_mov_b32 m0, s31
	v_lshl_add_u64 v[238:239], s[42:43], 0, v[128:129]
	global_load_lds_dwordx4 v[236:237], off
	s_add_i32 m0, s31, 0x2000
	v_lshl_add_u64 v[240:241], s[16:17], 0, v[134:135]
	global_load_lds_dwordx4 v[238:239], off
	s_mov_b32 m0, s39
	v_lshl_add_u64 v[242:243], s[16:17], 0, v[130:131]
	global_load_lds_dwordx4 v[240:241], off
	s_mov_b32 m0, s44
	s_nop 0
	global_load_lds_dwordx4 v[242:243], off
	s_waitcnt vmcnt(8)
	s_waitcnt lgkmcnt(0)
	s_barrier
	s_waitcnt lgkmcnt(0)
	v_mfma_f32_16x16x32_bf16 v[60:63], v[144:147], v[194:197], v[60:63]
	v_mfma_f32_16x16x32_bf16 v[56:59], v[152:155], v[194:197], v[56:59]
	v_mfma_f32_16x16x32_bf16 v[44:47], v[144:147], v[210:213], v[44:47]
	v_mfma_f32_16x16x32_bf16 v[40:43], v[152:155], v[210:213], v[40:43]
	v_mfma_f32_16x16x32_bf16 v[28:31], v[144:147], v[220:223], v[28:31]
	v_mfma_f32_16x16x32_bf16 v[24:27], v[152:155], v[220:223], v[24:27]
	v_mfma_f32_16x16x32_bf16 v[12:15], v[144:147], v[228:231], v[12:15]
	v_mfma_f32_16x16x32_bf16 v[8:11], v[152:155], v[228:231], v[8:11]
	v_mfma_f32_16x16x32_bf16 v[60:63], v[148:151], v[206:209], v[60:63]
	v_mfma_f32_16x16x32_bf16 v[56:59], v[156:159], v[206:209], v[56:59]
	v_mfma_f32_16x16x32_bf16 v[44:47], v[148:151], v[214:217], v[44:47]
	v_mfma_f32_16x16x32_bf16 v[40:43], v[156:159], v[214:217], v[40:43]
	v_mfma_f32_16x16x32_bf16 v[28:31], v[148:151], v[224:227], v[28:31]
	v_mfma_f32_16x16x32_bf16 v[24:27], v[156:159], v[224:227], v[24:27]
	v_mfma_f32_16x16x32_bf16 v[12:15], v[148:151], v[232:235], v[12:15]
	v_mfma_f32_16x16x32_bf16 v[8:11], v[156:159], v[232:235], v[8:11]
	v_mfma_f32_16x16x32_bf16 v[52:55], v[160:163], v[194:197], v[52:55]
	v_mfma_f32_16x16x32_bf16 v[48:51], v[172:175], v[194:197], v[48:51]
	v_mfma_f32_16x16x32_bf16 v[36:39], v[160:163], v[210:213], v[36:39]
	v_mfma_f32_16x16x32_bf16 v[32:35], v[172:175], v[210:213], v[32:35]
	v_mfma_f32_16x16x32_bf16 v[20:23], v[160:163], v[220:223], v[20:23]
	v_mfma_f32_16x16x32_bf16 v[16:19], v[172:175], v[220:223], v[16:19]
	v_mfma_f32_16x16x32_bf16 v[4:7], v[160:163], v[228:231], v[4:7]
	v_mfma_f32_16x16x32_bf16 v[0:3], v[172:175], v[228:231], v[0:3]
	v_mfma_f32_16x16x32_bf16 v[52:55], v[168:171], v[206:209], v[52:55]
	v_mfma_f32_16x16x32_bf16 v[48:51], v[176:179], v[206:209], v[48:51]
	v_mfma_f32_16x16x32_bf16 v[36:39], v[168:171], v[214:217], v[36:39]
	v_mfma_f32_16x16x32_bf16 v[32:35], v[176:179], v[214:217], v[32:35]
	v_mfma_f32_16x16x32_bf16 v[20:23], v[168:171], v[224:227], v[20:23]
	v_mfma_f32_16x16x32_bf16 v[16:19], v[176:179], v[224:227], v[16:19]
	v_mfma_f32_16x16x32_bf16 v[4:7], v[168:171], v[232:235], v[4:7]
	v_mfma_f32_16x16x32_bf16 v[0:3], v[176:179], v[232:235], v[0:3]
	s_barrier
	s_add_i32 s31, 0, 0x18000
	s_add_i32 s35, 0, 0x1c000
	v_add_u32_e32 v156, s31, v164
	v_add_u32_e32 v167, s35, v164
	ds_read_b128 v[144:147], v156
	ds_read_b128 v[148:151], v156 offset:1024
	ds_read_b128 v[152:155], v156 offset:2048
	ds_read_b128 v[156:159], v156 offset:3072
	ds_read_b128 v[160:163], v167
	ds_read_b128 v[168:171], v167 offset:1024
	ds_read_b128 v[172:175], v167 offset:2048
	ds_read_b128 v[176:179], v167 offset:3072
	s_add_u32 s16, s16, s6
	s_addc_u32 s17, s17, s7
	s_mov_b32 m0, s45
	v_lshl_add_u64 v[244:245], s[16:17], 0, v[134:135]
	ds_read_b128 v[194:197], v166 offset:32768
	ds_read_b128 v[206:209], v166 offset:33792
	ds_read_b128 v[210:213], v166 offset:34816
	ds_read_b128 v[214:217], v166 offset:35840
	ds_read_b128 v[220:223], v166 offset:36864
	ds_read_b128 v[224:227], v166 offset:37888
	ds_read_b128 v[228:231], v166 offset:38912
	ds_read_b128 v[232:235], v166 offset:39936
	global_load_lds_dwordx4 v[244:245], off
	v_lshl_add_u64 v[244:245], s[16:17], 0, v[130:131]
	s_mov_b32 m0, s46
	s_nop 0
	global_load_lds_dwordx4 v[244:245], off
	s_waitcnt vmcnt(8)
	s_waitcnt lgkmcnt(0)
	s_barrier
	s_waitcnt lgkmcnt(0)
	v_mfma_f32_16x16x32_bf16 v[124:127], v[144:147], v[194:197], v[124:127]
	v_mfma_f32_16x16x32_bf16 v[120:123], v[152:155], v[194:197], v[120:123]
	v_mfma_f32_16x16x32_bf16 v[108:111], v[144:147], v[210:213], v[108:111]
	v_mfma_f32_16x16x32_bf16 v[104:107], v[152:155], v[210:213], v[104:107]
	v_mfma_f32_16x16x32_bf16 v[92:95], v[144:147], v[220:223], v[92:95]
	v_mfma_f32_16x16x32_bf16 v[88:91], v[152:155], v[220:223], v[88:91]
	v_mfma_f32_16x16x32_bf16 v[76:79], v[144:147], v[228:231], v[76:79]
	v_mfma_f32_16x16x32_bf16 v[72:75], v[152:155], v[228:231], v[72:75]
	v_mfma_f32_16x16x32_bf16 v[124:127], v[148:151], v[206:209], v[124:127]
	v_mfma_f32_16x16x32_bf16 v[120:123], v[156:159], v[206:209], v[120:123]
	v_mfma_f32_16x16x32_bf16 v[108:111], v[148:151], v[214:217], v[108:111]
	v_mfma_f32_16x16x32_bf16 v[104:107], v[156:159], v[214:217], v[104:107]
	v_mfma_f32_16x16x32_bf16 v[92:95], v[148:151], v[224:227], v[92:95]
	v_mfma_f32_16x16x32_bf16 v[88:91], v[156:159], v[224:227], v[88:91]
	v_mfma_f32_16x16x32_bf16 v[76:79], v[148:151], v[232:235], v[76:79]
	v_mfma_f32_16x16x32_bf16 v[72:75], v[156:159], v[232:235], v[72:75]
	v_mfma_f32_16x16x32_bf16 v[116:119], v[160:163], v[194:197], v[116:119]
	v_mfma_f32_16x16x32_bf16 v[112:115], v[172:175], v[194:197], v[112:115]
	v_mfma_f32_16x16x32_bf16 v[100:103], v[160:163], v[210:213], v[100:103]
	v_mfma_f32_16x16x32_bf16 v[96:99], v[172:175], v[210:213], v[96:99]
	v_mfma_f32_16x16x32_bf16 v[84:87], v[160:163], v[220:223], v[84:87]
	v_mfma_f32_16x16x32_bf16 v[80:83], v[172:175], v[220:223], v[80:83]
	v_mfma_f32_16x16x32_bf16 v[68:71], v[160:163], v[228:231], v[68:71]
	v_mfma_f32_16x16x32_bf16 v[64:67], v[172:175], v[228:231], v[64:67]
	v_mfma_f32_16x16x32_bf16 v[116:119], v[168:171], v[206:209], v[116:119]
	v_mfma_f32_16x16x32_bf16 v[112:115], v[176:179], v[206:209], v[112:115]
	v_mfma_f32_16x16x32_bf16 v[100:103], v[168:171], v[214:217], v[100:103]
	v_mfma_f32_16x16x32_bf16 v[96:99], v[176:179], v[214:217], v[96:99]
	v_mfma_f32_16x16x32_bf16 v[84:87], v[168:171], v[224:227], v[84:87]
	v_mfma_f32_16x16x32_bf16 v[80:83], v[176:179], v[224:227], v[80:83]
	v_mfma_f32_16x16x32_bf16 v[68:71], v[168:171], v[232:235], v[68:71]
	v_mfma_f32_16x16x32_bf16 v[64:67], v[176:179], v[232:235], v[64:67]
	s_barrier
	s_add_i32 s16, s31, s38
	v_lshl_add_u64 v[198:199], v[198:199], 0, s[12:13]
	s_mov_b32 m0, s16
	ds_read_b128 v[194:197], v166 offset:49152
	ds_read_b128 v[206:209], v166 offset:50176
	ds_read_b128 v[210:213], v166 offset:51200
	ds_read_b128 v[214:217], v166 offset:52224
	ds_read_b128 v[220:223], v166 offset:53248
	ds_read_b128 v[224:227], v166 offset:54272
	ds_read_b128 v[228:231], v166 offset:55296
	ds_read_b128 v[232:235], v166 offset:56320
	global_load_lds_dwordx4 v[198:199], off
	v_lshl_add_u64 v[198:199], v[202:203], 0, s[12:13]
	s_add_i32 m0, s16, 0x2000
	s_add_i32 s16, s35, s38
	global_load_lds_dwordx4 v[198:199], off
	v_lshl_add_u64 v[198:199], v[236:237], 0, s[12:13]
	s_mov_b32 m0, s16
	s_nop 0
	global_load_lds_dwordx4 v[198:199], off
	v_lshl_add_u64 v[198:199], v[238:239], 0, s[12:13]
	s_add_i32 m0, s16, 0x2000
	s_nop 0
	global_load_lds_dwordx4 v[198:199], off
	v_lshl_add_u64 v[198:199], v[240:241], 0, s[12:13]
	s_mov_b32 m0, s47
	s_nop 0
	global_load_lds_dwordx4 v[198:199], off
	v_lshl_add_u64 v[198:199], v[242:243], 0, s[12:13]
	s_mov_b32 m0, s48
	s_nop 0
	global_load_lds_dwordx4 v[198:199], off
	s_waitcnt vmcnt(8)
	s_waitcnt lgkmcnt(0)
	s_barrier
	s_waitcnt lgkmcnt(0)
	v_mfma_f32_16x16x32_bf16 v[60:63], v[144:147], v[194:197], v[60:63]
	s_add_u32 s0, s0, 0x100
	v_mfma_f32_16x16x32_bf16 v[56:59], v[152:155], v[194:197], v[56:59]
	s_addc_u32 s1, s1, 0
	v_mfma_f32_16x16x32_bf16 v[44:47], v[144:147], v[210:213], v[44:47]
	s_add_u32 s10, s10, 0x100
	v_mfma_f32_16x16x32_bf16 v[40:43], v[152:155], v[210:213], v[40:43]
	s_addc_u32 s11, s11, 0
	v_mfma_f32_16x16x32_bf16 v[28:31], v[144:147], v[220:223], v[28:31]
	s_mov_b32 s16, s30
	v_mfma_f32_16x16x32_bf16 v[24:27], v[152:155], v[220:223], v[24:27]
	s_cmp_ge_i32 s30, s49
	v_mfma_f32_16x16x32_bf16 v[12:15], v[144:147], v[228:231], v[12:15]
	s_cselect_b32 s99, 1, 0
	v_mfma_f32_16x16x32_bf16 v[8:11], v[152:155], v[228:231], v[8:11]
	s_add_i32 s30, s16, 2
	v_mfma_f32_16x16x32_bf16 v[60:63], v[148:151], v[206:209], v[60:63]
	s_add_u32 s31, s0, 0x80
	v_mfma_f32_16x16x32_bf16 v[56:59], v[156:159], v[206:209], v[56:59]
	s_addc_u32 s17, s1, 0
	v_mfma_f32_16x16x32_bf16 v[44:47], v[148:151], v[214:217], v[44:47]
	s_add_i32 s35, 0, 0x10000
	v_mfma_f32_16x16x32_bf16 v[40:43], v[156:159], v[214:217], v[40:43]
	s_cmp_eq_u32 s57, s16
	v_mfma_f32_16x16x32_bf16 v[28:31], v[148:151], v[224:227], v[28:31]
	s_cselect_b32 s17, s27, s17
	v_mfma_f32_16x16x32_bf16 v[24:27], v[156:159], v[224:227], v[24:27]
	s_cselect_b32 s16, s26, s31
	v_mfma_f32_16x16x32_bf16 v[12:15], v[148:151], v[232:235], v[12:15]
	s_cselect_b32 s43, s29, s11
	v_mfma_f32_16x16x32_bf16 v[8:11], v[156:159], v[232:235], v[8:11]
	s_cselect_b32 s42, s28, s10
	v_mfma_f32_16x16x32_bf16 v[52:55], v[160:163], v[194:197], v[52:55]
	s_add_i32 s31, 0, 0x14000
	v_mfma_f32_16x16x32_bf16 v[48:51], v[172:175], v[194:197], v[48:51]
	v_mfma_f32_16x16x32_bf16 v[36:39], v[160:163], v[210:213], v[36:39]
	v_mfma_f32_16x16x32_bf16 v[32:35], v[172:175], v[210:213], v[32:35]
	v_mfma_f32_16x16x32_bf16 v[20:23], v[160:163], v[220:223], v[20:23]
	v_mfma_f32_16x16x32_bf16 v[16:19], v[172:175], v[220:223], v[16:19]
	v_mfma_f32_16x16x32_bf16 v[4:7], v[160:163], v[228:231], v[4:7]
	v_mfma_f32_16x16x32_bf16 v[0:3], v[172:175], v[228:231], v[0:3]
	v_mfma_f32_16x16x32_bf16 v[52:55], v[168:171], v[206:209], v[52:55]
	v_mfma_f32_16x16x32_bf16 v[48:51], v[176:179], v[206:209], v[48:51]
	v_mfma_f32_16x16x32_bf16 v[36:39], v[168:171], v[214:217], v[36:39]
	v_mfma_f32_16x16x32_bf16 v[32:35], v[176:179], v[214:217], v[32:35]
	v_mfma_f32_16x16x32_bf16 v[20:23], v[168:171], v[224:227], v[20:23]
	v_mfma_f32_16x16x32_bf16 v[16:19], v[176:179], v[224:227], v[16:19]
	v_mfma_f32_16x16x32_bf16 v[4:7], v[168:171], v[232:235], v[4:7]
	v_mfma_f32_16x16x32_bf16 v[0:3], v[176:179], v[232:235], v[0:3]
	s_barrier
	s_cmp_lg_u32 s99, 0
	s_cbranch_scc0 .LBB0_844

.Llbb_9:
	s_add_i32 s30, s16, 2
	s_add_u32 s31, s28, 0x80
	s_addc_u32 s17, s29, 0
	s_add_i32 s62, 0, 0x10000
	s_cmp_eq_u32 s56, s16
	s_cselect_b32 s17, s25, s17
	s_cselect_b32 s16, s24, s31
	s_cselect_b32 s45, s27, s11
	s_cselect_b32 s44, s26, s10
	s_add_i32 s31, 0, 0x14000
	v_add_u32_e32 v140, s62, v199
	v_add_u32_e32 v166, s31, v199
	ds_read_b128 v[128:131], v140
	ds_read_b128 v[132:135], v140 offset:1024
	ds_read_b128 v[136:139], v140 offset:2048
	ds_read_b128 v[140:143], v140 offset:3072
	ds_read_b128 v[144:147], v166
	ds_read_b128 v[148:151], v166 offset:1024
	ds_read_b128 v[152:155], v166 offset:2048
	ds_read_b128 v[166:169], v166 offset:3072
	v_lshl_add_u64 v[178:179], s[28:29], 0, v[162:163]
	s_add_i32 m0, s37, 0xc000
	ds_read_b128 v[170:173], v206
	ds_read_b128 v[174:177], v206 offset:1024
	ds_read_b128 v[194:197], v206 offset:2048
	ds_read_b128 v[208:211], v206 offset:3072
	ds_read_b128 v[212:215], v206 offset:4096
	ds_read_b128 v[220:223], v206 offset:5120
	ds_read_b128 v[224:227], v206 offset:6144
	ds_read_b128 v[228:231], v206 offset:7168
	global_load_lds_dwordx4 v[178:179], off
	v_lshl_add_u64 v[178:179], s[28:29], 0, v[164:165]
	s_add_i32 m0, s37, 0xe000
	s_nop 0
	global_load_lds_dwordx4 v[178:179], off
	s_waitcnt vmcnt(8)
	s_waitcnt lgkmcnt(0)
	s_barrier
	s_waitcnt lgkmcnt(0)
	v_mfma_f32_16x16x32_bf16 v[120:123], v[128:131], v[170:173], 0
	v_mfma_f32_16x16x32_bf16 v[124:127], v[136:139], v[170:173], 0
	v_mfma_f32_16x16x32_bf16 v[108:111], v[128:131], v[194:197], 0
	v_mfma_f32_16x16x32_bf16 v[104:107], v[136:139], v[194:197], 0
	v_mfma_f32_16x16x32_bf16 v[92:95], v[128:131], v[212:215], 0
	v_mfma_f32_16x16x32_bf16 v[88:91], v[136:139], v[212:215], 0
	v_mfma_f32_16x16x32_bf16 v[76:79], v[128:131], v[224:227], 0
	v_mfma_f32_16x16x32_bf16 v[72:75], v[136:139], v[224:227], 0
	v_mfma_f32_16x16x32_bf16 v[120:123], v[132:135], v[174:177], v[120:123]
	v_mfma_f32_16x16x32_bf16 v[124:127], v[140:143], v[174:177], v[124:127]
	v_mfma_f32_16x16x32_bf16 v[108:111], v[132:135], v[208:211], v[108:111]
	v_mfma_f32_16x16x32_bf16 v[104:107], v[140:143], v[208:211], v[104:107]
	v_mfma_f32_16x16x32_bf16 v[92:95], v[132:135], v[220:223], v[92:95]
	v_mfma_f32_16x16x32_bf16 v[88:91], v[140:143], v[220:223], v[88:91]
	v_mfma_f32_16x16x32_bf16 v[76:79], v[132:135], v[228:231], v[76:79]
	v_mfma_f32_16x16x32_bf16 v[72:75], v[140:143], v[228:231], v[72:75]
	v_mfma_f32_16x16x32_bf16 v[116:119], v[144:147], v[170:173], 0
	v_mfma_f32_16x16x32_bf16 v[112:115], v[152:155], v[170:173], 0
	v_mfma_f32_16x16x32_bf16 v[100:103], v[144:147], v[194:197], 0
	v_mfma_f32_16x16x32_bf16 v[96:99], v[152:155], v[194:197], 0
	v_mfma_f32_16x16x32_bf16 v[84:87], v[144:147], v[212:215], 0
	v_mfma_f32_16x16x32_bf16 v[80:83], v[152:155], v[212:215], 0
	v_mfma_f32_16x16x32_bf16 v[68:71], v[144:147], v[224:227], 0
	v_mfma_f32_16x16x32_bf16 v[64:67], v[152:155], v[224:227], 0
	v_mfma_f32_16x16x32_bf16 v[116:119], v[148:151], v[174:177], v[116:119]
	v_mfma_f32_16x16x32_bf16 v[112:115], v[166:169], v[174:177], v[112:115]
	v_mfma_f32_16x16x32_bf16 v[100:103], v[148:151], v[208:211], v[100:103]
	v_mfma_f32_16x16x32_bf16 v[96:99], v[166:169], v[208:211], v[96:99]
	v_mfma_f32_16x16x32_bf16 v[84:87], v[148:151], v[220:223], v[84:87]
	v_mfma_f32_16x16x32_bf16 v[80:83], v[166:169], v[220:223], v[80:83]
	v_mfma_f32_16x16x32_bf16 v[68:71], v[148:151], v[228:231], v[68:71]
	v_mfma_f32_16x16x32_bf16 v[64:67], v[166:169], v[228:231], v[64:67]
	s_barrier
	s_add_i32 s62, s62, s36
	v_lshl_add_u64 v[178:179], s[44:45], 0, v[180:181]
	s_mov_b32 m0, s62
	ds_read_b128 v[170:173], v206 offset:16384
	ds_read_b128 v[174:177], v206 offset:17408
	ds_read_b128 v[194:197], v206 offset:18432
	ds_read_b128 v[208:211], v206 offset:19456
	ds_read_b128 v[212:215], v206 offset:20480
	ds_read_b128 v[220:223], v206 offset:21504
	ds_read_b128 v[224:227], v206 offset:22528
	ds_read_b128 v[228:231], v206 offset:23552
	global_load_lds_dwordx4 v[178:179], off
	s_add_i32 m0, s62, 0x2000
	v_lshl_add_u64 v[202:203], s[44:45], 0, v[156:157]
	s_add_u32 s44, s44, s6
	s_addc_u32 s45, s45, s7
	s_add_i32 s31, s31, s36
	global_load_lds_dwordx4 v[202:203], off
	v_lshl_add_u64 v[216:217], s[44:45], 0, v[180:181]
	s_mov_b32 m0, s31
	v_lshl_add_u64 v[232:233], s[44:45], 0, v[156:157]
	global_load_lds_dwordx4 v[216:217], off
	s_add_i32 m0, s31, 0x2000
	v_lshl_add_u64 v[234:235], s[16:17], 0, v[160:161]
	global_load_lds_dwordx4 v[232:233], off
	s_mov_b32 m0, s37
	v_lshl_add_u64 v[236:237], s[16:17], 0, v[158:159]
	global_load_lds_dwordx4 v[234:235], off
	s_mov_b32 m0, s38
	s_nop 0
	global_load_lds_dwordx4 v[236:237], off
	s_waitcnt vmcnt(8)
	s_waitcnt lgkmcnt(0)
	s_barrier
	s_waitcnt lgkmcnt(0)
	v_mfma_f32_16x16x32_bf16 v[60:63], v[128:131], v[170:173], 0
	v_mfma_f32_16x16x32_bf16 v[56:59], v[136:139], v[170:173], 0
	v_mfma_f32_16x16x32_bf16 v[44:47], v[128:131], v[194:197], 0
	v_mfma_f32_16x16x32_bf16 v[40:43], v[136:139], v[194:197], 0
	v_mfma_f32_16x16x32_bf16 v[28:31], v[128:131], v[212:215], 0
	v_mfma_f32_16x16x32_bf16 v[24:27], v[136:139], v[212:215], 0
	v_mfma_f32_16x16x32_bf16 v[12:15], v[128:131], v[224:227], 0
	v_mfma_f32_16x16x32_bf16 v[8:11], v[136:139], v[224:227], 0
	v_mfma_f32_16x16x32_bf16 v[60:63], v[132:135], v[174:177], v[60:63]
	v_mfma_f32_16x16x32_bf16 v[56:59], v[140:143], v[174:177], v[56:59]
	v_mfma_f32_16x16x32_bf16 v[44:47], v[132:135], v[208:211], v[44:47]
	v_mfma_f32_16x16x32_bf16 v[40:43], v[140:143], v[208:211], v[40:43]
	v_mfma_f32_16x16x32_bf16 v[28:31], v[132:135], v[220:223], v[28:31]
	v_mfma_f32_16x16x32_bf16 v[24:27], v[140:143], v[220:223], v[24:27]
	v_mfma_f32_16x16x32_bf16 v[12:15], v[132:135], v[228:231], v[12:15]
	v_mfma_f32_16x16x32_bf16 v[8:11], v[140:143], v[228:231], v[8:11]
	v_mfma_f32_16x16x32_bf16 v[52:55], v[144:147], v[170:173], 0
	v_mfma_f32_16x16x32_bf16 v[48:51], v[152:155], v[170:173], 0
	v_mfma_f32_16x16x32_bf16 v[36:39], v[144:147], v[194:197], 0
	v_mfma_f32_16x16x32_bf16 v[32:35], v[152:155], v[194:197], 0
	v_mfma_f32_16x16x32_bf16 v[20:23], v[144:147], v[212:215], 0
	v_mfma_f32_16x16x32_bf16 v[16:19], v[152:155], v[212:215], 0
	v_mfma_f32_16x16x32_bf16 v[4:7], v[144:147], v[224:227], 0
	v_mfma_f32_16x16x32_bf16 v[0:3], v[152:155], v[224:227], 0
	v_mfma_f32_16x16x32_bf16 v[52:55], v[148:151], v[174:177], v[52:55]
	v_mfma_f32_16x16x32_bf16 v[48:51], v[166:169], v[174:177], v[48:51]
	v_mfma_f32_16x16x32_bf16 v[36:39], v[148:151], v[208:211], v[36:39]
	v_mfma_f32_16x16x32_bf16 v[32:35], v[166:169], v[208:211], v[32:35]
	v_mfma_f32_16x16x32_bf16 v[20:23], v[148:151], v[220:223], v[20:23]
	v_mfma_f32_16x16x32_bf16 v[16:19], v[166:169], v[220:223], v[16:19]
	v_mfma_f32_16x16x32_bf16 v[4:7], v[148:151], v[228:231], v[4:7]
	v_mfma_f32_16x16x32_bf16 v[0:3], v[166:169], v[228:231], v[0:3]
	s_barrier
	s_add_i32 s31, 0, 0x18000
	s_add_i32 s44, 0, 0x1c000
	v_add_u32_e32 v140, s31, v199
	v_add_u32_e32 v166, s44, v199
	ds_read_b128 v[128:131], v140
	ds_read_b128 v[132:135], v140 offset:1024
	ds_read_b128 v[136:139], v140 offset:2048
	ds_read_b128 v[140:143], v140 offset:3072
	ds_read_b128 v[144:147], v166
	ds_read_b128 v[148:151], v166 offset:1024
	ds_read_b128 v[152:155], v166 offset:2048
	ds_read_b128 v[166:169], v166 offset:3072
	s_add_u32 s16, s16, s6
	s_addc_u32 s17, s17, s7
	s_mov_b32 m0, s39
	v_lshl_add_u64 v[238:239], s[16:17], 0, v[160:161]
	ds_read_b128 v[170:173], v206 offset:32768
	ds_read_b128 v[174:177], v206 offset:33792
	ds_read_b128 v[194:197], v206 offset:34816
	ds_read_b128 v[208:211], v206 offset:35840
	ds_read_b128 v[212:215], v206 offset:36864
	ds_read_b128 v[220:223], v206 offset:37888
	ds_read_b128 v[224:227], v206 offset:38912
	ds_read_b128 v[228:231], v206 offset:39936
	global_load_lds_dwordx4 v[238:239], off
	v_lshl_add_u64 v[238:239], s[16:17], 0, v[158:159]
	s_mov_b32 m0, s46
	s_nop 0
	global_load_lds_dwordx4 v[238:239], off
	s_waitcnt vmcnt(8)
	s_waitcnt lgkmcnt(0)
	s_barrier
	s_waitcnt lgkmcnt(0)
	v_mfma_f32_16x16x32_bf16 v[120:123], v[128:131], v[170:173], v[120:123]
	v_mfma_f32_16x16x32_bf16 v[124:127], v[136:139], v[170:173], v[124:127]
	v_mfma_f32_16x16x32_bf16 v[108:111], v[128:131], v[194:197], v[108:111]
	v_mfma_f32_16x16x32_bf16 v[104:107], v[136:139], v[194:197], v[104:107]
	v_mfma_f32_16x16x32_bf16 v[92:95], v[128:131], v[212:215], v[92:95]
	v_mfma_f32_16x16x32_bf16 v[88:91], v[136:139], v[212:215], v[88:91]
	v_mfma_f32_16x16x32_bf16 v[76:79], v[128:131], v[224:227], v[76:79]
	v_mfma_f32_16x16x32_bf16 v[72:75], v[136:139], v[224:227], v[72:75]
	v_mfma_f32_16x16x32_bf16 v[120:123], v[132:135], v[174:177], v[120:123]
	v_mfma_f32_16x16x32_bf16 v[124:127], v[140:143], v[174:177], v[124:127]
	v_mfma_f32_16x16x32_bf16 v[108:111], v[132:135], v[208:211], v[108:111]
	v_mfma_f32_16x16x32_bf16 v[104:107], v[140:143], v[208:211], v[104:107]
	v_mfma_f32_16x16x32_bf16 v[92:95], v[132:135], v[220:223], v[92:95]
	v_mfma_f32_16x16x32_bf16 v[88:91], v[140:143], v[220:223], v[88:91]
	v_mfma_f32_16x16x32_bf16 v[76:79], v[132:135], v[228:231], v[76:79]
	v_mfma_f32_16x16x32_bf16 v[72:75], v[140:143], v[228:231], v[72:75]
	v_mfma_f32_16x16x32_bf16 v[116:119], v[144:147], v[170:173], v[116:119]
	v_mfma_f32_16x16x32_bf16 v[112:115], v[152:155], v[170:173], v[112:115]
	v_mfma_f32_16x16x32_bf16 v[100:103], v[144:147], v[194:197], v[100:103]
	v_mfma_f32_16x16x32_bf16 v[96:99], v[152:155], v[194:197], v[96:99]
	v_mfma_f32_16x16x32_bf16 v[84:87], v[144:147], v[212:215], v[84:87]
	v_mfma_f32_16x16x32_bf16 v[80:83], v[152:155], v[212:215], v[80:83]
	v_mfma_f32_16x16x32_bf16 v[68:71], v[144:147], v[224:227], v[68:71]
	v_mfma_f32_16x16x32_bf16 v[64:67], v[152:155], v[224:227], v[64:67]
	v_mfma_f32_16x16x32_bf16 v[116:119], v[148:151], v[174:177], v[116:119]
	v_mfma_f32_16x16x32_bf16 v[112:115], v[166:169], v[174:177], v[112:115]
	v_mfma_f32_16x16x32_bf16 v[100:103], v[148:151], v[208:211], v[100:103]
	v_mfma_f32_16x16x32_bf16 v[96:99], v[166:169], v[208:211], v[96:99]
	v_mfma_f32_16x16x32_bf16 v[84:87], v[148:151], v[220:223], v[84:87]
	v_mfma_f32_16x16x32_bf16 v[80:83], v[166:169], v[220:223], v[80:83]
	v_mfma_f32_16x16x32_bf16 v[68:71], v[148:151], v[228:231], v[68:71]
	v_mfma_f32_16x16x32_bf16 v[64:67], v[166:169], v[228:231], v[64:67]
	s_barrier
	s_add_i32 s16, s31, s36
	v_lshl_add_u64 v[178:179], v[178:179], 0, s[12:13]
	s_mov_b32 m0, s16
	ds_read_b128 v[170:173], v206 offset:49152
	ds_read_b128 v[174:177], v206 offset:50176
	ds_read_b128 v[194:197], v206 offset:51200
	ds_read_b128 v[208:211], v206 offset:52224
	ds_read_b128 v[212:215], v206 offset:53248
	ds_read_b128 v[220:223], v206 offset:54272
	ds_read_b128 v[224:227], v206 offset:55296
	ds_read_b128 v[228:231], v206 offset:56320
	global_load_lds_dwordx4 v[178:179], off
	v_lshl_add_u64 v[178:179], v[202:203], 0, s[12:13]
	s_add_i32 m0, s16, 0x2000
	s_add_i32 s16, s44, s36
	global_load_lds_dwordx4 v[178:179], off
	v_lshl_add_u64 v[178:179], v[216:217], 0, s[12:13]
	s_mov_b32 m0, s16
	s_nop 0
	global_load_lds_dwordx4 v[178:179], off
	v_lshl_add_u64 v[178:179], v[232:233], 0, s[12:13]
	s_add_i32 m0, s16, 0x2000
	s_nop 0
	global_load_lds_dwordx4 v[178:179], off
	v_lshl_add_u64 v[178:179], v[234:235], 0, s[12:13]
	s_mov_b32 m0, s49
	s_nop 0
	global_load_lds_dwordx4 v[178:179], off
	v_lshl_add_u64 v[178:179], v[236:237], 0, s[12:13]
	s_mov_b32 m0, s52
	s_nop 0
	global_load_lds_dwordx4 v[178:179], off
	s_waitcnt vmcnt(8)
	s_waitcnt lgkmcnt(0)
	s_barrier
	s_waitcnt lgkmcnt(0)
	v_mfma_f32_16x16x32_bf16 v[60:63], v[128:131], v[170:173], v[60:63]
	s_add_u32 s28, s28, 0x100
	v_mfma_f32_16x16x32_bf16 v[56:59], v[136:139], v[170:173], v[56:59]
	s_addc_u32 s29, s29, 0
	v_mfma_f32_16x16x32_bf16 v[44:47], v[128:131], v[194:197], v[44:47]
	s_add_u32 s10, s10, 0x100
	v_mfma_f32_16x16x32_bf16 v[40:43], v[136:139], v[194:197], v[40:43]
	s_addc_u32 s11, s11, 0
	v_mfma_f32_16x16x32_bf16 v[28:31], v[128:131], v[212:215], v[28:31]
	s_mov_b32 s16, s30
	v_mfma_f32_16x16x32_bf16 v[24:27], v[136:139], v[212:215], v[24:27]
	s_cmp_ge_i32 s30, s48
	v_mfma_f32_16x16x32_bf16 v[12:15], v[128:131], v[224:227], v[12:15]
	s_cselect_b32 s99, 1, 0
	v_mfma_f32_16x16x32_bf16 v[8:11], v[136:139], v[224:227], v[8:11]
	s_add_i32 s30, s16, 2
	v_mfma_f32_16x16x32_bf16 v[60:63], v[132:135], v[174:177], v[60:63]
	s_add_u32 s31, s28, 0x80
	v_mfma_f32_16x16x32_bf16 v[56:59], v[140:143], v[174:177], v[56:59]
	s_addc_u32 s17, s29, 0
	v_mfma_f32_16x16x32_bf16 v[44:47], v[132:135], v[208:211], v[44:47]
	s_add_i32 s62, 0, 0x10000
	v_mfma_f32_16x16x32_bf16 v[40:43], v[140:143], v[208:211], v[40:43]
	s_cmp_eq_u32 s56, s16
	v_mfma_f32_16x16x32_bf16 v[28:31], v[132:135], v[220:223], v[28:31]
	s_cselect_b32 s17, s25, s17
	v_mfma_f32_16x16x32_bf16 v[24:27], v[140:143], v[220:223], v[24:27]
	s_cselect_b32 s16, s24, s31
	v_mfma_f32_16x16x32_bf16 v[12:15], v[132:135], v[228:231], v[12:15]
	s_cselect_b32 s45, s27, s11
	v_mfma_f32_16x16x32_bf16 v[8:11], v[140:143], v[228:231], v[8:11]
	s_cselect_b32 s44, s26, s10
	v_mfma_f32_16x16x32_bf16 v[52:55], v[144:147], v[170:173], v[52:55]
	s_add_i32 s31, 0, 0x14000
	v_mfma_f32_16x16x32_bf16 v[48:51], v[152:155], v[170:173], v[48:51]
	v_mfma_f32_16x16x32_bf16 v[36:39], v[144:147], v[194:197], v[36:39]
	v_mfma_f32_16x16x32_bf16 v[32:35], v[152:155], v[194:197], v[32:35]
	v_mfma_f32_16x16x32_bf16 v[20:23], v[144:147], v[212:215], v[20:23]
	v_mfma_f32_16x16x32_bf16 v[16:19], v[152:155], v[212:215], v[16:19]
	v_mfma_f32_16x16x32_bf16 v[4:7], v[144:147], v[224:227], v[4:7]
	v_mfma_f32_16x16x32_bf16 v[0:3], v[152:155], v[224:227], v[0:3]
	v_mfma_f32_16x16x32_bf16 v[52:55], v[148:151], v[174:177], v[52:55]
	v_mfma_f32_16x16x32_bf16 v[48:51], v[166:169], v[174:177], v[48:51]
	v_mfma_f32_16x16x32_bf16 v[36:39], v[148:151], v[208:211], v[36:39]
	v_mfma_f32_16x16x32_bf16 v[32:35], v[166:169], v[208:211], v[32:35]
	v_mfma_f32_16x16x32_bf16 v[20:23], v[148:151], v[220:223], v[20:23]
	v_mfma_f32_16x16x32_bf16 v[16:19], v[166:169], v[220:223], v[16:19]
	v_mfma_f32_16x16x32_bf16 v[4:7], v[148:151], v[228:231], v[4:7]
	v_mfma_f32_16x16x32_bf16 v[0:3], v[166:169], v[228:231], v[0:3]
	s_barrier
	s_cmp_lg_u32 s99, 0
	s_cbranch_scc1 .Lpeelx_13
.LBB0_1053:
	v_add_u32_e32 v140, s62, v199
	v_add_u32_e32 v166, s31, v199
	ds_read_b128 v[128:131], v140
	ds_read_b128 v[132:135], v140 offset:1024
	ds_read_b128 v[136:139], v140 offset:2048
	ds_read_b128 v[140:143], v140 offset:3072
	ds_read_b128 v[144:147], v166
	ds_read_b128 v[148:151], v166 offset:1024
	ds_read_b128 v[152:155], v166 offset:2048
	ds_read_b128 v[166:169], v166 offset:3072
	v_lshl_add_u64 v[178:179], s[28:29], 0, v[162:163]
	s_add_i32 m0, s37, 0xc000
	ds_read_b128 v[170:173], v206
	ds_read_b128 v[174:177], v206 offset:1024
	ds_read_b128 v[194:197], v206 offset:2048
	ds_read_b128 v[208:211], v206 offset:3072
	ds_read_b128 v[212:215], v206 offset:4096
	ds_read_b128 v[220:223], v206 offset:5120
	ds_read_b128 v[224:227], v206 offset:6144
	ds_read_b128 v[228:231], v206 offset:7168
	global_load_lds_dwordx4 v[178:179], off
	v_lshl_add_u64 v[178:179], s[28:29], 0, v[164:165]
	s_add_i32 m0, s37, 0xe000
	s_nop 0
	global_load_lds_dwordx4 v[178:179], off
	s_waitcnt vmcnt(8)
	s_waitcnt lgkmcnt(0)
	s_barrier
	s_waitcnt lgkmcnt(0)
	v_mfma_f32_16x16x32_bf16 v[120:123], v[128:131], v[170:173], v[120:123]
	v_mfma_f32_16x16x32_bf16 v[124:127], v[136:139], v[170:173], v[124:127]
	v_mfma_f32_16x16x32_bf16 v[108:111], v[128:131], v[194:197], v[108:111]
	v_mfma_f32_16x16x32_bf16 v[104:107], v[136:139], v[194:197], v[104:107]
	v_mfma_f32_16x16x32_bf16 v[92:95], v[128:131], v[212:215], v[92:95]
	v_mfma_f32_16x16x32_bf16 v[88:91], v[136:139], v[212:215], v[88:91]
	v_mfma_f32_16x16x32_bf16 v[76:79], v[128:131], v[224:227], v[76:79]
	v_mfma_f32_16x16x32_bf16 v[72:75], v[136:139], v[224:227], v[72:75]
	v_mfma_f32_16x16x32_bf16 v[120:123], v[132:135], v[174:177], v[120:123]
	v_mfma_f32_16x16x32_bf16 v[124:127], v[140:143], v[174:177], v[124:127]
	v_mfma_f32_16x16x32_bf16 v[108:111], v[132:135], v[208:211], v[108:111]
	v_mfma_f32_16x16x32_bf16 v[104:107], v[140:143], v[208:211], v[104:107]
	v_mfma_f32_16x16x32_bf16 v[92:95], v[132:135], v[220:223], v[92:95]
	v_mfma_f32_16x16x32_bf16 v[88:91], v[140:143], v[220:223], v[88:91]
	v_mfma_f32_16x16x32_bf16 v[76:79], v[132:135], v[228:231], v[76:79]
	v_mfma_f32_16x16x32_bf16 v[72:75], v[140:143], v[228:231], v[72:75]
	v_mfma_f32_16x16x32_bf16 v[116:119], v[144:147], v[170:173], v[116:119]
	v_mfma_f32_16x16x32_bf16 v[112:115], v[152:155], v[170:173], v[112:115]
	v_mfma_f32_16x16x32_bf16 v[100:103], v[144:147], v[194:197], v[100:103]
	v_mfma_f32_16x16x32_bf16 v[96:99], v[152:155], v[194:197], v[96:99]
	v_mfma_f32_16x16x32_bf16 v[84:87], v[144:147], v[212:215], v[84:87]
	v_mfma_f32_16x16x32_bf16 v[80:83], v[152:155], v[212:215], v[80:83]
	v_mfma_f32_16x16x32_bf16 v[68:71], v[144:147], v[224:227], v[68:71]
	v_mfma_f32_16x16x32_bf16 v[64:67], v[152:155], v[224:227], v[64:67]
	v_mfma_f32_16x16x32_bf16 v[116:119], v[148:151], v[174:177], v[116:119]
	v_mfma_f32_16x16x32_bf16 v[112:115], v[166:169], v[174:177], v[112:115]
	v_mfma_f32_16x16x32_bf16 v[100:103], v[148:151], v[208:211], v[100:103]
	v_mfma_f32_16x16x32_bf16 v[96:99], v[166:169], v[208:211], v[96:99]
	v_mfma_f32_16x16x32_bf16 v[84:87], v[148:151], v[220:223], v[84:87]
	v_mfma_f32_16x16x32_bf16 v[80:83], v[166:169], v[220:223], v[80:83]
	v_mfma_f32_16x16x32_bf16 v[68:71], v[148:151], v[228:231], v[68:71]
	v_mfma_f32_16x16x32_bf16 v[64:67], v[166:169], v[228:231], v[64:67]
	s_barrier
	s_add_i32 s62, s62, s36
	v_lshl_add_u64 v[178:179], s[44:45], 0, v[180:181]
	s_mov_b32 m0, s62
	ds_read_b128 v[170:173], v206 offset:16384
	ds_read_b128 v[174:177], v206 offset:17408
	ds_read_b128 v[194:197], v206 offset:18432
	ds_read_b128 v[208:211], v206 offset:19456
	ds_read_b128 v[212:215], v206 offset:20480
	ds_read_b128 v[220:223], v206 offset:21504
	ds_read_b128 v[224:227], v206 offset:22528
	ds_read_b128 v[228:231], v206 offset:23552
	global_load_lds_dwordx4 v[178:179], off
	s_add_i32 m0, s62, 0x2000
	v_lshl_add_u64 v[202:203], s[44:45], 0, v[156:157]
	s_add_u32 s44, s44, s6
	s_addc_u32 s45, s45, s7
	s_add_i32 s31, s31, s36
	global_load_lds_dwordx4 v[202:203], off
	v_lshl_add_u64 v[216:217], s[44:45], 0, v[180:181]
	s_mov_b32 m0, s31
	v_lshl_add_u64 v[232:233], s[44:45], 0, v[156:157]
	global_load_lds_dwordx4 v[216:217], off
	s_add_i32 m0, s31, 0x2000
	v_lshl_add_u64 v[234:235], s[16:17], 0, v[160:161]
	global_load_lds_dwordx4 v[232:233], off
	s_mov_b32 m0, s37
	v_lshl_add_u64 v[236:237], s[16:17], 0, v[158:159]
	global_load_lds_dwordx4 v[234:235], off
	s_mov_b32 m0, s38
	s_nop 0
	global_load_lds_dwordx4 v[236:237], off
	s_waitcnt vmcnt(8)
	s_waitcnt lgkmcnt(0)
	s_barrier
	s_waitcnt lgkmcnt(0)
	v_mfma_f32_16x16x32_bf16 v[60:63], v[128:131], v[170:173], v[60:63]
	v_mfma_f32_16x16x32_bf16 v[56:59], v[136:139], v[170:173], v[56:59]
	v_mfma_f32_16x16x32_bf16 v[44:47], v[128:131], v[194:197], v[44:47]
	v_mfma_f32_16x16x32_bf16 v[40:43], v[136:139], v[194:197], v[40:43]
	v_mfma_f32_16x16x32_bf16 v[28:31], v[128:131], v[212:215], v[28:31]
	v_mfma_f32_16x16x32_bf16 v[24:27], v[136:139], v[212:215], v[24:27]
	v_mfma_f32_16x16x32_bf16 v[12:15], v[128:131], v[224:227], v[12:15]
	v_mfma_f32_16x16x32_bf16 v[8:11], v[136:139], v[224:227], v[8:11]
	v_mfma_f32_16x16x32_bf16 v[60:63], v[132:135], v[174:177], v[60:63]
	v_mfma_f32_16x16x32_bf16 v[56:59], v[140:143], v[174:177], v[56:59]
	v_mfma_f32_16x16x32_bf16 v[44:47], v[132:135], v[208:211], v[44:47]
	v_mfma_f32_16x16x32_bf16 v[40:43], v[140:143], v[208:211], v[40:43]
	v_mfma_f32_16x16x32_bf16 v[28:31], v[132:135], v[220:223], v[28:31]
	v_mfma_f32_16x16x32_bf16 v[24:27], v[140:143], v[220:223], v[24:27]
	v_mfma_f32_16x16x32_bf16 v[12:15], v[132:135], v[228:231], v[12:15]
	v_mfma_f32_16x16x32_bf16 v[8:11], v[140:143], v[228:231], v[8:11]
	v_mfma_f32_16x16x32_bf16 v[52:55], v[144:147], v[170:173], v[52:55]
	v_mfma_f32_16x16x32_bf16 v[48:51], v[152:155], v[170:173], v[48:51]
	v_mfma_f32_16x16x32_bf16 v[36:39], v[144:147], v[194:197], v[36:39]
	v_mfma_f32_16x16x32_bf16 v[32:35], v[152:155], v[194:197], v[32:35]
	v_mfma_f32_16x16x32_bf16 v[20:23], v[144:147], v[212:215], v[20:23]
	v_mfma_f32_16x16x32_bf16 v[16:19], v[152:155], v[212:215], v[16:19]
	v_mfma_f32_16x16x32_bf16 v[4:7], v[144:147], v[224:227], v[4:7]
	v_mfma_f32_16x16x32_bf16 v[0:3], v[152:155], v[224:227], v[0:3]
	v_mfma_f32_16x16x32_bf16 v[52:55], v[148:151], v[174:177], v[52:55]
	v_mfma_f32_16x16x32_bf16 v[48:51], v[166:169], v[174:177], v[48:51]
	v_mfma_f32_16x16x32_bf16 v[36:39], v[148:151], v[208:211], v[36:39]
	v_mfma_f32_16x16x32_bf16 v[32:35], v[166:169], v[208:211], v[32:35]
	v_mfma_f32_16x16x32_bf16 v[20:23], v[148:151], v[220:223], v[20:23]
	v_mfma_f32_16x16x32_bf16 v[16:19], v[166:169], v[220:223], v[16:19]
	v_mfma_f32_16x16x32_bf16 v[4:7], v[148:151], v[228:231], v[4:7]
	v_mfma_f32_16x16x32_bf16 v[0:3], v[166:169], v[228:231], v[0:3]
	s_barrier
	s_add_i32 s31, 0, 0x18000
	s_add_i32 s44, 0, 0x1c000
	v_add_u32_e32 v140, s31, v199
	v_add_u32_e32 v166, s44, v199
	ds_read_b128 v[128:131], v140
	ds_read_b128 v[132:135], v140 offset:1024
	ds_read_b128 v[136:139], v140 offset:2048
	ds_read_b128 v[140:143], v140 offset:3072
	ds_read_b128 v[144:147], v166
	ds_read_b128 v[148:151], v166 offset:1024
	ds_read_b128 v[152:155], v166 offset:2048
	ds_read_b128 v[166:169], v166 offset:3072
	s_add_u32 s16, s16, s6
	s_addc_u32 s17, s17, s7
	s_mov_b32 m0, s39
	v_lshl_add_u64 v[238:239], s[16:17], 0, v[160:161]
	ds_read_b128 v[170:173], v206 offset:32768
	ds_read_b128 v[174:177], v206 offset:33792
	ds_read_b128 v[194:197], v206 offset:34816
	ds_read_b128 v[208:211], v206 offset:35840
	ds_read_b128 v[212:215], v206 offset:36864
	ds_read_b128 v[220:223], v206 offset:37888
	ds_read_b128 v[224:227], v206 offset:38912
	ds_read_b128 v[228:231], v206 offset:39936
	global_load_lds_dwordx4 v[238:239], off
	v_lshl_add_u64 v[238:239], s[16:17], 0, v[158:159]
	s_mov_b32 m0, s46
	s_nop 0
	global_load_lds_dwordx4 v[238:239], off
	s_waitcnt vmcnt(8)
	s_waitcnt lgkmcnt(0)
	s_barrier
	s_waitcnt lgkmcnt(0)
	v_mfma_f32_16x16x32_bf16 v[120:123], v[128:131], v[170:173], v[120:123]
	v_mfma_f32_16x16x32_bf16 v[124:127], v[136:139], v[170:173], v[124:127]
	v_mfma_f32_16x16x32_bf16 v[108:111], v[128:131], v[194:197], v[108:111]
	v_mfma_f32_16x16x32_bf16 v[104:107], v[136:139], v[194:197], v[104:107]
	v_mfma_f32_16x16x32_bf16 v[92:95], v[128:131], v[212:215], v[92:95]
	v_mfma_f32_16x16x32_bf16 v[88:91], v[136:139], v[212:215], v[88:91]
	v_mfma_f32_16x16x32_bf16 v[76:79], v[128:131], v[224:227], v[76:79]
	v_mfma_f32_16x16x32_bf16 v[72:75], v[136:139], v[224:227], v[72:75]
	v_mfma_f32_16x16x32_bf16 v[120:123], v[132:135], v[174:177], v[120:123]
	v_mfma_f32_16x16x32_bf16 v[124:127], v[140:143], v[174:177], v[124:127]
	v_mfma_f32_16x16x32_bf16 v[108:111], v[132:135], v[208:211], v[108:111]
	v_mfma_f32_16x16x32_bf16 v[104:107], v[140:143], v[208:211], v[104:107]
	v_mfma_f32_16x16x32_bf16 v[92:95], v[132:135], v[220:223], v[92:95]
	v_mfma_f32_16x16x32_bf16 v[88:91], v[140:143], v[220:223], v[88:91]
	v_mfma_f32_16x16x32_bf16 v[76:79], v[132:135], v[228:231], v[76:79]
	v_mfma_f32_16x16x32_bf16 v[72:75], v[140:143], v[228:231], v[72:75]
	v_mfma_f32_16x16x32_bf16 v[116:119], v[144:147], v[170:173], v[116:119]
	v_mfma_f32_16x16x32_bf16 v[112:115], v[152:155], v[170:173], v[112:115]
	v_mfma_f32_16x16x32_bf16 v[100:103], v[144:147], v[194:197], v[100:103]
	v_mfma_f32_16x16x32_bf16 v[96:99], v[152:155], v[194:197], v[96:99]
	v_mfma_f32_16x16x32_bf16 v[84:87], v[144:147], v[212:215], v[84:87]
	v_mfma_f32_16x16x32_bf16 v[80:83], v[152:155], v[212:215], v[80:83]
	v_mfma_f32_16x16x32_bf16 v[68:71], v[144:147], v[224:227], v[68:71]
	v_mfma_f32_16x16x32_bf16 v[64:67], v[152:155], v[224:227], v[64:67]
	v_mfma_f32_16x16x32_bf16 v[116:119], v[148:151], v[174:177], v[116:119]
	v_mfma_f32_16x16x32_bf16 v[112:115], v[166:169], v[174:177], v[112:115]
	v_mfma_f32_16x16x32_bf16 v[100:103], v[148:151], v[208:211], v[100:103]
	v_mfma_f32_16x16x32_bf16 v[96:99], v[166:169], v[208:211], v[96:99]
	v_mfma_f32_16x16x32_bf16 v[84:87], v[148:151], v[220:223], v[84:87]
	v_mfma_f32_16x16x32_bf16 v[80:83], v[166:169], v[220:223], v[80:83]
	v_mfma_f32_16x16x32_bf16 v[68:71], v[148:151], v[228:231], v[68:71]
	v_mfma_f32_16x16x32_bf16 v[64:67], v[166:169], v[228:231], v[64:67]
	s_barrier
	s_add_i32 s16, s31, s36
	v_lshl_add_u64 v[178:179], v[178:179], 0, s[12:13]
	s_mov_b32 m0, s16
	ds_read_b128 v[170:173], v206 offset:49152
	ds_read_b128 v[174:177], v206 offset:50176
	ds_read_b128 v[194:197], v206 offset:51200
	ds_read_b128 v[208:211], v206 offset:52224
	ds_read_b128 v[212:215], v206 offset:53248
	ds_read_b128 v[220:223], v206 offset:54272
	ds_read_b128 v[224:227], v206 offset:55296
	ds_read_b128 v[228:231], v206 offset:56320
	global_load_lds_dwordx4 v[178:179], off
	v_lshl_add_u64 v[178:179], v[202:203], 0, s[12:13]
	s_add_i32 m0, s16, 0x2000
	s_add_i32 s16, s44, s36
	global_load_lds_dwordx4 v[178:179], off
	v_lshl_add_u64 v[178:179], v[216:217], 0, s[12:13]
	s_mov_b32 m0, s16
	s_nop 0
	global_load_lds_dwordx4 v[178:179], off
	v_lshl_add_u64 v[178:179], v[232:233], 0, s[12:13]
	s_add_i32 m0, s16, 0x2000
	s_nop 0
	global_load_lds_dwordx4 v[178:179], off
	v_lshl_add_u64 v[178:179], v[234:235], 0, s[12:13]
	s_mov_b32 m0, s49
	s_nop 0
	global_load_lds_dwordx4 v[178:179], off
	v_lshl_add_u64 v[178:179], v[236:237], 0, s[12:13]
	s_mov_b32 m0, s52
	s_nop 0
	global_load_lds_dwordx4 v[178:179], off
	s_waitcnt vmcnt(8)
	s_waitcnt lgkmcnt(0)
	s_barrier
	s_waitcnt lgkmcnt(0)
	v_mfma_f32_16x16x32_bf16 v[60:63], v[128:131], v[170:173], v[60:63]
	s_add_u32 s28, s28, 0x100
	v_mfma_f32_16x16x32_bf16 v[56:59], v[136:139], v[170:173], v[56:59]
	s_addc_u32 s29, s29, 0
	v_mfma_f32_16x16x32_bf16 v[44:47], v[128:131], v[194:197], v[44:47]
	s_add_u32 s10, s10, 0x100
	v_mfma_f32_16x16x32_bf16 v[40:43], v[136:139], v[194:197], v[40:43]
	s_addc_u32 s11, s11, 0
	v_mfma_f32_16x16x32_bf16 v[28:31], v[128:131], v[212:215], v[28:31]
	s_mov_b32 s16, s30
	v_mfma_f32_16x16x32_bf16 v[24:27], v[136:139], v[212:215], v[24:27]
	s_cmp_ge_i32 s30, s48
	v_mfma_f32_16x16x32_bf16 v[12:15], v[128:131], v[224:227], v[12:15]
	s_cselect_b32 s99, 1, 0
	v_mfma_f32_16x16x32_bf16 v[8:11], v[136:139], v[224:227], v[8:11]
	s_add_i32 s30, s16, 2
	v_mfma_f32_16x16x32_bf16 v[60:63], v[132:135], v[174:177], v[60:63]
	s_add_u32 s31, s28, 0x80
	v_mfma_f32_16x16x32_bf16 v[56:59], v[140:143], v[174:177], v[56:59]
	s_addc_u32 s17, s29, 0
	v_mfma_f32_16x16x32_bf16 v[44:47], v[132:135], v[208:211], v[44:47]
	s_add_i32 s62, 0, 0x10000
	v_mfma_f32_16x16x32_bf16 v[40:43], v[140:143], v[208:211], v[40:43]
	s_cmp_eq_u32 s56, s16
	v_mfma_f32_16x16x32_bf16 v[28:31], v[132:135], v[220:223], v[28:31]
	s_cselect_b32 s17, s25, s17
	v_mfma_f32_16x16x32_bf16 v[24:27], v[140:143], v[220:223], v[24:27]
	s_cselect_b32 s16, s24, s31
	v_mfma_f32_16x16x32_bf16 v[12:15], v[132:135], v[228:231], v[12:15]
	s_cselect_b32 s45, s27, s11
	v_mfma_f32_16x16x32_bf16 v[8:11], v[140:143], v[228:231], v[8:11]
	s_cselect_b32 s44, s26, s10
	v_mfma_f32_16x16x32_bf16 v[52:55], v[144:147], v[170:173], v[52:55]
	s_add_i32 s31, 0, 0x14000
	v_mfma_f32_16x16x32_bf16 v[48:51], v[152:155], v[170:173], v[48:51]
	v_mfma_f32_16x16x32_bf16 v[36:39], v[144:147], v[194:197], v[36:39]
	v_mfma_f32_16x16x32_bf16 v[32:35], v[152:155], v[194:197], v[32:35]
	v_mfma_f32_16x16x32_bf16 v[20:23], v[144:147], v[212:215], v[20:23]
	v_mfma_f32_16x16x32_bf16 v[16:19], v[152:155], v[212:215], v[16:19]
	v_mfma_f32_16x16x32_bf16 v[4:7], v[144:147], v[224:227], v[4:7]
	v_mfma_f32_16x16x32_bf16 v[0:3], v[152:155], v[224:227], v[0:3]
	v_mfma_f32_16x16x32_bf16 v[52:55], v[148:151], v[174:177], v[52:55]
	v_mfma_f32_16x16x32_bf16 v[48:51], v[166:169], v[174:177], v[48:51]
	v_mfma_f32_16x16x32_bf16 v[36:39], v[148:151], v[208:211], v[36:39]
	v_mfma_f32_16x16x32_bf16 v[32:35], v[166:169], v[208:211], v[32:35]
	v_mfma_f32_16x16x32_bf16 v[20:23], v[148:151], v[220:223], v[20:23]
	v_mfma_f32_16x16x32_bf16 v[16:19], v[166:169], v[220:223], v[16:19]
	v_mfma_f32_16x16x32_bf16 v[4:7], v[148:151], v[228:231], v[4:7]
	v_mfma_f32_16x16x32_bf16 v[0:3], v[166:169], v[228:231], v[0:3]
	s_barrier
	s_cmp_lg_u32 s99, 0
	s_cbranch_scc0 .LBB0_1053

.Llbb_10:
	s_add_i32 s30, s16, 2
	s_add_u32 s31, s28, 0x80
	s_addc_u32 s17, s29, 0
	s_add_i32 s63, 0, 0x10000
	s_cmp_eq_u32 s56, s16
	s_cselect_b32 s17, s25, s17
	s_cselect_b32 s16, s24, s31
	s_cselect_b32 s45, s27, s11
	s_cselect_b32 s44, s26, s10
	s_add_i32 s31, 0, 0x14000
	v_add_u32_e32 v156, s63, v151
	v_add_u32_e32 v172, s31, v151
	ds_read_b128 v[128:131], v156
	ds_read_b128 v[142:145], v156 offset:1024
	ds_read_b128 v[146:149], v156 offset:2048
	ds_read_b128 v[156:159], v156 offset:3072
	ds_read_b128 v[160:163], v172
	ds_read_b128 v[164:167], v172 offset:1024
	ds_read_b128 v[168:171], v172 offset:2048
	ds_read_b128 v[172:175], v172 offset:3072
	v_lshl_add_u64 v[198:199], s[28:29], 0, v[138:139]
	s_add_i32 m0, s37, 0xc000
	ds_read_b128 v[176:179], v155
	ds_read_b128 v[194:197], v155 offset:1024
	ds_read_b128 v[206:209], v155 offset:2048
	ds_read_b128 v[210:213], v155 offset:3072
	ds_read_b128 v[214:217], v155 offset:4096
	ds_read_b128 v[220:223], v155 offset:5120
	ds_read_b128 v[224:227], v155 offset:6144
	ds_read_b128 v[228:231], v155 offset:7168
	global_load_lds_dwordx4 v[198:199], off
	v_lshl_add_u64 v[198:199], s[28:29], 0, v[140:141]
	s_add_i32 m0, s37, 0xe000
	s_nop 0
	global_load_lds_dwordx4 v[198:199], off
	s_waitcnt vmcnt(8)
	s_waitcnt lgkmcnt(0)
	s_barrier
	s_waitcnt lgkmcnt(0)
	v_mfma_f32_16x16x32_bf16 v[120:123], v[128:131], v[176:179], 0
	v_mfma_f32_16x16x32_bf16 v[116:119], v[146:149], v[176:179], 0
	v_mfma_f32_16x16x32_bf16 v[108:111], v[128:131], v[206:209], 0
	v_mfma_f32_16x16x32_bf16 v[100:103], v[146:149], v[206:209], 0
	v_mfma_f32_16x16x32_bf16 v[92:95], v[128:131], v[214:217], 0
	v_mfma_f32_16x16x32_bf16 v[84:87], v[146:149], v[214:217], 0
	v_mfma_f32_16x16x32_bf16 v[76:79], v[128:131], v[224:227], 0
	v_mfma_f32_16x16x32_bf16 v[68:71], v[146:149], v[224:227], 0
	v_mfma_f32_16x16x32_bf16 v[120:123], v[142:145], v[194:197], v[120:123]
	v_mfma_f32_16x16x32_bf16 v[116:119], v[156:159], v[194:197], v[116:119]
	v_mfma_f32_16x16x32_bf16 v[108:111], v[142:145], v[210:213], v[108:111]
	v_mfma_f32_16x16x32_bf16 v[100:103], v[156:159], v[210:213], v[100:103]
	v_mfma_f32_16x16x32_bf16 v[92:95], v[142:145], v[220:223], v[92:95]
	v_mfma_f32_16x16x32_bf16 v[84:87], v[156:159], v[220:223], v[84:87]
	v_mfma_f32_16x16x32_bf16 v[76:79], v[142:145], v[228:231], v[76:79]
	v_mfma_f32_16x16x32_bf16 v[68:71], v[156:159], v[228:231], v[68:71]
	v_mfma_f32_16x16x32_bf16 v[124:127], v[160:163], v[176:179], 0
	v_mfma_f32_16x16x32_bf16 v[112:115], v[168:171], v[176:179], 0
	v_mfma_f32_16x16x32_bf16 v[104:107], v[160:163], v[206:209], 0
	v_mfma_f32_16x16x32_bf16 v[96:99], v[168:171], v[206:209], 0
	v_mfma_f32_16x16x32_bf16 v[88:91], v[160:163], v[214:217], 0
	v_mfma_f32_16x16x32_bf16 v[80:83], v[168:171], v[214:217], 0
	v_mfma_f32_16x16x32_bf16 v[72:75], v[160:163], v[224:227], 0
	v_mfma_f32_16x16x32_bf16 v[64:67], v[168:171], v[224:227], 0
	v_mfma_f32_16x16x32_bf16 v[124:127], v[164:167], v[194:197], v[124:127]
	v_mfma_f32_16x16x32_bf16 v[112:115], v[172:175], v[194:197], v[112:115]
	v_mfma_f32_16x16x32_bf16 v[104:107], v[164:167], v[210:213], v[104:107]
	v_mfma_f32_16x16x32_bf16 v[96:99], v[172:175], v[210:213], v[96:99]
	v_mfma_f32_16x16x32_bf16 v[88:91], v[164:167], v[220:223], v[88:91]
	v_mfma_f32_16x16x32_bf16 v[80:83], v[172:175], v[220:223], v[80:83]
	v_mfma_f32_16x16x32_bf16 v[72:75], v[164:167], v[228:231], v[72:75]
	v_mfma_f32_16x16x32_bf16 v[64:67], v[172:175], v[228:231], v[64:67]
	s_barrier
	s_add_i32 s63, s63, s36
	v_lshl_add_u64 v[198:199], s[44:45], 0, v[180:181]
	s_mov_b32 m0, s63
	ds_read_b128 v[176:179], v155 offset:16384
	ds_read_b128 v[194:197], v155 offset:17408
	ds_read_b128 v[206:209], v155 offset:18432
	ds_read_b128 v[210:213], v155 offset:19456
	ds_read_b128 v[214:217], v155 offset:20480
	ds_read_b128 v[220:223], v155 offset:21504
	ds_read_b128 v[224:227], v155 offset:22528
	ds_read_b128 v[228:231], v155 offset:23552
	global_load_lds_dwordx4 v[198:199], off
	s_add_i32 m0, s63, 0x2000
	v_lshl_add_u64 v[202:203], s[44:45], 0, v[132:133]
	s_add_u32 s44, s44, s6
	s_addc_u32 s45, s45, s7
	s_add_i32 s31, s31, s36
	global_load_lds_dwordx4 v[202:203], off
	v_lshl_add_u64 v[232:233], s[44:45], 0, v[180:181]
	s_mov_b32 m0, s31
	v_lshl_add_u64 v[234:235], s[44:45], 0, v[132:133]
	global_load_lds_dwordx4 v[232:233], off
	s_add_i32 m0, s31, 0x2000
	v_lshl_add_u64 v[236:237], s[16:17], 0, v[136:137]
	global_load_lds_dwordx4 v[234:235], off
	s_mov_b32 m0, s37
	v_lshl_add_u64 v[238:239], s[16:17], 0, v[134:135]
	global_load_lds_dwordx4 v[236:237], off
	s_mov_b32 m0, s38
	s_nop 0
	global_load_lds_dwordx4 v[238:239], off
	s_waitcnt vmcnt(8)
	s_waitcnt lgkmcnt(0)
	s_barrier
	s_waitcnt lgkmcnt(0)
	v_mfma_f32_16x16x32_bf16 v[60:63], v[128:131], v[176:179], 0
	v_mfma_f32_16x16x32_bf16 v[52:55], v[146:149], v[176:179], 0
	v_mfma_f32_16x16x32_bf16 v[44:47], v[128:131], v[206:209], 0
	v_mfma_f32_16x16x32_bf16 v[36:39], v[146:149], v[206:209], 0
	v_mfma_f32_16x16x32_bf16 v[28:31], v[128:131], v[214:217], 0
	v_mfma_f32_16x16x32_bf16 v[20:23], v[146:149], v[214:217], 0
	v_mfma_f32_16x16x32_bf16 v[12:15], v[128:131], v[224:227], 0
	v_mfma_f32_16x16x32_bf16 v[4:7], v[146:149], v[224:227], 0
	v_mfma_f32_16x16x32_bf16 v[60:63], v[142:145], v[194:197], v[60:63]
	v_mfma_f32_16x16x32_bf16 v[52:55], v[156:159], v[194:197], v[52:55]
	v_mfma_f32_16x16x32_bf16 v[44:47], v[142:145], v[210:213], v[44:47]
	v_mfma_f32_16x16x32_bf16 v[36:39], v[156:159], v[210:213], v[36:39]
	v_mfma_f32_16x16x32_bf16 v[28:31], v[142:145], v[220:223], v[28:31]
	v_mfma_f32_16x16x32_bf16 v[20:23], v[156:159], v[220:223], v[20:23]
	v_mfma_f32_16x16x32_bf16 v[12:15], v[142:145], v[228:231], v[12:15]
	v_mfma_f32_16x16x32_bf16 v[4:7], v[156:159], v[228:231], v[4:7]
	v_mfma_f32_16x16x32_bf16 v[56:59], v[160:163], v[176:179], 0
	v_mfma_f32_16x16x32_bf16 v[48:51], v[168:171], v[176:179], 0
	v_mfma_f32_16x16x32_bf16 v[40:43], v[160:163], v[206:209], 0
	v_mfma_f32_16x16x32_bf16 v[32:35], v[168:171], v[206:209], 0
	v_mfma_f32_16x16x32_bf16 v[24:27], v[160:163], v[214:217], 0
	v_mfma_f32_16x16x32_bf16 v[16:19], v[168:171], v[214:217], 0
	v_mfma_f32_16x16x32_bf16 v[8:11], v[160:163], v[224:227], 0
	v_mfma_f32_16x16x32_bf16 v[0:3], v[168:171], v[224:227], 0
	v_mfma_f32_16x16x32_bf16 v[56:59], v[164:167], v[194:197], v[56:59]
	v_mfma_f32_16x16x32_bf16 v[48:51], v[172:175], v[194:197], v[48:51]
	v_mfma_f32_16x16x32_bf16 v[40:43], v[164:167], v[210:213], v[40:43]
	v_mfma_f32_16x16x32_bf16 v[32:35], v[172:175], v[210:213], v[32:35]
	v_mfma_f32_16x16x32_bf16 v[24:27], v[164:167], v[220:223], v[24:27]
	v_mfma_f32_16x16x32_bf16 v[16:19], v[172:175], v[220:223], v[16:19]
	v_mfma_f32_16x16x32_bf16 v[8:11], v[164:167], v[228:231], v[8:11]
	v_mfma_f32_16x16x32_bf16 v[0:3], v[172:175], v[228:231], v[0:3]
	s_barrier
	s_add_i32 s31, 0, 0x18000
	s_add_i32 s44, 0, 0x1c000
	v_add_u32_e32 v156, s31, v151
	v_add_u32_e32 v172, s44, v151
	ds_read_b128 v[128:131], v156
	ds_read_b128 v[142:145], v156 offset:1024
	ds_read_b128 v[146:149], v156 offset:2048
	ds_read_b128 v[156:159], v156 offset:3072
	ds_read_b128 v[160:163], v172
	ds_read_b128 v[164:167], v172 offset:1024
	ds_read_b128 v[168:171], v172 offset:2048
	ds_read_b128 v[172:175], v172 offset:3072
	s_add_u32 s16, s16, s6
	s_addc_u32 s17, s17, s7
	s_mov_b32 m0, s39
	v_lshl_add_u64 v[240:241], s[16:17], 0, v[136:137]
	ds_read_b128 v[176:179], v155 offset:32768
	ds_read_b128 v[194:197], v155 offset:33792
	ds_read_b128 v[206:209], v155 offset:34816
	ds_read_b128 v[210:213], v155 offset:35840
	ds_read_b128 v[214:217], v155 offset:36864
	ds_read_b128 v[220:223], v155 offset:37888
	ds_read_b128 v[224:227], v155 offset:38912
	ds_read_b128 v[228:231], v155 offset:39936
	global_load_lds_dwordx4 v[240:241], off
	v_lshl_add_u64 v[240:241], s[16:17], 0, v[134:135]
	s_mov_b32 m0, s46
	s_nop 0
	global_load_lds_dwordx4 v[240:241], off
	s_waitcnt vmcnt(8)
	s_waitcnt lgkmcnt(0)
	s_barrier
	s_waitcnt lgkmcnt(0)
	v_mfma_f32_16x16x32_bf16 v[120:123], v[128:131], v[176:179], v[120:123]
	v_mfma_f32_16x16x32_bf16 v[116:119], v[146:149], v[176:179], v[116:119]
	v_mfma_f32_16x16x32_bf16 v[108:111], v[128:131], v[206:209], v[108:111]
	v_mfma_f32_16x16x32_bf16 v[100:103], v[146:149], v[206:209], v[100:103]
	v_mfma_f32_16x16x32_bf16 v[92:95], v[128:131], v[214:217], v[92:95]
	v_mfma_f32_16x16x32_bf16 v[84:87], v[146:149], v[214:217], v[84:87]
	v_mfma_f32_16x16x32_bf16 v[76:79], v[128:131], v[224:227], v[76:79]
	v_mfma_f32_16x16x32_bf16 v[68:71], v[146:149], v[224:227], v[68:71]
	v_mfma_f32_16x16x32_bf16 v[120:123], v[142:145], v[194:197], v[120:123]
	v_mfma_f32_16x16x32_bf16 v[116:119], v[156:159], v[194:197], v[116:119]
	v_mfma_f32_16x16x32_bf16 v[108:111], v[142:145], v[210:213], v[108:111]
	v_mfma_f32_16x16x32_bf16 v[100:103], v[156:159], v[210:213], v[100:103]
	v_mfma_f32_16x16x32_bf16 v[92:95], v[142:145], v[220:223], v[92:95]
	v_mfma_f32_16x16x32_bf16 v[84:87], v[156:159], v[220:223], v[84:87]
	v_mfma_f32_16x16x32_bf16 v[76:79], v[142:145], v[228:231], v[76:79]
	v_mfma_f32_16x16x32_bf16 v[68:71], v[156:159], v[228:231], v[68:71]
	v_mfma_f32_16x16x32_bf16 v[124:127], v[160:163], v[176:179], v[124:127]
	v_mfma_f32_16x16x32_bf16 v[112:115], v[168:171], v[176:179], v[112:115]
	v_mfma_f32_16x16x32_bf16 v[104:107], v[160:163], v[206:209], v[104:107]
	v_mfma_f32_16x16x32_bf16 v[96:99], v[168:171], v[206:209], v[96:99]
	v_mfma_f32_16x16x32_bf16 v[88:91], v[160:163], v[214:217], v[88:91]
	v_mfma_f32_16x16x32_bf16 v[80:83], v[168:171], v[214:217], v[80:83]
	v_mfma_f32_16x16x32_bf16 v[72:75], v[160:163], v[224:227], v[72:75]
	v_mfma_f32_16x16x32_bf16 v[64:67], v[168:171], v[224:227], v[64:67]
	v_mfma_f32_16x16x32_bf16 v[124:127], v[164:167], v[194:197], v[124:127]
	v_mfma_f32_16x16x32_bf16 v[112:115], v[172:175], v[194:197], v[112:115]
	v_mfma_f32_16x16x32_bf16 v[104:107], v[164:167], v[210:213], v[104:107]
	v_mfma_f32_16x16x32_bf16 v[96:99], v[172:175], v[210:213], v[96:99]
	v_mfma_f32_16x16x32_bf16 v[88:91], v[164:167], v[220:223], v[88:91]
	v_mfma_f32_16x16x32_bf16 v[80:83], v[172:175], v[220:223], v[80:83]
	v_mfma_f32_16x16x32_bf16 v[72:75], v[164:167], v[228:231], v[72:75]
	v_mfma_f32_16x16x32_bf16 v[64:67], v[172:175], v[228:231], v[64:67]
	s_barrier
	s_add_i32 s16, s31, s36
	v_lshl_add_u64 v[198:199], v[198:199], 0, s[12:13]
	s_mov_b32 m0, s16
	ds_read_b128 v[176:179], v155 offset:49152
	ds_read_b128 v[194:197], v155 offset:50176
	ds_read_b128 v[206:209], v155 offset:51200
	ds_read_b128 v[210:213], v155 offset:52224
	ds_read_b128 v[214:217], v155 offset:53248
	ds_read_b128 v[220:223], v155 offset:54272
	ds_read_b128 v[224:227], v155 offset:55296
	ds_read_b128 v[228:231], v155 offset:56320
	global_load_lds_dwordx4 v[198:199], off
	v_lshl_add_u64 v[198:199], v[202:203], 0, s[12:13]
	s_add_i32 m0, s16, 0x2000
	s_add_i32 s16, s44, s36
	global_load_lds_dwordx4 v[198:199], off
	v_lshl_add_u64 v[198:199], v[232:233], 0, s[12:13]
	s_mov_b32 m0, s16
	s_nop 0
	global_load_lds_dwordx4 v[198:199], off
	v_lshl_add_u64 v[198:199], v[234:235], 0, s[12:13]
	s_add_i32 m0, s16, 0x2000
	s_nop 0
	global_load_lds_dwordx4 v[198:199], off
	v_lshl_add_u64 v[198:199], v[236:237], 0, s[12:13]
	s_mov_b32 m0, s49
	s_nop 0
	global_load_lds_dwordx4 v[198:199], off
	v_lshl_add_u64 v[198:199], v[238:239], 0, s[12:13]
	s_mov_b32 m0, s52
	s_nop 0
	global_load_lds_dwordx4 v[198:199], off
	s_waitcnt vmcnt(8)
	s_waitcnt lgkmcnt(0)
	s_barrier
	s_waitcnt lgkmcnt(0)
	v_mfma_f32_16x16x32_bf16 v[60:63], v[128:131], v[176:179], v[60:63]
	s_add_u32 s28, s28, 0x100
	v_mfma_f32_16x16x32_bf16 v[52:55], v[146:149], v[176:179], v[52:55]
	s_addc_u32 s29, s29, 0
	v_mfma_f32_16x16x32_bf16 v[44:47], v[128:131], v[206:209], v[44:47]
	s_add_u32 s10, s10, 0x100
	v_mfma_f32_16x16x32_bf16 v[36:39], v[146:149], v[206:209], v[36:39]
	s_addc_u32 s11, s11, 0
	v_mfma_f32_16x16x32_bf16 v[28:31], v[128:131], v[214:217], v[28:31]
	s_mov_b32 s16, s30
	v_mfma_f32_16x16x32_bf16 v[20:23], v[146:149], v[214:217], v[20:23]
	s_cmp_ge_i32 s30, s47
	v_mfma_f32_16x16x32_bf16 v[12:15], v[128:131], v[224:227], v[12:15]
	s_cselect_b32 s99, 1, 0
	v_mfma_f32_16x16x32_bf16 v[4:7], v[146:149], v[224:227], v[4:7]
	s_add_i32 s30, s16, 2
	v_mfma_f32_16x16x32_bf16 v[60:63], v[142:145], v[194:197], v[60:63]
	s_add_u32 s31, s28, 0x80
	v_mfma_f32_16x16x32_bf16 v[52:55], v[156:159], v[194:197], v[52:55]
	s_addc_u32 s17, s29, 0
	v_mfma_f32_16x16x32_bf16 v[44:47], v[142:145], v[210:213], v[44:47]
	s_add_i32 s63, 0, 0x10000
	v_mfma_f32_16x16x32_bf16 v[36:39], v[156:159], v[210:213], v[36:39]
	s_cmp_eq_u32 s56, s16
	v_mfma_f32_16x16x32_bf16 v[28:31], v[142:145], v[220:223], v[28:31]
	s_cselect_b32 s17, s25, s17
	v_mfma_f32_16x16x32_bf16 v[20:23], v[156:159], v[220:223], v[20:23]
	s_cselect_b32 s16, s24, s31
	v_mfma_f32_16x16x32_bf16 v[12:15], v[142:145], v[228:231], v[12:15]
	s_cselect_b32 s45, s27, s11
	v_mfma_f32_16x16x32_bf16 v[4:7], v[156:159], v[228:231], v[4:7]
	s_cselect_b32 s44, s26, s10
	v_mfma_f32_16x16x32_bf16 v[56:59], v[160:163], v[176:179], v[56:59]
	s_add_i32 s31, 0, 0x14000
	v_mfma_f32_16x16x32_bf16 v[48:51], v[168:171], v[176:179], v[48:51]
	v_mfma_f32_16x16x32_bf16 v[40:43], v[160:163], v[206:209], v[40:43]
	v_mfma_f32_16x16x32_bf16 v[32:35], v[168:171], v[206:209], v[32:35]
	v_mfma_f32_16x16x32_bf16 v[24:27], v[160:163], v[214:217], v[24:27]
	v_mfma_f32_16x16x32_bf16 v[16:19], v[168:171], v[214:217], v[16:19]
	v_mfma_f32_16x16x32_bf16 v[8:11], v[160:163], v[224:227], v[8:11]
	v_mfma_f32_16x16x32_bf16 v[0:3], v[168:171], v[224:227], v[0:3]
	v_mfma_f32_16x16x32_bf16 v[56:59], v[164:167], v[194:197], v[56:59]
	v_mfma_f32_16x16x32_bf16 v[48:51], v[172:175], v[194:197], v[48:51]
	v_mfma_f32_16x16x32_bf16 v[40:43], v[164:167], v[210:213], v[40:43]
	v_mfma_f32_16x16x32_bf16 v[32:35], v[172:175], v[210:213], v[32:35]
	v_mfma_f32_16x16x32_bf16 v[24:27], v[164:167], v[220:223], v[24:27]
	v_mfma_f32_16x16x32_bf16 v[16:19], v[172:175], v[220:223], v[16:19]
	v_mfma_f32_16x16x32_bf16 v[8:11], v[164:167], v[228:231], v[8:11]
	v_mfma_f32_16x16x32_bf16 v[0:3], v[172:175], v[228:231], v[0:3]
	s_barrier
	s_cmp_lg_u32 s99, 0
	s_cbranch_scc1 .Lpeelx_14
.LBB0_1144:
	v_add_u32_e32 v156, s63, v151
	v_add_u32_e32 v172, s31, v151
	ds_read_b128 v[128:131], v156
	ds_read_b128 v[142:145], v156 offset:1024
	ds_read_b128 v[146:149], v156 offset:2048
	ds_read_b128 v[156:159], v156 offset:3072
	ds_read_b128 v[160:163], v172
	ds_read_b128 v[164:167], v172 offset:1024
	ds_read_b128 v[168:171], v172 offset:2048
	ds_read_b128 v[172:175], v172 offset:3072
	v_lshl_add_u64 v[198:199], s[28:29], 0, v[138:139]
	s_add_i32 m0, s37, 0xc000
	ds_read_b128 v[176:179], v155
	ds_read_b128 v[194:197], v155 offset:1024
	ds_read_b128 v[206:209], v155 offset:2048
	ds_read_b128 v[210:213], v155 offset:3072
	ds_read_b128 v[214:217], v155 offset:4096
	ds_read_b128 v[220:223], v155 offset:5120
	ds_read_b128 v[224:227], v155 offset:6144
	ds_read_b128 v[228:231], v155 offset:7168
	global_load_lds_dwordx4 v[198:199], off
	v_lshl_add_u64 v[198:199], s[28:29], 0, v[140:141]
	s_add_i32 m0, s37, 0xe000
	s_nop 0
	global_load_lds_dwordx4 v[198:199], off
	s_waitcnt vmcnt(8)
	s_waitcnt lgkmcnt(0)
	s_barrier
	s_waitcnt lgkmcnt(0)
	v_mfma_f32_16x16x32_bf16 v[120:123], v[128:131], v[176:179], v[120:123]
	v_mfma_f32_16x16x32_bf16 v[116:119], v[146:149], v[176:179], v[116:119]
	v_mfma_f32_16x16x32_bf16 v[108:111], v[128:131], v[206:209], v[108:111]
	v_mfma_f32_16x16x32_bf16 v[100:103], v[146:149], v[206:209], v[100:103]
	v_mfma_f32_16x16x32_bf16 v[92:95], v[128:131], v[214:217], v[92:95]
	v_mfma_f32_16x16x32_bf16 v[84:87], v[146:149], v[214:217], v[84:87]
	v_mfma_f32_16x16x32_bf16 v[76:79], v[128:131], v[224:227], v[76:79]
	v_mfma_f32_16x16x32_bf16 v[68:71], v[146:149], v[224:227], v[68:71]
	v_mfma_f32_16x16x32_bf16 v[120:123], v[142:145], v[194:197], v[120:123]
	v_mfma_f32_16x16x32_bf16 v[116:119], v[156:159], v[194:197], v[116:119]
	v_mfma_f32_16x16x32_bf16 v[108:111], v[142:145], v[210:213], v[108:111]
	v_mfma_f32_16x16x32_bf16 v[100:103], v[156:159], v[210:213], v[100:103]
	v_mfma_f32_16x16x32_bf16 v[92:95], v[142:145], v[220:223], v[92:95]
	v_mfma_f32_16x16x32_bf16 v[84:87], v[156:159], v[220:223], v[84:87]
	v_mfma_f32_16x16x32_bf16 v[76:79], v[142:145], v[228:231], v[76:79]
	v_mfma_f32_16x16x32_bf16 v[68:71], v[156:159], v[228:231], v[68:71]
	v_mfma_f32_16x16x32_bf16 v[124:127], v[160:163], v[176:179], v[124:127]
	v_mfma_f32_16x16x32_bf16 v[112:115], v[168:171], v[176:179], v[112:115]
	v_mfma_f32_16x16x32_bf16 v[104:107], v[160:163], v[206:209], v[104:107]
	v_mfma_f32_16x16x32_bf16 v[96:99], v[168:171], v[206:209], v[96:99]
	v_mfma_f32_16x16x32_bf16 v[88:91], v[160:163], v[214:217], v[88:91]
	v_mfma_f32_16x16x32_bf16 v[80:83], v[168:171], v[214:217], v[80:83]
	v_mfma_f32_16x16x32_bf16 v[72:75], v[160:163], v[224:227], v[72:75]
	v_mfma_f32_16x16x32_bf16 v[64:67], v[168:171], v[224:227], v[64:67]
	v_mfma_f32_16x16x32_bf16 v[124:127], v[164:167], v[194:197], v[124:127]
	v_mfma_f32_16x16x32_bf16 v[112:115], v[172:175], v[194:197], v[112:115]
	v_mfma_f32_16x16x32_bf16 v[104:107], v[164:167], v[210:213], v[104:107]
	v_mfma_f32_16x16x32_bf16 v[96:99], v[172:175], v[210:213], v[96:99]
	v_mfma_f32_16x16x32_bf16 v[88:91], v[164:167], v[220:223], v[88:91]
	v_mfma_f32_16x16x32_bf16 v[80:83], v[172:175], v[220:223], v[80:83]
	v_mfma_f32_16x16x32_bf16 v[72:75], v[164:167], v[228:231], v[72:75]
	v_mfma_f32_16x16x32_bf16 v[64:67], v[172:175], v[228:231], v[64:67]
	s_barrier
	s_add_i32 s63, s63, s36
	v_lshl_add_u64 v[198:199], s[44:45], 0, v[180:181]
	s_mov_b32 m0, s63
	ds_read_b128 v[176:179], v155 offset:16384
	ds_read_b128 v[194:197], v155 offset:17408
	ds_read_b128 v[206:209], v155 offset:18432
	ds_read_b128 v[210:213], v155 offset:19456
	ds_read_b128 v[214:217], v155 offset:20480
	ds_read_b128 v[220:223], v155 offset:21504
	ds_read_b128 v[224:227], v155 offset:22528
	ds_read_b128 v[228:231], v155 offset:23552
	global_load_lds_dwordx4 v[198:199], off
	s_add_i32 m0, s63, 0x2000
	v_lshl_add_u64 v[202:203], s[44:45], 0, v[132:133]
	s_add_u32 s44, s44, s6
	s_addc_u32 s45, s45, s7
	s_add_i32 s31, s31, s36
	global_load_lds_dwordx4 v[202:203], off
	v_lshl_add_u64 v[232:233], s[44:45], 0, v[180:181]
	s_mov_b32 m0, s31
	v_lshl_add_u64 v[234:235], s[44:45], 0, v[132:133]
	global_load_lds_dwordx4 v[232:233], off
	s_add_i32 m0, s31, 0x2000
	v_lshl_add_u64 v[236:237], s[16:17], 0, v[136:137]
	global_load_lds_dwordx4 v[234:235], off
	s_mov_b32 m0, s37
	v_lshl_add_u64 v[238:239], s[16:17], 0, v[134:135]
	global_load_lds_dwordx4 v[236:237], off
	s_mov_b32 m0, s38
	s_nop 0
	global_load_lds_dwordx4 v[238:239], off
	s_waitcnt vmcnt(8)
	s_waitcnt lgkmcnt(0)
	s_barrier
	s_waitcnt lgkmcnt(0)
	v_mfma_f32_16x16x32_bf16 v[60:63], v[128:131], v[176:179], v[60:63]
	v_mfma_f32_16x16x32_bf16 v[52:55], v[146:149], v[176:179], v[52:55]
	v_mfma_f32_16x16x32_bf16 v[44:47], v[128:131], v[206:209], v[44:47]
	v_mfma_f32_16x16x32_bf16 v[36:39], v[146:149], v[206:209], v[36:39]
	v_mfma_f32_16x16x32_bf16 v[28:31], v[128:131], v[214:217], v[28:31]
	v_mfma_f32_16x16x32_bf16 v[20:23], v[146:149], v[214:217], v[20:23]
	v_mfma_f32_16x16x32_bf16 v[12:15], v[128:131], v[224:227], v[12:15]
	v_mfma_f32_16x16x32_bf16 v[4:7], v[146:149], v[224:227], v[4:7]
	v_mfma_f32_16x16x32_bf16 v[60:63], v[142:145], v[194:197], v[60:63]
	v_mfma_f32_16x16x32_bf16 v[52:55], v[156:159], v[194:197], v[52:55]
	v_mfma_f32_16x16x32_bf16 v[44:47], v[142:145], v[210:213], v[44:47]
	v_mfma_f32_16x16x32_bf16 v[36:39], v[156:159], v[210:213], v[36:39]
	v_mfma_f32_16x16x32_bf16 v[28:31], v[142:145], v[220:223], v[28:31]
	v_mfma_f32_16x16x32_bf16 v[20:23], v[156:159], v[220:223], v[20:23]
	v_mfma_f32_16x16x32_bf16 v[12:15], v[142:145], v[228:231], v[12:15]
	v_mfma_f32_16x16x32_bf16 v[4:7], v[156:159], v[228:231], v[4:7]
	v_mfma_f32_16x16x32_bf16 v[56:59], v[160:163], v[176:179], v[56:59]
	v_mfma_f32_16x16x32_bf16 v[48:51], v[168:171], v[176:179], v[48:51]
	v_mfma_f32_16x16x32_bf16 v[40:43], v[160:163], v[206:209], v[40:43]
	v_mfma_f32_16x16x32_bf16 v[32:35], v[168:171], v[206:209], v[32:35]
	v_mfma_f32_16x16x32_bf16 v[24:27], v[160:163], v[214:217], v[24:27]
	v_mfma_f32_16x16x32_bf16 v[16:19], v[168:171], v[214:217], v[16:19]
	v_mfma_f32_16x16x32_bf16 v[8:11], v[160:163], v[224:227], v[8:11]
	v_mfma_f32_16x16x32_bf16 v[0:3], v[168:171], v[224:227], v[0:3]
	v_mfma_f32_16x16x32_bf16 v[56:59], v[164:167], v[194:197], v[56:59]
	v_mfma_f32_16x16x32_bf16 v[48:51], v[172:175], v[194:197], v[48:51]
	v_mfma_f32_16x16x32_bf16 v[40:43], v[164:167], v[210:213], v[40:43]
	v_mfma_f32_16x16x32_bf16 v[32:35], v[172:175], v[210:213], v[32:35]
	v_mfma_f32_16x16x32_bf16 v[24:27], v[164:167], v[220:223], v[24:27]
	v_mfma_f32_16x16x32_bf16 v[16:19], v[172:175], v[220:223], v[16:19]
	v_mfma_f32_16x16x32_bf16 v[8:11], v[164:167], v[228:231], v[8:11]
	v_mfma_f32_16x16x32_bf16 v[0:3], v[172:175], v[228:231], v[0:3]
	s_barrier
	s_add_i32 s31, 0, 0x18000
	s_add_i32 s44, 0, 0x1c000
	v_add_u32_e32 v156, s31, v151
	v_add_u32_e32 v172, s44, v151
	ds_read_b128 v[128:131], v156
	ds_read_b128 v[142:145], v156 offset:1024
	ds_read_b128 v[146:149], v156 offset:2048
	ds_read_b128 v[156:159], v156 offset:3072
	ds_read_b128 v[160:163], v172
	ds_read_b128 v[164:167], v172 offset:1024
	ds_read_b128 v[168:171], v172 offset:2048
	ds_read_b128 v[172:175], v172 offset:3072
	s_add_u32 s16, s16, s6
	s_addc_u32 s17, s17, s7
	s_mov_b32 m0, s39
	v_lshl_add_u64 v[240:241], s[16:17], 0, v[136:137]
	ds_read_b128 v[176:179], v155 offset:32768
	ds_read_b128 v[194:197], v155 offset:33792
	ds_read_b128 v[206:209], v155 offset:34816
	ds_read_b128 v[210:213], v155 offset:35840
	ds_read_b128 v[214:217], v155 offset:36864
	ds_read_b128 v[220:223], v155 offset:37888
	ds_read_b128 v[224:227], v155 offset:38912
	ds_read_b128 v[228:231], v155 offset:39936
	global_load_lds_dwordx4 v[240:241], off
	v_lshl_add_u64 v[240:241], s[16:17], 0, v[134:135]
	s_mov_b32 m0, s46
	s_nop 0
	global_load_lds_dwordx4 v[240:241], off
	s_waitcnt vmcnt(8)
	s_waitcnt lgkmcnt(0)
	s_barrier
	s_waitcnt lgkmcnt(0)
	v_mfma_f32_16x16x32_bf16 v[120:123], v[128:131], v[176:179], v[120:123]
	v_mfma_f32_16x16x32_bf16 v[116:119], v[146:149], v[176:179], v[116:119]
	v_mfma_f32_16x16x32_bf16 v[108:111], v[128:131], v[206:209], v[108:111]
	v_mfma_f32_16x16x32_bf16 v[100:103], v[146:149], v[206:209], v[100:103]
	v_mfma_f32_16x16x32_bf16 v[92:95], v[128:131], v[214:217], v[92:95]
	v_mfma_f32_16x16x32_bf16 v[84:87], v[146:149], v[214:217], v[84:87]
	v_mfma_f32_16x16x32_bf16 v[76:79], v[128:131], v[224:227], v[76:79]
	v_mfma_f32_16x16x32_bf16 v[68:71], v[146:149], v[224:227], v[68:71]
	v_mfma_f32_16x16x32_bf16 v[120:123], v[142:145], v[194:197], v[120:123]
	v_mfma_f32_16x16x32_bf16 v[116:119], v[156:159], v[194:197], v[116:119]
	v_mfma_f32_16x16x32_bf16 v[108:111], v[142:145], v[210:213], v[108:111]
	v_mfma_f32_16x16x32_bf16 v[100:103], v[156:159], v[210:213], v[100:103]
	v_mfma_f32_16x16x32_bf16 v[92:95], v[142:145], v[220:223], v[92:95]
	v_mfma_f32_16x16x32_bf16 v[84:87], v[156:159], v[220:223], v[84:87]
	v_mfma_f32_16x16x32_bf16 v[76:79], v[142:145], v[228:231], v[76:79]
	v_mfma_f32_16x16x32_bf16 v[68:71], v[156:159], v[228:231], v[68:71]
	v_mfma_f32_16x16x32_bf16 v[124:127], v[160:163], v[176:179], v[124:127]
	v_mfma_f32_16x16x32_bf16 v[112:115], v[168:171], v[176:179], v[112:115]
	v_mfma_f32_16x16x32_bf16 v[104:107], v[160:163], v[206:209], v[104:107]
	v_mfma_f32_16x16x32_bf16 v[96:99], v[168:171], v[206:209], v[96:99]
	v_mfma_f32_16x16x32_bf16 v[88:91], v[160:163], v[214:217], v[88:91]
	v_mfma_f32_16x16x32_bf16 v[80:83], v[168:171], v[214:217], v[80:83]
	v_mfma_f32_16x16x32_bf16 v[72:75], v[160:163], v[224:227], v[72:75]
	v_mfma_f32_16x16x32_bf16 v[64:67], v[168:171], v[224:227], v[64:67]
	v_mfma_f32_16x16x32_bf16 v[124:127], v[164:167], v[194:197], v[124:127]
	v_mfma_f32_16x16x32_bf16 v[112:115], v[172:175], v[194:197], v[112:115]
	v_mfma_f32_16x16x32_bf16 v[104:107], v[164:167], v[210:213], v[104:107]
	v_mfma_f32_16x16x32_bf16 v[96:99], v[172:175], v[210:213], v[96:99]
	v_mfma_f32_16x16x32_bf16 v[88:91], v[164:167], v[220:223], v[88:91]
	v_mfma_f32_16x16x32_bf16 v[80:83], v[172:175], v[220:223], v[80:83]
	v_mfma_f32_16x16x32_bf16 v[72:75], v[164:167], v[228:231], v[72:75]
	v_mfma_f32_16x16x32_bf16 v[64:67], v[172:175], v[228:231], v[64:67]
	s_barrier
	s_add_i32 s16, s31, s36
	v_lshl_add_u64 v[198:199], v[198:199], 0, s[12:13]
	s_mov_b32 m0, s16
	ds_read_b128 v[176:179], v155 offset:49152
	ds_read_b128 v[194:197], v155 offset:50176
	ds_read_b128 v[206:209], v155 offset:51200
	ds_read_b128 v[210:213], v155 offset:52224
	ds_read_b128 v[214:217], v155 offset:53248
	ds_read_b128 v[220:223], v155 offset:54272
	ds_read_b128 v[224:227], v155 offset:55296
	ds_read_b128 v[228:231], v155 offset:56320
	global_load_lds_dwordx4 v[198:199], off
	v_lshl_add_u64 v[198:199], v[202:203], 0, s[12:13]
	s_add_i32 m0, s16, 0x2000
	s_add_i32 s16, s44, s36
	global_load_lds_dwordx4 v[198:199], off
	v_lshl_add_u64 v[198:199], v[232:233], 0, s[12:13]
	s_mov_b32 m0, s16
	s_nop 0
	global_load_lds_dwordx4 v[198:199], off
	v_lshl_add_u64 v[198:199], v[234:235], 0, s[12:13]
	s_add_i32 m0, s16, 0x2000
	s_nop 0
	global_load_lds_dwordx4 v[198:199], off
	v_lshl_add_u64 v[198:199], v[236:237], 0, s[12:13]
	s_mov_b32 m0, s49
	s_nop 0
	global_load_lds_dwordx4 v[198:199], off
	v_lshl_add_u64 v[198:199], v[238:239], 0, s[12:13]
	s_mov_b32 m0, s52
	s_nop 0
	global_load_lds_dwordx4 v[198:199], off
	s_waitcnt vmcnt(8)
	s_waitcnt lgkmcnt(0)
	s_barrier
	s_waitcnt lgkmcnt(0)
	v_mfma_f32_16x16x32_bf16 v[60:63], v[128:131], v[176:179], v[60:63]
	s_add_u32 s28, s28, 0x100
	v_mfma_f32_16x16x32_bf16 v[52:55], v[146:149], v[176:179], v[52:55]
	s_addc_u32 s29, s29, 0
	v_mfma_f32_16x16x32_bf16 v[44:47], v[128:131], v[206:209], v[44:47]
	s_add_u32 s10, s10, 0x100
	v_mfma_f32_16x16x32_bf16 v[36:39], v[146:149], v[206:209], v[36:39]
	s_addc_u32 s11, s11, 0
	v_mfma_f32_16x16x32_bf16 v[28:31], v[128:131], v[214:217], v[28:31]
	s_mov_b32 s16, s30
	v_mfma_f32_16x16x32_bf16 v[20:23], v[146:149], v[214:217], v[20:23]
	s_cmp_ge_i32 s30, s47
	v_mfma_f32_16x16x32_bf16 v[12:15], v[128:131], v[224:227], v[12:15]
	s_cselect_b32 s99, 1, 0
	v_mfma_f32_16x16x32_bf16 v[4:7], v[146:149], v[224:227], v[4:7]
	s_add_i32 s30, s16, 2
	v_mfma_f32_16x16x32_bf16 v[60:63], v[142:145], v[194:197], v[60:63]
	s_add_u32 s31, s28, 0x80
	v_mfma_f32_16x16x32_bf16 v[52:55], v[156:159], v[194:197], v[52:55]
	s_addc_u32 s17, s29, 0
	v_mfma_f32_16x16x32_bf16 v[44:47], v[142:145], v[210:213], v[44:47]
	s_add_i32 s63, 0, 0x10000
	v_mfma_f32_16x16x32_bf16 v[36:39], v[156:159], v[210:213], v[36:39]
	s_cmp_eq_u32 s56, s16
	v_mfma_f32_16x16x32_bf16 v[28:31], v[142:145], v[220:223], v[28:31]
	s_cselect_b32 s17, s25, s17
	v_mfma_f32_16x16x32_bf16 v[20:23], v[156:159], v[220:223], v[20:23]
	s_cselect_b32 s16, s24, s31
	v_mfma_f32_16x16x32_bf16 v[12:15], v[142:145], v[228:231], v[12:15]
	s_cselect_b32 s45, s27, s11
	v_mfma_f32_16x16x32_bf16 v[4:7], v[156:159], v[228:231], v[4:7]
	s_cselect_b32 s44, s26, s10
	v_mfma_f32_16x16x32_bf16 v[56:59], v[160:163], v[176:179], v[56:59]
	s_add_i32 s31, 0, 0x14000
	v_mfma_f32_16x16x32_bf16 v[48:51], v[168:171], v[176:179], v[48:51]
	v_mfma_f32_16x16x32_bf16 v[40:43], v[160:163], v[206:209], v[40:43]
	v_mfma_f32_16x16x32_bf16 v[32:35], v[168:171], v[206:209], v[32:35]
	v_mfma_f32_16x16x32_bf16 v[24:27], v[160:163], v[214:217], v[24:27]
	v_mfma_f32_16x16x32_bf16 v[16:19], v[168:171], v[214:217], v[16:19]
	v_mfma_f32_16x16x32_bf16 v[8:11], v[160:163], v[224:227], v[8:11]
	v_mfma_f32_16x16x32_bf16 v[0:3], v[168:171], v[224:227], v[0:3]
	v_mfma_f32_16x16x32_bf16 v[56:59], v[164:167], v[194:197], v[56:59]
	v_mfma_f32_16x16x32_bf16 v[48:51], v[172:175], v[194:197], v[48:51]
	v_mfma_f32_16x16x32_bf16 v[40:43], v[164:167], v[210:213], v[40:43]
	v_mfma_f32_16x16x32_bf16 v[32:35], v[172:175], v[210:213], v[32:35]
	v_mfma_f32_16x16x32_bf16 v[24:27], v[164:167], v[220:223], v[24:27]
	v_mfma_f32_16x16x32_bf16 v[16:19], v[172:175], v[220:223], v[16:19]
	v_mfma_f32_16x16x32_bf16 v[8:11], v[164:167], v[228:231], v[8:11]
	v_mfma_f32_16x16x32_bf16 v[0:3], v[172:175], v[228:231], v[0:3]
	s_barrier
	s_cmp_lg_u32 s99, 0
	s_cbranch_scc0 .LBB0_1144

.Llbb_11:
	s_add_i32 s44, s28, 2
	s_add_u32 s45, s26, 0x80
	s_addc_u32 s29, s27, 0
	s_add_i32 s62, 0, 0x10000
	s_cmp_eq_u32 s49, s28
	s_cselect_b32 s29, s23, s29
	s_cselect_b32 s28, s22, s45
	s_cselect_b32 s61, s25, s11
	s_cselect_b32 s60, s24, s10
	s_add_i32 s45, 0, 0x14000
	v_add_u32_e32 v140, s62, v199
	v_add_u32_e32 v166, s45, v199
	ds_read_b128 v[128:131], v140
	ds_read_b128 v[132:135], v140 offset:1024
	ds_read_b128 v[136:139], v140 offset:2048
	ds_read_b128 v[140:143], v140 offset:3072
	ds_read_b128 v[144:147], v166
	ds_read_b128 v[148:151], v166 offset:1024
	ds_read_b128 v[152:155], v166 offset:2048
	ds_read_b128 v[166:169], v166 offset:3072
	v_lshl_add_u64 v[178:179], s[26:27], 0, v[162:163]
	s_add_i32 m0, s35, 0xc000
	ds_read_b128 v[170:173], v206
	ds_read_b128 v[174:177], v206 offset:1024
	ds_read_b128 v[194:197], v206 offset:2048
	ds_read_b128 v[208:211], v206 offset:3072
	ds_read_b128 v[212:215], v206 offset:4096
	ds_read_b128 v[220:223], v206 offset:5120
	ds_read_b128 v[224:227], v206 offset:6144
	ds_read_b128 v[228:231], v206 offset:7168
	global_load_lds_dwordx4 v[178:179], off
	v_lshl_add_u64 v[178:179], s[26:27], 0, v[164:165]
	s_add_i32 m0, s35, 0xe000
	s_nop 0
	global_load_lds_dwordx4 v[178:179], off
	s_waitcnt vmcnt(8)
	s_waitcnt lgkmcnt(0)
	s_barrier
	s_waitcnt lgkmcnt(0)
	v_mfma_f32_16x16x32_bf16 v[120:123], v[128:131], v[170:173], 0
	v_mfma_f32_16x16x32_bf16 v[124:127], v[136:139], v[170:173], 0
	v_mfma_f32_16x16x32_bf16 v[108:111], v[128:131], v[194:197], 0
	v_mfma_f32_16x16x32_bf16 v[104:107], v[136:139], v[194:197], 0
	v_mfma_f32_16x16x32_bf16 v[92:95], v[128:131], v[212:215], 0
	v_mfma_f32_16x16x32_bf16 v[88:91], v[136:139], v[212:215], 0
	v_mfma_f32_16x16x32_bf16 v[76:79], v[128:131], v[224:227], 0
	v_mfma_f32_16x16x32_bf16 v[72:75], v[136:139], v[224:227], 0
	v_mfma_f32_16x16x32_bf16 v[120:123], v[132:135], v[174:177], v[120:123]
	v_mfma_f32_16x16x32_bf16 v[124:127], v[140:143], v[174:177], v[124:127]
	v_mfma_f32_16x16x32_bf16 v[108:111], v[132:135], v[208:211], v[108:111]
	v_mfma_f32_16x16x32_bf16 v[104:107], v[140:143], v[208:211], v[104:107]
	v_mfma_f32_16x16x32_bf16 v[92:95], v[132:135], v[220:223], v[92:95]
	v_mfma_f32_16x16x32_bf16 v[88:91], v[140:143], v[220:223], v[88:91]
	v_mfma_f32_16x16x32_bf16 v[76:79], v[132:135], v[228:231], v[76:79]
	v_mfma_f32_16x16x32_bf16 v[72:75], v[140:143], v[228:231], v[72:75]
	v_mfma_f32_16x16x32_bf16 v[116:119], v[144:147], v[170:173], 0
	v_mfma_f32_16x16x32_bf16 v[112:115], v[152:155], v[170:173], 0
	v_mfma_f32_16x16x32_bf16 v[100:103], v[144:147], v[194:197], 0
	v_mfma_f32_16x16x32_bf16 v[96:99], v[152:155], v[194:197], 0
	v_mfma_f32_16x16x32_bf16 v[84:87], v[144:147], v[212:215], 0
	v_mfma_f32_16x16x32_bf16 v[80:83], v[152:155], v[212:215], 0
	v_mfma_f32_16x16x32_bf16 v[68:71], v[144:147], v[224:227], 0
	v_mfma_f32_16x16x32_bf16 v[64:67], v[152:155], v[224:227], 0
	v_mfma_f32_16x16x32_bf16 v[116:119], v[148:151], v[174:177], v[116:119]
	v_mfma_f32_16x16x32_bf16 v[112:115], v[166:169], v[174:177], v[112:115]
	v_mfma_f32_16x16x32_bf16 v[100:103], v[148:151], v[208:211], v[100:103]
	v_mfma_f32_16x16x32_bf16 v[96:99], v[166:169], v[208:211], v[96:99]
	v_mfma_f32_16x16x32_bf16 v[84:87], v[148:151], v[220:223], v[84:87]
	v_mfma_f32_16x16x32_bf16 v[80:83], v[166:169], v[220:223], v[80:83]
	v_mfma_f32_16x16x32_bf16 v[68:71], v[148:151], v[228:231], v[68:71]
	v_mfma_f32_16x16x32_bf16 v[64:67], v[166:169], v[228:231], v[64:67]
	s_barrier
	s_add_i32 s62, s62, s34
	v_lshl_add_u64 v[178:179], s[60:61], 0, v[180:181]
	s_mov_b32 m0, s62
	ds_read_b128 v[170:173], v206 offset:16384
	ds_read_b128 v[174:177], v206 offset:17408
	ds_read_b128 v[194:197], v206 offset:18432
	ds_read_b128 v[208:211], v206 offset:19456
	ds_read_b128 v[212:215], v206 offset:20480
	ds_read_b128 v[220:223], v206 offset:21504
	ds_read_b128 v[224:227], v206 offset:22528
	ds_read_b128 v[228:231], v206 offset:23552
	global_load_lds_dwordx4 v[178:179], off
	s_add_i32 m0, s62, 0x2000
	v_lshl_add_u64 v[202:203], s[60:61], 0, v[156:157]
	s_add_u32 s60, s60, s6
	s_addc_u32 s61, s61, s7
	s_add_i32 s45, s45, s34
	global_load_lds_dwordx4 v[202:203], off
	v_lshl_add_u64 v[216:217], s[60:61], 0, v[180:181]
	s_mov_b32 m0, s45
	v_lshl_add_u64 v[232:233], s[60:61], 0, v[156:157]
	global_load_lds_dwordx4 v[216:217], off
	s_add_i32 m0, s45, 0x2000
	v_lshl_add_u64 v[234:235], s[28:29], 0, v[160:161]
	global_load_lds_dwordx4 v[232:233], off
	s_mov_b32 m0, s35
	v_lshl_add_u64 v[236:237], s[28:29], 0, v[158:159]
	global_load_lds_dwordx4 v[234:235], off
	s_mov_b32 m0, s36
	s_nop 0
	global_load_lds_dwordx4 v[236:237], off
	s_waitcnt vmcnt(8)
	s_waitcnt lgkmcnt(0)
	s_barrier
	s_waitcnt lgkmcnt(0)
	v_mfma_f32_16x16x32_bf16 v[60:63], v[128:131], v[170:173], 0
	v_mfma_f32_16x16x32_bf16 v[56:59], v[136:139], v[170:173], 0
	v_mfma_f32_16x16x32_bf16 v[44:47], v[128:131], v[194:197], 0
	v_mfma_f32_16x16x32_bf16 v[40:43], v[136:139], v[194:197], 0
	v_mfma_f32_16x16x32_bf16 v[28:31], v[128:131], v[212:215], 0
	v_mfma_f32_16x16x32_bf16 v[24:27], v[136:139], v[212:215], 0
	v_mfma_f32_16x16x32_bf16 v[12:15], v[128:131], v[224:227], 0
	v_mfma_f32_16x16x32_bf16 v[8:11], v[136:139], v[224:227], 0
	v_mfma_f32_16x16x32_bf16 v[60:63], v[132:135], v[174:177], v[60:63]
	v_mfma_f32_16x16x32_bf16 v[56:59], v[140:143], v[174:177], v[56:59]
	v_mfma_f32_16x16x32_bf16 v[44:47], v[132:135], v[208:211], v[44:47]
	v_mfma_f32_16x16x32_bf16 v[40:43], v[140:143], v[208:211], v[40:43]
	v_mfma_f32_16x16x32_bf16 v[28:31], v[132:135], v[220:223], v[28:31]
	v_mfma_f32_16x16x32_bf16 v[24:27], v[140:143], v[220:223], v[24:27]
	v_mfma_f32_16x16x32_bf16 v[12:15], v[132:135], v[228:231], v[12:15]
	v_mfma_f32_16x16x32_bf16 v[8:11], v[140:143], v[228:231], v[8:11]
	v_mfma_f32_16x16x32_bf16 v[52:55], v[144:147], v[170:173], 0
	v_mfma_f32_16x16x32_bf16 v[48:51], v[152:155], v[170:173], 0
	v_mfma_f32_16x16x32_bf16 v[36:39], v[144:147], v[194:197], 0
	v_mfma_f32_16x16x32_bf16 v[32:35], v[152:155], v[194:197], 0
	v_mfma_f32_16x16x32_bf16 v[20:23], v[144:147], v[212:215], 0
	v_mfma_f32_16x16x32_bf16 v[16:19], v[152:155], v[212:215], 0
	v_mfma_f32_16x16x32_bf16 v[4:7], v[144:147], v[224:227], 0
	v_mfma_f32_16x16x32_bf16 v[0:3], v[152:155], v[224:227], 0
	v_mfma_f32_16x16x32_bf16 v[52:55], v[148:151], v[174:177], v[52:55]
	v_mfma_f32_16x16x32_bf16 v[48:51], v[166:169], v[174:177], v[48:51]
	v_mfma_f32_16x16x32_bf16 v[36:39], v[148:151], v[208:211], v[36:39]
	v_mfma_f32_16x16x32_bf16 v[32:35], v[166:169], v[208:211], v[32:35]
	v_mfma_f32_16x16x32_bf16 v[20:23], v[148:151], v[220:223], v[20:23]
	v_mfma_f32_16x16x32_bf16 v[16:19], v[166:169], v[220:223], v[16:19]
	v_mfma_f32_16x16x32_bf16 v[4:7], v[148:151], v[228:231], v[4:7]
	v_mfma_f32_16x16x32_bf16 v[0:3], v[166:169], v[228:231], v[0:3]
	s_barrier
	s_add_i32 s45, 0, 0x18000
	s_add_i32 s60, 0, 0x1c000
	v_add_u32_e32 v140, s45, v199
	v_add_u32_e32 v166, s60, v199
	ds_read_b128 v[128:131], v140
	ds_read_b128 v[132:135], v140 offset:1024
	ds_read_b128 v[136:139], v140 offset:2048
	ds_read_b128 v[140:143], v140 offset:3072
	ds_read_b128 v[144:147], v166
	ds_read_b128 v[148:151], v166 offset:1024
	ds_read_b128 v[152:155], v166 offset:2048
	ds_read_b128 v[166:169], v166 offset:3072
	s_add_u32 s28, s28, s6
	s_addc_u32 s29, s29, s7
	s_mov_b32 m0, s37
	v_lshl_add_u64 v[238:239], s[28:29], 0, v[160:161]
	ds_read_b128 v[170:173], v206 offset:32768
	ds_read_b128 v[174:177], v206 offset:33792
	ds_read_b128 v[194:197], v206 offset:34816
	ds_read_b128 v[208:211], v206 offset:35840
	ds_read_b128 v[212:215], v206 offset:36864
	ds_read_b128 v[220:223], v206 offset:37888
	ds_read_b128 v[224:227], v206 offset:38912
	ds_read_b128 v[228:231], v206 offset:39936
	global_load_lds_dwordx4 v[238:239], off
	v_lshl_add_u64 v[238:239], s[28:29], 0, v[158:159]
	s_mov_b32 m0, s38
	s_nop 0
	global_load_lds_dwordx4 v[238:239], off
	s_waitcnt vmcnt(8)
	s_waitcnt lgkmcnt(0)
	s_barrier
	s_waitcnt lgkmcnt(0)
	v_mfma_f32_16x16x32_bf16 v[120:123], v[128:131], v[170:173], v[120:123]
	v_mfma_f32_16x16x32_bf16 v[124:127], v[136:139], v[170:173], v[124:127]
	v_mfma_f32_16x16x32_bf16 v[108:111], v[128:131], v[194:197], v[108:111]
	v_mfma_f32_16x16x32_bf16 v[104:107], v[136:139], v[194:197], v[104:107]
	v_mfma_f32_16x16x32_bf16 v[92:95], v[128:131], v[212:215], v[92:95]
	v_mfma_f32_16x16x32_bf16 v[88:91], v[136:139], v[212:215], v[88:91]
	v_mfma_f32_16x16x32_bf16 v[76:79], v[128:131], v[224:227], v[76:79]
	v_mfma_f32_16x16x32_bf16 v[72:75], v[136:139], v[224:227], v[72:75]
	v_mfma_f32_16x16x32_bf16 v[120:123], v[132:135], v[174:177], v[120:123]
	v_mfma_f32_16x16x32_bf16 v[124:127], v[140:143], v[174:177], v[124:127]
	v_mfma_f32_16x16x32_bf16 v[108:111], v[132:135], v[208:211], v[108:111]
	v_mfma_f32_16x16x32_bf16 v[104:107], v[140:143], v[208:211], v[104:107]
	v_mfma_f32_16x16x32_bf16 v[92:95], v[132:135], v[220:223], v[92:95]
	v_mfma_f32_16x16x32_bf16 v[88:91], v[140:143], v[220:223], v[88:91]
	v_mfma_f32_16x16x32_bf16 v[76:79], v[132:135], v[228:231], v[76:79]
	v_mfma_f32_16x16x32_bf16 v[72:75], v[140:143], v[228:231], v[72:75]
	v_mfma_f32_16x16x32_bf16 v[116:119], v[144:147], v[170:173], v[116:119]
	v_mfma_f32_16x16x32_bf16 v[112:115], v[152:155], v[170:173], v[112:115]
	v_mfma_f32_16x16x32_bf16 v[100:103], v[144:147], v[194:197], v[100:103]
	v_mfma_f32_16x16x32_bf16 v[96:99], v[152:155], v[194:197], v[96:99]
	v_mfma_f32_16x16x32_bf16 v[84:87], v[144:147], v[212:215], v[84:87]
	v_mfma_f32_16x16x32_bf16 v[80:83], v[152:155], v[212:215], v[80:83]
	v_mfma_f32_16x16x32_bf16 v[68:71], v[144:147], v[224:227], v[68:71]
	v_mfma_f32_16x16x32_bf16 v[64:67], v[152:155], v[224:227], v[64:67]
	v_mfma_f32_16x16x32_bf16 v[116:119], v[148:151], v[174:177], v[116:119]
	v_mfma_f32_16x16x32_bf16 v[112:115], v[166:169], v[174:177], v[112:115]
	v_mfma_f32_16x16x32_bf16 v[100:103], v[148:151], v[208:211], v[100:103]
	v_mfma_f32_16x16x32_bf16 v[96:99], v[166:169], v[208:211], v[96:99]
	v_mfma_f32_16x16x32_bf16 v[84:87], v[148:151], v[220:223], v[84:87]
	v_mfma_f32_16x16x32_bf16 v[80:83], v[166:169], v[220:223], v[80:83]
	v_mfma_f32_16x16x32_bf16 v[68:71], v[148:151], v[228:231], v[68:71]
	v_mfma_f32_16x16x32_bf16 v[64:67], v[166:169], v[228:231], v[64:67]
	s_barrier
	s_add_i32 s28, s45, s34
	v_lshl_add_u64 v[178:179], v[178:179], 0, s[12:13]
	s_mov_b32 m0, s28
	ds_read_b128 v[170:173], v206 offset:49152
	ds_read_b128 v[174:177], v206 offset:50176
	ds_read_b128 v[194:197], v206 offset:51200
	ds_read_b128 v[208:211], v206 offset:52224
	ds_read_b128 v[212:215], v206 offset:53248
	ds_read_b128 v[220:223], v206 offset:54272
	ds_read_b128 v[224:227], v206 offset:55296
	ds_read_b128 v[228:231], v206 offset:56320
	global_load_lds_dwordx4 v[178:179], off
	v_lshl_add_u64 v[178:179], v[202:203], 0, s[12:13]
	s_add_i32 m0, s28, 0x2000
	s_add_i32 s28, s60, s34
	global_load_lds_dwordx4 v[178:179], off
	v_lshl_add_u64 v[178:179], v[216:217], 0, s[12:13]
	s_mov_b32 m0, s28
	s_nop 0
	global_load_lds_dwordx4 v[178:179], off
	v_lshl_add_u64 v[178:179], v[232:233], 0, s[12:13]
	s_add_i32 m0, s28, 0x2000
	s_nop 0
	global_load_lds_dwordx4 v[178:179], off
	v_lshl_add_u64 v[178:179], v[234:235], 0, s[12:13]
	s_mov_b32 m0, s47
	s_nop 0
	global_load_lds_dwordx4 v[178:179], off
	v_lshl_add_u64 v[178:179], v[236:237], 0, s[12:13]
	s_mov_b32 m0, s48
	s_nop 0
	global_load_lds_dwordx4 v[178:179], off
	s_waitcnt vmcnt(8)
	s_waitcnt lgkmcnt(0)
	s_barrier
	s_waitcnt lgkmcnt(0)
	v_mfma_f32_16x16x32_bf16 v[60:63], v[128:131], v[170:173], v[60:63]
	s_add_u32 s26, s26, 0x100
	v_mfma_f32_16x16x32_bf16 v[56:59], v[136:139], v[170:173], v[56:59]
	s_addc_u32 s27, s27, 0
	v_mfma_f32_16x16x32_bf16 v[44:47], v[128:131], v[194:197], v[44:47]
	s_add_u32 s10, s10, 0x100
	v_mfma_f32_16x16x32_bf16 v[40:43], v[136:139], v[194:197], v[40:43]
	s_addc_u32 s11, s11, 0
	v_mfma_f32_16x16x32_bf16 v[28:31], v[128:131], v[212:215], v[28:31]
	s_mov_b32 s28, s44
	v_mfma_f32_16x16x32_bf16 v[24:27], v[136:139], v[212:215], v[24:27]
	s_cmp_ge_i32 s44, s46
	v_mfma_f32_16x16x32_bf16 v[12:15], v[128:131], v[224:227], v[12:15]
	s_cselect_b32 s99, 1, 0
	v_mfma_f32_16x16x32_bf16 v[8:11], v[136:139], v[224:227], v[8:11]
	s_add_i32 s44, s28, 2
	v_mfma_f32_16x16x32_bf16 v[60:63], v[132:135], v[174:177], v[60:63]
	s_add_u32 s45, s26, 0x80
	v_mfma_f32_16x16x32_bf16 v[56:59], v[140:143], v[174:177], v[56:59]
	s_addc_u32 s29, s27, 0
	v_mfma_f32_16x16x32_bf16 v[44:47], v[132:135], v[208:211], v[44:47]
	s_add_i32 s62, 0, 0x10000
	v_mfma_f32_16x16x32_bf16 v[40:43], v[140:143], v[208:211], v[40:43]
	s_cmp_eq_u32 s49, s28
	v_mfma_f32_16x16x32_bf16 v[28:31], v[132:135], v[220:223], v[28:31]
	s_cselect_b32 s29, s23, s29
	v_mfma_f32_16x16x32_bf16 v[24:27], v[140:143], v[220:223], v[24:27]
	s_cselect_b32 s28, s22, s45
	v_mfma_f32_16x16x32_bf16 v[12:15], v[132:135], v[228:231], v[12:15]
	s_cselect_b32 s61, s25, s11
	v_mfma_f32_16x16x32_bf16 v[8:11], v[140:143], v[228:231], v[8:11]
	s_cselect_b32 s60, s24, s10
	v_mfma_f32_16x16x32_bf16 v[52:55], v[144:147], v[170:173], v[52:55]
	s_add_i32 s45, 0, 0x14000
	v_mfma_f32_16x16x32_bf16 v[48:51], v[152:155], v[170:173], v[48:51]
	v_mfma_f32_16x16x32_bf16 v[36:39], v[144:147], v[194:197], v[36:39]
	v_mfma_f32_16x16x32_bf16 v[32:35], v[152:155], v[194:197], v[32:35]
	v_mfma_f32_16x16x32_bf16 v[20:23], v[144:147], v[212:215], v[20:23]
	v_mfma_f32_16x16x32_bf16 v[16:19], v[152:155], v[212:215], v[16:19]
	v_mfma_f32_16x16x32_bf16 v[4:7], v[144:147], v[224:227], v[4:7]
	v_mfma_f32_16x16x32_bf16 v[0:3], v[152:155], v[224:227], v[0:3]
	v_mfma_f32_16x16x32_bf16 v[52:55], v[148:151], v[174:177], v[52:55]
	v_mfma_f32_16x16x32_bf16 v[48:51], v[166:169], v[174:177], v[48:51]
	v_mfma_f32_16x16x32_bf16 v[36:39], v[148:151], v[208:211], v[36:39]
	v_mfma_f32_16x16x32_bf16 v[32:35], v[166:169], v[208:211], v[32:35]
	v_mfma_f32_16x16x32_bf16 v[20:23], v[148:151], v[220:223], v[20:23]
	v_mfma_f32_16x16x32_bf16 v[16:19], v[166:169], v[220:223], v[16:19]
	v_mfma_f32_16x16x32_bf16 v[4:7], v[148:151], v[228:231], v[4:7]
	v_mfma_f32_16x16x32_bf16 v[0:3], v[166:169], v[228:231], v[0:3]
	s_barrier
	s_cmp_lg_u32 s99, 0
	s_cbranch_scc1 .Lpeelx_15
.LBB0_1224:
	v_add_u32_e32 v140, s62, v199
	v_add_u32_e32 v166, s45, v199
	ds_read_b128 v[128:131], v140
	ds_read_b128 v[132:135], v140 offset:1024
	ds_read_b128 v[136:139], v140 offset:2048
	ds_read_b128 v[140:143], v140 offset:3072
	ds_read_b128 v[144:147], v166
	ds_read_b128 v[148:151], v166 offset:1024
	ds_read_b128 v[152:155], v166 offset:2048
	ds_read_b128 v[166:169], v166 offset:3072
	v_lshl_add_u64 v[178:179], s[26:27], 0, v[162:163]
	s_add_i32 m0, s35, 0xc000
	ds_read_b128 v[170:173], v206
	ds_read_b128 v[174:177], v206 offset:1024
	ds_read_b128 v[194:197], v206 offset:2048
	ds_read_b128 v[208:211], v206 offset:3072
	ds_read_b128 v[212:215], v206 offset:4096
	ds_read_b128 v[220:223], v206 offset:5120
	ds_read_b128 v[224:227], v206 offset:6144
	ds_read_b128 v[228:231], v206 offset:7168
	global_load_lds_dwordx4 v[178:179], off
	v_lshl_add_u64 v[178:179], s[26:27], 0, v[164:165]
	s_add_i32 m0, s35, 0xe000
	s_nop 0
	global_load_lds_dwordx4 v[178:179], off
	s_waitcnt vmcnt(8)
	s_waitcnt lgkmcnt(0)
	s_barrier
	s_waitcnt lgkmcnt(0)
	v_mfma_f32_16x16x32_bf16 v[120:123], v[128:131], v[170:173], v[120:123]
	v_mfma_f32_16x16x32_bf16 v[124:127], v[136:139], v[170:173], v[124:127]
	v_mfma_f32_16x16x32_bf16 v[108:111], v[128:131], v[194:197], v[108:111]
	v_mfma_f32_16x16x32_bf16 v[104:107], v[136:139], v[194:197], v[104:107]
	v_mfma_f32_16x16x32_bf16 v[92:95], v[128:131], v[212:215], v[92:95]
	v_mfma_f32_16x16x32_bf16 v[88:91], v[136:139], v[212:215], v[88:91]
	v_mfma_f32_16x16x32_bf16 v[76:79], v[128:131], v[224:227], v[76:79]
	v_mfma_f32_16x16x32_bf16 v[72:75], v[136:139], v[224:227], v[72:75]
	v_mfma_f32_16x16x32_bf16 v[120:123], v[132:135], v[174:177], v[120:123]
	v_mfma_f32_16x16x32_bf16 v[124:127], v[140:143], v[174:177], v[124:127]
	v_mfma_f32_16x16x32_bf16 v[108:111], v[132:135], v[208:211], v[108:111]
	v_mfma_f32_16x16x32_bf16 v[104:107], v[140:143], v[208:211], v[104:107]
	v_mfma_f32_16x16x32_bf16 v[92:95], v[132:135], v[220:223], v[92:95]
	v_mfma_f32_16x16x32_bf16 v[88:91], v[140:143], v[220:223], v[88:91]
	v_mfma_f32_16x16x32_bf16 v[76:79], v[132:135], v[228:231], v[76:79]
	v_mfma_f32_16x16x32_bf16 v[72:75], v[140:143], v[228:231], v[72:75]
	v_mfma_f32_16x16x32_bf16 v[116:119], v[144:147], v[170:173], v[116:119]
	v_mfma_f32_16x16x32_bf16 v[112:115], v[152:155], v[170:173], v[112:115]
	v_mfma_f32_16x16x32_bf16 v[100:103], v[144:147], v[194:197], v[100:103]
	v_mfma_f32_16x16x32_bf16 v[96:99], v[152:155], v[194:197], v[96:99]
	v_mfma_f32_16x16x32_bf16 v[84:87], v[144:147], v[212:215], v[84:87]
	v_mfma_f32_16x16x32_bf16 v[80:83], v[152:155], v[212:215], v[80:83]
	v_mfma_f32_16x16x32_bf16 v[68:71], v[144:147], v[224:227], v[68:71]
	v_mfma_f32_16x16x32_bf16 v[64:67], v[152:155], v[224:227], v[64:67]
	v_mfma_f32_16x16x32_bf16 v[116:119], v[148:151], v[174:177], v[116:119]
	v_mfma_f32_16x16x32_bf16 v[112:115], v[166:169], v[174:177], v[112:115]
	v_mfma_f32_16x16x32_bf16 v[100:103], v[148:151], v[208:211], v[100:103]
	v_mfma_f32_16x16x32_bf16 v[96:99], v[166:169], v[208:211], v[96:99]
	v_mfma_f32_16x16x32_bf16 v[84:87], v[148:151], v[220:223], v[84:87]
	v_mfma_f32_16x16x32_bf16 v[80:83], v[166:169], v[220:223], v[80:83]
	v_mfma_f32_16x16x32_bf16 v[68:71], v[148:151], v[228:231], v[68:71]
	v_mfma_f32_16x16x32_bf16 v[64:67], v[166:169], v[228:231], v[64:67]
	s_barrier
	s_add_i32 s62, s62, s34
	v_lshl_add_u64 v[178:179], s[60:61], 0, v[180:181]
	s_mov_b32 m0, s62
	ds_read_b128 v[170:173], v206 offset:16384
	ds_read_b128 v[174:177], v206 offset:17408
	ds_read_b128 v[194:197], v206 offset:18432
	ds_read_b128 v[208:211], v206 offset:19456
	ds_read_b128 v[212:215], v206 offset:20480
	ds_read_b128 v[220:223], v206 offset:21504
	ds_read_b128 v[224:227], v206 offset:22528
	ds_read_b128 v[228:231], v206 offset:23552
	global_load_lds_dwordx4 v[178:179], off
	s_add_i32 m0, s62, 0x2000
	v_lshl_add_u64 v[202:203], s[60:61], 0, v[156:157]
	s_add_u32 s60, s60, s6
	s_addc_u32 s61, s61, s7
	s_add_i32 s45, s45, s34
	global_load_lds_dwordx4 v[202:203], off
	v_lshl_add_u64 v[216:217], s[60:61], 0, v[180:181]
	s_mov_b32 m0, s45
	v_lshl_add_u64 v[232:233], s[60:61], 0, v[156:157]
	global_load_lds_dwordx4 v[216:217], off
	s_add_i32 m0, s45, 0x2000
	v_lshl_add_u64 v[234:235], s[28:29], 0, v[160:161]
	global_load_lds_dwordx4 v[232:233], off
	s_mov_b32 m0, s35
	v_lshl_add_u64 v[236:237], s[28:29], 0, v[158:159]
	global_load_lds_dwordx4 v[234:235], off
	s_mov_b32 m0, s36
	s_nop 0
	global_load_lds_dwordx4 v[236:237], off
	s_waitcnt vmcnt(8)
	s_waitcnt lgkmcnt(0)
	s_barrier
	s_waitcnt lgkmcnt(0)
	v_mfma_f32_16x16x32_bf16 v[60:63], v[128:131], v[170:173], v[60:63]
	v_mfma_f32_16x16x32_bf16 v[56:59], v[136:139], v[170:173], v[56:59]
	v_mfma_f32_16x16x32_bf16 v[44:47], v[128:131], v[194:197], v[44:47]
	v_mfma_f32_16x16x32_bf16 v[40:43], v[136:139], v[194:197], v[40:43]
	v_mfma_f32_16x16x32_bf16 v[28:31], v[128:131], v[212:215], v[28:31]
	v_mfma_f32_16x16x32_bf16 v[24:27], v[136:139], v[212:215], v[24:27]
	v_mfma_f32_16x16x32_bf16 v[12:15], v[128:131], v[224:227], v[12:15]
	v_mfma_f32_16x16x32_bf16 v[8:11], v[136:139], v[224:227], v[8:11]
	v_mfma_f32_16x16x32_bf16 v[60:63], v[132:135], v[174:177], v[60:63]
	v_mfma_f32_16x16x32_bf16 v[56:59], v[140:143], v[174:177], v[56:59]
	v_mfma_f32_16x16x32_bf16 v[44:47], v[132:135], v[208:211], v[44:47]
	v_mfma_f32_16x16x32_bf16 v[40:43], v[140:143], v[208:211], v[40:43]
	v_mfma_f32_16x16x32_bf16 v[28:31], v[132:135], v[220:223], v[28:31]
	v_mfma_f32_16x16x32_bf16 v[24:27], v[140:143], v[220:223], v[24:27]
	v_mfma_f32_16x16x32_bf16 v[12:15], v[132:135], v[228:231], v[12:15]
	v_mfma_f32_16x16x32_bf16 v[8:11], v[140:143], v[228:231], v[8:11]
	v_mfma_f32_16x16x32_bf16 v[52:55], v[144:147], v[170:173], v[52:55]
	v_mfma_f32_16x16x32_bf16 v[48:51], v[152:155], v[170:173], v[48:51]
	v_mfma_f32_16x16x32_bf16 v[36:39], v[144:147], v[194:197], v[36:39]
	v_mfma_f32_16x16x32_bf16 v[32:35], v[152:155], v[194:197], v[32:35]
	v_mfma_f32_16x16x32_bf16 v[20:23], v[144:147], v[212:215], v[20:23]
	v_mfma_f32_16x16x32_bf16 v[16:19], v[152:155], v[212:215], v[16:19]
	v_mfma_f32_16x16x32_bf16 v[4:7], v[144:147], v[224:227], v[4:7]
	v_mfma_f32_16x16x32_bf16 v[0:3], v[152:155], v[224:227], v[0:3]
	v_mfma_f32_16x16x32_bf16 v[52:55], v[148:151], v[174:177], v[52:55]
	v_mfma_f32_16x16x32_bf16 v[48:51], v[166:169], v[174:177], v[48:51]
	v_mfma_f32_16x16x32_bf16 v[36:39], v[148:151], v[208:211], v[36:39]
	v_mfma_f32_16x16x32_bf16 v[32:35], v[166:169], v[208:211], v[32:35]
	v_mfma_f32_16x16x32_bf16 v[20:23], v[148:151], v[220:223], v[20:23]
	v_mfma_f32_16x16x32_bf16 v[16:19], v[166:169], v[220:223], v[16:19]
	v_mfma_f32_16x16x32_bf16 v[4:7], v[148:151], v[228:231], v[4:7]
	v_mfma_f32_16x16x32_bf16 v[0:3], v[166:169], v[228:231], v[0:3]
	s_barrier
	s_add_i32 s45, 0, 0x18000
	s_add_i32 s60, 0, 0x1c000
	v_add_u32_e32 v140, s45, v199
	v_add_u32_e32 v166, s60, v199
	ds_read_b128 v[128:131], v140
	ds_read_b128 v[132:135], v140 offset:1024
	ds_read_b128 v[136:139], v140 offset:2048
	ds_read_b128 v[140:143], v140 offset:3072
	ds_read_b128 v[144:147], v166
	ds_read_b128 v[148:151], v166 offset:1024
	ds_read_b128 v[152:155], v166 offset:2048
	ds_read_b128 v[166:169], v166 offset:3072
	s_add_u32 s28, s28, s6
	s_addc_u32 s29, s29, s7
	s_mov_b32 m0, s37
	v_lshl_add_u64 v[238:239], s[28:29], 0, v[160:161]
	ds_read_b128 v[170:173], v206 offset:32768
	ds_read_b128 v[174:177], v206 offset:33792
	ds_read_b128 v[194:197], v206 offset:34816
	ds_read_b128 v[208:211], v206 offset:35840
	ds_read_b128 v[212:215], v206 offset:36864
	ds_read_b128 v[220:223], v206 offset:37888
	ds_read_b128 v[224:227], v206 offset:38912
	ds_read_b128 v[228:231], v206 offset:39936
	global_load_lds_dwordx4 v[238:239], off
	v_lshl_add_u64 v[238:239], s[28:29], 0, v[158:159]
	s_mov_b32 m0, s38
	s_nop 0
	global_load_lds_dwordx4 v[238:239], off
	s_waitcnt vmcnt(8)
	s_waitcnt lgkmcnt(0)
	s_barrier
	s_waitcnt lgkmcnt(0)
	v_mfma_f32_16x16x32_bf16 v[120:123], v[128:131], v[170:173], v[120:123]
	v_mfma_f32_16x16x32_bf16 v[124:127], v[136:139], v[170:173], v[124:127]
	v_mfma_f32_16x16x32_bf16 v[108:111], v[128:131], v[194:197], v[108:111]
	v_mfma_f32_16x16x32_bf16 v[104:107], v[136:139], v[194:197], v[104:107]
	v_mfma_f32_16x16x32_bf16 v[92:95], v[128:131], v[212:215], v[92:95]
	v_mfma_f32_16x16x32_bf16 v[88:91], v[136:139], v[212:215], v[88:91]
	v_mfma_f32_16x16x32_bf16 v[76:79], v[128:131], v[224:227], v[76:79]
	v_mfma_f32_16x16x32_bf16 v[72:75], v[136:139], v[224:227], v[72:75]
	v_mfma_f32_16x16x32_bf16 v[120:123], v[132:135], v[174:177], v[120:123]
	v_mfma_f32_16x16x32_bf16 v[124:127], v[140:143], v[174:177], v[124:127]
	v_mfma_f32_16x16x32_bf16 v[108:111], v[132:135], v[208:211], v[108:111]
	v_mfma_f32_16x16x32_bf16 v[104:107], v[140:143], v[208:211], v[104:107]
	v_mfma_f32_16x16x32_bf16 v[92:95], v[132:135], v[220:223], v[92:95]
	v_mfma_f32_16x16x32_bf16 v[88:91], v[140:143], v[220:223], v[88:91]
	v_mfma_f32_16x16x32_bf16 v[76:79], v[132:135], v[228:231], v[76:79]
	v_mfma_f32_16x16x32_bf16 v[72:75], v[140:143], v[228:231], v[72:75]
	v_mfma_f32_16x16x32_bf16 v[116:119], v[144:147], v[170:173], v[116:119]
	v_mfma_f32_16x16x32_bf16 v[112:115], v[152:155], v[170:173], v[112:115]
	v_mfma_f32_16x16x32_bf16 v[100:103], v[144:147], v[194:197], v[100:103]
	v_mfma_f32_16x16x32_bf16 v[96:99], v[152:155], v[194:197], v[96:99]
	v_mfma_f32_16x16x32_bf16 v[84:87], v[144:147], v[212:215], v[84:87]
	v_mfma_f32_16x16x32_bf16 v[80:83], v[152:155], v[212:215], v[80:83]
	v_mfma_f32_16x16x32_bf16 v[68:71], v[144:147], v[224:227], v[68:71]
	v_mfma_f32_16x16x32_bf16 v[64:67], v[152:155], v[224:227], v[64:67]
	v_mfma_f32_16x16x32_bf16 v[116:119], v[148:151], v[174:177], v[116:119]
	v_mfma_f32_16x16x32_bf16 v[112:115], v[166:169], v[174:177], v[112:115]
	v_mfma_f32_16x16x32_bf16 v[100:103], v[148:151], v[208:211], v[100:103]
	v_mfma_f32_16x16x32_bf16 v[96:99], v[166:169], v[208:211], v[96:99]
	v_mfma_f32_16x16x32_bf16 v[84:87], v[148:151], v[220:223], v[84:87]
	v_mfma_f32_16x16x32_bf16 v[80:83], v[166:169], v[220:223], v[80:83]
	v_mfma_f32_16x16x32_bf16 v[68:71], v[148:151], v[228:231], v[68:71]
	v_mfma_f32_16x16x32_bf16 v[64:67], v[166:169], v[228:231], v[64:67]
	s_barrier
	s_add_i32 s28, s45, s34
	v_lshl_add_u64 v[178:179], v[178:179], 0, s[12:13]
	s_mov_b32 m0, s28
	ds_read_b128 v[170:173], v206 offset:49152
	ds_read_b128 v[174:177], v206 offset:50176
	ds_read_b128 v[194:197], v206 offset:51200
	ds_read_b128 v[208:211], v206 offset:52224
	ds_read_b128 v[212:215], v206 offset:53248
	ds_read_b128 v[220:223], v206 offset:54272
	ds_read_b128 v[224:227], v206 offset:55296
	ds_read_b128 v[228:231], v206 offset:56320
	global_load_lds_dwordx4 v[178:179], off
	v_lshl_add_u64 v[178:179], v[202:203], 0, s[12:13]
	s_add_i32 m0, s28, 0x2000
	s_add_i32 s28, s60, s34
	global_load_lds_dwordx4 v[178:179], off
	v_lshl_add_u64 v[178:179], v[216:217], 0, s[12:13]
	s_mov_b32 m0, s28
	s_nop 0
	global_load_lds_dwordx4 v[178:179], off
	v_lshl_add_u64 v[178:179], v[232:233], 0, s[12:13]
	s_add_i32 m0, s28, 0x2000
	s_nop 0
	global_load_lds_dwordx4 v[178:179], off
	v_lshl_add_u64 v[178:179], v[234:235], 0, s[12:13]
	s_mov_b32 m0, s47
	s_nop 0
	global_load_lds_dwordx4 v[178:179], off
	v_lshl_add_u64 v[178:179], v[236:237], 0, s[12:13]
	s_mov_b32 m0, s48
	s_nop 0
	global_load_lds_dwordx4 v[178:179], off
	s_waitcnt vmcnt(8)
	s_waitcnt lgkmcnt(0)
	s_barrier
	s_waitcnt lgkmcnt(0)
	v_mfma_f32_16x16x32_bf16 v[60:63], v[128:131], v[170:173], v[60:63]
	s_add_u32 s26, s26, 0x100
	v_mfma_f32_16x16x32_bf16 v[56:59], v[136:139], v[170:173], v[56:59]
	s_addc_u32 s27, s27, 0
	v_mfma_f32_16x16x32_bf16 v[44:47], v[128:131], v[194:197], v[44:47]
	s_add_u32 s10, s10, 0x100
	v_mfma_f32_16x16x32_bf16 v[40:43], v[136:139], v[194:197], v[40:43]
	s_addc_u32 s11, s11, 0
	v_mfma_f32_16x16x32_bf16 v[28:31], v[128:131], v[212:215], v[28:31]
	s_mov_b32 s28, s44
	v_mfma_f32_16x16x32_bf16 v[24:27], v[136:139], v[212:215], v[24:27]
	s_cmp_ge_i32 s44, s46
	v_mfma_f32_16x16x32_bf16 v[12:15], v[128:131], v[224:227], v[12:15]
	s_cselect_b32 s99, 1, 0
	v_mfma_f32_16x16x32_bf16 v[8:11], v[136:139], v[224:227], v[8:11]
	s_add_i32 s44, s28, 2
	v_mfma_f32_16x16x32_bf16 v[60:63], v[132:135], v[174:177], v[60:63]
	s_add_u32 s45, s26, 0x80
	v_mfma_f32_16x16x32_bf16 v[56:59], v[140:143], v[174:177], v[56:59]
	s_addc_u32 s29, s27, 0
	v_mfma_f32_16x16x32_bf16 v[44:47], v[132:135], v[208:211], v[44:47]
	s_add_i32 s62, 0, 0x10000
	v_mfma_f32_16x16x32_bf16 v[40:43], v[140:143], v[208:211], v[40:43]
	s_cmp_eq_u32 s49, s28
	v_mfma_f32_16x16x32_bf16 v[28:31], v[132:135], v[220:223], v[28:31]
	s_cselect_b32 s29, s23, s29
	v_mfma_f32_16x16x32_bf16 v[24:27], v[140:143], v[220:223], v[24:27]
	s_cselect_b32 s28, s22, s45
	v_mfma_f32_16x16x32_bf16 v[12:15], v[132:135], v[228:231], v[12:15]
	s_cselect_b32 s61, s25, s11
	v_mfma_f32_16x16x32_bf16 v[8:11], v[140:143], v[228:231], v[8:11]
	s_cselect_b32 s60, s24, s10
	v_mfma_f32_16x16x32_bf16 v[52:55], v[144:147], v[170:173], v[52:55]
	s_add_i32 s45, 0, 0x14000
	v_mfma_f32_16x16x32_bf16 v[48:51], v[152:155], v[170:173], v[48:51]
	v_mfma_f32_16x16x32_bf16 v[36:39], v[144:147], v[194:197], v[36:39]
	v_mfma_f32_16x16x32_bf16 v[32:35], v[152:155], v[194:197], v[32:35]
	v_mfma_f32_16x16x32_bf16 v[20:23], v[144:147], v[212:215], v[20:23]
	v_mfma_f32_16x16x32_bf16 v[16:19], v[152:155], v[212:215], v[16:19]
	v_mfma_f32_16x16x32_bf16 v[4:7], v[144:147], v[224:227], v[4:7]
	v_mfma_f32_16x16x32_bf16 v[0:3], v[152:155], v[224:227], v[0:3]
	v_mfma_f32_16x16x32_bf16 v[52:55], v[148:151], v[174:177], v[52:55]
	v_mfma_f32_16x16x32_bf16 v[48:51], v[166:169], v[174:177], v[48:51]
	v_mfma_f32_16x16x32_bf16 v[36:39], v[148:151], v[208:211], v[36:39]
	v_mfma_f32_16x16x32_bf16 v[32:35], v[166:169], v[208:211], v[32:35]
	v_mfma_f32_16x16x32_bf16 v[20:23], v[148:151], v[220:223], v[20:23]
	v_mfma_f32_16x16x32_bf16 v[16:19], v[166:169], v[220:223], v[16:19]
	v_mfma_f32_16x16x32_bf16 v[4:7], v[148:151], v[228:231], v[4:7]
	v_mfma_f32_16x16x32_bf16 v[0:3], v[166:169], v[228:231], v[0:3]
	s_barrier
	s_cmp_lg_u32 s99, 0
	s_cbranch_scc0 .LBB0_1224
